# de-serialised EpiRes epilogues (residual loads hoisted, counted vmcnt) for out0/dn0/out1/dn1; EpiUp dead DPP-init movs removed; s1/s3 pipelined
# speedup vs baseline: 1.0126x; 1.0126x over previous
; DI unsigned pk2(float lo, float hi) { f32x2 v = {lo, hi}; bf16x2_t b = __builtin_convertvector(v, bf16x2_t); return __builtin_bit_cast(unsigned, b); }
; DI float bflo(unsigned u) { return __uint_as_float(u << 16); }
; DI float bfhi(unsigned u) { return __uint_as_float(u & 0xffff0000u); }
; DI u64 ss_to_fix(float ss) { return (u64)(ss * 1048576.f); }
;     DI void operator()(const AccT& acc, const Unit& u, int wr, int wc, int fr, int fq) const {
;         const int row0 = u.pm * 256 + wr * 64 + fr, col0 = u.pn * 256 + wc * 32 + 8 * fq;
; #pragma unroll
;         for (int ai = 0; ai < 2; ++ai)
; #pragma unroll
;             for (int m = 0; m < 4; ++m) { const int t = row0 + ai * 128 + m * 16; float ss = 0.f;
; #pragma unroll
;                 for (int bj = 0; bj < 2; ++bj) { const size_t o = (size_t)t * 1024 + col0 + bj * 128;
;                     f32x4 r0, r1;
;                     if (RESBF) { const u32x4 rb = *(const u32x4*)(XB + o); r0 = (f32x4){bflo(rb.x), bfhi(rb.x), bflo(rb.y), bfhi(rb.y)}; r1 = (f32x4){bflo(rb.z), bfhi(rb.z), bflo(rb.w), bfhi(rb.w)}; }
;                     else { r0 = __builtin_nontemporal_load((const f32x4*)(res + o)); r1 = __builtin_nontemporal_load((const f32x4*)(res + o + 4)); }
;                     const f32x4 v0 = acc[ai][bj][m][0] + r0, v1 = acc[ai][bj][m][1] + r1;
;                     u32x4 w; w.x = pk2(v0[0], v0[1]); w.y = pk2(v0[2], v0[3]); w.z = pk2(v1[0], v1[1]); w.w = pk2(v1[2], v1[3]);
;                     if (!dry) *(u32x4*)(XB + o) = w;
;                     ss += v0[0] * v0[0] + v0[1] * v0[1] + v0[2] * v0[2] + v0[3] * v0[3] + v1[0] * v1[0] + v1[1] * v1[1] + v1[2] * v1[2] + v1[3] * v1[3]; }
;                 { const auto r16 = __builtin_amdgcn_permlane16_swap(__float_as_uint(ss), __float_as_uint(ss), false, false); ss = __uint_as_float(r16[0]) + __uint_as_float(r16[1]);
;                   const auto r32 = __builtin_amdgcn_permlane32_swap(__float_as_uint(ss), __float_as_uint(ss), false, false); ss = __uint_as_float(r32[0]) + __uint_as_float(r32[1]); }
;                 if (fq == 0 && !dry) atomicAdd(rowss + t, ss_to_fix(ss)); }
.LBB0_1023:
	v_lshl_add_u32 v146, s26, 8, v148
	v_lshl_or_b32 v144, s28, 8, v150
	v_ashrrev_i32_e32 v147, 31, v146
	v_ashrrev_i32_e32 v145, 31, v144
	v_lshlrev_b64 v[154:155], 10, v[146:147]
	v_lshl_add_u64 v[162:163], v[154:155], 0, v[144:145]
	v_lshl_add_u64 v[164:165], v[162:163], 2, s[0:1]
	v_mov_b32_e32 v168, v146
	v_ashrrev_i32_e32 v169, 31, v168
	v_lshlrev_b64 v[170:171], 10, v[168:169]
	v_lshl_add_u64 v[170:171], v[170:171], 0, v[144:145]
	v_lshl_add_u64 v[172:173], v[170:171], 2, s[0:1]
	global_load_dwordx4 v[174:177], v[172:173], off nt
	global_load_dwordx4 v[178:181], v[172:173], off offset:16 nt
	global_load_dwordx4 v[182:185], v[172:173], off offset:512 nt
	global_load_dwordx4 v[186:189], v[172:173], off offset:528 nt
	v_add_u32_e32 v168, 0x10, v146
	v_ashrrev_i32_e32 v169, 31, v168
	v_lshlrev_b64 v[170:171], 10, v[168:169]
	v_lshl_add_u64 v[170:171], v[170:171], 0, v[144:145]
	v_lshl_add_u64 v[172:173], v[170:171], 2, s[0:1]
	global_load_dwordx4 v[200:203], v[172:173], off nt
	global_load_dwordx4 v[204:207], v[172:173], off offset:16 nt
	global_load_dwordx4 v[208:211], v[172:173], off offset:512 nt
	global_load_dwordx4 v[212:215], v[172:173], off offset:528 nt
	v_add_u32_e32 v168, 0x20, v146
	v_ashrrev_i32_e32 v169, 31, v168
	v_lshlrev_b64 v[170:171], 10, v[168:169]
	v_lshl_add_u64 v[170:171], v[170:171], 0, v[144:145]
	v_lshl_add_u64 v[172:173], v[170:171], 2, s[0:1]
	global_load_dwordx4 v[216:219], v[172:173], off nt
	global_load_dwordx4 v[220:223], v[172:173], off offset:16 nt
	global_load_dwordx4 v[224:227], v[172:173], off offset:512 nt
	global_load_dwordx4 v[228:231], v[172:173], off offset:528 nt
	v_add_u32_e32 v168, 0x30, v146
	v_ashrrev_i32_e32 v169, 31, v168
	v_lshlrev_b64 v[170:171], 10, v[168:169]
	v_lshl_add_u64 v[170:171], v[170:171], 0, v[144:145]
	v_lshl_add_u64 v[172:173], v[170:171], 2, s[0:1]
	global_load_dwordx4 v[232:235], v[172:173], off nt
	global_load_dwordx4 v[236:239], v[172:173], off offset:16 nt
	global_load_dwordx4 v[242:245], v[172:173], off offset:512 nt
	global_load_dwordx4 v[246:249], v[172:173], off offset:528 nt
	s_nop 0
	s_nop 0
	v_lshlrev_b64 v[162:163], 1, v[162:163]
	v_lshl_add_u64 v[166:167], s[4:5], 0, v[162:163]
	v_or_b32_e32 v162, 0x100, v162
	v_lshl_add_u64 v[162:163], s[4:5], 0, v[162:163]
	s_waitcnt vmcnt(14)
	v_mov_b32_e32 v154, v174
	v_mov_b32_e32 v155, v175
	v_mov_b32_e32 v156, v176
	v_mov_b32_e32 v157, v177
	v_mov_b32_e32 v158, v178
	v_mov_b32_e32 v159, v179
	v_mov_b32_e32 v160, v180
	v_mov_b32_e32 v161, v181
	v_pk_add_f32 v[156:157], v[122:123], v[156:157]
	v_pk_add_f32 v[154:155], v[120:121], v[154:155]
	v_pk_add_f32 v[160:161], v[126:127], v[160:161]
	v_pk_add_f32 v[158:159], v[124:125], v[158:159]
	v_cvt_pk_bf16_f32 v120, v154, v155
	v_cvt_pk_bf16_f32 v121, v156, v157
	v_cvt_pk_bf16_f32 v122, v158, v159
	v_cvt_pk_bf16_f32 v123, v160, v161
	global_store_dwordx4 v[166:167], v[120:123], off
	s_nop 0
	s_nop 0
	s_nop 0
	v_mul_f32_e32 v155, v155, v155
	v_fmac_f32_e32 v155, v154, v154
	v_fmac_f32_e32 v155, v156, v156
	v_fmac_f32_e32 v155, v157, v157
	v_fmac_f32_e32 v155, v158, v158
	v_fmac_f32_e32 v155, v159, v159
	v_fmac_f32_e32 v155, v160, v160
	v_fmac_f32_e32 v155, v161, v161
	s_waitcnt vmcnt(13)
	v_mov_b32_e32 v120, v182
	v_mov_b32_e32 v121, v183
	v_mov_b32_e32 v122, v184
	v_mov_b32_e32 v123, v185
	v_mov_b32_e32 v124, v186
	v_mov_b32_e32 v125, v187
	v_mov_b32_e32 v126, v188
	v_mov_b32_e32 v127, v189
	v_pk_add_f32 v[116:117], v[116:117], v[120:121]
	v_pk_add_f32 v[118:119], v[118:119], v[122:123]
	v_pk_add_f32 v[122:123], v[112:113], v[124:125]
	v_cvt_pk_bf16_f32 v112, v116, v117
	v_mul_f32_e32 v117, v117, v117
	v_fmac_f32_e32 v117, v116, v116
	v_fmac_f32_e32 v117, v118, v118
	v_fmac_f32_e32 v117, v119, v119
	v_fmac_f32_e32 v117, v122, v122
	v_pk_add_f32 v[120:121], v[114:115], v[126:127]
	v_fmac_f32_e32 v117, v123, v123
	v_fmac_f32_e32 v117, v120, v120
	v_cvt_pk_bf16_f32 v113, v118, v119
	v_cvt_pk_bf16_f32 v114, v122, v123
	v_cvt_pk_bf16_f32 v115, v120, v121
	v_fmac_f32_e32 v117, v121, v121
	global_store_dwordx4 v[162:163], v[112:115], off
	s_nop 1
	v_add_f32_e32 v112, v155, v117
	v_mov_b32_e32 v113, v112
	s_nop 1
	v_permlane16_swap_b32_e32 v112, v113
	v_add_f32_e32 v112, v112, v113
	v_mov_b32_e32 v113, v112
	s_nop 1
	v_permlane32_swap_b32_e32 v112, v113
	s_and_saveexec_b64 s[26:27], s[6:7]
	s_cbranch_execz .LBB0_1025
	v_add_f32_e32 v112, v112, v113
	v_mul_f32_e32 v112, 0x49800000, v112
	v_trunc_f32_e32 v112, v112
	v_mul_f32_e32 v113, 0x2f800000, v112
	v_floor_f32_e32 v113, v113
	v_fmac_f32_e32 v112, 0xcf800000, v113
	v_cvt_u32_f32_e32 v112, v112
	v_cvt_u32_f32_e32 v113, v113
	v_lshl_add_u64 v[114:115], v[146:147], 3, s[10:11]
	global_atomic_add_x2 v[114:115], v[112:113], off
; DI unsigned pk2(float lo, float hi) { f32x2 v = {lo, hi}; bf16x2_t b = __builtin_convertvector(v, bf16x2_t); return __builtin_bit_cast(unsigned, b); }
; DI float bflo(unsigned u) { return __uint_as_float(u << 16); }
; DI float bfhi(unsigned u) { return __uint_as_float(u & 0xffff0000u); }
; DI u64 ss_to_fix(float ss) { return (u64)(ss * 1048576.f); }
;     DI void operator()(const AccT& acc, const Unit& u, int wr, int wc, int fr, int fq) const {
;         const int row0 = u.pm * 256 + wr * 64 + fr, col0 = u.pn * 256 + wc * 32 + 8 * fq;
; #pragma unroll
;         for (int ai = 0; ai < 2; ++ai)
; #pragma unroll
;             for (int m = 0; m < 4; ++m) { const int t = row0 + ai * 128 + m * 16; float ss = 0.f;
; #pragma unroll
;                 for (int bj = 0; bj < 2; ++bj) { const size_t o = (size_t)t * 1024 + col0 + bj * 128;
;                     f32x4 r0, r1;
;                     if (RESBF) { const u32x4 rb = *(const u32x4*)(XB + o); r0 = (f32x4){bflo(rb.x), bfhi(rb.x), bflo(rb.y), bfhi(rb.y)}; r1 = (f32x4){bflo(rb.z), bfhi(rb.z), bflo(rb.w), bfhi(rb.w)}; }
;                     else { r0 = __builtin_nontemporal_load((const f32x4*)(res + o)); r1 = __builtin_nontemporal_load((const f32x4*)(res + o + 4)); }
;                     const f32x4 v0 = acc[ai][bj][m][0] + r0, v1 = acc[ai][bj][m][1] + r1;
;                     u32x4 w; w.x = pk2(v0[0], v0[1]); w.y = pk2(v0[2], v0[3]); w.z = pk2(v1[0], v1[1]); w.w = pk2(v1[2], v1[3]);
;                     if (!dry) *(u32x4*)(XB + o) = w;
;                     ss += v0[0] * v0[0] + v0[1] * v0[1] + v0[2] * v0[2] + v0[3] * v0[3] + v1[0] * v1[0] + v1[1] * v1[1] + v1[2] * v1[2] + v1[3] * v1[3]; }
;                 { const auto r16 = __builtin_amdgcn_permlane16_swap(__float_as_uint(ss), __float_as_uint(ss), false, false); ss = __uint_as_float(r16[0]) + __uint_as_float(r16[1]);
;                   const auto r32 = __builtin_amdgcn_permlane32_swap(__float_as_uint(ss), __float_as_uint(ss), false, false); ss = __uint_as_float(r32[0]) + __uint_as_float(r32[1]); }
;                 if (fq == 0 && !dry) atomicAdd(rowss + t, ss_to_fix(ss)); }
.LBB0_1025:
	s_or_b64 exec, exec, s[26:27]
	v_or_b32_e32 v112, 16, v146
	v_ashrrev_i32_e32 v113, 31, v112
	v_lshlrev_b64 v[114:115], 10, v[112:113]
	v_lshl_add_u64 v[122:123], v[114:115], 0, v[144:145]
	v_lshl_add_u64 v[124:125], v[122:123], 2, s[0:1]
	s_nop 0
	s_nop 0
	v_lshlrev_b64 v[122:123], 1, v[122:123]
	v_lshl_add_u64 v[126:127], s[4:5], 0, v[122:123]
	v_or_b32_e32 v122, 0x100, v122
	v_lshl_add_u64 v[122:123], s[4:5], 0, v[122:123]
	s_waitcnt vmcnt(12)
	v_mov_b32_e32 v114, v200
	v_mov_b32_e32 v115, v201
	v_mov_b32_e32 v116, v202
	v_mov_b32_e32 v117, v203
	v_mov_b32_e32 v118, v204
	v_mov_b32_e32 v119, v205
	v_mov_b32_e32 v120, v206
	v_mov_b32_e32 v121, v207
	v_pk_add_f32 v[116:117], v[110:111], v[116:117]
	v_pk_add_f32 v[114:115], v[108:109], v[114:115]
	v_pk_add_f32 v[120:121], v[106:107], v[120:121]
	v_pk_add_f32 v[118:119], v[104:105], v[118:119]
	v_cvt_pk_bf16_f32 v104, v114, v115
	v_cvt_pk_bf16_f32 v105, v116, v117
	v_cvt_pk_bf16_f32 v106, v118, v119
	v_cvt_pk_bf16_f32 v107, v120, v121
	global_store_dwordx4 v[126:127], v[104:107], off
	s_nop 0
	s_nop 0
	s_nop 0
	v_mul_f32_e32 v115, v115, v115
	v_fmac_f32_e32 v115, v114, v114
	v_fmac_f32_e32 v115, v116, v116
	v_fmac_f32_e32 v115, v117, v117
	v_fmac_f32_e32 v115, v118, v118
	v_fmac_f32_e32 v115, v119, v119
	v_fmac_f32_e32 v115, v120, v120
	v_fmac_f32_e32 v115, v121, v121
	s_waitcnt vmcnt(11)
	v_mov_b32_e32 v104, v208
	v_mov_b32_e32 v105, v209
	v_mov_b32_e32 v106, v210
	v_mov_b32_e32 v107, v211
	v_mov_b32_e32 v108, v212
	v_mov_b32_e32 v109, v213
	v_mov_b32_e32 v110, v214
	v_mov_b32_e32 v111, v215
	v_pk_add_f32 v[100:101], v[100:101], v[104:105]
	v_pk_add_f32 v[102:103], v[102:103], v[106:107]
	v_pk_add_f32 v[106:107], v[96:97], v[108:109]
	v_cvt_pk_bf16_f32 v96, v100, v101
	v_mul_f32_e32 v101, v101, v101
	v_fmac_f32_e32 v101, v100, v100
	v_fmac_f32_e32 v101, v102, v102
	v_fmac_f32_e32 v101, v103, v103
	v_fmac_f32_e32 v101, v106, v106
	v_pk_add_f32 v[104:105], v[98:99], v[110:111]
	v_fmac_f32_e32 v101, v107, v107
	v_fmac_f32_e32 v101, v104, v104
	v_cvt_pk_bf16_f32 v97, v102, v103
	v_cvt_pk_bf16_f32 v98, v106, v107
	v_cvt_pk_bf16_f32 v99, v104, v105
	v_fmac_f32_e32 v101, v105, v105
	global_store_dwordx4 v[122:123], v[96:99], off
	s_nop 1
	v_add_f32_e32 v96, v115, v101
	v_mov_b32_e32 v97, v96
	s_nop 1
	v_permlane16_swap_b32_e32 v96, v97
	v_add_f32_e32 v96, v96, v97
	v_mov_b32_e32 v97, v96
	s_nop 1
	v_permlane32_swap_b32_e32 v96, v97
	s_and_saveexec_b64 s[26:27], s[6:7]
	s_cbranch_execz .LBB0_1027
	v_add_f32_e32 v96, v96, v97
	v_mul_f32_e32 v96, 0x49800000, v96
	v_trunc_f32_e32 v96, v96
	v_mul_f32_e32 v97, 0x2f800000, v96
	v_floor_f32_e32 v97, v97
	v_fmac_f32_e32 v96, 0xcf800000, v97
	v_cvt_u32_f32_e32 v96, v96
	v_cvt_u32_f32_e32 v97, v97
	v_lshl_add_u64 v[98:99], v[112:113], 3, s[10:11]
	global_atomic_add_x2 v[98:99], v[96:97], off
.LBB0_1027:
	s_or_b64 exec, exec, s[26:27]
	v_or_b32_e32 v96, 32, v146
	v_ashrrev_i32_e32 v97, 31, v96
	v_lshlrev_b64 v[98:99], 10, v[96:97]
	v_lshl_add_u64 v[106:107], v[98:99], 0, v[144:145]
	v_lshl_add_u64 v[108:109], v[106:107], 2, s[0:1]
	s_nop 0
	s_nop 0
	v_lshlrev_b64 v[106:107], 1, v[106:107]
	v_lshl_add_u64 v[110:111], s[4:5], 0, v[106:107]
	v_or_b32_e32 v106, 0x100, v106
	v_lshl_add_u64 v[106:107], s[4:5], 0, v[106:107]
	s_waitcnt vmcnt(10)
	v_mov_b32_e32 v98, v216
	v_mov_b32_e32 v99, v217
	v_mov_b32_e32 v100, v218
	v_mov_b32_e32 v101, v219
	v_mov_b32_e32 v102, v220
	v_mov_b32_e32 v103, v221
	v_mov_b32_e32 v104, v222
	v_mov_b32_e32 v105, v223
	v_pk_add_f32 v[100:101], v[94:95], v[100:101]
	v_pk_add_f32 v[98:99], v[92:93], v[98:99]
	v_pk_add_f32 v[104:105], v[90:91], v[104:105]
	v_pk_add_f32 v[102:103], v[88:89], v[102:103]
	v_cvt_pk_bf16_f32 v88, v98, v99
	v_cvt_pk_bf16_f32 v89, v100, v101
	v_cvt_pk_bf16_f32 v90, v102, v103
	v_cvt_pk_bf16_f32 v91, v104, v105
	global_store_dwordx4 v[110:111], v[88:91], off
	s_nop 0
	s_nop 0
	s_nop 0
	v_mul_f32_e32 v99, v99, v99
	v_fmac_f32_e32 v99, v98, v98
	v_fmac_f32_e32 v99, v100, v100
	v_fmac_f32_e32 v99, v101, v101
	v_fmac_f32_e32 v99, v102, v102
	v_fmac_f32_e32 v99, v103, v103
	v_fmac_f32_e32 v99, v104, v104
	v_fmac_f32_e32 v99, v105, v105
	s_waitcnt vmcnt(9)
	v_mov_b32_e32 v88, v224
	v_mov_b32_e32 v89, v225
	v_mov_b32_e32 v90, v226
	v_mov_b32_e32 v91, v227
	v_mov_b32_e32 v92, v228
	v_mov_b32_e32 v93, v229
	v_mov_b32_e32 v94, v230
	v_mov_b32_e32 v95, v231
	v_pk_add_f32 v[84:85], v[84:85], v[88:89]
	v_pk_add_f32 v[86:87], v[86:87], v[90:91]
	v_pk_add_f32 v[90:91], v[80:81], v[92:93]
	v_cvt_pk_bf16_f32 v80, v84, v85
	v_mul_f32_e32 v85, v85, v85
	v_fmac_f32_e32 v85, v84, v84
	v_fmac_f32_e32 v85, v86, v86
	v_fmac_f32_e32 v85, v87, v87
	v_fmac_f32_e32 v85, v90, v90
	v_pk_add_f32 v[88:89], v[82:83], v[94:95]
	v_fmac_f32_e32 v85, v91, v91
	v_fmac_f32_e32 v85, v88, v88
	v_cvt_pk_bf16_f32 v81, v86, v87
	v_cvt_pk_bf16_f32 v82, v90, v91
	v_cvt_pk_bf16_f32 v83, v88, v89
	v_fmac_f32_e32 v85, v89, v89
	global_store_dwordx4 v[106:107], v[80:83], off
	s_nop 1
	v_add_f32_e32 v80, v99, v85
	v_mov_b32_e32 v81, v80
	s_nop 1
	v_permlane16_swap_b32_e32 v80, v81
	v_add_f32_e32 v80, v80, v81
	v_mov_b32_e32 v81, v80
	s_nop 1
	v_permlane32_swap_b32_e32 v80, v81
	s_and_saveexec_b64 s[26:27], s[6:7]
	s_cbranch_execz .LBB0_1029
	v_add_f32_e32 v80, v80, v81
	v_mul_f32_e32 v80, 0x49800000, v80
	v_trunc_f32_e32 v80, v80
	v_mul_f32_e32 v81, 0x2f800000, v80
	v_floor_f32_e32 v81, v81
	v_fmac_f32_e32 v80, 0xcf800000, v81
	v_cvt_u32_f32_e32 v80, v80
	v_cvt_u32_f32_e32 v81, v81
	v_lshl_add_u64 v[82:83], v[96:97], 3, s[10:11]
	global_atomic_add_x2 v[82:83], v[80:81], off
; DI unsigned pk2(float lo, float hi) { f32x2 v = {lo, hi}; bf16x2_t b = __builtin_convertvector(v, bf16x2_t); return __builtin_bit_cast(unsigned, b); }
; DI float bflo(unsigned u) { return __uint_as_float(u << 16); }
; DI float bfhi(unsigned u) { return __uint_as_float(u & 0xffff0000u); }
; DI u64 ss_to_fix(float ss) { return (u64)(ss * 1048576.f); }
;     DI void operator()(const AccT& acc, const Unit& u, int wr, int wc, int fr, int fq) const {
;         const int row0 = u.pm * 256 + wr * 64 + fr, col0 = u.pn * 256 + wc * 32 + 8 * fq;
; #pragma unroll
;         for (int ai = 0; ai < 2; ++ai)
; #pragma unroll
;             for (int m = 0; m < 4; ++m) { const int t = row0 + ai * 128 + m * 16; float ss = 0.f;
; #pragma unroll
;                 for (int bj = 0; bj < 2; ++bj) { const size_t o = (size_t)t * 1024 + col0 + bj * 128;
;                     f32x4 r0, r1;
;                     if (RESBF) { const u32x4 rb = *(const u32x4*)(XB + o); r0 = (f32x4){bflo(rb.x), bfhi(rb.x), bflo(rb.y), bfhi(rb.y)}; r1 = (f32x4){bflo(rb.z), bfhi(rb.z), bflo(rb.w), bfhi(rb.w)}; }
;                     else { r0 = __builtin_nontemporal_load((const f32x4*)(res + o)); r1 = __builtin_nontemporal_load((const f32x4*)(res + o + 4)); }
;                     const f32x4 v0 = acc[ai][bj][m][0] + r0, v1 = acc[ai][bj][m][1] + r1;
;                     u32x4 w; w.x = pk2(v0[0], v0[1]); w.y = pk2(v0[2], v0[3]); w.z = pk2(v1[0], v1[1]); w.w = pk2(v1[2], v1[3]);
;                     if (!dry) *(u32x4*)(XB + o) = w;
;                     ss += v0[0] * v0[0] + v0[1] * v0[1] + v0[2] * v0[2] + v0[3] * v0[3] + v1[0] * v1[0] + v1[1] * v1[1] + v1[2] * v1[2] + v1[3] * v1[3]; }
;                 { const auto r16 = __builtin_amdgcn_permlane16_swap(__float_as_uint(ss), __float_as_uint(ss), false, false); ss = __uint_as_float(r16[0]) + __uint_as_float(r16[1]);
;                   const auto r32 = __builtin_amdgcn_permlane32_swap(__float_as_uint(ss), __float_as_uint(ss), false, false); ss = __uint_as_float(r32[0]) + __uint_as_float(r32[1]); }
;                 if (fq == 0 && !dry) atomicAdd(rowss + t, ss_to_fix(ss)); }
.LBB0_1029:
	s_or_b64 exec, exec, s[26:27]
	v_or_b32_e32 v80, 48, v146
	v_ashrrev_i32_e32 v81, 31, v80
	v_lshlrev_b64 v[82:83], 10, v[80:81]
	v_lshl_add_u64 v[90:91], v[82:83], 0, v[144:145]
	v_lshl_add_u64 v[92:93], v[90:91], 2, s[0:1]
	s_nop 0
	s_nop 0
	v_lshlrev_b64 v[90:91], 1, v[90:91]
	v_lshl_add_u64 v[94:95], s[4:5], 0, v[90:91]
	v_or_b32_e32 v90, 0x100, v90
	v_lshl_add_u64 v[90:91], s[4:5], 0, v[90:91]
	s_waitcnt vmcnt(8)
	v_mov_b32_e32 v82, v232
	v_mov_b32_e32 v83, v233
	v_mov_b32_e32 v84, v234
	v_mov_b32_e32 v85, v235
	v_mov_b32_e32 v86, v236
	v_mov_b32_e32 v87, v237
	v_mov_b32_e32 v88, v238
	v_mov_b32_e32 v89, v239
	v_pk_add_f32 v[84:85], v[78:79], v[84:85]
	v_pk_add_f32 v[82:83], v[76:77], v[82:83]
	v_pk_add_f32 v[88:89], v[74:75], v[88:89]
	v_pk_add_f32 v[86:87], v[72:73], v[86:87]
	v_cvt_pk_bf16_f32 v72, v82, v83
	v_cvt_pk_bf16_f32 v73, v84, v85
	v_cvt_pk_bf16_f32 v74, v86, v87
	v_cvt_pk_bf16_f32 v75, v88, v89
	global_store_dwordx4 v[94:95], v[72:75], off
	s_nop 0
	s_nop 0
	s_nop 0
	v_mul_f32_e32 v83, v83, v83
	v_fmac_f32_e32 v83, v82, v82
	v_fmac_f32_e32 v83, v84, v84
	v_fmac_f32_e32 v83, v85, v85
	v_fmac_f32_e32 v83, v86, v86
	v_fmac_f32_e32 v83, v87, v87
	v_fmac_f32_e32 v83, v88, v88
	v_fmac_f32_e32 v83, v89, v89
	s_waitcnt vmcnt(7)
	v_mov_b32_e32 v72, v242
	v_mov_b32_e32 v73, v243
	v_mov_b32_e32 v74, v244
	v_mov_b32_e32 v75, v245
	v_mov_b32_e32 v76, v246
	v_mov_b32_e32 v77, v247
	v_mov_b32_e32 v78, v248
	v_mov_b32_e32 v79, v249
	v_pk_add_f32 v[68:69], v[68:69], v[72:73]
	v_pk_add_f32 v[70:71], v[70:71], v[74:75]
	v_pk_add_f32 v[74:75], v[64:65], v[76:77]
	v_cvt_pk_bf16_f32 v64, v68, v69
	v_mul_f32_e32 v69, v69, v69
	v_fmac_f32_e32 v69, v68, v68
	v_fmac_f32_e32 v69, v70, v70
	v_fmac_f32_e32 v69, v71, v71
	v_fmac_f32_e32 v69, v74, v74
	v_pk_add_f32 v[72:73], v[66:67], v[78:79]
	v_fmac_f32_e32 v69, v75, v75
	v_fmac_f32_e32 v69, v72, v72
	v_cvt_pk_bf16_f32 v65, v70, v71
	v_cvt_pk_bf16_f32 v66, v74, v75
	v_cvt_pk_bf16_f32 v67, v72, v73
	v_fmac_f32_e32 v69, v73, v73
	global_store_dwordx4 v[90:91], v[64:67], off
	s_nop 1
	v_add_f32_e32 v64, v83, v69
	v_mov_b32_e32 v65, v64
	s_nop 1
	v_permlane16_swap_b32_e32 v64, v65
	v_add_f32_e32 v64, v64, v65
	v_mov_b32_e32 v65, v64
	s_nop 1
	v_permlane32_swap_b32_e32 v64, v65
	s_and_saveexec_b64 s[26:27], s[6:7]
	s_cbranch_execz .LBB0_1031
	v_add_f32_e32 v64, v64, v65
	v_mul_f32_e32 v64, 0x49800000, v64
	v_trunc_f32_e32 v64, v64
	v_mul_f32_e32 v65, 0x2f800000, v64
	v_floor_f32_e32 v65, v65
	v_fmac_f32_e32 v64, 0xcf800000, v65
	v_cvt_u32_f32_e32 v64, v64
	v_cvt_u32_f32_e32 v65, v65
	v_lshl_add_u64 v[66:67], v[80:81], 3, s[10:11]
	global_atomic_add_x2 v[66:67], v[64:65], off
.LBB0_1031:
	s_or_b64 exec, exec, s[26:27]
	v_add_u32_e32 v64, 0x80, v146
	v_ashrrev_i32_e32 v65, 31, v64
	v_lshlrev_b64 v[66:67], 10, v[64:65]
	v_lshl_add_u64 v[74:75], v[66:67], 0, v[144:145]
	v_lshl_add_u64 v[76:77], v[74:75], 2, s[0:1]
	v_add_u32_e32 v168, 0x80, v146
	v_ashrrev_i32_e32 v169, 31, v168
	v_lshlrev_b64 v[170:171], 10, v[168:169]
	v_lshl_add_u64 v[170:171], v[170:171], 0, v[144:145]
	v_lshl_add_u64 v[172:173], v[170:171], 2, s[0:1]
	global_load_dwordx4 v[174:177], v[172:173], off nt
	global_load_dwordx4 v[178:181], v[172:173], off offset:16 nt
	global_load_dwordx4 v[182:185], v[172:173], off offset:512 nt
	global_load_dwordx4 v[186:189], v[172:173], off offset:528 nt
	v_add_u32_e32 v168, 0x90, v146
	v_ashrrev_i32_e32 v169, 31, v168
	v_lshlrev_b64 v[170:171], 10, v[168:169]
	v_lshl_add_u64 v[170:171], v[170:171], 0, v[144:145]
	v_lshl_add_u64 v[172:173], v[170:171], 2, s[0:1]
	global_load_dwordx4 v[200:203], v[172:173], off nt
	global_load_dwordx4 v[204:207], v[172:173], off offset:16 nt
	global_load_dwordx4 v[208:211], v[172:173], off offset:512 nt
	global_load_dwordx4 v[212:215], v[172:173], off offset:528 nt
	v_add_u32_e32 v168, 0xa0, v146
	v_ashrrev_i32_e32 v169, 31, v168
	v_lshlrev_b64 v[170:171], 10, v[168:169]
	v_lshl_add_u64 v[170:171], v[170:171], 0, v[144:145]
	v_lshl_add_u64 v[172:173], v[170:171], 2, s[0:1]
	global_load_dwordx4 v[216:219], v[172:173], off nt
	global_load_dwordx4 v[220:223], v[172:173], off offset:16 nt
	global_load_dwordx4 v[224:227], v[172:173], off offset:512 nt
	global_load_dwordx4 v[228:231], v[172:173], off offset:528 nt
	v_add_u32_e32 v168, 0xb0, v146
	v_ashrrev_i32_e32 v169, 31, v168
	v_lshlrev_b64 v[170:171], 10, v[168:169]
	v_lshl_add_u64 v[170:171], v[170:171], 0, v[144:145]
	v_lshl_add_u64 v[172:173], v[170:171], 2, s[0:1]
	global_load_dwordx4 v[232:235], v[172:173], off nt
	global_load_dwordx4 v[236:239], v[172:173], off offset:16 nt
	global_load_dwordx4 v[242:245], v[172:173], off offset:512 nt
	global_load_dwordx4 v[246:249], v[172:173], off offset:528 nt
	s_nop 0
	s_nop 0
	v_lshlrev_b64 v[74:75], 1, v[74:75]
	v_lshl_add_u64 v[78:79], s[4:5], 0, v[74:75]
	v_or_b32_e32 v74, 0x100, v74
	v_lshl_add_u64 v[74:75], s[4:5], 0, v[74:75]
	s_waitcnt vmcnt(14)
	v_mov_b32_e32 v66, v174
	v_mov_b32_e32 v67, v175
	v_mov_b32_e32 v68, v176
	v_mov_b32_e32 v69, v177
	v_mov_b32_e32 v70, v178
	v_mov_b32_e32 v71, v179
	v_mov_b32_e32 v72, v180
	v_mov_b32_e32 v73, v181
	v_pk_add_f32 v[68:69], v[62:63], v[68:69]
	v_pk_add_f32 v[66:67], v[60:61], v[66:67]
	v_pk_add_f32 v[72:73], v[58:59], v[72:73]
	v_pk_add_f32 v[70:71], v[56:57], v[70:71]
	v_cvt_pk_bf16_f32 v56, v66, v67
	v_cvt_pk_bf16_f32 v57, v68, v69
	v_cvt_pk_bf16_f32 v58, v70, v71
	v_cvt_pk_bf16_f32 v59, v72, v73
	global_store_dwordx4 v[78:79], v[56:59], off
	s_nop 0
	s_nop 0
	s_nop 0
	v_mul_f32_e32 v67, v67, v67
	v_fmac_f32_e32 v67, v66, v66
	v_fmac_f32_e32 v67, v68, v68
	v_fmac_f32_e32 v67, v69, v69
	v_fmac_f32_e32 v67, v70, v70
	v_fmac_f32_e32 v67, v71, v71
	v_fmac_f32_e32 v67, v72, v72
	v_fmac_f32_e32 v67, v73, v73
	s_waitcnt vmcnt(13)
	v_mov_b32_e32 v56, v182
	v_mov_b32_e32 v57, v183
	v_mov_b32_e32 v58, v184
	v_mov_b32_e32 v59, v185
	v_mov_b32_e32 v60, v186
	v_mov_b32_e32 v61, v187
	v_mov_b32_e32 v62, v188
	v_mov_b32_e32 v63, v189
	v_pk_add_f32 v[52:53], v[52:53], v[56:57]
	v_pk_add_f32 v[54:55], v[54:55], v[58:59]
	v_pk_add_f32 v[58:59], v[48:49], v[60:61]
	v_cvt_pk_bf16_f32 v48, v52, v53
	v_mul_f32_e32 v53, v53, v53
	v_fmac_f32_e32 v53, v52, v52
	v_fmac_f32_e32 v53, v54, v54
	v_fmac_f32_e32 v53, v55, v55
	v_fmac_f32_e32 v53, v58, v58
	v_pk_add_f32 v[56:57], v[50:51], v[62:63]
	v_fmac_f32_e32 v53, v59, v59
	v_fmac_f32_e32 v53, v56, v56
	v_cvt_pk_bf16_f32 v49, v54, v55
	v_cvt_pk_bf16_f32 v50, v58, v59
	v_cvt_pk_bf16_f32 v51, v56, v57
	v_fmac_f32_e32 v53, v57, v57
	global_store_dwordx4 v[74:75], v[48:51], off
	s_nop 1
	v_add_f32_e32 v48, v67, v53
	v_mov_b32_e32 v49, v48
	s_nop 1
	v_permlane16_swap_b32_e32 v48, v49
	v_add_f32_e32 v48, v48, v49
	v_mov_b32_e32 v49, v48
	s_nop 1
	v_permlane32_swap_b32_e32 v48, v49
	s_and_saveexec_b64 s[26:27], s[6:7]
	s_cbranch_execz .LBB0_1033
; DI unsigned pk2(float lo, float hi) { f32x2 v = {lo, hi}; bf16x2_t b = __builtin_convertvector(v, bf16x2_t); return __builtin_bit_cast(unsigned, b); }
; DI float bflo(unsigned u) { return __uint_as_float(u << 16); }
; DI float bfhi(unsigned u) { return __uint_as_float(u & 0xffff0000u); }
; DI u64 ss_to_fix(float ss) { return (u64)(ss * 1048576.f); }
;     DI void operator()(const AccT& acc, const Unit& u, int wr, int wc, int fr, int fq) const {
;         const int row0 = u.pm * 256 + wr * 64 + fr, col0 = u.pn * 256 + wc * 32 + 8 * fq;
; #pragma unroll
;         for (int ai = 0; ai < 2; ++ai)
; #pragma unroll
;             for (int m = 0; m < 4; ++m) { const int t = row0 + ai * 128 + m * 16; float ss = 0.f;
; #pragma unroll
;                 for (int bj = 0; bj < 2; ++bj) { const size_t o = (size_t)t * 1024 + col0 + bj * 128;
;                     f32x4 r0, r1;
;                     if (RESBF) { const u32x4 rb = *(const u32x4*)(XB + o); r0 = (f32x4){bflo(rb.x), bfhi(rb.x), bflo(rb.y), bfhi(rb.y)}; r1 = (f32x4){bflo(rb.z), bfhi(rb.z), bflo(rb.w), bfhi(rb.w)}; }
;                     else { r0 = __builtin_nontemporal_load((const f32x4*)(res + o)); r1 = __builtin_nontemporal_load((const f32x4*)(res + o + 4)); }
;                     const f32x4 v0 = acc[ai][bj][m][0] + r0, v1 = acc[ai][bj][m][1] + r1;
;                     u32x4 w; w.x = pk2(v0[0], v0[1]); w.y = pk2(v0[2], v0[3]); w.z = pk2(v1[0], v1[1]); w.w = pk2(v1[2], v1[3]);
;                     if (!dry) *(u32x4*)(XB + o) = w;
;                     ss += v0[0] * v0[0] + v0[1] * v0[1] + v0[2] * v0[2] + v0[3] * v0[3] + v1[0] * v1[0] + v1[1] * v1[1] + v1[2] * v1[2] + v1[3] * v1[3]; }
;                 { const auto r16 = __builtin_amdgcn_permlane16_swap(__float_as_uint(ss), __float_as_uint(ss), false, false); ss = __uint_as_float(r16[0]) + __uint_as_float(r16[1]);
;                   const auto r32 = __builtin_amdgcn_permlane32_swap(__float_as_uint(ss), __float_as_uint(ss), false, false); ss = __uint_as_float(r32[0]) + __uint_as_float(r32[1]); }
;                 if (fq == 0 && !dry) atomicAdd(rowss + t, ss_to_fix(ss)); }
	v_add_f32_e32 v48, v48, v49
	v_mul_f32_e32 v48, 0x49800000, v48
	v_trunc_f32_e32 v48, v48
	v_mul_f32_e32 v49, 0x2f800000, v48
	v_floor_f32_e32 v49, v49
	v_fmac_f32_e32 v48, 0xcf800000, v49
	v_cvt_u32_f32_e32 v48, v48
	v_cvt_u32_f32_e32 v49, v49
	v_lshl_add_u64 v[50:51], v[64:65], 3, s[10:11]
	global_atomic_add_x2 v[50:51], v[48:49], off
.LBB0_1033:
	s_or_b64 exec, exec, s[26:27]
	v_add_u32_e32 v48, 0x90, v146
	v_ashrrev_i32_e32 v49, 31, v48
	v_lshlrev_b64 v[50:51], 10, v[48:49]
	v_lshl_add_u64 v[58:59], v[50:51], 0, v[144:145]
	v_lshl_add_u64 v[60:61], v[58:59], 2, s[0:1]
	s_nop 0
	s_nop 0
	v_lshlrev_b64 v[58:59], 1, v[58:59]
	v_lshl_add_u64 v[62:63], s[4:5], 0, v[58:59]
	v_or_b32_e32 v58, 0x100, v58
	v_lshl_add_u64 v[58:59], s[4:5], 0, v[58:59]
	s_waitcnt vmcnt(12)
	v_mov_b32_e32 v50, v200
	v_mov_b32_e32 v51, v201
	v_mov_b32_e32 v52, v202
	v_mov_b32_e32 v53, v203
	v_mov_b32_e32 v54, v204
	v_mov_b32_e32 v55, v205
	v_mov_b32_e32 v56, v206
	v_mov_b32_e32 v57, v207
	v_pk_add_f32 v[52:53], v[46:47], v[52:53]
	v_pk_add_f32 v[50:51], v[44:45], v[50:51]
	v_pk_add_f32 v[56:57], v[42:43], v[56:57]
	v_pk_add_f32 v[54:55], v[40:41], v[54:55]
	v_cvt_pk_bf16_f32 v40, v50, v51
	v_cvt_pk_bf16_f32 v41, v52, v53
	v_cvt_pk_bf16_f32 v42, v54, v55
	v_cvt_pk_bf16_f32 v43, v56, v57
	global_store_dwordx4 v[62:63], v[40:43], off
	s_nop 0
	s_nop 0
	s_nop 0
	v_mul_f32_e32 v51, v51, v51
	v_fmac_f32_e32 v51, v50, v50
	v_fmac_f32_e32 v51, v52, v52
	v_fmac_f32_e32 v51, v53, v53
	v_fmac_f32_e32 v51, v54, v54
	v_fmac_f32_e32 v51, v55, v55
	v_fmac_f32_e32 v51, v56, v56
	v_fmac_f32_e32 v51, v57, v57
	s_waitcnt vmcnt(11)
	v_mov_b32_e32 v40, v208
	v_mov_b32_e32 v41, v209
	v_mov_b32_e32 v42, v210
	v_mov_b32_e32 v43, v211
	v_mov_b32_e32 v44, v212
	v_mov_b32_e32 v45, v213
	v_mov_b32_e32 v46, v214
	v_mov_b32_e32 v47, v215
	v_pk_add_f32 v[36:37], v[36:37], v[40:41]
	v_pk_add_f32 v[38:39], v[38:39], v[42:43]
	v_pk_add_f32 v[42:43], v[32:33], v[44:45]
	v_cvt_pk_bf16_f32 v32, v36, v37
	v_mul_f32_e32 v37, v37, v37
	v_fmac_f32_e32 v37, v36, v36
	v_fmac_f32_e32 v37, v38, v38
	v_fmac_f32_e32 v37, v39, v39
	v_fmac_f32_e32 v37, v42, v42
	v_pk_add_f32 v[40:41], v[34:35], v[46:47]
	v_fmac_f32_e32 v37, v43, v43
	v_fmac_f32_e32 v37, v40, v40
	v_cvt_pk_bf16_f32 v33, v38, v39
	v_cvt_pk_bf16_f32 v34, v42, v43
	v_cvt_pk_bf16_f32 v35, v40, v41
	v_fmac_f32_e32 v37, v41, v41
	global_store_dwordx4 v[58:59], v[32:35], off
	s_nop 1
	v_add_f32_e32 v32, v51, v37
	v_mov_b32_e32 v33, v32
	s_nop 1
	v_permlane16_swap_b32_e32 v32, v33
	v_add_f32_e32 v32, v32, v33
	v_mov_b32_e32 v33, v32
	s_nop 1
	v_permlane32_swap_b32_e32 v32, v33
	s_and_saveexec_b64 s[26:27], s[6:7]
	s_cbranch_execz .LBB0_1035
	v_add_f32_e32 v32, v32, v33
	v_mul_f32_e32 v32, 0x49800000, v32
	v_trunc_f32_e32 v32, v32
	v_mul_f32_e32 v33, 0x2f800000, v32
	v_floor_f32_e32 v33, v33
	v_fmac_f32_e32 v32, 0xcf800000, v33
	v_cvt_u32_f32_e32 v32, v32
	v_cvt_u32_f32_e32 v33, v33
	v_lshl_add_u64 v[34:35], v[48:49], 3, s[10:11]
	global_atomic_add_x2 v[34:35], v[32:33], off
; DI unsigned pk2(float lo, float hi) { f32x2 v = {lo, hi}; bf16x2_t b = __builtin_convertvector(v, bf16x2_t); return __builtin_bit_cast(unsigned, b); }
; DI float bflo(unsigned u) { return __uint_as_float(u << 16); }
; DI float bfhi(unsigned u) { return __uint_as_float(u & 0xffff0000u); }
; DI u64 ss_to_fix(float ss) { return (u64)(ss * 1048576.f); }
;     DI void operator()(const AccT& acc, const Unit& u, int wr, int wc, int fr, int fq) const {
;         const int row0 = u.pm * 256 + wr * 64 + fr, col0 = u.pn * 256 + wc * 32 + 8 * fq;
; #pragma unroll
;         for (int ai = 0; ai < 2; ++ai)
; #pragma unroll
;             for (int m = 0; m < 4; ++m) { const int t = row0 + ai * 128 + m * 16; float ss = 0.f;
; #pragma unroll
;                 for (int bj = 0; bj < 2; ++bj) { const size_t o = (size_t)t * 1024 + col0 + bj * 128;
;                     f32x4 r0, r1;
;                     if (RESBF) { const u32x4 rb = *(const u32x4*)(XB + o); r0 = (f32x4){bflo(rb.x), bfhi(rb.x), bflo(rb.y), bfhi(rb.y)}; r1 = (f32x4){bflo(rb.z), bfhi(rb.z), bflo(rb.w), bfhi(rb.w)}; }
;                     else { r0 = __builtin_nontemporal_load((const f32x4*)(res + o)); r1 = __builtin_nontemporal_load((const f32x4*)(res + o + 4)); }
;                     const f32x4 v0 = acc[ai][bj][m][0] + r0, v1 = acc[ai][bj][m][1] + r1;
;                     u32x4 w; w.x = pk2(v0[0], v0[1]); w.y = pk2(v0[2], v0[3]); w.z = pk2(v1[0], v1[1]); w.w = pk2(v1[2], v1[3]);
;                     if (!dry) *(u32x4*)(XB + o) = w;
;                     ss += v0[0] * v0[0] + v0[1] * v0[1] + v0[2] * v0[2] + v0[3] * v0[3] + v1[0] * v1[0] + v1[1] * v1[1] + v1[2] * v1[2] + v1[3] * v1[3]; }
;                 { const auto r16 = __builtin_amdgcn_permlane16_swap(__float_as_uint(ss), __float_as_uint(ss), false, false); ss = __uint_as_float(r16[0]) + __uint_as_float(r16[1]);
;                   const auto r32 = __builtin_amdgcn_permlane32_swap(__float_as_uint(ss), __float_as_uint(ss), false, false); ss = __uint_as_float(r32[0]) + __uint_as_float(r32[1]); }
;                 if (fq == 0 && !dry) atomicAdd(rowss + t, ss_to_fix(ss)); }
.LBB0_1035:
	s_or_b64 exec, exec, s[26:27]
	v_add_u32_e32 v32, 0xa0, v146
	v_ashrrev_i32_e32 v33, 31, v32
	v_lshlrev_b64 v[34:35], 10, v[32:33]
	v_lshl_add_u64 v[42:43], v[34:35], 0, v[144:145]
	v_lshl_add_u64 v[44:45], v[42:43], 2, s[0:1]
	s_nop 0
	s_nop 0
	v_lshlrev_b64 v[42:43], 1, v[42:43]
	v_lshl_add_u64 v[46:47], s[4:5], 0, v[42:43]
	v_or_b32_e32 v42, 0x100, v42
	v_lshl_add_u64 v[42:43], s[4:5], 0, v[42:43]
	s_waitcnt vmcnt(10)
	v_mov_b32_e32 v34, v216
	v_mov_b32_e32 v35, v217
	v_mov_b32_e32 v36, v218
	v_mov_b32_e32 v37, v219
	v_mov_b32_e32 v38, v220
	v_mov_b32_e32 v39, v221
	v_mov_b32_e32 v40, v222
	v_mov_b32_e32 v41, v223
	v_pk_add_f32 v[36:37], v[30:31], v[36:37]
	v_pk_add_f32 v[34:35], v[28:29], v[34:35]
	v_pk_add_f32 v[40:41], v[26:27], v[40:41]
	v_pk_add_f32 v[38:39], v[24:25], v[38:39]
	v_cvt_pk_bf16_f32 v24, v34, v35
	v_cvt_pk_bf16_f32 v25, v36, v37
	v_cvt_pk_bf16_f32 v26, v38, v39
	v_cvt_pk_bf16_f32 v27, v40, v41
	global_store_dwordx4 v[46:47], v[24:27], off
	s_nop 0
	s_nop 0
	s_nop 0
	v_mul_f32_e32 v35, v35, v35
	v_fmac_f32_e32 v35, v34, v34
	v_fmac_f32_e32 v35, v36, v36
	v_fmac_f32_e32 v35, v37, v37
	v_fmac_f32_e32 v35, v38, v38
	v_fmac_f32_e32 v35, v39, v39
	v_fmac_f32_e32 v35, v40, v40
	v_fmac_f32_e32 v35, v41, v41
	s_waitcnt vmcnt(9)
	v_mov_b32_e32 v24, v224
	v_mov_b32_e32 v25, v225
	v_mov_b32_e32 v26, v226
	v_mov_b32_e32 v27, v227
	v_mov_b32_e32 v28, v228
	v_mov_b32_e32 v29, v229
	v_mov_b32_e32 v30, v230
	v_mov_b32_e32 v31, v231
	v_pk_add_f32 v[20:21], v[20:21], v[24:25]
	v_pk_add_f32 v[22:23], v[22:23], v[26:27]
	v_pk_add_f32 v[26:27], v[16:17], v[28:29]
	v_cvt_pk_bf16_f32 v16, v20, v21
	v_mul_f32_e32 v21, v21, v21
	v_fmac_f32_e32 v21, v20, v20
	v_fmac_f32_e32 v21, v22, v22
	v_fmac_f32_e32 v21, v23, v23
	v_fmac_f32_e32 v21, v26, v26
	v_pk_add_f32 v[24:25], v[18:19], v[30:31]
	v_fmac_f32_e32 v21, v27, v27
	v_fmac_f32_e32 v21, v24, v24
	v_cvt_pk_bf16_f32 v17, v22, v23
	v_cvt_pk_bf16_f32 v18, v26, v27
	v_cvt_pk_bf16_f32 v19, v24, v25
	v_fmac_f32_e32 v21, v25, v25
	global_store_dwordx4 v[42:43], v[16:19], off
	s_nop 1
	v_add_f32_e32 v16, v35, v21
	v_mov_b32_e32 v17, v16
	s_nop 1
	v_permlane16_swap_b32_e32 v16, v17
	v_add_f32_e32 v16, v16, v17
	v_mov_b32_e32 v17, v16
	s_nop 1
	v_permlane32_swap_b32_e32 v16, v17
	s_and_saveexec_b64 s[26:27], s[6:7]
	s_cbranch_execz .LBB0_1037
	v_add_f32_e32 v16, v16, v17
	v_mul_f32_e32 v16, 0x49800000, v16
	v_trunc_f32_e32 v16, v16
	v_mul_f32_e32 v17, 0x2f800000, v16
	v_floor_f32_e32 v17, v17
	v_fmac_f32_e32 v16, 0xcf800000, v17
	v_cvt_u32_f32_e32 v16, v16
	v_cvt_u32_f32_e32 v17, v17
	v_lshl_add_u64 v[18:19], v[32:33], 3, s[10:11]
	global_atomic_add_x2 v[18:19], v[16:17], off
.LBB0_1037:
	s_or_b64 exec, exec, s[26:27]
	v_add_u32_e32 v16, 0xb0, v146
	v_ashrrev_i32_e32 v17, 31, v16
	v_lshlrev_b64 v[18:19], 10, v[16:17]
	v_lshl_add_u64 v[26:27], v[18:19], 0, v[144:145]
	v_lshl_add_u64 v[28:29], v[26:27], 2, s[0:1]
	s_nop 0
	s_nop 0
	v_lshlrev_b64 v[26:27], 1, v[26:27]
	v_lshl_add_u64 v[30:31], s[4:5], 0, v[26:27]
	v_or_b32_e32 v26, 0x100, v26
	v_lshl_add_u64 v[26:27], s[4:5], 0, v[26:27]
	s_waitcnt vmcnt(8)
	v_mov_b32_e32 v18, v232
	v_mov_b32_e32 v19, v233
	v_mov_b32_e32 v20, v234
	v_mov_b32_e32 v21, v235
	v_mov_b32_e32 v22, v236
	v_mov_b32_e32 v23, v237
	v_mov_b32_e32 v24, v238
	v_mov_b32_e32 v25, v239
	v_pk_add_f32 v[20:21], v[14:15], v[20:21]
	v_pk_add_f32 v[18:19], v[12:13], v[18:19]
	v_pk_add_f32 v[24:25], v[10:11], v[24:25]
	v_pk_add_f32 v[22:23], v[8:9], v[22:23]
	v_cvt_pk_bf16_f32 v8, v18, v19
	v_cvt_pk_bf16_f32 v9, v20, v21
	v_cvt_pk_bf16_f32 v10, v22, v23
	v_cvt_pk_bf16_f32 v11, v24, v25
	global_store_dwordx4 v[30:31], v[8:11], off
	s_nop 0
	s_nop 0
	s_nop 0
	v_mul_f32_e32 v19, v19, v19
	v_fmac_f32_e32 v19, v18, v18
	v_fmac_f32_e32 v19, v20, v20
	v_fmac_f32_e32 v19, v21, v21
	v_fmac_f32_e32 v19, v22, v22
	v_fmac_f32_e32 v19, v23, v23
	v_fmac_f32_e32 v19, v24, v24
	v_fmac_f32_e32 v19, v25, v25
	s_waitcnt vmcnt(7)
	v_mov_b32_e32 v8, v242
	v_mov_b32_e32 v9, v243
	v_mov_b32_e32 v10, v244
	v_mov_b32_e32 v11, v245
	v_mov_b32_e32 v12, v246
	v_mov_b32_e32 v13, v247
	v_mov_b32_e32 v14, v248
	v_mov_b32_e32 v15, v249
	v_pk_add_f32 v[4:5], v[4:5], v[8:9]
	v_pk_add_f32 v[6:7], v[6:7], v[10:11]
	v_pk_add_f32 v[10:11], v[0:1], v[12:13]
	v_cvt_pk_bf16_f32 v0, v4, v5
	v_mul_f32_e32 v5, v5, v5
	v_fmac_f32_e32 v5, v4, v4
	v_fmac_f32_e32 v5, v6, v6
	v_fmac_f32_e32 v5, v7, v7
	v_fmac_f32_e32 v5, v10, v10
	v_pk_add_f32 v[8:9], v[2:3], v[14:15]
	v_fmac_f32_e32 v5, v11, v11
	v_fmac_f32_e32 v5, v8, v8
	v_cvt_pk_bf16_f32 v1, v6, v7
	v_cvt_pk_bf16_f32 v2, v10, v11
	v_cvt_pk_bf16_f32 v3, v8, v9
	v_fmac_f32_e32 v5, v9, v9
	global_store_dwordx4 v[26:27], v[0:3], off
	s_nop 1
	v_add_f32_e32 v0, v19, v5
	v_mov_b32_e32 v1, v0
	s_nop 1
	v_permlane16_swap_b32_e32 v0, v1
	v_add_f32_e32 v0, v0, v1
	v_mov_b32_e32 v1, v0
	s_nop 1
	v_permlane32_swap_b32_e32 v0, v1
	s_and_saveexec_b64 s[26:27], s[6:7]
	s_cbranch_execz .LBB0_1039
	v_add_f32_e32 v0, v0, v1
	v_mul_f32_e32 v0, 0x49800000, v0
	v_trunc_f32_e32 v0, v0
	v_mul_f32_e32 v1, 0x2f800000, v0
	v_floor_f32_e32 v1, v1
	v_fmac_f32_e32 v0, 0xcf800000, v1
	v_cvt_u32_f32_e32 v0, v0
	v_cvt_u32_f32_e32 v1, v1
	v_lshl_add_u64 v[2:3], v[16:17], 3, s[10:11]
	global_atomic_add_x2 v[2:3], v[0:1], off

; #define LAS __attribute__((address_space(3)))
;     DI void operator()(const AccT& acc, const Unit& u, int wr, int wc, int fr, int fq) const {
;     ...
;         { const int lane = fq * 16 + fr, kind = lane >> 3, c4 = 4 * (lane & 7), k3 = kind & 3;
;           const float* src = (k3 == 0 ? cb : cw + (k3 - 1) * 5632) + (kind >= 4 ? 2816 : 0) + u.pn * 128 + wc * 32 + c4;
;           *(LAS f32x4*)(P + kind * 32 + c4) = *(const f32x4*)src; }
; #pragma unroll
;         for (int ai = 0; ai < 2; ++ai) {
;             const int tok0 = u.pm * 248 + 62 * (2 * ai + wr) - 2 + fr;
;             float rs[4];
; #pragma unroll
;             for (int m = 0; m < 4; ++m) { const int t = tok0 + 16 * m; const int tc = t < 0 ? 0 : (t >= S ? S - 1 : t); const float r = rs_from_ss(rowss[tc]); rs[m] = t < 0 ? 0.f : r; }
;             const int row0 = fr < 2 ? (S + 236 + fr) : tok0;
; #pragma unroll
;             for (int n = 0; n < 2; ++n) {
;                 const int lc = 8 * fq + 4 * n;
;                 unsigned wpk[4][2];
; #pragma unroll
;                 for (int jp = 0; jp < 2; ++jp) {
;                     const f32x2 bg = *(const LAS f32x2*)(P + lc + 2 * jp), g0 = *(const LAS f32x2*)(P + 32 + lc + 2 * jp), g1 = *(const LAS f32x2*)(P + 64 + lc + 2 * jp), g2 = *(const LAS f32x2*)(P + 96 + lc + 2 * jp);
;                     const f32x2 bv = *(const LAS f32x2*)(P + 128 + lc + 2 * jp), v0 = *(const LAS f32x2*)(P + 160 + lc + 2 * jp), v1 = *(const LAS f32x2*)(P + 192 + lc + 2 * jp), v2 = *(const LAS f32x2*)(P + 224 + lc + 2 * jp);
;                     f32x2 G[4], V[4];
; #pragma unroll
;                     for (int m = 0; m < 4; ++m) { G[m] = (f32x2){acc[ai][0][m][n][2 * jp], acc[ai][0][m][n][2 * jp + 1]} * rs[m]; V[m] = (f32x2){acc[ai][1][m][n][2 * jp], acc[ai][1][m][n][2 * jp + 1]} * rs[m]; }
; #pragma unroll
;                     for (int m = 0; m < 4; ++m) {
;                         const f32x2 zz = {0.f, 0.f}; const f32x2 Gp = m ? G[m - 1] : zz, Vp = m ? V[m - 1] : zz;
;                         const f32x2 gp1 = {dpp_prev1(G[m].x, Gp.x), dpp_prev1(G[m].y, Gp.y)}, gp2 = {dpp_prev2(G[m].x, Gp.x), dpp_prev2(G[m].y, Gp.y)};
;                         const f32x2 vp1 = {dpp_prev1(V[m].x, Vp.x), dpp_prev1(V[m].y, Vp.y)}, vp2 = {dpp_prev2(V[m].x, Vp.x), dpp_prev2(V[m].y, Vp.y)};
;                         const f32x2 gc = bg + g0 * gp2 + g1 * gp1 + g2 * G[m];
.LBB0_1122:
	s_lshl_b32 s10, s58, 7
	s_ashr_i32 s11, s10, 31
	v_lshl_add_u64 v[128:129], s[10:11], 2, v[168:169]
	s_mul_i32 s11, s57, 0xf8
	v_add_u32_e32 v204, s11, v170
	v_med3_i32 v132, v204, 0, s51
	v_lshlrev_b32_e32 v132, 3, v132
	global_load_dwordx2 v[180:181], v132, s[16:17]
	v_add_u32_e32 v205, 16, v204
	v_med3_i32 v132, v205, 0, s51
	v_add_u32_e32 v206, 32, v204
	v_add_u32_e32 v207, 48, v204
	v_lshlrev_b32_e32 v132, 3, v132
	v_med3_i32 v133, v206, 0, s51
	v_med3_i32 v134, v207, 0, s51
	global_load_dwordx4 v[128:131], v[128:129], off
	v_lshlrev_b32_e32 v133, 3, v133
	v_lshlrev_b32_e32 v134, 3, v134
	global_load_dwordx2 v[182:183], v132, s[16:17]
	global_load_dwordx2 v[210:211], v133, s[16:17]
	global_load_dwordx2 v[212:213], v134, s[16:17]
	v_or_b32_e32 v188, s10, v187
	v_ashrrev_i32_e32 v189, 31, v188
	v_cndmask_b32_e64 v208, v204, v190, s[6:7]
	s_waitcnt vmcnt(0)
	v_ffbh_u32_e32 v184, v181
	v_min_u32_e32 v184, 32, v184
	v_lshlrev_b64 v[180:181], v184, v[180:181]
	v_min_u32_e32 v180, 1, v180
	v_or_b32_e32 v180, v181, v180
	v_cvt_f32_u32_e32 v180, v180
	v_sub_u32_e32 v184, 32, v184
	ds_write_b128 v191, v[128:131]
	v_ffbh_u32_e32 v186, v183
	v_ffbh_u32_e32 v209, v211
	v_min_u32_e32 v186, 32, v186
	v_ffbh_u32_e32 v214, v213
	v_min_u32_e32 v209, 32, v209
	v_lshlrev_b64 v[182:183], v186, v[182:183]
	v_min_u32_e32 v214, 32, v214
	v_lshlrev_b64 v[210:211], v209, v[210:211]
	v_min_u32_e32 v181, 1, v182
	v_lshlrev_b64 v[212:213], v214, v[212:213]
	v_min_u32_e32 v182, 1, v210
	v_or_b32_e32 v181, v183, v181
	v_min_u32_e32 v210, 1, v212
	v_or_b32_e32 v182, v211, v182
	v_cvt_f32_u32_e32 v181, v181
	v_or_b32_e32 v183, v213, v210
	v_cvt_f32_u32_e32 v182, v182
	v_cvt_f32_u32_e32 v183, v183
	v_sub_u32_e32 v186, 32, v186
	v_ldexp_f32 v180, v180, v184
	v_sub_u32_e32 v209, 32, v209
	v_fmamk_f32 v180, v180, 0x30800000, v203
	v_ldexp_f32 v181, v181, v186
	v_sub_u32_e32 v214, 32, v214
	v_ldexp_f32 v182, v182, v209
	v_mul_f32_e32 v184, 0x4b800000, v180
	v_fmamk_f32 v181, v181, 0x30800000, v203
	v_cmp_gt_f32_e32 vcc, s52, v180
	v_ldexp_f32 v183, v183, v214
	v_fmamk_f32 v182, v182, 0x30800000, v203
	v_cndmask_b32_e32 v180, v180, v184, vcc
	v_mul_f32_e32 v184, 0x4b800000, v181
	v_cmp_gt_f32_e64 s[10:11], s52, v181
	v_fmamk_f32 v183, v183, 0x30800000, v203
	v_mul_f32_e32 v186, 0x4b800000, v182
	v_rsq_f32_e32 v180, v180
	v_cndmask_b32_e64 v181, v181, v184, s[10:11]
	v_cmp_gt_f32_e64 s[12:13], s52, v182
	v_mul_f32_e32 v209, 0x4b800000, v183
	v_cmp_gt_f32_e64 s[14:15], s52, v183
	v_cndmask_b32_e64 v182, v182, v186, s[12:13]
	v_rsq_f32_e32 v181, v181
	v_cndmask_b32_e64 v183, v183, v209, s[14:15]
	v_rsq_f32_e32 v182, v182
	v_rsq_f32_e32 v183, v183
	v_mul_f32_e32 v184, 0x45800000, v180
	v_cndmask_b32_e32 v180, v180, v184, vcc
	v_mul_f32_e32 v184, 0x45800000, v181
	v_cmp_lt_i32_e32 vcc, -1, v204
	v_mul_f32_e32 v209, 0x45800000, v182
	v_mul_f32_e32 v210, 0x45800000, v183
	v_cndmask_b32_e32 v186, 0, v180, vcc
	v_cndmask_b32_e64 v180, v181, v184, s[10:11]
	v_cmp_lt_i32_e32 vcc, s53, v204
	v_cndmask_b32_e64 v181, v182, v209, s[12:13]
	v_cndmask_b32_e64 v183, v183, v210, s[14:15]
	v_cndmask_b32_e32 v184, 0, v180, vcc
	v_cmp_lt_i32_e32 vcc, s54, v204
	v_pk_mul_f32 v[124:125], v[124:125], v[186:187] op_sel_hi:[1,0]
	ds_read_b128 v[136:139], v200
	ds_read_b128 v[148:151], v200 offset:128
	ds_read_b128 v[152:155], v200 offset:256
	ds_read_b128 v[156:159], v200 offset:384
	ds_read_b128 v[128:131], v200 offset:512
	ds_read_b128 v[132:135], v200 offset:640
	ds_read_b128 v[140:143], v200 offset:768
	ds_read_b128 v[144:147], v200 offset:896
	v_cndmask_b32_e32 v182, 0, v181, vcc
	v_cmp_lt_i32_e32 vcc, s55, v204
	v_pk_mul_f32 v[108:109], v[108:109], v[182:183] op_sel_hi:[1,0]
	v_pk_mul_f32 v[210:211], v[104:105], v[182:183] op_sel_hi:[1,0]
	v_cndmask_b32_e32 v180, 0, v183, vcc
	v_mov_b32_e32 v183, 0
	v_pk_mul_f32 v[212:213], v[100:101], v[180:181] op_sel_hi:[1,0]
	v_pk_mul_f32 v[214:215], v[96:97], v[180:181] op_sel_hi:[1,0]
	v_mov_b32_e32 v181, 0
	v_mov_b32_dpp v183, v183 row_ror:2 row_mask:0xf bank_mask:0xf
	v_mov_b32_e32 v100, v183
	v_mov_b32_dpp v181, v181 row_ror:1 row_mask:0xf bank_mask:0xf
	v_mov_b32_e32 v101, v183
	v_mov_b32_e32 v96, v181
	v_mov_b32_e32 v97, v181
	v_mov_b32_dpp v100, v124 row_shr:2 row_mask:0xf bank_mask:0xf
	v_mov_b32_dpp v101, v125 row_shr:2 row_mask:0xf bank_mask:0xf
	v_mov_b32_dpp v96, v124 row_shr:1 row_mask:0xf bank_mask:0xf
	v_mov_b32_dpp v97, v125 row_shr:1 row_mask:0xf bank_mask:0xf
	s_waitcnt lgkmcnt(6)
	v_pk_fma_f32 v[100:101], v[148:149], v[100:101], v[136:137]
	v_pk_mul_f32 v[120:121], v[120:121], v[186:187] op_sel_hi:[1,0]
	s_waitcnt lgkmcnt(5)
	v_pk_fma_f32 v[96:97], v[152:153], v[96:97], v[100:101]
	v_mov_b32_e32 v216, v183
	s_waitcnt lgkmcnt(4)
	v_pk_fma_f32 v[96:97], v[156:157], v[124:125], v[96:97]
	v_mov_b32_e32 v217, v183
	v_pk_mul_f32 v[100:101], v[96:97], s[0:1] op_sel_hi:[1,0]
	v_mov_b32_e32 v104, v181
	v_exp_f32_e32 v100, v100
	v_exp_f32_e32 v101, v101
	v_mov_b32_e32 v105, v181
	v_mov_b32_dpp v216, v120 row_shr:2 row_mask:0xf bank_mask:0xf
	v_mov_b32_dpp v217, v121 row_shr:2 row_mask:0xf bank_mask:0xf
	v_pk_add_f32 v[100:101], v[100:101], 1.0 op_sel_hi:[1,0]
	v_mov_b32_dpp v104, v120 row_shr:1 row_mask:0xf bank_mask:0xf
	v_rcp_f32_e32 v100, v100
	v_rcp_f32_e32 v101, v101
	v_mov_b32_dpp v105, v121 row_shr:1 row_mask:0xf bank_mask:0xf
	s_waitcnt lgkmcnt(2)
	v_pk_fma_f32 v[216:217], v[132:133], v[216:217], v[128:129]
	v_pk_mul_f32 v[116:117], v[116:117], v[184:185] op_sel_hi:[1,0]
	s_waitcnt lgkmcnt(1)
	v_pk_fma_f32 v[104:105], v[140:141], v[104:105], v[216:217]
	v_pk_mul_f32 v[96:97], v[96:97], v[100:101]
	s_waitcnt lgkmcnt(0)
; #define LAS __attribute__((address_space(3)))
; DI float dpp_prev1(float cur, float prevm) {
;     const int o = __builtin_amdgcn_update_dpp(0, __builtin_bit_cast(int, prevm), 0x121, 0xf, 0xf, false);
;     return __builtin_bit_cast(float, __builtin_amdgcn_update_dpp(o, __builtin_bit_cast(int, cur), 0x111, 0xf, 0xf, false));
; }
; DI float dpp_prev2(float cur, float prevm) {
;     const int o = __builtin_amdgcn_update_dpp(0, __builtin_bit_cast(int, prevm), 0x122, 0xf, 0xf, false);
;     DI void operator()(const AccT& acc, const Unit& u, int wr, int wc, int fr, int fq) const {
;     ...
;                     const f32x2 bg = *(const LAS f32x2*)(P + lc + 2 * jp), g0 = *(const LAS f32x2*)(P + 32 + lc + 2 * jp), g1 = *(const LAS f32x2*)(P + 64 + lc + 2 * jp), g2 = *(const LAS f32x2*)(P + 96 + lc + 2 * jp);
;                     const f32x2 bv = *(const LAS f32x2*)(P + 128 + lc + 2 * jp), v0 = *(const LAS f32x2*)(P + 160 + lc + 2 * jp), v1 = *(const LAS f32x2*)(P + 192 + lc + 2 * jp), v2 = *(const LAS f32x2*)(P + 224 + lc + 2 * jp);
;                     f32x2 G[4], V[4];
; #pragma unroll
;                     for (int m = 0; m < 4; ++m) { G[m] = (f32x2){acc[ai][0][m][n][2 * jp], acc[ai][0][m][n][2 * jp + 1]} * rs[m]; V[m] = (f32x2){acc[ai][1][m][n][2 * jp], acc[ai][1][m][n][2 * jp + 1]} * rs[m]; }
; #pragma unroll
;                     for (int m = 0; m < 4; ++m) {
;                         const f32x2 zz = {0.f, 0.f}; const f32x2 Gp = m ? G[m - 1] : zz, Vp = m ? V[m - 1] : zz;
;                         const f32x2 gp1 = {dpp_prev1(G[m].x, Gp.x), dpp_prev1(G[m].y, Gp.y)}, gp2 = {dpp_prev2(G[m].x, Gp.x), dpp_prev2(G[m].y, Gp.y)};
;                         const f32x2 vp1 = {dpp_prev1(V[m].x, Vp.x), dpp_prev1(V[m].y, Vp.y)}, vp2 = {dpp_prev2(V[m].x, Vp.x), dpp_prev2(V[m].y, Vp.y)};
;                         const f32x2 gc = bg + g0 * gp2 + g1 * gp1 + g2 * G[m];
;                         const f32x2 vc = bv + v0 * vp2 + v1 * vp1 + v2 * V[m];
;                         const f32x2 xe = gc * (-LOG2E);
;                         f32x2 dn = {__builtin_amdgcn_exp2f(xe.x), __builtin_amdgcn_exp2f(xe.y)}; dn = dn + 1.0f;
;                         const f32x2 rc = {__builtin_amdgcn_rcpf(dn.x), __builtin_amdgcn_rcpf(dn.y)};
;                         const f32x2 rr = gc * rc * vc;
;                         wpk[m][jp] = pk2(rr.x, rr.y); }
	v_pk_fma_f32 v[104:105], v[144:145], v[120:121], v[104:105]
	v_pk_mul_f32 v[96:97], v[104:105], v[96:97]
	v_mov_b32_dpp v104, v124 row_ror:2 row_mask:0xf bank_mask:0xf
	v_mov_b32_dpp v105, v125 row_ror:2 row_mask:0xf bank_mask:0xf
	v_mov_b32_dpp v100, v124 row_ror:1 row_mask:0xf bank_mask:0xf
	v_mov_b32_dpp v101, v125 row_ror:1 row_mask:0xf bank_mask:0xf
	v_mov_b32_dpp v104, v116 row_shr:2 row_mask:0xf bank_mask:0xf
	v_mov_b32_dpp v105, v117 row_shr:2 row_mask:0xf bank_mask:0xf
	v_mov_b32_dpp v100, v116 row_shr:1 row_mask:0xf bank_mask:0xf
	v_mov_b32_dpp v101, v117 row_shr:1 row_mask:0xf bank_mask:0xf
	v_pk_fma_f32 v[104:105], v[148:149], v[104:105], v[136:137]
	v_pk_fma_f32 v[100:101], v[152:153], v[100:101], v[104:105]
	v_pk_fma_f32 v[100:101], v[156:157], v[116:117], v[100:101]
	v_pk_mul_f32 v[112:113], v[112:113], v[184:185] op_sel_hi:[1,0]
	v_pk_mul_f32 v[104:105], v[100:101], s[0:1] op_sel_hi:[1,0]
	v_exp_f32_e32 v104, v104
	v_exp_f32_e32 v105, v105
	v_mov_b32_dpp v216, v120 row_ror:2 row_mask:0xf bank_mask:0xf
	v_mov_b32_dpp v217, v121 row_ror:2 row_mask:0xf bank_mask:0xf
	v_pk_add_f32 v[104:105], v[104:105], 1.0 op_sel_hi:[1,0]
	v_mov_b32_dpp v124, v120 row_ror:1 row_mask:0xf bank_mask:0xf
	v_rcp_f32_e32 v104, v104
	v_rcp_f32_e32 v105, v105
	v_mov_b32_dpp v125, v121 row_ror:1 row_mask:0xf bank_mask:0xf
	v_mov_b32_dpp v216, v112 row_shr:2 row_mask:0xf bank_mask:0xf
	v_mov_b32_dpp v217, v113 row_shr:2 row_mask:0xf bank_mask:0xf
	v_mov_b32_dpp v124, v112 row_shr:1 row_mask:0xf bank_mask:0xf
	v_mov_b32_dpp v125, v113 row_shr:1 row_mask:0xf bank_mask:0xf
	v_pk_fma_f32 v[120:121], v[132:133], v[216:217], v[128:129]
	v_pk_mul_f32 v[100:101], v[100:101], v[104:105]
	v_pk_fma_f32 v[120:121], v[140:141], v[124:125], v[120:121]
	v_pk_fma_f32 v[120:121], v[144:145], v[112:113], v[120:121]
	v_pk_mul_f32 v[100:101], v[120:121], v[100:101]
	v_mov_b32_dpp v104, v116 row_ror:1 row_mask:0xf bank_mask:0xf
	v_mov_b32_dpp v120, v116 row_ror:2 row_mask:0xf bank_mask:0xf
	v_mov_b32_dpp v121, v117 row_ror:2 row_mask:0xf bank_mask:0xf
	v_mov_b32_dpp v105, v117 row_ror:1 row_mask:0xf bank_mask:0xf
	v_mov_b32_dpp v120, v108 row_shr:2 row_mask:0xf bank_mask:0xf
	v_mov_b32_dpp v121, v109 row_shr:2 row_mask:0xf bank_mask:0xf
	v_mov_b32_dpp v104, v108 row_shr:1 row_mask:0xf bank_mask:0xf
	v_mov_b32_dpp v105, v109 row_shr:1 row_mask:0xf bank_mask:0xf
	v_pk_fma_f32 v[120:121], v[148:149], v[120:121], v[136:137]
	v_pk_fma_f32 v[104:105], v[152:153], v[104:105], v[120:121]
	v_pk_fma_f32 v[104:105], v[156:157], v[108:109], v[104:105]
	v_pk_mul_f32 v[120:121], v[104:105], s[0:1] op_sel_hi:[1,0]
	v_exp_f32_e32 v120, v120
	v_exp_f32_e32 v121, v121
	v_mov_b32_dpp v116, v112 row_ror:1 row_mask:0xf bank_mask:0xf
	v_mov_b32_dpp v117, v113 row_ror:1 row_mask:0xf bank_mask:0xf
	v_mov_b32_dpp v124, v112 row_ror:2 row_mask:0xf bank_mask:0xf
	v_mov_b32_dpp v125, v113 row_ror:2 row_mask:0xf bank_mask:0xf
	v_pk_add_f32 v[112:113], v[120:121], 1.0 op_sel_hi:[1,0]
	v_mov_b32_dpp v124, v210 row_shr:2 row_mask:0xf bank_mask:0xf
	v_rcp_f32_e32 v112, v112
	v_rcp_f32_e32 v113, v113
	v_mov_b32_dpp v125, v211 row_shr:2 row_mask:0xf bank_mask:0xf
	v_mov_b32_dpp v116, v210 row_shr:1 row_mask:0xf bank_mask:0xf
	v_mov_b32_dpp v117, v211 row_shr:1 row_mask:0xf bank_mask:0xf
	v_pk_fma_f32 v[120:121], v[132:133], v[124:125], v[128:129]
	v_pk_mul_f32 v[104:105], v[104:105], v[112:113]
	v_pk_fma_f32 v[116:117], v[140:141], v[116:117], v[120:121]
	v_pk_fma_f32 v[116:117], v[144:145], v[210:211], v[116:117]
	v_pk_mul_f32 v[104:105], v[116:117], v[104:105]
	v_mov_b32_dpp v112, v108 row_ror:1 row_mask:0xf bank_mask:0xf
	v_mov_b32_dpp v116, v108 row_ror:2 row_mask:0xf bank_mask:0xf
	v_mov_b32_dpp v117, v109 row_ror:2 row_mask:0xf bank_mask:0xf
	v_mov_b32_dpp v113, v109 row_ror:1 row_mask:0xf bank_mask:0xf
	v_mov_b32_dpp v116, v212 row_shr:2 row_mask:0xf bank_mask:0xf
	v_mov_b32_dpp v117, v213 row_shr:2 row_mask:0xf bank_mask:0xf
	v_mov_b32_dpp v112, v212 row_shr:1 row_mask:0xf bank_mask:0xf
	v_mov_b32_dpp v113, v213 row_shr:1 row_mask:0xf bank_mask:0xf
	v_pk_fma_f32 v[116:117], v[148:149], v[116:117], v[136:137]
	v_pk_fma_f32 v[112:113], v[152:153], v[112:113], v[116:117]
	v_pk_fma_f32 v[112:113], v[156:157], v[212:213], v[112:113]
	v_pk_mul_f32 v[116:117], v[112:113], s[0:1] op_sel_hi:[1,0]
	v_exp_f32_e32 v116, v116
	v_exp_f32_e32 v117, v117
	v_mov_b32_dpp v120, v210 row_ror:2 row_mask:0xf bank_mask:0xf
	v_mov_b32_dpp v121, v211 row_ror:2 row_mask:0xf bank_mask:0xf
	v_mov_b32_dpp v108, v210 row_ror:1 row_mask:0xf bank_mask:0xf
	v_pk_add_f32 v[116:117], v[116:117], 1.0 op_sel_hi:[1,0]
	v_mov_b32_dpp v109, v211 row_ror:1 row_mask:0xf bank_mask:0xf
	v_rcp_f32_e32 v116, v116
	v_rcp_f32_e32 v117, v117
	v_mov_b32_dpp v120, v214 row_shr:2 row_mask:0xf bank_mask:0xf
	v_mov_b32_dpp v121, v215 row_shr:2 row_mask:0xf bank_mask:0xf
	v_mov_b32_dpp v108, v214 row_shr:1 row_mask:0xf bank_mask:0xf
	v_mov_b32_dpp v109, v215 row_shr:1 row_mask:0xf bank_mask:0xf
	v_pk_fma_f32 v[120:121], v[132:133], v[120:121], v[128:129]
	v_pk_mul_f32 v[112:113], v[112:113], v[116:117]
	v_pk_fma_f32 v[108:109], v[140:141], v[108:109], v[120:121]
	v_pk_mul_f32 v[116:117], v[122:123], v[186:187] op_sel_hi:[1,0]
	v_pk_fma_f32 v[108:109], v[144:145], v[214:215], v[108:109]
	v_mov_b32_e32 v122, v183
	v_pk_mul_f32 v[108:109], v[108:109], v[112:113]
	v_pk_mul_f32 v[112:113], v[126:127], v[186:187] op_sel_hi:[1,0]
	v_mov_b32_e32 v123, v183
	v_mov_b32_e32 v120, v181
	v_mov_b32_e32 v121, v181
	v_mov_b32_dpp v122, v112 row_shr:2 row_mask:0xf bank_mask:0xf
	v_mov_b32_dpp v123, v113 row_shr:2 row_mask:0xf bank_mask:0xf
; #define LAS __attribute__((address_space(3)))
; DI float dpp_prev1(float cur, float prevm) {
;     const int o = __builtin_amdgcn_update_dpp(0, __builtin_bit_cast(int, prevm), 0x121, 0xf, 0xf, false);
;     return __builtin_bit_cast(float, __builtin_amdgcn_update_dpp(o, __builtin_bit_cast(int, cur), 0x111, 0xf, 0xf, false));
; }
; DI float dpp_prev2(float cur, float prevm) {
;     const int o = __builtin_amdgcn_update_dpp(0, __builtin_bit_cast(int, prevm), 0x122, 0xf, 0xf, false);
;     DI void operator()(const AccT& acc, const Unit& u, int wr, int wc, int fr, int fq) const {
;     ...
;                     const f32x2 bg = *(const LAS f32x2*)(P + lc + 2 * jp), g0 = *(const LAS f32x2*)(P + 32 + lc + 2 * jp), g1 = *(const LAS f32x2*)(P + 64 + lc + 2 * jp), g2 = *(const LAS f32x2*)(P + 96 + lc + 2 * jp);
;                     const f32x2 bv = *(const LAS f32x2*)(P + 128 + lc + 2 * jp), v0 = *(const LAS f32x2*)(P + 160 + lc + 2 * jp), v1 = *(const LAS f32x2*)(P + 192 + lc + 2 * jp), v2 = *(const LAS f32x2*)(P + 224 + lc + 2 * jp);
;                     f32x2 G[4], V[4];
; #pragma unroll
;                     for (int m = 0; m < 4; ++m) { G[m] = (f32x2){acc[ai][0][m][n][2 * jp], acc[ai][0][m][n][2 * jp + 1]} * rs[m]; V[m] = (f32x2){acc[ai][1][m][n][2 * jp], acc[ai][1][m][n][2 * jp + 1]} * rs[m]; }
; #pragma unroll
;                     for (int m = 0; m < 4; ++m) {
;                         const f32x2 zz = {0.f, 0.f}; const f32x2 Gp = m ? G[m - 1] : zz, Vp = m ? V[m - 1] : zz;
;                         const f32x2 gp1 = {dpp_prev1(G[m].x, Gp.x), dpp_prev1(G[m].y, Gp.y)}, gp2 = {dpp_prev2(G[m].x, Gp.x), dpp_prev2(G[m].y, Gp.y)};
;                         const f32x2 vp1 = {dpp_prev1(V[m].x, Vp.x), dpp_prev1(V[m].y, Vp.y)}, vp2 = {dpp_prev2(V[m].x, Vp.x), dpp_prev2(V[m].y, Vp.y)};
;                         const f32x2 gc = bg + g0 * gp2 + g1 * gp1 + g2 * G[m];
;                         const f32x2 vc = bv + v0 * vp2 + v1 * vp1 + v2 * V[m];
;                         const f32x2 xe = gc * (-LOG2E);
;                         f32x2 dn = {__builtin_amdgcn_exp2f(xe.x), __builtin_amdgcn_exp2f(xe.y)}; dn = dn + 1.0f;
;                         const f32x2 rc = {__builtin_amdgcn_rcpf(dn.x), __builtin_amdgcn_rcpf(dn.y)};
;                         const f32x2 rr = gc * rc * vc;
;                         wpk[m][jp] = pk2(rr.x, rr.y); }
	v_mov_b32_dpp v120, v112 row_shr:1 row_mask:0xf bank_mask:0xf
	v_mov_b32_dpp v121, v113 row_shr:1 row_mask:0xf bank_mask:0xf
	v_pk_fma_f32 v[122:123], v[150:151], v[122:123], v[138:139]
	v_mov_b32_e32 v126, v183
	v_pk_fma_f32 v[120:121], v[154:155], v[120:121], v[122:123]
	v_mov_b32_e32 v127, v183
	v_pk_fma_f32 v[120:121], v[112:113], v[158:159], v[120:121]
	v_mov_b32_e32 v124, v181
	v_pk_mul_f32 v[122:123], v[120:121], s[0:1] op_sel_hi:[1,0]
	v_mov_b32_e32 v125, v181
	v_exp_f32_e32 v122, v122
	v_exp_f32_e32 v123, v123
	v_mov_b32_dpp v126, v116 row_shr:2 row_mask:0xf bank_mask:0xf
	v_mov_b32_dpp v127, v117 row_shr:2 row_mask:0xf bank_mask:0xf
	v_mov_b32_dpp v124, v116 row_shr:1 row_mask:0xf bank_mask:0xf
	v_pk_add_f32 v[122:123], v[122:123], 1.0 op_sel_hi:[1,0]
	v_mov_b32_dpp v125, v117 row_shr:1 row_mask:0xf bank_mask:0xf
	v_rcp_f32_e32 v122, v122
	v_rcp_f32_e32 v123, v123
	v_pk_fma_f32 v[126:127], v[134:135], v[126:127], v[130:131]
	v_cvt_pk_bf16_f32 v96, v96, v97
	v_pk_fma_f32 v[124:125], v[142:143], v[124:125], v[126:127]
	v_pk_mul_f32 v[120:121], v[120:121], v[122:123]
	v_pk_fma_f32 v[124:125], v[116:117], v[146:147], v[124:125]
	v_pk_mul_f32 v[120:121], v[124:125], v[120:121]
	v_pk_mul_f32 v[118:119], v[118:119], v[184:185] op_sel_hi:[1,0]
	v_cvt_pk_bf16_f32 v97, v120, v121
	v_mov_b32_dpp v122, v112 row_ror:2 row_mask:0xf bank_mask:0xf
	v_mov_b32_dpp v123, v113 row_ror:2 row_mask:0xf bank_mask:0xf
	v_mov_b32_dpp v120, v112 row_ror:1 row_mask:0xf bank_mask:0xf
	v_mov_b32_dpp v121, v113 row_ror:1 row_mask:0xf bank_mask:0xf
	v_mov_b32_dpp v122, v118 row_shr:2 row_mask:0xf bank_mask:0xf
	v_mov_b32_dpp v123, v119 row_shr:2 row_mask:0xf bank_mask:0xf
	v_mov_b32_dpp v120, v118 row_shr:1 row_mask:0xf bank_mask:0xf
	v_mov_b32_dpp v121, v119 row_shr:1 row_mask:0xf bank_mask:0xf
	v_pk_fma_f32 v[122:123], v[150:151], v[122:123], v[138:139]
	v_pk_fma_f32 v[120:121], v[154:155], v[120:121], v[122:123]
	v_pk_fma_f32 v[120:121], v[118:119], v[158:159], v[120:121]
	v_pk_mul_f32 v[122:123], v[120:121], s[0:1] op_sel_hi:[1,0]
	v_exp_f32_e32 v122, v122
	v_exp_f32_e32 v123, v123
	v_mov_b32_dpp v112, v116 row_ror:1 row_mask:0xf bank_mask:0xf
	v_mov_b32_dpp v113, v117 row_ror:1 row_mask:0xf bank_mask:0xf
	v_mov_b32_dpp v124, v116 row_ror:2 row_mask:0xf bank_mask:0xf
	v_mov_b32_dpp v125, v117 row_ror:2 row_mask:0xf bank_mask:0xf
	v_pk_add_f32 v[116:117], v[122:123], 1.0 op_sel_hi:[1,0]
	v_pk_mul_f32 v[114:115], v[114:115], v[184:185] op_sel_hi:[1,0]
	v_rcp_f32_e32 v116, v116
	v_rcp_f32_e32 v117, v117
	v_mov_b32_dpp v124, v114 row_shr:2 row_mask:0xf bank_mask:0xf
	v_mov_b32_dpp v125, v115 row_shr:2 row_mask:0xf bank_mask:0xf
	v_mov_b32_dpp v112, v114 row_shr:1 row_mask:0xf bank_mask:0xf
	v_mov_b32_dpp v113, v115 row_shr:1 row_mask:0xf bank_mask:0xf
	v_pk_fma_f32 v[122:123], v[134:135], v[124:125], v[130:131]
	v_pk_mul_f32 v[116:117], v[120:121], v[116:117]
	v_pk_fma_f32 v[112:113], v[142:143], v[112:113], v[122:123]
	v_cvt_pk_bf16_f32 v100, v100, v101
	v_pk_fma_f32 v[112:113], v[114:115], v[146:147], v[112:113]
	v_pk_mul_f32 v[110:111], v[110:111], v[182:183] op_sel_hi:[1,0]
	v_pk_mul_f32 v[112:113], v[112:113], v[116:117]
	v_cvt_pk_bf16_f32 v101, v112, v113
	v_mov_b32_dpp v116, v118 row_ror:2 row_mask:0xf bank_mask:0xf
	v_mov_b32_dpp v117, v119 row_ror:2 row_mask:0xf bank_mask:0xf
	v_mov_b32_dpp v112, v118 row_ror:1 row_mask:0xf bank_mask:0xf
	v_mov_b32_dpp v113, v119 row_ror:1 row_mask:0xf bank_mask:0xf
	v_mov_b32_dpp v116, v110 row_shr:2 row_mask:0xf bank_mask:0xf
	v_mov_b32_dpp v117, v111 row_shr:2 row_mask:0xf bank_mask:0xf
	v_mov_b32_dpp v112, v110 row_shr:1 row_mask:0xf bank_mask:0xf
	v_mov_b32_dpp v113, v111 row_shr:1 row_mask:0xf bank_mask:0xf
	v_pk_fma_f32 v[116:117], v[150:151], v[116:117], v[138:139]
	v_pk_fma_f32 v[112:113], v[154:155], v[112:113], v[116:117]
	v_pk_fma_f32 v[112:113], v[110:111], v[158:159], v[112:113]
	v_pk_mul_f32 v[116:117], v[112:113], s[0:1] op_sel_hi:[1,0]
	v_exp_f32_e32 v116, v116
	v_exp_f32_e32 v117, v117
	v_mov_b32_dpp v118, v114 row_ror:1 row_mask:0xf bank_mask:0xf
	v_mov_b32_dpp v119, v115 row_ror:1 row_mask:0xf bank_mask:0xf
	v_mov_b32_dpp v120, v114 row_ror:2 row_mask:0xf bank_mask:0xf
	v_mov_b32_dpp v121, v115 row_ror:2 row_mask:0xf bank_mask:0xf
	v_pk_add_f32 v[114:115], v[116:117], 1.0 op_sel_hi:[1,0]
	v_pk_mul_f32 v[106:107], v[106:107], v[182:183] op_sel_hi:[1,0]
	v_rcp_f32_e32 v114, v114
	v_rcp_f32_e32 v115, v115
	v_mov_b32_dpp v120, v106 row_shr:2 row_mask:0xf bank_mask:0xf
	v_mov_b32_dpp v121, v107 row_shr:2 row_mask:0xf bank_mask:0xf
	v_mov_b32_dpp v118, v106 row_shr:1 row_mask:0xf bank_mask:0xf
	v_mov_b32_dpp v119, v107 row_shr:1 row_mask:0xf bank_mask:0xf
	v_pk_fma_f32 v[116:117], v[134:135], v[120:121], v[130:131]
	v_pk_mul_f32 v[112:113], v[112:113], v[114:115]
	v_pk_fma_f32 v[116:117], v[142:143], v[118:119], v[116:117]
	v_pk_fma_f32 v[116:117], v[106:107], v[146:147], v[116:117]
	v_pk_mul_f32 v[112:113], v[116:117], v[112:113]
	v_cvt_pk_bf16_f32 v104, v104, v105
	v_pk_mul_f32 v[102:103], v[102:103], v[180:181] op_sel_hi:[1,0]
	v_cvt_pk_bf16_f32 v105, v112, v113
	v_mov_b32_dpp v114, v110 row_ror:2 row_mask:0xf bank_mask:0xf
	v_mov_b32_dpp v115, v111 row_ror:2 row_mask:0xf bank_mask:0xf
	v_mov_b32_dpp v112, v110 row_ror:1 row_mask:0xf bank_mask:0xf
	v_mov_b32_dpp v113, v111 row_ror:1 row_mask:0xf bank_mask:0xf
	v_mov_b32_dpp v114, v102 row_shr:2 row_mask:0xf bank_mask:0xf
	v_mov_b32_dpp v115, v103 row_shr:2 row_mask:0xf bank_mask:0xf
	v_mov_b32_dpp v112, v102 row_shr:1 row_mask:0xf bank_mask:0xf
	v_mov_b32_dpp v113, v103 row_shr:1 row_mask:0xf bank_mask:0xf
	v_pk_fma_f32 v[114:115], v[150:151], v[114:115], v[138:139]
; DI float dpp_prev1(float cur, float prevm) {
;     const int o = __builtin_amdgcn_update_dpp(0, __builtin_bit_cast(int, prevm), 0x121, 0xf, 0xf, false);
;     return __builtin_bit_cast(float, __builtin_amdgcn_update_dpp(o, __builtin_bit_cast(int, cur), 0x111, 0xf, 0xf, false));
; }
;     DI void operator()(const AccT& acc, const Unit& u, int wr, int wc, int fr, int fq) const {
;     ...
;                     const f32x2 bg = *(const LAS f32x2*)(P + lc + 2 * jp), g0 = *(const LAS f32x2*)(P + 32 + lc + 2 * jp), g1 = *(const LAS f32x2*)(P + 64 + lc + 2 * jp), g2 = *(const LAS f32x2*)(P + 96 + lc + 2 * jp);
;                     const f32x2 bv = *(const LAS f32x2*)(P + 128 + lc + 2 * jp), v0 = *(const LAS f32x2*)(P + 160 + lc + 2 * jp), v1 = *(const LAS f32x2*)(P + 192 + lc + 2 * jp), v2 = *(const LAS f32x2*)(P + 224 + lc + 2 * jp);
;                     f32x2 G[4], V[4];
; #pragma unroll
;                     for (int m = 0; m < 4; ++m) { G[m] = (f32x2){acc[ai][0][m][n][2 * jp], acc[ai][0][m][n][2 * jp + 1]} * rs[m]; V[m] = (f32x2){acc[ai][1][m][n][2 * jp], acc[ai][1][m][n][2 * jp + 1]} * rs[m]; }
; #pragma unroll
;                     for (int m = 0; m < 4; ++m) {
;                         const f32x2 zz = {0.f, 0.f}; const f32x2 Gp = m ? G[m - 1] : zz, Vp = m ? V[m - 1] : zz;
;                         const f32x2 gp1 = {dpp_prev1(G[m].x, Gp.x), dpp_prev1(G[m].y, Gp.y)}, gp2 = {dpp_prev2(G[m].x, Gp.x), dpp_prev2(G[m].y, Gp.y)};
;                         const f32x2 vp1 = {dpp_prev1(V[m].x, Vp.x), dpp_prev1(V[m].y, Vp.y)}, vp2 = {dpp_prev2(V[m].x, Vp.x), dpp_prev2(V[m].y, Vp.y)};
;                         const f32x2 gc = bg + g0 * gp2 + g1 * gp1 + g2 * G[m];
;                         const f32x2 vc = bv + v0 * vp2 + v1 * vp1 + v2 * V[m];
;                         const f32x2 xe = gc * (-LOG2E);
;                         f32x2 dn = {__builtin_amdgcn_exp2f(xe.x), __builtin_amdgcn_exp2f(xe.y)}; dn = dn + 1.0f;
;                         const f32x2 rc = {__builtin_amdgcn_rcpf(dn.x), __builtin_amdgcn_rcpf(dn.y)};
;                         const f32x2 rr = gc * rc * vc;
;                         wpk[m][jp] = pk2(rr.x, rr.y); }
;                 }
; #pragma unroll
;                 for (int m = 0; m < 4; ++m) { const int row = m ? tok0 + 16 * m : row0;
;                     *(u32x2*)(ACT + (size_t)row * 2816 + cl + 4 * n) = (u32x2){wpk[m][0], wpk[m][1]}; }
	v_pk_fma_f32 v[112:113], v[154:155], v[112:113], v[114:115]
	v_pk_fma_f32 v[102:103], v[102:103], v[158:159], v[112:113]
	v_pk_mul_f32 v[112:113], v[102:103], s[0:1] op_sel_hi:[1,0]
	v_exp_f32_e32 v112, v112
	v_exp_f32_e32 v113, v113
	v_mov_b32_dpp v110, v106 row_ror:1 row_mask:0xf bank_mask:0xf
	v_mov_b32_dpp v111, v107 row_ror:1 row_mask:0xf bank_mask:0xf
	v_mov_b32_dpp v116, v106 row_ror:2 row_mask:0xf bank_mask:0xf
	v_mov_b32_dpp v117, v107 row_ror:2 row_mask:0xf bank_mask:0xf
	v_pk_add_f32 v[106:107], v[112:113], 1.0 op_sel_hi:[1,0]
	v_pk_mul_f32 v[98:99], v[98:99], v[180:181] op_sel_hi:[1,0]
	v_rcp_f32_e32 v106, v106
	v_rcp_f32_e32 v107, v107
	v_mov_b32_dpp v116, v98 row_shr:2 row_mask:0xf bank_mask:0xf
	v_mov_b32_dpp v117, v99 row_shr:2 row_mask:0xf bank_mask:0xf
	v_mov_b32_dpp v110, v98 row_shr:1 row_mask:0xf bank_mask:0xf
	v_mov_b32_dpp v111, v99 row_shr:1 row_mask:0xf bank_mask:0xf
	v_pk_fma_f32 v[112:113], v[134:135], v[116:117], v[130:131]
	v_pk_mul_f32 v[102:103], v[102:103], v[106:107]
	v_pk_fma_f32 v[110:111], v[142:143], v[110:111], v[112:113]
	v_mov_b64_e32 v[128:129], s[4:5]
	v_pk_fma_f32 v[98:99], v[98:99], v[146:147], v[110:111]
	v_cvt_pk_bf16_f32 v108, v108, v109
	v_pk_mul_f32 v[98:99], v[98:99], v[102:103]
	v_lshlrev_b64 v[130:131], 1, v[188:189]
	v_cvt_pk_bf16_f32 v109, v98, v99
	v_mad_i64_i32 v[98:99], s[10:11], v208, s48, v[128:129]
	v_lshl_add_u64 v[132:133], v[98:99], 0, v[130:131]
	global_store_dwordx2 v[132:133], v[96:97], off
	v_mad_i64_i32 v[96:97], s[10:11], v205, s48, v[128:129]
	v_lshl_add_u64 v[134:135], v[96:97], 0, v[130:131]
	v_mad_i64_i32 v[96:97], s[10:11], v206, s48, v[128:129]
	v_lshl_add_u64 v[136:137], v[96:97], 0, v[130:131]
	v_mad_i64_i32 v[96:97], s[10:11], v207, s48, v[128:129]
	v_lshl_add_u64 v[138:139], v[96:97], 0, v[130:131]
	global_store_dwordx2 v[134:135], v[100:101], off
	global_store_dwordx2 v[136:137], v[104:105], off
	global_store_dwordx2 v[138:139], v[108:109], off
	v_pk_mul_f32 v[92:93], v[92:93], v[186:187] op_sel_hi:[1,0]
	v_pk_mul_f32 v[142:143], v[68:69], v[180:181] op_sel_hi:[1,0]
	v_mov_b32_e32 v68, v183
	v_mov_b32_e32 v69, v183
	v_pk_mul_f32 v[144:145], v[64:65], v[180:181] op_sel_hi:[1,0]
	v_mov_b32_e32 v64, v181
	v_mov_b32_e32 v65, v181
	v_mov_b32_dpp v68, v92 row_shr:2 row_mask:0xf bank_mask:0xf
	v_mov_b32_dpp v69, v93 row_shr:2 row_mask:0xf bank_mask:0xf
	ds_read_b128 v[104:107], v200 offset:16
	ds_read_b128 v[116:119], v200 offset:144
	ds_read_b128 v[120:123], v200 offset:272
	ds_read_b128 v[124:127], v200 offset:400
	ds_read_b128 v[96:99], v200 offset:528
	ds_read_b128 v[100:103], v200 offset:656
	ds_read_b128 v[108:111], v200 offset:784
	ds_read_b128 v[112:115], v200 offset:912
	v_mov_b32_dpp v64, v92 row_shr:1 row_mask:0xf bank_mask:0xf
	v_mov_b32_dpp v65, v93 row_shr:1 row_mask:0xf bank_mask:0xf
	s_waitcnt lgkmcnt(6)
	v_pk_fma_f32 v[68:69], v[116:117], v[68:69], v[104:105]
	v_pk_mul_f32 v[88:89], v[88:89], v[186:187] op_sel_hi:[1,0]
	s_waitcnt lgkmcnt(5)
	v_pk_fma_f32 v[64:65], v[120:121], v[64:65], v[68:69]
	v_mov_b32_e32 v146, v183
	s_waitcnt lgkmcnt(4)
	v_pk_fma_f32 v[64:65], v[92:93], v[124:125], v[64:65]
	v_mov_b32_e32 v147, v183
	v_pk_mul_f32 v[68:69], v[64:65], s[0:1] op_sel_hi:[1,0]
	v_pk_mul_f32 v[140:141], v[72:73], v[182:183] op_sel_hi:[1,0]
	v_exp_f32_e32 v68, v68
	v_exp_f32_e32 v69, v69
	v_mov_b32_e32 v72, v181
	v_mov_b32_e32 v73, v181
	v_mov_b32_dpp v146, v88 row_shr:2 row_mask:0xf bank_mask:0xf
	v_pk_add_f32 v[68:69], v[68:69], 1.0 op_sel_hi:[1,0]
	v_mov_b32_dpp v147, v89 row_shr:2 row_mask:0xf bank_mask:0xf
	v_rcp_f32_e32 v68, v68
	v_rcp_f32_e32 v69, v69
	v_mov_b32_dpp v72, v88 row_shr:1 row_mask:0xf bank_mask:0xf
	v_mov_b32_dpp v73, v89 row_shr:1 row_mask:0xf bank_mask:0xf
	s_waitcnt lgkmcnt(2)
	v_pk_fma_f32 v[146:147], v[100:101], v[146:147], v[96:97]
	v_pk_mul_f32 v[64:65], v[64:65], v[68:69]
	s_waitcnt lgkmcnt(1)
	v_pk_fma_f32 v[72:73], v[108:109], v[72:73], v[146:147]
	v_pk_mul_f32 v[84:85], v[84:85], v[184:185] op_sel_hi:[1,0]
	s_waitcnt lgkmcnt(0)
	v_pk_fma_f32 v[72:73], v[88:89], v[112:113], v[72:73]
	v_pk_mul_f32 v[64:65], v[72:73], v[64:65]
	v_mov_b32_dpp v72, v92 row_ror:2 row_mask:0xf bank_mask:0xf
	v_mov_b32_dpp v73, v93 row_ror:2 row_mask:0xf bank_mask:0xf
	v_mov_b32_dpp v68, v92 row_ror:1 row_mask:0xf bank_mask:0xf
	v_mov_b32_dpp v69, v93 row_ror:1 row_mask:0xf bank_mask:0xf
	v_mov_b32_dpp v72, v84 row_shr:2 row_mask:0xf bank_mask:0xf
	v_mov_b32_dpp v73, v85 row_shr:2 row_mask:0xf bank_mask:0xf
	v_mov_b32_dpp v68, v84 row_shr:1 row_mask:0xf bank_mask:0xf
	v_mov_b32_dpp v69, v85 row_shr:1 row_mask:0xf bank_mask:0xf
	v_pk_fma_f32 v[72:73], v[116:117], v[72:73], v[104:105]
	v_pk_fma_f32 v[68:69], v[120:121], v[68:69], v[72:73]
	v_pk_fma_f32 v[68:69], v[84:85], v[124:125], v[68:69]
	v_pk_mul_f32 v[80:81], v[80:81], v[184:185] op_sel_hi:[1,0]
	v_pk_mul_f32 v[72:73], v[68:69], s[0:1] op_sel_hi:[1,0]
	v_exp_f32_e32 v72, v72
	v_exp_f32_e32 v73, v73
	v_mov_b32_dpp v146, v88 row_ror:2 row_mask:0xf bank_mask:0xf
	v_mov_b32_dpp v147, v89 row_ror:2 row_mask:0xf bank_mask:0xf
	v_pk_add_f32 v[72:73], v[72:73], 1.0 op_sel_hi:[1,0]
	v_mov_b32_dpp v92, v88 row_ror:1 row_mask:0xf bank_mask:0xf
	v_rcp_f32_e32 v72, v72
	v_rcp_f32_e32 v73, v73
	v_mov_b32_dpp v93, v89 row_ror:1 row_mask:0xf bank_mask:0xf
	v_mov_b32_dpp v146, v80 row_shr:2 row_mask:0xf bank_mask:0xf
	v_mov_b32_dpp v147, v81 row_shr:2 row_mask:0xf bank_mask:0xf
	v_mov_b32_dpp v92, v80 row_shr:1 row_mask:0xf bank_mask:0xf
	v_mov_b32_dpp v93, v81 row_shr:1 row_mask:0xf bank_mask:0xf
	v_pk_fma_f32 v[88:89], v[100:101], v[146:147], v[96:97]
	v_pk_mul_f32 v[68:69], v[68:69], v[72:73]
; #define LAS __attribute__((address_space(3)))
; DI float dpp_prev1(float cur, float prevm) {
;     const int o = __builtin_amdgcn_update_dpp(0, __builtin_bit_cast(int, prevm), 0x121, 0xf, 0xf, false);
;     return __builtin_bit_cast(float, __builtin_amdgcn_update_dpp(o, __builtin_bit_cast(int, cur), 0x111, 0xf, 0xf, false));
; }
; DI float dpp_prev2(float cur, float prevm) {
;     const int o = __builtin_amdgcn_update_dpp(0, __builtin_bit_cast(int, prevm), 0x122, 0xf, 0xf, false);
;     DI void operator()(const AccT& acc, const Unit& u, int wr, int wc, int fr, int fq) const {
;     ...
;                     const f32x2 bg = *(const LAS f32x2*)(P + lc + 2 * jp), g0 = *(const LAS f32x2*)(P + 32 + lc + 2 * jp), g1 = *(const LAS f32x2*)(P + 64 + lc + 2 * jp), g2 = *(const LAS f32x2*)(P + 96 + lc + 2 * jp);
;                     const f32x2 bv = *(const LAS f32x2*)(P + 128 + lc + 2 * jp), v0 = *(const LAS f32x2*)(P + 160 + lc + 2 * jp), v1 = *(const LAS f32x2*)(P + 192 + lc + 2 * jp), v2 = *(const LAS f32x2*)(P + 224 + lc + 2 * jp);
;                     f32x2 G[4], V[4];
; #pragma unroll
;                     for (int m = 0; m < 4; ++m) { G[m] = (f32x2){acc[ai][0][m][n][2 * jp], acc[ai][0][m][n][2 * jp + 1]} * rs[m]; V[m] = (f32x2){acc[ai][1][m][n][2 * jp], acc[ai][1][m][n][2 * jp + 1]} * rs[m]; }
; #pragma unroll
;                     for (int m = 0; m < 4; ++m) {
;                         const f32x2 zz = {0.f, 0.f}; const f32x2 Gp = m ? G[m - 1] : zz, Vp = m ? V[m - 1] : zz;
;                         const f32x2 gp1 = {dpp_prev1(G[m].x, Gp.x), dpp_prev1(G[m].y, Gp.y)}, gp2 = {dpp_prev2(G[m].x, Gp.x), dpp_prev2(G[m].y, Gp.y)};
;                         const f32x2 vp1 = {dpp_prev1(V[m].x, Vp.x), dpp_prev1(V[m].y, Vp.y)}, vp2 = {dpp_prev2(V[m].x, Vp.x), dpp_prev2(V[m].y, Vp.y)};
;                         const f32x2 gc = bg + g0 * gp2 + g1 * gp1 + g2 * G[m];
;                         const f32x2 vc = bv + v0 * vp2 + v1 * vp1 + v2 * V[m];
;                         const f32x2 xe = gc * (-LOG2E);
;                         f32x2 dn = {__builtin_amdgcn_exp2f(xe.x), __builtin_amdgcn_exp2f(xe.y)}; dn = dn + 1.0f;
;                         const f32x2 rc = {__builtin_amdgcn_rcpf(dn.x), __builtin_amdgcn_rcpf(dn.y)};
;                         const f32x2 rr = gc * rc * vc;
;                         wpk[m][jp] = pk2(rr.x, rr.y); }
	v_pk_fma_f32 v[88:89], v[108:109], v[92:93], v[88:89]
	v_pk_mul_f32 v[76:77], v[76:77], v[182:183] op_sel_hi:[1,0]
	v_pk_fma_f32 v[88:89], v[80:81], v[112:113], v[88:89]
	v_pk_mul_f32 v[68:69], v[88:89], v[68:69]
	v_mov_b32_dpp v88, v84 row_ror:2 row_mask:0xf bank_mask:0xf
	v_mov_b32_dpp v89, v85 row_ror:2 row_mask:0xf bank_mask:0xf
	v_mov_b32_dpp v72, v84 row_ror:1 row_mask:0xf bank_mask:0xf
	v_mov_b32_dpp v73, v85 row_ror:1 row_mask:0xf bank_mask:0xf
	v_mov_b32_dpp v88, v76 row_shr:2 row_mask:0xf bank_mask:0xf
	v_mov_b32_dpp v89, v77 row_shr:2 row_mask:0xf bank_mask:0xf
	v_mov_b32_dpp v72, v76 row_shr:1 row_mask:0xf bank_mask:0xf
	v_mov_b32_dpp v73, v77 row_shr:1 row_mask:0xf bank_mask:0xf
	v_pk_fma_f32 v[88:89], v[116:117], v[88:89], v[104:105]
	v_pk_fma_f32 v[72:73], v[120:121], v[72:73], v[88:89]
	v_pk_fma_f32 v[72:73], v[76:77], v[124:125], v[72:73]
	v_pk_mul_f32 v[88:89], v[72:73], s[0:1] op_sel_hi:[1,0]
	v_exp_f32_e32 v88, v88
	v_exp_f32_e32 v89, v89
	v_mov_b32_dpp v84, v80 row_ror:1 row_mask:0xf bank_mask:0xf
	v_mov_b32_dpp v85, v81 row_ror:1 row_mask:0xf bank_mask:0xf
	v_mov_b32_dpp v92, v80 row_ror:2 row_mask:0xf bank_mask:0xf
	v_mov_b32_dpp v93, v81 row_ror:2 row_mask:0xf bank_mask:0xf
	v_pk_add_f32 v[80:81], v[88:89], 1.0 op_sel_hi:[1,0]
	v_mov_b32_dpp v92, v140 row_shr:2 row_mask:0xf bank_mask:0xf
	v_rcp_f32_e32 v80, v80
	v_rcp_f32_e32 v81, v81
	v_mov_b32_dpp v93, v141 row_shr:2 row_mask:0xf bank_mask:0xf
	v_mov_b32_dpp v84, v140 row_shr:1 row_mask:0xf bank_mask:0xf
	v_mov_b32_dpp v85, v141 row_shr:1 row_mask:0xf bank_mask:0xf
	v_pk_fma_f32 v[88:89], v[100:101], v[92:93], v[96:97]
	v_pk_mul_f32 v[72:73], v[72:73], v[80:81]
	v_pk_fma_f32 v[84:85], v[108:109], v[84:85], v[88:89]
	v_pk_fma_f32 v[84:85], v[140:141], v[112:113], v[84:85]
	v_pk_mul_f32 v[72:73], v[84:85], v[72:73]
	v_mov_b32_dpp v80, v76 row_ror:1 row_mask:0xf bank_mask:0xf
	v_mov_b32_dpp v84, v76 row_ror:2 row_mask:0xf bank_mask:0xf
	v_mov_b32_dpp v85, v77 row_ror:2 row_mask:0xf bank_mask:0xf
	v_mov_b32_dpp v81, v77 row_ror:1 row_mask:0xf bank_mask:0xf
	v_mov_b32_dpp v84, v142 row_shr:2 row_mask:0xf bank_mask:0xf
	v_mov_b32_dpp v85, v143 row_shr:2 row_mask:0xf bank_mask:0xf
	v_mov_b32_dpp v80, v142 row_shr:1 row_mask:0xf bank_mask:0xf
	v_mov_b32_dpp v81, v143 row_shr:1 row_mask:0xf bank_mask:0xf
	v_pk_fma_f32 v[84:85], v[116:117], v[84:85], v[104:105]
	v_pk_fma_f32 v[80:81], v[120:121], v[80:81], v[84:85]
	v_pk_fma_f32 v[80:81], v[142:143], v[124:125], v[80:81]
	v_pk_mul_f32 v[84:85], v[80:81], s[0:1] op_sel_hi:[1,0]
	v_exp_f32_e32 v84, v84
	v_exp_f32_e32 v85, v85
	v_mov_b32_dpp v88, v140 row_ror:2 row_mask:0xf bank_mask:0xf
	v_mov_b32_dpp v89, v141 row_ror:2 row_mask:0xf bank_mask:0xf
	v_mov_b32_dpp v76, v140 row_ror:1 row_mask:0xf bank_mask:0xf
	v_pk_add_f32 v[84:85], v[84:85], 1.0 op_sel_hi:[1,0]
	v_mov_b32_dpp v77, v141 row_ror:1 row_mask:0xf bank_mask:0xf
	v_rcp_f32_e32 v84, v84
	v_rcp_f32_e32 v85, v85
	v_mov_b32_dpp v88, v144 row_shr:2 row_mask:0xf bank_mask:0xf
	v_mov_b32_dpp v89, v145 row_shr:2 row_mask:0xf bank_mask:0xf
	v_mov_b32_dpp v76, v144 row_shr:1 row_mask:0xf bank_mask:0xf
	v_mov_b32_dpp v77, v145 row_shr:1 row_mask:0xf bank_mask:0xf
	v_pk_fma_f32 v[88:89], v[100:101], v[88:89], v[96:97]
	v_pk_mul_f32 v[80:81], v[80:81], v[84:85]
	v_pk_fma_f32 v[76:77], v[108:109], v[76:77], v[88:89]
	v_pk_mul_f32 v[84:85], v[90:91], v[186:187] op_sel_hi:[1,0]
	v_pk_fma_f32 v[76:77], v[144:145], v[112:113], v[76:77]
	v_mov_b32_e32 v90, v183
	v_pk_mul_f32 v[76:77], v[76:77], v[80:81]
	v_pk_mul_f32 v[80:81], v[94:95], v[186:187] op_sel_hi:[1,0]
	v_mov_b32_e32 v91, v183
	v_mov_b32_e32 v88, v181
	v_mov_b32_e32 v89, v181
	v_mov_b32_dpp v90, v80 row_shr:2 row_mask:0xf bank_mask:0xf
	v_mov_b32_dpp v91, v81 row_shr:2 row_mask:0xf bank_mask:0xf
	v_mov_b32_dpp v88, v80 row_shr:1 row_mask:0xf bank_mask:0xf
	v_mov_b32_dpp v89, v81 row_shr:1 row_mask:0xf bank_mask:0xf
	v_pk_fma_f32 v[90:91], v[118:119], v[90:91], v[106:107]
	v_mov_b32_e32 v94, v183
	v_pk_fma_f32 v[88:89], v[122:123], v[88:89], v[90:91]
	v_mov_b32_e32 v95, v183
	v_pk_fma_f32 v[88:89], v[80:81], v[126:127], v[88:89]
	v_mov_b32_e32 v92, v181
	v_pk_mul_f32 v[90:91], v[88:89], s[0:1] op_sel_hi:[1,0]
	v_mov_b32_e32 v93, v181
	v_exp_f32_e32 v90, v90
	v_exp_f32_e32 v91, v91
	v_mov_b32_dpp v94, v84 row_shr:2 row_mask:0xf bank_mask:0xf
	v_mov_b32_dpp v95, v85 row_shr:2 row_mask:0xf bank_mask:0xf
	v_mov_b32_dpp v92, v84 row_shr:1 row_mask:0xf bank_mask:0xf
	v_pk_add_f32 v[90:91], v[90:91], 1.0 op_sel_hi:[1,0]
	v_mov_b32_dpp v93, v85 row_shr:1 row_mask:0xf bank_mask:0xf
	v_rcp_f32_e32 v90, v90
	v_rcp_f32_e32 v91, v91
	v_pk_fma_f32 v[94:95], v[102:103], v[94:95], v[98:99]
	v_cvt_pk_bf16_f32 v64, v64, v65
	v_pk_fma_f32 v[92:93], v[110:111], v[92:93], v[94:95]
	v_pk_mul_f32 v[88:89], v[88:89], v[90:91]
	v_pk_fma_f32 v[92:93], v[84:85], v[114:115], v[92:93]
	v_pk_mul_f32 v[88:89], v[92:93], v[88:89]
	v_pk_mul_f32 v[86:87], v[86:87], v[184:185] op_sel_hi:[1,0]
	v_cvt_pk_bf16_f32 v65, v88, v89
	v_mov_b32_dpp v90, v80 row_ror:2 row_mask:0xf bank_mask:0xf
	v_mov_b32_dpp v91, v81 row_ror:2 row_mask:0xf bank_mask:0xf
	v_mov_b32_dpp v88, v80 row_ror:1 row_mask:0xf bank_mask:0xf
	v_mov_b32_dpp v89, v81 row_ror:1 row_mask:0xf bank_mask:0xf
	v_mov_b32_dpp v90, v86 row_shr:2 row_mask:0xf bank_mask:0xf
	v_mov_b32_dpp v91, v87 row_shr:2 row_mask:0xf bank_mask:0xf
	v_mov_b32_dpp v88, v86 row_shr:1 row_mask:0xf bank_mask:0xf
	v_mov_b32_dpp v89, v87 row_shr:1 row_mask:0xf bank_mask:0xf
	v_pk_fma_f32 v[90:91], v[118:119], v[90:91], v[106:107]
	v_pk_fma_f32 v[88:89], v[122:123], v[88:89], v[90:91]
	v_pk_fma_f32 v[88:89], v[86:87], v[126:127], v[88:89]
; DI float dpp_prev1(float cur, float prevm) {
;     const int o = __builtin_amdgcn_update_dpp(0, __builtin_bit_cast(int, prevm), 0x121, 0xf, 0xf, false);
;     return __builtin_bit_cast(float, __builtin_amdgcn_update_dpp(o, __builtin_bit_cast(int, cur), 0x111, 0xf, 0xf, false));
; }
;     DI void operator()(const AccT& acc, const Unit& u, int wr, int wc, int fr, int fq) const {
;     ...
;                     const f32x2 bg = *(const LAS f32x2*)(P + lc + 2 * jp), g0 = *(const LAS f32x2*)(P + 32 + lc + 2 * jp), g1 = *(const LAS f32x2*)(P + 64 + lc + 2 * jp), g2 = *(const LAS f32x2*)(P + 96 + lc + 2 * jp);
;                     const f32x2 bv = *(const LAS f32x2*)(P + 128 + lc + 2 * jp), v0 = *(const LAS f32x2*)(P + 160 + lc + 2 * jp), v1 = *(const LAS f32x2*)(P + 192 + lc + 2 * jp), v2 = *(const LAS f32x2*)(P + 224 + lc + 2 * jp);
;                     f32x2 G[4], V[4];
; #pragma unroll
;                     for (int m = 0; m < 4; ++m) { G[m] = (f32x2){acc[ai][0][m][n][2 * jp], acc[ai][0][m][n][2 * jp + 1]} * rs[m]; V[m] = (f32x2){acc[ai][1][m][n][2 * jp], acc[ai][1][m][n][2 * jp + 1]} * rs[m]; }
; #pragma unroll
;                     for (int m = 0; m < 4; ++m) {
;                         const f32x2 zz = {0.f, 0.f}; const f32x2 Gp = m ? G[m - 1] : zz, Vp = m ? V[m - 1] : zz;
;                         const f32x2 gp1 = {dpp_prev1(G[m].x, Gp.x), dpp_prev1(G[m].y, Gp.y)}, gp2 = {dpp_prev2(G[m].x, Gp.x), dpp_prev2(G[m].y, Gp.y)};
;                         const f32x2 vp1 = {dpp_prev1(V[m].x, Vp.x), dpp_prev1(V[m].y, Vp.y)}, vp2 = {dpp_prev2(V[m].x, Vp.x), dpp_prev2(V[m].y, Vp.y)};
;                         const f32x2 gc = bg + g0 * gp2 + g1 * gp1 + g2 * G[m];
;                         const f32x2 vc = bv + v0 * vp2 + v1 * vp1 + v2 * V[m];
;                         const f32x2 xe = gc * (-LOG2E);
;                         f32x2 dn = {__builtin_amdgcn_exp2f(xe.x), __builtin_amdgcn_exp2f(xe.y)}; dn = dn + 1.0f;
;                         const f32x2 rc = {__builtin_amdgcn_rcpf(dn.x), __builtin_amdgcn_rcpf(dn.y)};
;                         const f32x2 rr = gc * rc * vc;
;                         wpk[m][jp] = pk2(rr.x, rr.y); }
;                 }
; #pragma unroll
;                 for (int m = 0; m < 4; ++m) { const int row = m ? tok0 + 16 * m : row0;
;                     *(u32x2*)(ACT + (size_t)row * 2816 + cl + 4 * n) = (u32x2){wpk[m][0], wpk[m][1]}; }
	v_pk_mul_f32 v[90:91], v[88:89], s[0:1] op_sel_hi:[1,0]
	v_exp_f32_e32 v90, v90
	v_exp_f32_e32 v91, v91
	v_mov_b32_dpp v80, v84 row_ror:1 row_mask:0xf bank_mask:0xf
	v_mov_b32_dpp v81, v85 row_ror:1 row_mask:0xf bank_mask:0xf
	v_mov_b32_dpp v92, v84 row_ror:2 row_mask:0xf bank_mask:0xf
	v_mov_b32_dpp v93, v85 row_ror:2 row_mask:0xf bank_mask:0xf
	v_pk_add_f32 v[84:85], v[90:91], 1.0 op_sel_hi:[1,0]
	v_pk_mul_f32 v[82:83], v[82:83], v[184:185] op_sel_hi:[1,0]
	v_rcp_f32_e32 v84, v84
	v_rcp_f32_e32 v85, v85
	v_mov_b32_dpp v92, v82 row_shr:2 row_mask:0xf bank_mask:0xf
	v_mov_b32_dpp v93, v83 row_shr:2 row_mask:0xf bank_mask:0xf
	v_mov_b32_dpp v80, v82 row_shr:1 row_mask:0xf bank_mask:0xf
	v_mov_b32_dpp v81, v83 row_shr:1 row_mask:0xf bank_mask:0xf
	v_pk_fma_f32 v[90:91], v[102:103], v[92:93], v[98:99]
	v_pk_mul_f32 v[84:85], v[88:89], v[84:85]
	v_pk_fma_f32 v[80:81], v[110:111], v[80:81], v[90:91]
	v_cvt_pk_bf16_f32 v68, v68, v69
	v_pk_fma_f32 v[80:81], v[82:83], v[114:115], v[80:81]
	v_pk_mul_f32 v[78:79], v[78:79], v[182:183] op_sel_hi:[1,0]
	v_pk_mul_f32 v[80:81], v[80:81], v[84:85]
	v_cvt_pk_bf16_f32 v69, v80, v81
	v_mov_b32_dpp v84, v86 row_ror:2 row_mask:0xf bank_mask:0xf
	v_mov_b32_dpp v85, v87 row_ror:2 row_mask:0xf bank_mask:0xf
	v_mov_b32_dpp v80, v86 row_ror:1 row_mask:0xf bank_mask:0xf
	v_mov_b32_dpp v81, v87 row_ror:1 row_mask:0xf bank_mask:0xf
	v_mov_b32_dpp v84, v78 row_shr:2 row_mask:0xf bank_mask:0xf
	v_mov_b32_dpp v85, v79 row_shr:2 row_mask:0xf bank_mask:0xf
	v_mov_b32_dpp v80, v78 row_shr:1 row_mask:0xf bank_mask:0xf
	v_mov_b32_dpp v81, v79 row_shr:1 row_mask:0xf bank_mask:0xf
	v_pk_fma_f32 v[84:85], v[118:119], v[84:85], v[106:107]
	v_pk_fma_f32 v[80:81], v[122:123], v[80:81], v[84:85]
	v_pk_fma_f32 v[80:81], v[78:79], v[126:127], v[80:81]
	v_pk_mul_f32 v[84:85], v[80:81], s[0:1] op_sel_hi:[1,0]
	v_exp_f32_e32 v84, v84
	v_exp_f32_e32 v85, v85
	v_mov_b32_dpp v86, v82 row_ror:1 row_mask:0xf bank_mask:0xf
	v_mov_b32_dpp v87, v83 row_ror:1 row_mask:0xf bank_mask:0xf
	v_mov_b32_dpp v88, v82 row_ror:2 row_mask:0xf bank_mask:0xf
	v_mov_b32_dpp v89, v83 row_ror:2 row_mask:0xf bank_mask:0xf
	v_pk_add_f32 v[82:83], v[84:85], 1.0 op_sel_hi:[1,0]
	v_pk_mul_f32 v[74:75], v[74:75], v[182:183] op_sel_hi:[1,0]
	v_rcp_f32_e32 v82, v82
	v_rcp_f32_e32 v83, v83
	v_mov_b32_dpp v88, v74 row_shr:2 row_mask:0xf bank_mask:0xf
	v_mov_b32_dpp v89, v75 row_shr:2 row_mask:0xf bank_mask:0xf
	v_mov_b32_dpp v86, v74 row_shr:1 row_mask:0xf bank_mask:0xf
	v_mov_b32_dpp v87, v75 row_shr:1 row_mask:0xf bank_mask:0xf
	v_pk_fma_f32 v[84:85], v[102:103], v[88:89], v[98:99]
	v_pk_mul_f32 v[80:81], v[80:81], v[82:83]
	v_pk_fma_f32 v[84:85], v[110:111], v[86:87], v[84:85]
	v_pk_fma_f32 v[84:85], v[74:75], v[114:115], v[84:85]
	v_pk_mul_f32 v[80:81], v[84:85], v[80:81]
	v_cvt_pk_bf16_f32 v72, v72, v73
	v_pk_mul_f32 v[70:71], v[70:71], v[180:181] op_sel_hi:[1,0]
	v_cvt_pk_bf16_f32 v73, v80, v81
	v_mov_b32_dpp v82, v78 row_ror:2 row_mask:0xf bank_mask:0xf
	v_mov_b32_dpp v83, v79 row_ror:2 row_mask:0xf bank_mask:0xf
	v_mov_b32_dpp v80, v78 row_ror:1 row_mask:0xf bank_mask:0xf
	v_mov_b32_dpp v81, v79 row_ror:1 row_mask:0xf bank_mask:0xf
	v_mov_b32_dpp v82, v70 row_shr:2 row_mask:0xf bank_mask:0xf
	v_mov_b32_dpp v83, v71 row_shr:2 row_mask:0xf bank_mask:0xf
	v_mov_b32_dpp v80, v70 row_shr:1 row_mask:0xf bank_mask:0xf
	v_mov_b32_dpp v81, v71 row_shr:1 row_mask:0xf bank_mask:0xf
	v_pk_fma_f32 v[82:83], v[118:119], v[82:83], v[106:107]
	v_pk_fma_f32 v[80:81], v[122:123], v[80:81], v[82:83]
	v_pk_fma_f32 v[70:71], v[70:71], v[126:127], v[80:81]
	v_pk_mul_f32 v[80:81], v[70:71], s[0:1] op_sel_hi:[1,0]
	v_exp_f32_e32 v80, v80
	v_exp_f32_e32 v81, v81
	v_mov_b32_dpp v78, v74 row_ror:1 row_mask:0xf bank_mask:0xf
	v_mov_b32_dpp v79, v75 row_ror:1 row_mask:0xf bank_mask:0xf
	v_mov_b32_dpp v84, v74 row_ror:2 row_mask:0xf bank_mask:0xf
	v_mov_b32_dpp v85, v75 row_ror:2 row_mask:0xf bank_mask:0xf
	v_pk_add_f32 v[74:75], v[80:81], 1.0 op_sel_hi:[1,0]
	v_pk_mul_f32 v[66:67], v[66:67], v[180:181] op_sel_hi:[1,0]
	v_rcp_f32_e32 v74, v74
	v_rcp_f32_e32 v75, v75
	v_mov_b32_dpp v84, v66 row_shr:2 row_mask:0xf bank_mask:0xf
	v_mov_b32_dpp v85, v67 row_shr:2 row_mask:0xf bank_mask:0xf
	v_mov_b32_dpp v78, v66 row_shr:1 row_mask:0xf bank_mask:0xf
	v_mov_b32_dpp v79, v67 row_shr:1 row_mask:0xf bank_mask:0xf
	v_pk_fma_f32 v[80:81], v[102:103], v[84:85], v[98:99]
	v_pk_mul_f32 v[70:71], v[70:71], v[74:75]
	v_pk_fma_f32 v[78:79], v[110:111], v[78:79], v[80:81]
	v_cvt_pk_bf16_f32 v76, v76, v77
	v_pk_fma_f32 v[66:67], v[66:67], v[114:115], v[78:79]
	s_nop 0
	v_pk_mul_f32 v[66:67], v[66:67], v[70:71]
	s_nop 0
	v_cvt_pk_bf16_f32 v77, v66, v67
	global_store_dwordx2 v[132:133], v[64:65], off offset:8
	global_store_dwordx2 v[134:135], v[68:69], off offset:8
	global_store_dwordx2 v[136:137], v[72:73], off offset:8
	global_store_dwordx2 v[138:139], v[76:77], off offset:8
	v_add_u32_e32 v96, 0x7c, v204
	v_med3_i32 v64, v96, 0, s51
	v_add_u32_e32 v97, 0x8c, v204
	v_add_u32_e32 v99, 0x9c, v204
	v_add_u32_e32 v101, 0xac, v204
	v_lshlrev_b32_e32 v64, 3, v64
	v_med3_i32 v65, v97, 0, s51
	v_med3_i32 v66, v99, 0, s51
	v_med3_i32 v67, v101, 0, s51
	v_lshlrev_b32_e32 v65, 3, v65
	v_lshlrev_b32_e32 v66, 3, v66
	v_lshlrev_b32_e32 v67, 3, v67
	global_load_dwordx2 v[104:105], v64, s[16:17]
	global_load_dwordx2 v[106:107], v65, s[16:17]
	global_load_dwordx2 v[108:109], v66, s[16:17]
	global_load_dwordx2 v[110:111], v67, s[16:17]
	v_cndmask_b32_e64 v103, v96, v190, s[6:7]
	v_mov_b32_e32 v112, v181
	v_mov_b32_e32 v113, v181
	ds_read_b128 v[72:75], v200
	ds_read_b128 v[84:87], v200 offset:128
	ds_read_b128 v[88:91], v200 offset:256
	ds_read_b128 v[92:95], v200 offset:384
	ds_read_b128 v[64:67], v200 offset:512
	ds_read_b128 v[68:71], v200 offset:640
	ds_read_b128 v[76:79], v200 offset:768
	ds_read_b128 v[80:83], v200 offset:896
	s_waitcnt vmcnt(3)
; DI float dpp_prev1(float cur, float prevm) {
;     DI void operator()(const AccT& acc, const Unit& u, int wr, int wc, int fr, int fq) const {
;     ...
;             for (int m = 0; m < 4; ++m) { const int t = tok0 + 16 * m; const int tc = t < 0 ? 0 : (t >= S ? S - 1 : t); const float r = rs_from_ss(rowss[tc]); rs[m] = t < 0 ? 0.f : r; }
;             const int row0 = fr < 2 ? (S + 236 + fr) : tok0;
; #pragma unroll
;             for (int n = 0; n < 2; ++n) {
;                 const int lc = 8 * fq + 4 * n;
;                 unsigned wpk[4][2];
; #pragma unroll
;                 for (int jp = 0; jp < 2; ++jp) {
;                     const f32x2 bg = *(const LAS f32x2*)(P + lc + 2 * jp), g0 = *(const LAS f32x2*)(P + 32 + lc + 2 * jp), g1 = *(const LAS f32x2*)(P + 64 + lc + 2 * jp), g2 = *(const LAS f32x2*)(P + 96 + lc + 2 * jp);
;                     const f32x2 bv = *(const LAS f32x2*)(P + 128 + lc + 2 * jp), v0 = *(const LAS f32x2*)(P + 160 + lc + 2 * jp), v1 = *(const LAS f32x2*)(P + 192 + lc + 2 * jp), v2 = *(const LAS f32x2*)(P + 224 + lc + 2 * jp);
;                     f32x2 G[4], V[4];
; #pragma unroll
;                     for (int m = 0; m < 4; ++m) { G[m] = (f32x2){acc[ai][0][m][n][2 * jp], acc[ai][0][m][n][2 * jp + 1]} * rs[m]; V[m] = (f32x2){acc[ai][1][m][n][2 * jp], acc[ai][1][m][n][2 * jp + 1]} * rs[m]; }
; #pragma unroll
;                     for (int m = 0; m < 4; ++m) {
;                         const f32x2 zz = {0.f, 0.f}; const f32x2 Gp = m ? G[m - 1] : zz, Vp = m ? V[m - 1] : zz;
;                         const f32x2 gp1 = {dpp_prev1(G[m].x, Gp.x), dpp_prev1(G[m].y, Gp.y)}, gp2 = {dpp_prev2(G[m].x, Gp.x), dpp_prev2(G[m].y, Gp.y)};
;                         const f32x2 vp1 = {dpp_prev1(V[m].x, Vp.x), dpp_prev1(V[m].y, Vp.y)}, vp2 = {dpp_prev2(V[m].x, Vp.x), dpp_prev2(V[m].y, Vp.y)};
;                         const f32x2 gc = bg + g0 * gp2 + g1 * gp1 + g2 * G[m];
;                         const f32x2 vc = bv + v0 * vp2 + v1 * vp1 + v2 * V[m];
;                         const f32x2 xe = gc * (-LOG2E);
;                         f32x2 dn = {__builtin_amdgcn_exp2f(xe.x), __builtin_amdgcn_exp2f(xe.y)}; dn = dn + 1.0f;
;                         const f32x2 rc = {__builtin_amdgcn_rcpf(dn.x), __builtin_amdgcn_rcpf(dn.y)};
;                         const f32x2 rr = gc * rc * vc;
;                         wpk[m][jp] = pk2(rr.x, rr.y); }
	v_ffbh_u32_e32 v98, v105
	s_waitcnt vmcnt(2)
	v_ffbh_u32_e32 v100, v107
	s_waitcnt vmcnt(1)
	v_ffbh_u32_e32 v102, v109
	v_min_u32_e32 v98, 32, v98
	v_min_u32_e32 v100, 32, v100
	v_min_u32_e32 v102, 32, v102
	v_lshlrev_b64 v[104:105], v98, v[104:105]
	s_waitcnt vmcnt(0)
	v_ffbh_u32_e32 v114, v111
	v_lshlrev_b64 v[106:107], v100, v[106:107]
	v_lshlrev_b64 v[108:109], v102, v[108:109]
	v_min_u32_e32 v104, 1, v104
	v_min_u32_e32 v114, 32, v114
	v_min_u32_e32 v106, 1, v106
	v_min_u32_e32 v108, 1, v108
	v_or_b32_e32 v104, v105, v104
	v_lshlrev_b64 v[110:111], v114, v[110:111]
	v_or_b32_e32 v105, v107, v106
	v_or_b32_e32 v106, v109, v108
	v_cvt_f32_u32_e32 v104, v104
	v_min_u32_e32 v110, 1, v110
	v_cvt_f32_u32_e32 v105, v105
	v_cvt_f32_u32_e32 v106, v106
	v_or_b32_e32 v107, v111, v110
	v_sub_u32_e32 v98, 32, v98
	v_cvt_f32_u32_e32 v107, v107
	v_sub_u32_e32 v100, 32, v100
	v_sub_u32_e32 v102, 32, v102
	v_ldexp_f32 v98, v104, v98
	v_ldexp_f32 v100, v105, v100
	v_ldexp_f32 v102, v106, v102
	v_fmamk_f32 v98, v98, 0x30800000, v203
	v_sub_u32_e32 v114, 32, v114
	v_fmamk_f32 v100, v100, 0x30800000, v203
	v_fmamk_f32 v102, v102, 0x30800000, v203
	v_mul_f32_e32 v105, 0x4b800000, v98
	v_cmp_gt_f32_e32 vcc, s52, v98
	v_ldexp_f32 v104, v107, v114
	v_mul_f32_e32 v106, 0x4b800000, v100
	v_mul_f32_e32 v107, 0x4b800000, v102
	v_cndmask_b32_e32 v98, v98, v105, vcc
	v_cmp_gt_f32_e64 s[10:11], s52, v100
	v_cmp_gt_f32_e64 s[12:13], s52, v102
	v_fmamk_f32 v104, v104, 0x30800000, v203
	v_cndmask_b32_e64 v100, v100, v106, s[10:11]
	v_cndmask_b32_e64 v102, v102, v107, s[12:13]
	v_rsq_f32_e32 v98, v98
	v_mul_f32_e32 v108, 0x4b800000, v104
	v_cmp_gt_f32_e64 s[14:15], s52, v104
	v_rsq_f32_e32 v100, v100
	v_rsq_f32_e32 v102, v102
	v_cndmask_b32_e64 v104, v104, v108, s[14:15]
	v_rsq_f32_e32 v104, v104
	v_mul_f32_e32 v105, 0x45800000, v98
	v_mul_f32_e32 v106, 0x45800000, v100
	v_mul_f32_e32 v107, 0x45800000, v102
	v_cndmask_b32_e32 v98, v98, v105, vcc
	v_cmp_lt_i32_e32 vcc, -1, v96
	v_cndmask_b32_e64 v100, v100, v106, s[10:11]
	v_cndmask_b32_e64 v105, v102, v107, s[12:13]
	v_cndmask_b32_e32 v102, 0, v98, vcc
	v_cmp_lt_i32_e32 vcc, s53, v96
	v_mul_f32_e32 v108, 0x45800000, v104
	v_cndmask_b32_e64 v104, v104, v108, s[14:15]
	v_cndmask_b32_e32 v100, 0, v100, vcc
	v_cmp_lt_i32_e32 vcc, s54, v96
	v_pk_mul_f32 v[60:61], v[60:61], v[102:103] op_sel_hi:[1,0]
	v_pk_mul_f32 v[56:57], v[56:57], v[102:103] op_sel_hi:[1,0]
	v_cndmask_b32_e32 v98, 0, v105, vcc
	v_cmp_lt_i32_e32 vcc, s55, v96
	v_mov_b32_dpp v112, v60 row_shr:1 row_mask:0xf bank_mask:0xf
	v_mov_b32_dpp v113, v61 row_shr:1 row_mask:0xf bank_mask:0xf
	v_cndmask_b32_e32 v96, 0, v104, vcc
	v_pk_mul_f32 v[108:109], v[32:33], v[96:97] op_sel_hi:[1,0]
	v_mov_b32_e32 v32, v183
	v_mov_b32_e32 v33, v183
	v_pk_mul_f32 v[104:105], v[40:41], v[98:99] op_sel_hi:[1,0]
	v_mov_b32_dpp v32, v60 row_shr:2 row_mask:0xf bank_mask:0xf
	v_mov_b32_dpp v33, v61 row_shr:2 row_mask:0xf bank_mask:0xf
	s_waitcnt lgkmcnt(6)
	v_pk_fma_f32 v[32:33], v[84:85], v[32:33], v[72:73]
	v_mov_b32_e32 v40, v183
	s_waitcnt lgkmcnt(5)
	v_pk_fma_f32 v[32:33], v[88:89], v[112:113], v[32:33]
	v_mov_b32_e32 v41, v183
	s_waitcnt lgkmcnt(4)
	v_pk_fma_f32 v[32:33], v[92:93], v[60:61], v[32:33]
	v_pk_mul_f32 v[106:107], v[36:37], v[96:97] op_sel_hi:[1,0]
	v_pk_mul_f32 v[110:111], v[32:33], s[0:1] op_sel_hi:[1,0]
	v_mov_b32_e32 v36, v181
	v_exp_f32_e32 v110, v110
	v_exp_f32_e32 v111, v111
	v_mov_b32_e32 v37, v181
	v_mov_b32_dpp v40, v56 row_shr:2 row_mask:0xf bank_mask:0xf
	v_mov_b32_dpp v41, v57 row_shr:2 row_mask:0xf bank_mask:0xf
	v_pk_add_f32 v[110:111], v[110:111], 1.0 op_sel_hi:[1,0]
	v_mov_b32_dpp v36, v56 row_shr:1 row_mask:0xf bank_mask:0xf
	v_rcp_f32_e32 v110, v110
	v_rcp_f32_e32 v111, v111
	v_mov_b32_dpp v37, v57 row_shr:1 row_mask:0xf bank_mask:0xf
	s_waitcnt lgkmcnt(2)
	v_pk_fma_f32 v[40:41], v[68:69], v[40:41], v[64:65]
	v_pk_mul_f32 v[52:53], v[52:53], v[100:101] op_sel_hi:[1,0]
	s_waitcnt lgkmcnt(1)
	v_pk_fma_f32 v[36:37], v[76:77], v[36:37], v[40:41]
	v_pk_mul_f32 v[32:33], v[32:33], v[110:111]
	s_waitcnt lgkmcnt(0)
	v_pk_fma_f32 v[36:37], v[80:81], v[56:57], v[36:37]
	v_pk_mul_f32 v[32:33], v[36:37], v[32:33]
	v_mov_b32_dpp v40, v60 row_ror:2 row_mask:0xf bank_mask:0xf
	v_mov_b32_dpp v41, v61 row_ror:2 row_mask:0xf bank_mask:0xf
	v_mov_b32_dpp v36, v60 row_ror:1 row_mask:0xf bank_mask:0xf
	v_mov_b32_dpp v37, v61 row_ror:1 row_mask:0xf bank_mask:0xf
	v_mov_b32_dpp v40, v52 row_shr:2 row_mask:0xf bank_mask:0xf
	v_mov_b32_dpp v41, v53 row_shr:2 row_mask:0xf bank_mask:0xf
	v_mov_b32_dpp v36, v52 row_shr:1 row_mask:0xf bank_mask:0xf
	v_mov_b32_dpp v37, v53 row_shr:1 row_mask:0xf bank_mask:0xf
	v_pk_fma_f32 v[40:41], v[84:85], v[40:41], v[72:73]
	v_pk_fma_f32 v[36:37], v[88:89], v[36:37], v[40:41]
	v_pk_fma_f32 v[36:37], v[92:93], v[52:53], v[36:37]
	v_pk_mul_f32 v[48:49], v[48:49], v[100:101] op_sel_hi:[1,0]
	v_pk_mul_f32 v[40:41], v[36:37], s[0:1] op_sel_hi:[1,0]
	v_exp_f32_e32 v40, v40
	v_exp_f32_e32 v41, v41
	v_mov_b32_dpp v110, v56 row_ror:2 row_mask:0xf bank_mask:0xf
	v_mov_b32_dpp v111, v57 row_ror:2 row_mask:0xf bank_mask:0xf
	v_pk_add_f32 v[40:41], v[40:41], 1.0 op_sel_hi:[1,0]
	v_mov_b32_dpp v60, v56 row_ror:1 row_mask:0xf bank_mask:0xf
	v_rcp_f32_e32 v40, v40
	v_rcp_f32_e32 v41, v41
	v_mov_b32_dpp v61, v57 row_ror:1 row_mask:0xf bank_mask:0xf
	v_mov_b32_dpp v110, v48 row_shr:2 row_mask:0xf bank_mask:0xf
	v_mov_b32_dpp v111, v49 row_shr:2 row_mask:0xf bank_mask:0xf
	v_mov_b32_dpp v60, v48 row_shr:1 row_mask:0xf bank_mask:0xf
	v_mov_b32_dpp v61, v49 row_shr:1 row_mask:0xf bank_mask:0xf
	v_pk_fma_f32 v[56:57], v[68:69], v[110:111], v[64:65]
; #define LAS __attribute__((address_space(3)))
; DI float dpp_prev1(float cur, float prevm) {
;     const int o = __builtin_amdgcn_update_dpp(0, __builtin_bit_cast(int, prevm), 0x121, 0xf, 0xf, false);
;     return __builtin_bit_cast(float, __builtin_amdgcn_update_dpp(o, __builtin_bit_cast(int, cur), 0x111, 0xf, 0xf, false));
; }
; DI float dpp_prev2(float cur, float prevm) {
;     const int o = __builtin_amdgcn_update_dpp(0, __builtin_bit_cast(int, prevm), 0x122, 0xf, 0xf, false);
;     DI void operator()(const AccT& acc, const Unit& u, int wr, int wc, int fr, int fq) const {
;     ...
;                     const f32x2 bg = *(const LAS f32x2*)(P + lc + 2 * jp), g0 = *(const LAS f32x2*)(P + 32 + lc + 2 * jp), g1 = *(const LAS f32x2*)(P + 64 + lc + 2 * jp), g2 = *(const LAS f32x2*)(P + 96 + lc + 2 * jp);
;                     const f32x2 bv = *(const LAS f32x2*)(P + 128 + lc + 2 * jp), v0 = *(const LAS f32x2*)(P + 160 + lc + 2 * jp), v1 = *(const LAS f32x2*)(P + 192 + lc + 2 * jp), v2 = *(const LAS f32x2*)(P + 224 + lc + 2 * jp);
;                     f32x2 G[4], V[4];
; #pragma unroll
;                     for (int m = 0; m < 4; ++m) { G[m] = (f32x2){acc[ai][0][m][n][2 * jp], acc[ai][0][m][n][2 * jp + 1]} * rs[m]; V[m] = (f32x2){acc[ai][1][m][n][2 * jp], acc[ai][1][m][n][2 * jp + 1]} * rs[m]; }
; #pragma unroll
;                     for (int m = 0; m < 4; ++m) {
;                         const f32x2 zz = {0.f, 0.f}; const f32x2 Gp = m ? G[m - 1] : zz, Vp = m ? V[m - 1] : zz;
;                         const f32x2 gp1 = {dpp_prev1(G[m].x, Gp.x), dpp_prev1(G[m].y, Gp.y)}, gp2 = {dpp_prev2(G[m].x, Gp.x), dpp_prev2(G[m].y, Gp.y)};
;                         const f32x2 vp1 = {dpp_prev1(V[m].x, Vp.x), dpp_prev1(V[m].y, Vp.y)}, vp2 = {dpp_prev2(V[m].x, Vp.x), dpp_prev2(V[m].y, Vp.y)};
;                         const f32x2 gc = bg + g0 * gp2 + g1 * gp1 + g2 * G[m];
;                         const f32x2 vc = bv + v0 * vp2 + v1 * vp1 + v2 * V[m];
;                         const f32x2 xe = gc * (-LOG2E);
;                         f32x2 dn = {__builtin_amdgcn_exp2f(xe.x), __builtin_amdgcn_exp2f(xe.y)}; dn = dn + 1.0f;
;                         const f32x2 rc = {__builtin_amdgcn_rcpf(dn.x), __builtin_amdgcn_rcpf(dn.y)};
;                         const f32x2 rr = gc * rc * vc;
;                         wpk[m][jp] = pk2(rr.x, rr.y); }
	v_pk_mul_f32 v[36:37], v[36:37], v[40:41]
	v_pk_fma_f32 v[56:57], v[76:77], v[60:61], v[56:57]
	v_pk_mul_f32 v[44:45], v[44:45], v[98:99] op_sel_hi:[1,0]
	v_pk_fma_f32 v[56:57], v[80:81], v[48:49], v[56:57]
	v_pk_mul_f32 v[36:37], v[56:57], v[36:37]
	v_mov_b32_dpp v56, v52 row_ror:2 row_mask:0xf bank_mask:0xf
	v_mov_b32_dpp v57, v53 row_ror:2 row_mask:0xf bank_mask:0xf
	v_mov_b32_dpp v40, v52 row_ror:1 row_mask:0xf bank_mask:0xf
	v_mov_b32_dpp v41, v53 row_ror:1 row_mask:0xf bank_mask:0xf
	v_mov_b32_dpp v56, v44 row_shr:2 row_mask:0xf bank_mask:0xf
	v_mov_b32_dpp v57, v45 row_shr:2 row_mask:0xf bank_mask:0xf
	v_mov_b32_dpp v40, v44 row_shr:1 row_mask:0xf bank_mask:0xf
	v_mov_b32_dpp v41, v45 row_shr:1 row_mask:0xf bank_mask:0xf
	v_pk_fma_f32 v[56:57], v[84:85], v[56:57], v[72:73]
	v_pk_fma_f32 v[40:41], v[88:89], v[40:41], v[56:57]
	v_pk_fma_f32 v[40:41], v[92:93], v[44:45], v[40:41]
	v_pk_mul_f32 v[56:57], v[40:41], s[0:1] op_sel_hi:[1,0]
	v_exp_f32_e32 v56, v56
	v_exp_f32_e32 v57, v57
	v_mov_b32_dpp v52, v48 row_ror:1 row_mask:0xf bank_mask:0xf
	v_mov_b32_dpp v53, v49 row_ror:1 row_mask:0xf bank_mask:0xf
	v_mov_b32_dpp v60, v48 row_ror:2 row_mask:0xf bank_mask:0xf
	v_mov_b32_dpp v61, v49 row_ror:2 row_mask:0xf bank_mask:0xf
	v_pk_add_f32 v[48:49], v[56:57], 1.0 op_sel_hi:[1,0]
	v_mov_b32_dpp v60, v104 row_shr:2 row_mask:0xf bank_mask:0xf
	v_rcp_f32_e32 v48, v48
	v_rcp_f32_e32 v49, v49
	v_mov_b32_dpp v61, v105 row_shr:2 row_mask:0xf bank_mask:0xf
	v_mov_b32_dpp v52, v104 row_shr:1 row_mask:0xf bank_mask:0xf
	v_mov_b32_dpp v53, v105 row_shr:1 row_mask:0xf bank_mask:0xf
	v_pk_fma_f32 v[56:57], v[68:69], v[60:61], v[64:65]
	v_pk_mul_f32 v[40:41], v[40:41], v[48:49]
	v_pk_fma_f32 v[52:53], v[76:77], v[52:53], v[56:57]
	v_pk_fma_f32 v[52:53], v[80:81], v[104:105], v[52:53]
	v_pk_mul_f32 v[40:41], v[52:53], v[40:41]
	v_mov_b32_dpp v48, v44 row_ror:1 row_mask:0xf bank_mask:0xf
	v_mov_b32_dpp v52, v44 row_ror:2 row_mask:0xf bank_mask:0xf
	v_mov_b32_dpp v53, v45 row_ror:2 row_mask:0xf bank_mask:0xf
	v_mov_b32_dpp v49, v45 row_ror:1 row_mask:0xf bank_mask:0xf
	v_mov_b32_dpp v52, v106 row_shr:2 row_mask:0xf bank_mask:0xf
	v_mov_b32_dpp v53, v107 row_shr:2 row_mask:0xf bank_mask:0xf
	v_mov_b32_dpp v48, v106 row_shr:1 row_mask:0xf bank_mask:0xf
	v_mov_b32_dpp v49, v107 row_shr:1 row_mask:0xf bank_mask:0xf
	v_pk_fma_f32 v[52:53], v[84:85], v[52:53], v[72:73]
	v_pk_fma_f32 v[48:49], v[88:89], v[48:49], v[52:53]
	v_pk_fma_f32 v[48:49], v[92:93], v[106:107], v[48:49]
	v_pk_mul_f32 v[52:53], v[48:49], s[0:1] op_sel_hi:[1,0]
	v_exp_f32_e32 v52, v52
	v_exp_f32_e32 v53, v53
	v_mov_b32_dpp v56, v104 row_ror:2 row_mask:0xf bank_mask:0xf
	v_mov_b32_dpp v57, v105 row_ror:2 row_mask:0xf bank_mask:0xf
	v_mov_b32_dpp v44, v104 row_ror:1 row_mask:0xf bank_mask:0xf
	v_pk_add_f32 v[52:53], v[52:53], 1.0 op_sel_hi:[1,0]
	v_mov_b32_dpp v45, v105 row_ror:1 row_mask:0xf bank_mask:0xf
	v_rcp_f32_e32 v52, v52
	v_rcp_f32_e32 v53, v53
	v_mov_b32_dpp v56, v108 row_shr:2 row_mask:0xf bank_mask:0xf
	v_mov_b32_dpp v57, v109 row_shr:2 row_mask:0xf bank_mask:0xf
	v_mov_b32_dpp v44, v108 row_shr:1 row_mask:0xf bank_mask:0xf
	v_mov_b32_dpp v45, v109 row_shr:1 row_mask:0xf bank_mask:0xf
	v_pk_fma_f32 v[56:57], v[68:69], v[56:57], v[64:65]
	v_pk_mul_f32 v[48:49], v[48:49], v[52:53]
	v_pk_fma_f32 v[44:45], v[76:77], v[44:45], v[56:57]
	v_pk_mul_f32 v[52:53], v[58:59], v[102:103] op_sel_hi:[1,0]
	v_pk_fma_f32 v[44:45], v[80:81], v[108:109], v[44:45]
	v_mov_b32_e32 v58, v183
	v_pk_mul_f32 v[44:45], v[44:45], v[48:49]
	v_pk_mul_f32 v[48:49], v[62:63], v[102:103] op_sel_hi:[1,0]
	v_mov_b32_e32 v59, v183
	v_mov_b32_e32 v56, v181
	v_mov_b32_e32 v57, v181
	v_mov_b32_dpp v58, v48 row_shr:2 row_mask:0xf bank_mask:0xf
	v_mov_b32_dpp v59, v49 row_shr:2 row_mask:0xf bank_mask:0xf
	v_mov_b32_dpp v56, v48 row_shr:1 row_mask:0xf bank_mask:0xf
	v_mov_b32_dpp v57, v49 row_shr:1 row_mask:0xf bank_mask:0xf
	v_pk_fma_f32 v[58:59], v[86:87], v[58:59], v[74:75]
	v_mov_b32_e32 v62, v183
	v_pk_fma_f32 v[56:57], v[90:91], v[56:57], v[58:59]
	v_mov_b32_e32 v63, v183
	v_pk_fma_f32 v[56:57], v[48:49], v[94:95], v[56:57]
	v_mov_b32_e32 v60, v181
	v_pk_mul_f32 v[58:59], v[56:57], s[0:1] op_sel_hi:[1,0]
	v_mov_b32_e32 v61, v181
	v_exp_f32_e32 v58, v58
	v_exp_f32_e32 v59, v59
	v_mov_b32_dpp v62, v52 row_shr:2 row_mask:0xf bank_mask:0xf
	v_mov_b32_dpp v63, v53 row_shr:2 row_mask:0xf bank_mask:0xf
	v_mov_b32_dpp v60, v52 row_shr:1 row_mask:0xf bank_mask:0xf
	v_pk_add_f32 v[58:59], v[58:59], 1.0 op_sel_hi:[1,0]
	v_mov_b32_dpp v61, v53 row_shr:1 row_mask:0xf bank_mask:0xf
	v_rcp_f32_e32 v58, v58
	v_rcp_f32_e32 v59, v59
	v_pk_fma_f32 v[62:63], v[70:71], v[62:63], v[66:67]
	v_cvt_pk_bf16_f32 v32, v32, v33
	v_pk_fma_f32 v[60:61], v[78:79], v[60:61], v[62:63]
	v_pk_mul_f32 v[56:57], v[56:57], v[58:59]
	v_pk_fma_f32 v[60:61], v[52:53], v[82:83], v[60:61]
	v_pk_mul_f32 v[56:57], v[60:61], v[56:57]
	v_pk_mul_f32 v[54:55], v[54:55], v[100:101] op_sel_hi:[1,0]
	v_cvt_pk_bf16_f32 v33, v56, v57
	v_mov_b32_dpp v58, v48 row_ror:2 row_mask:0xf bank_mask:0xf
	v_mov_b32_dpp v59, v49 row_ror:2 row_mask:0xf bank_mask:0xf
	v_mov_b32_dpp v56, v48 row_ror:1 row_mask:0xf bank_mask:0xf
	v_mov_b32_dpp v57, v49 row_ror:1 row_mask:0xf bank_mask:0xf
	v_mov_b32_dpp v58, v54 row_shr:2 row_mask:0xf bank_mask:0xf
	v_mov_b32_dpp v59, v55 row_shr:2 row_mask:0xf bank_mask:0xf
	v_mov_b32_dpp v56, v54 row_shr:1 row_mask:0xf bank_mask:0xf
	v_mov_b32_dpp v57, v55 row_shr:1 row_mask:0xf bank_mask:0xf
	v_pk_fma_f32 v[58:59], v[86:87], v[58:59], v[74:75]
	v_pk_fma_f32 v[56:57], v[90:91], v[56:57], v[58:59]
	v_pk_fma_f32 v[56:57], v[54:55], v[94:95], v[56:57]
; DI float dpp_prev1(float cur, float prevm) {
;     const int o = __builtin_amdgcn_update_dpp(0, __builtin_bit_cast(int, prevm), 0x121, 0xf, 0xf, false);
;     return __builtin_bit_cast(float, __builtin_amdgcn_update_dpp(o, __builtin_bit_cast(int, cur), 0x111, 0xf, 0xf, false));
; }
;     DI void operator()(const AccT& acc, const Unit& u, int wr, int wc, int fr, int fq) const {
;     ...
;                     const f32x2 bg = *(const LAS f32x2*)(P + lc + 2 * jp), g0 = *(const LAS f32x2*)(P + 32 + lc + 2 * jp), g1 = *(const LAS f32x2*)(P + 64 + lc + 2 * jp), g2 = *(const LAS f32x2*)(P + 96 + lc + 2 * jp);
;                     const f32x2 bv = *(const LAS f32x2*)(P + 128 + lc + 2 * jp), v0 = *(const LAS f32x2*)(P + 160 + lc + 2 * jp), v1 = *(const LAS f32x2*)(P + 192 + lc + 2 * jp), v2 = *(const LAS f32x2*)(P + 224 + lc + 2 * jp);
;                     f32x2 G[4], V[4];
; #pragma unroll
;                     for (int m = 0; m < 4; ++m) { G[m] = (f32x2){acc[ai][0][m][n][2 * jp], acc[ai][0][m][n][2 * jp + 1]} * rs[m]; V[m] = (f32x2){acc[ai][1][m][n][2 * jp], acc[ai][1][m][n][2 * jp + 1]} * rs[m]; }
; #pragma unroll
;                     for (int m = 0; m < 4; ++m) {
;                         const f32x2 zz = {0.f, 0.f}; const f32x2 Gp = m ? G[m - 1] : zz, Vp = m ? V[m - 1] : zz;
;                         const f32x2 gp1 = {dpp_prev1(G[m].x, Gp.x), dpp_prev1(G[m].y, Gp.y)}, gp2 = {dpp_prev2(G[m].x, Gp.x), dpp_prev2(G[m].y, Gp.y)};
;                         const f32x2 vp1 = {dpp_prev1(V[m].x, Vp.x), dpp_prev1(V[m].y, Vp.y)}, vp2 = {dpp_prev2(V[m].x, Vp.x), dpp_prev2(V[m].y, Vp.y)};
;                         const f32x2 gc = bg + g0 * gp2 + g1 * gp1 + g2 * G[m];
;                         const f32x2 vc = bv + v0 * vp2 + v1 * vp1 + v2 * V[m];
;                         const f32x2 xe = gc * (-LOG2E);
;                         f32x2 dn = {__builtin_amdgcn_exp2f(xe.x), __builtin_amdgcn_exp2f(xe.y)}; dn = dn + 1.0f;
;                         const f32x2 rc = {__builtin_amdgcn_rcpf(dn.x), __builtin_amdgcn_rcpf(dn.y)};
;                         const f32x2 rr = gc * rc * vc;
;                         wpk[m][jp] = pk2(rr.x, rr.y); }
;                 }
; #pragma unroll
;                 for (int m = 0; m < 4; ++m) { const int row = m ? tok0 + 16 * m : row0;
;                     *(u32x2*)(ACT + (size_t)row * 2816 + cl + 4 * n) = (u32x2){wpk[m][0], wpk[m][1]}; }
	v_pk_mul_f32 v[58:59], v[56:57], s[0:1] op_sel_hi:[1,0]
	v_exp_f32_e32 v58, v58
	v_exp_f32_e32 v59, v59
	v_mov_b32_dpp v48, v52 row_ror:1 row_mask:0xf bank_mask:0xf
	v_mov_b32_dpp v49, v53 row_ror:1 row_mask:0xf bank_mask:0xf
	v_mov_b32_dpp v60, v52 row_ror:2 row_mask:0xf bank_mask:0xf
	v_mov_b32_dpp v61, v53 row_ror:2 row_mask:0xf bank_mask:0xf
	v_pk_add_f32 v[52:53], v[58:59], 1.0 op_sel_hi:[1,0]
	v_pk_mul_f32 v[50:51], v[50:51], v[100:101] op_sel_hi:[1,0]
	v_rcp_f32_e32 v52, v52
	v_rcp_f32_e32 v53, v53
	v_mov_b32_dpp v60, v50 row_shr:2 row_mask:0xf bank_mask:0xf
	v_mov_b32_dpp v61, v51 row_shr:2 row_mask:0xf bank_mask:0xf
	v_mov_b32_dpp v48, v50 row_shr:1 row_mask:0xf bank_mask:0xf
	v_mov_b32_dpp v49, v51 row_shr:1 row_mask:0xf bank_mask:0xf
	v_pk_fma_f32 v[58:59], v[70:71], v[60:61], v[66:67]
	v_pk_mul_f32 v[52:53], v[56:57], v[52:53]
	v_pk_fma_f32 v[48:49], v[78:79], v[48:49], v[58:59]
	v_cvt_pk_bf16_f32 v36, v36, v37
	v_pk_fma_f32 v[48:49], v[50:51], v[82:83], v[48:49]
	v_pk_mul_f32 v[46:47], v[46:47], v[98:99] op_sel_hi:[1,0]
	v_pk_mul_f32 v[48:49], v[48:49], v[52:53]
	v_cvt_pk_bf16_f32 v37, v48, v49
	v_mov_b32_dpp v52, v54 row_ror:2 row_mask:0xf bank_mask:0xf
	v_mov_b32_dpp v53, v55 row_ror:2 row_mask:0xf bank_mask:0xf
	v_mov_b32_dpp v48, v54 row_ror:1 row_mask:0xf bank_mask:0xf
	v_mov_b32_dpp v49, v55 row_ror:1 row_mask:0xf bank_mask:0xf
	v_mov_b32_dpp v52, v46 row_shr:2 row_mask:0xf bank_mask:0xf
	v_mov_b32_dpp v53, v47 row_shr:2 row_mask:0xf bank_mask:0xf
	v_mov_b32_dpp v48, v46 row_shr:1 row_mask:0xf bank_mask:0xf
	v_mov_b32_dpp v49, v47 row_shr:1 row_mask:0xf bank_mask:0xf
	v_pk_fma_f32 v[52:53], v[86:87], v[52:53], v[74:75]
	v_pk_fma_f32 v[48:49], v[90:91], v[48:49], v[52:53]
	v_pk_fma_f32 v[48:49], v[46:47], v[94:95], v[48:49]
	v_pk_mul_f32 v[52:53], v[48:49], s[0:1] op_sel_hi:[1,0]
	v_exp_f32_e32 v52, v52
	v_exp_f32_e32 v53, v53
	v_mov_b32_dpp v54, v50 row_ror:1 row_mask:0xf bank_mask:0xf
	v_mov_b32_dpp v55, v51 row_ror:1 row_mask:0xf bank_mask:0xf
	v_mov_b32_dpp v56, v50 row_ror:2 row_mask:0xf bank_mask:0xf
	v_mov_b32_dpp v57, v51 row_ror:2 row_mask:0xf bank_mask:0xf
	v_pk_add_f32 v[50:51], v[52:53], 1.0 op_sel_hi:[1,0]
	v_pk_mul_f32 v[42:43], v[42:43], v[98:99] op_sel_hi:[1,0]
	v_rcp_f32_e32 v50, v50
	v_rcp_f32_e32 v51, v51
	v_mov_b32_dpp v56, v42 row_shr:2 row_mask:0xf bank_mask:0xf
	v_mov_b32_dpp v57, v43 row_shr:2 row_mask:0xf bank_mask:0xf
	v_mov_b32_dpp v54, v42 row_shr:1 row_mask:0xf bank_mask:0xf
	v_mov_b32_dpp v55, v43 row_shr:1 row_mask:0xf bank_mask:0xf
	v_pk_fma_f32 v[52:53], v[70:71], v[56:57], v[66:67]
	v_pk_mul_f32 v[48:49], v[48:49], v[50:51]
	v_pk_fma_f32 v[52:53], v[78:79], v[54:55], v[52:53]
	v_pk_fma_f32 v[52:53], v[42:43], v[82:83], v[52:53]
	v_pk_mul_f32 v[48:49], v[52:53], v[48:49]
	v_cvt_pk_bf16_f32 v40, v40, v41
	v_pk_mul_f32 v[38:39], v[38:39], v[96:97] op_sel_hi:[1,0]
	v_cvt_pk_bf16_f32 v41, v48, v49
	v_mov_b32_dpp v50, v46 row_ror:2 row_mask:0xf bank_mask:0xf
	v_mov_b32_dpp v51, v47 row_ror:2 row_mask:0xf bank_mask:0xf
	v_mov_b32_dpp v48, v46 row_ror:1 row_mask:0xf bank_mask:0xf
	v_mov_b32_dpp v49, v47 row_ror:1 row_mask:0xf bank_mask:0xf
	v_mov_b32_dpp v50, v38 row_shr:2 row_mask:0xf bank_mask:0xf
	v_mov_b32_dpp v51, v39 row_shr:2 row_mask:0xf bank_mask:0xf
	v_mov_b32_dpp v48, v38 row_shr:1 row_mask:0xf bank_mask:0xf
	v_mov_b32_dpp v49, v39 row_shr:1 row_mask:0xf bank_mask:0xf
	v_pk_fma_f32 v[50:51], v[86:87], v[50:51], v[74:75]
	v_pk_fma_f32 v[48:49], v[90:91], v[48:49], v[50:51]
	v_pk_fma_f32 v[38:39], v[38:39], v[94:95], v[48:49]
	v_pk_mul_f32 v[48:49], v[38:39], s[0:1] op_sel_hi:[1,0]
	v_exp_f32_e32 v48, v48
	v_exp_f32_e32 v49, v49
	v_mov_b32_dpp v46, v42 row_ror:1 row_mask:0xf bank_mask:0xf
	v_mov_b32_dpp v47, v43 row_ror:1 row_mask:0xf bank_mask:0xf
	v_mov_b32_dpp v52, v42 row_ror:2 row_mask:0xf bank_mask:0xf
	v_mov_b32_dpp v53, v43 row_ror:2 row_mask:0xf bank_mask:0xf
	v_pk_add_f32 v[42:43], v[48:49], 1.0 op_sel_hi:[1,0]
	v_pk_mul_f32 v[34:35], v[34:35], v[96:97] op_sel_hi:[1,0]
	v_rcp_f32_e32 v42, v42
	v_rcp_f32_e32 v43, v43
	v_mov_b32_dpp v52, v34 row_shr:2 row_mask:0xf bank_mask:0xf
	v_mov_b32_dpp v53, v35 row_shr:2 row_mask:0xf bank_mask:0xf
	v_mov_b32_dpp v46, v34 row_shr:1 row_mask:0xf bank_mask:0xf
	v_mov_b32_dpp v47, v35 row_shr:1 row_mask:0xf bank_mask:0xf
	v_pk_fma_f32 v[48:49], v[70:71], v[52:53], v[66:67]
	v_pk_mul_f32 v[38:39], v[38:39], v[42:43]
	v_pk_fma_f32 v[46:47], v[78:79], v[46:47], v[48:49]
	v_cvt_pk_bf16_f32 v44, v44, v45
	v_pk_fma_f32 v[34:35], v[34:35], v[82:83], v[46:47]
	s_nop 0
	v_pk_mul_f32 v[34:35], v[34:35], v[38:39]
	s_nop 0
	v_cvt_pk_bf16_f32 v45, v34, v35
	v_mad_i64_i32 v[34:35], s[10:11], v103, s48, v[128:129]
	v_lshl_add_u64 v[64:65], v[34:35], 0, v[130:131]
	global_store_dwordx2 v[64:65], v[32:33], off
	v_mad_i64_i32 v[32:33], s[10:11], v97, s48, v[128:129]
	v_lshl_add_u64 v[66:67], v[32:33], 0, v[130:131]
	v_mad_i64_i32 v[32:33], s[10:11], v99, s48, v[128:129]
	v_lshl_add_u64 v[68:69], v[32:33], 0, v[130:131]
	v_mad_i64_i32 v[32:33], s[10:11], v101, s48, v[128:129]
	v_lshl_add_u64 v[70:71], v[32:33], 0, v[130:131]
	global_store_dwordx2 v[66:67], v[36:37], off
	global_store_dwordx2 v[68:69], v[40:41], off
	global_store_dwordx2 v[70:71], v[44:45], off
	v_pk_mul_f32 v[30:31], v[30:31], v[102:103] op_sel_hi:[1,0]
	v_pk_mul_f32 v[22:23], v[22:23], v[100:101] op_sel_hi:[1,0]
	s_nop 0
	v_mov_b32_dpp v114, v30 row_ror:2 row_mask:0xf bank_mask:0xf
	v_mov_b32_dpp v115, v31 row_ror:2 row_mask:0xf bank_mask:0xf
	v_mov_b32_dpp v112, v30 row_ror:1 row_mask:0xf bank_mask:0xf
	v_mov_b32_dpp v113, v31 row_ror:1 row_mask:0xf bank_mask:0xf
	v_mov_b32_dpp v114, v22 row_shr:2 row_mask:0xf bank_mask:0xf
	v_mov_b32_dpp v115, v23 row_shr:2 row_mask:0xf bank_mask:0xf
	ds_read_b128 v[40:43], v200 offset:16
	ds_read_b128 v[52:55], v200 offset:144
	ds_read_b128 v[56:59], v200 offset:272
	ds_read_b128 v[60:63], v200 offset:400
	ds_read_b128 v[32:35], v200 offset:528
	ds_read_b128 v[36:39], v200 offset:656
	ds_read_b128 v[44:47], v200 offset:784
	ds_read_b128 v[48:51], v200 offset:912
	v_mov_b32_dpp v112, v22 row_shr:1 row_mask:0xf bank_mask:0xf
	v_mov_b32_dpp v113, v23 row_shr:1 row_mask:0xf bank_mask:0xf
	s_waitcnt lgkmcnt(6)
; #define LAS __attribute__((address_space(3)))
; DI float dpp_prev1(float cur, float prevm) {
;     const int o = __builtin_amdgcn_update_dpp(0, __builtin_bit_cast(int, prevm), 0x121, 0xf, 0xf, false);
;     return __builtin_bit_cast(float, __builtin_amdgcn_update_dpp(o, __builtin_bit_cast(int, cur), 0x111, 0xf, 0xf, false));
; }
; DI float dpp_prev2(float cur, float prevm) {
;     const int o = __builtin_amdgcn_update_dpp(0, __builtin_bit_cast(int, prevm), 0x122, 0xf, 0xf, false);
;     DI void operator()(const AccT& acc, const Unit& u, int wr, int wc, int fr, int fq) const {
;     ...
;                     const f32x2 bg = *(const LAS f32x2*)(P + lc + 2 * jp), g0 = *(const LAS f32x2*)(P + 32 + lc + 2 * jp), g1 = *(const LAS f32x2*)(P + 64 + lc + 2 * jp), g2 = *(const LAS f32x2*)(P + 96 + lc + 2 * jp);
;                     const f32x2 bv = *(const LAS f32x2*)(P + 128 + lc + 2 * jp), v0 = *(const LAS f32x2*)(P + 160 + lc + 2 * jp), v1 = *(const LAS f32x2*)(P + 192 + lc + 2 * jp), v2 = *(const LAS f32x2*)(P + 224 + lc + 2 * jp);
;                     f32x2 G[4], V[4];
; #pragma unroll
;                     for (int m = 0; m < 4; ++m) { G[m] = (f32x2){acc[ai][0][m][n][2 * jp], acc[ai][0][m][n][2 * jp + 1]} * rs[m]; V[m] = (f32x2){acc[ai][1][m][n][2 * jp], acc[ai][1][m][n][2 * jp + 1]} * rs[m]; }
; #pragma unroll
;                     for (int m = 0; m < 4; ++m) {
;                         const f32x2 zz = {0.f, 0.f}; const f32x2 Gp = m ? G[m - 1] : zz, Vp = m ? V[m - 1] : zz;
;                         const f32x2 gp1 = {dpp_prev1(G[m].x, Gp.x), dpp_prev1(G[m].y, Gp.y)}, gp2 = {dpp_prev2(G[m].x, Gp.x), dpp_prev2(G[m].y, Gp.y)};
;                         const f32x2 vp1 = {dpp_prev1(V[m].x, Vp.x), dpp_prev1(V[m].y, Vp.y)}, vp2 = {dpp_prev2(V[m].x, Vp.x), dpp_prev2(V[m].y, Vp.y)};
;                         const f32x2 gc = bg + g0 * gp2 + g1 * gp1 + g2 * G[m];
;                         const f32x2 vc = bv + v0 * vp2 + v1 * vp1 + v2 * V[m];
;                         const f32x2 xe = gc * (-LOG2E);
;                         f32x2 dn = {__builtin_amdgcn_exp2f(xe.x), __builtin_amdgcn_exp2f(xe.y)}; dn = dn + 1.0f;
;                         const f32x2 rc = {__builtin_amdgcn_rcpf(dn.x), __builtin_amdgcn_rcpf(dn.y)};
;                         const f32x2 rr = gc * rc * vc;
;                         wpk[m][jp] = pk2(rr.x, rr.y); }
	v_pk_fma_f32 v[114:115], v[54:55], v[114:115], v[42:43]
	v_pk_mul_f32 v[28:29], v[28:29], v[102:103] op_sel_hi:[1,0]
	v_pk_mul_f32 v[24:25], v[24:25], v[102:103] op_sel_hi:[1,0]
	v_pk_mul_f32 v[20:21], v[20:21], v[100:101] op_sel_hi:[1,0]
	v_pk_mul_f32 v[16:17], v[16:17], v[100:101] op_sel_hi:[1,0]
	v_pk_mul_f32 v[26:27], v[26:27], v[102:103] op_sel_hi:[1,0]
	v_pk_mul_f32 v[100:101], v[18:19], v[100:101] op_sel_hi:[1,0]
	v_mov_b32_e32 v102, v183
	v_mov_b32_e32 v103, v183
	s_waitcnt lgkmcnt(5)
	v_pk_fma_f32 v[112:113], v[58:59], v[112:113], v[114:115]
	v_pk_mul_f32 v[76:77], v[12:13], v[98:99] op_sel_hi:[1,0]
	v_pk_mul_f32 v[72:73], v[8:9], v[98:99] op_sel_hi:[1,0]
	v_pk_mul_f32 v[14:15], v[14:15], v[98:99] op_sel_hi:[1,0]
	v_pk_mul_f32 v[10:11], v[10:11], v[98:99] op_sel_hi:[1,0]
	v_mov_b32_e32 v98, v181
	v_mov_b32_e32 v99, v181
	v_mov_b32_dpp v102, v30 row_shr:2 row_mask:0xf bank_mask:0xf
	v_mov_b32_dpp v103, v31 row_shr:2 row_mask:0xf bank_mask:0xf
	v_mov_b32_dpp v18, v22 row_ror:1 row_mask:0xf bank_mask:0xf
	v_mov_b32_dpp v19, v23 row_ror:1 row_mask:0xf bank_mask:0xf
	v_mov_b32_dpp v120, v22 row_ror:2 row_mask:0xf bank_mask:0xf
	v_mov_b32_dpp v121, v23 row_ror:2 row_mask:0xf bank_mask:0xf
	s_waitcnt lgkmcnt(4)
	v_pk_fma_f32 v[22:23], v[22:23], v[62:63], v[112:113]
	v_mov_b32_dpp v98, v30 row_shr:1 row_mask:0xf bank_mask:0xf
	v_mov_b32_dpp v99, v31 row_shr:1 row_mask:0xf bank_mask:0xf
	v_pk_mul_f32 v[112:113], v[22:23], s[0:1] op_sel_hi:[1,0]
	v_pk_fma_f32 v[102:103], v[54:55], v[102:103], v[42:43]
	v_exp_f32_e32 v112, v112
	v_exp_f32_e32 v113, v113
	v_pk_fma_f32 v[98:99], v[58:59], v[98:99], v[102:103]
	v_pk_fma_f32 v[30:31], v[30:31], v[62:63], v[98:99]
	v_pk_mul_f32 v[98:99], v[30:31], s[0:1] op_sel_hi:[1,0]
	v_pk_add_f32 v[112:113], v[112:113], 1.0 op_sel_hi:[1,0]
	v_exp_f32_e32 v98, v98
	v_exp_f32_e32 v99, v99
	v_mov_b32_dpp v118, v26 row_ror:2 row_mask:0xf bank_mask:0xf
	v_mov_b32_dpp v119, v27 row_ror:2 row_mask:0xf bank_mask:0xf
	v_rcp_f32_e32 v112, v112
	v_rcp_f32_e32 v113, v113
	v_mov_b32_dpp v116, v26 row_ror:1 row_mask:0xf bank_mask:0xf
	v_mov_b32_dpp v117, v27 row_ror:1 row_mask:0xf bank_mask:0xf
	v_mov_b32_dpp v118, v100 row_shr:2 row_mask:0xf bank_mask:0xf
	v_mov_b32_dpp v119, v101 row_shr:2 row_mask:0xf bank_mask:0xf
	v_mov_b32_dpp v116, v100 row_shr:1 row_mask:0xf bank_mask:0xf
	v_mov_b32_dpp v117, v101 row_shr:1 row_mask:0xf bank_mask:0xf
	s_waitcnt lgkmcnt(2)
	v_pk_fma_f32 v[114:115], v[38:39], v[118:119], v[34:35]
	v_pk_add_f32 v[98:99], v[98:99], 1.0 op_sel_hi:[1,0]
	v_mov_b32_e32 v182, v183
	s_waitcnt lgkmcnt(1)
	v_pk_fma_f32 v[114:115], v[46:47], v[116:117], v[114:115]
	v_rcp_f32_e32 v98, v98
	v_rcp_f32_e32 v99, v99
	v_pk_mul_f32 v[86:87], v[4:5], v[96:97] op_sel_hi:[1,0]
	v_mov_b32_e32 v12, v183
	v_mov_b32_e32 v13, v183
	v_mov_b32_e32 v4, v183
	v_mov_b32_e32 v5, v183
	v_mov_b32_e32 v180, v181
	v_mov_b32_dpp v182, v26 row_shr:2 row_mask:0xf bank_mask:0xf
	v_mov_b32_dpp v183, v27 row_shr:2 row_mask:0xf bank_mask:0xf
	v_mov_b32_dpp v122, v100 row_ror:1 row_mask:0xf bank_mask:0xf
	v_mov_b32_dpp v123, v101 row_ror:1 row_mask:0xf bank_mask:0xf
	v_mov_b32_dpp v124, v100 row_ror:2 row_mask:0xf bank_mask:0xf
	v_mov_b32_dpp v125, v101 row_ror:2 row_mask:0xf bank_mask:0xf
	s_waitcnt lgkmcnt(0)
	v_pk_fma_f32 v[100:101], v[100:101], v[50:51], v[114:115]
	v_pk_mul_f32 v[22:23], v[22:23], v[112:113]
	v_pk_mul_f32 v[84:85], v[0:1], v[96:97] op_sel_hi:[1,0]
	v_mov_b32_e32 v8, v181
	v_mov_b32_e32 v9, v181
	v_mov_b32_e32 v0, v181
	v_mov_b32_e32 v1, v181
	v_mov_b32_dpp v180, v26 row_shr:1 row_mask:0xf bank_mask:0xf
	v_mov_b32_dpp v181, v27 row_shr:1 row_mask:0xf bank_mask:0xf
	v_pk_mul_f32 v[22:23], v[100:101], v[22:23]
	v_pk_fma_f32 v[100:101], v[38:39], v[182:183], v[34:35]
	v_mov_b32_dpp v106, v76 row_ror:2 row_mask:0xf bank_mask:0xf
	v_mov_b32_dpp v107, v77 row_ror:2 row_mask:0xf bank_mask:0xf
	v_pk_fma_f32 v[100:101], v[46:47], v[180:181], v[100:101]
	v_mov_b32_dpp v104, v76 row_ror:1 row_mask:0xf bank_mask:0xf
	v_mov_b32_dpp v105, v77 row_ror:1 row_mask:0xf bank_mask:0xf
	v_mov_b32_dpp v106, v86 row_shr:2 row_mask:0xf bank_mask:0xf
	v_mov_b32_dpp v107, v87 row_shr:2 row_mask:0xf bank_mask:0xf
	v_pk_fma_f32 v[26:27], v[26:27], v[50:51], v[100:101]
	v_pk_mul_f32 v[30:31], v[30:31], v[98:99]
	v_mov_b32_dpp v104, v86 row_shr:1 row_mask:0xf bank_mask:0xf
	v_mov_b32_dpp v105, v87 row_shr:1 row_mask:0xf bank_mask:0xf
	v_pk_mul_f32 v[26:27], v[26:27], v[30:31]
	v_pk_fma_f32 v[30:31], v[52:53], v[106:107], v[40:41]
	v_mov_b32_dpp v12, v28 row_shr:2 row_mask:0xf bank_mask:0xf
	v_pk_fma_f32 v[30:31], v[56:57], v[104:105], v[30:31]
	v_mov_b32_dpp v13, v29 row_shr:2 row_mask:0xf bank_mask:0xf
	v_pk_fma_f32 v[30:31], v[86:87], v[60:61], v[30:31]
	v_pk_mul_f32 v[86:87], v[30:31], s[0:1] op_sel_hi:[1,0]
	v_mov_b32_dpp v8, v28 row_shr:1 row_mask:0xf bank_mask:0xf
	v_mov_b32_dpp v9, v29 row_shr:1 row_mask:0xf bank_mask:0xf
	v_mov_b32_dpp v92, v20 row_ror:2 row_mask:0xf bank_mask:0xf
	v_mov_b32_dpp v93, v21 row_ror:2 row_mask:0xf bank_mask:0xf
	v_exp_f32_e32 v86, v86
	v_exp_f32_e32 v87, v87
	v_pk_fma_f32 v[12:13], v[52:53], v[12:13], v[40:41]
	v_mov_b32_dpp v88, v20 row_ror:1 row_mask:0xf bank_mask:0xf
	v_mov_b32_dpp v89, v21 row_ror:1 row_mask:0xf bank_mask:0xf
	v_mov_b32_dpp v92, v76 row_shr:2 row_mask:0xf bank_mask:0xf
	v_mov_b32_dpp v93, v77 row_shr:2 row_mask:0xf bank_mask:0xf
	v_mov_b32_dpp v120, v14 row_shr:2 row_mask:0xf bank_mask:0xf
	v_mov_b32_dpp v121, v15 row_shr:2 row_mask:0xf bank_mask:0xf
	v_pk_fma_f32 v[8:9], v[56:57], v[8:9], v[12:13]
	v_mov_b32_dpp v88, v76 row_shr:1 row_mask:0xf bank_mask:0xf
; #define LAS __attribute__((address_space(3)))
; DI float dpp_prev1(float cur, float prevm) {
;     const int o = __builtin_amdgcn_update_dpp(0, __builtin_bit_cast(int, prevm), 0x121, 0xf, 0xf, false);
;     return __builtin_bit_cast(float, __builtin_amdgcn_update_dpp(o, __builtin_bit_cast(int, cur), 0x111, 0xf, 0xf, false));
; }
; DI float dpp_prev2(float cur, float prevm) {
;     const int o = __builtin_amdgcn_update_dpp(0, __builtin_bit_cast(int, prevm), 0x122, 0xf, 0xf, false);
;     DI void operator()(const AccT& acc, const Unit& u, int wr, int wc, int fr, int fq) const {
;     ...
;                     const f32x2 bg = *(const LAS f32x2*)(P + lc + 2 * jp), g0 = *(const LAS f32x2*)(P + 32 + lc + 2 * jp), g1 = *(const LAS f32x2*)(P + 64 + lc + 2 * jp), g2 = *(const LAS f32x2*)(P + 96 + lc + 2 * jp);
;                     const f32x2 bv = *(const LAS f32x2*)(P + 128 + lc + 2 * jp), v0 = *(const LAS f32x2*)(P + 160 + lc + 2 * jp), v1 = *(const LAS f32x2*)(P + 192 + lc + 2 * jp), v2 = *(const LAS f32x2*)(P + 224 + lc + 2 * jp);
;                     f32x2 G[4], V[4];
; #pragma unroll
;                     for (int m = 0; m < 4; ++m) { G[m] = (f32x2){acc[ai][0][m][n][2 * jp], acc[ai][0][m][n][2 * jp + 1]} * rs[m]; V[m] = (f32x2){acc[ai][1][m][n][2 * jp], acc[ai][1][m][n][2 * jp + 1]} * rs[m]; }
; #pragma unroll
;                     for (int m = 0; m < 4; ++m) {
;                         const f32x2 zz = {0.f, 0.f}; const f32x2 Gp = m ? G[m - 1] : zz, Vp = m ? V[m - 1] : zz;
;                         const f32x2 gp1 = {dpp_prev1(G[m].x, Gp.x), dpp_prev1(G[m].y, Gp.y)}, gp2 = {dpp_prev2(G[m].x, Gp.x), dpp_prev2(G[m].y, Gp.y)};
;                         const f32x2 vp1 = {dpp_prev1(V[m].x, Vp.x), dpp_prev1(V[m].y, Vp.y)}, vp2 = {dpp_prev2(V[m].x, Vp.x), dpp_prev2(V[m].y, Vp.y)};
;                         const f32x2 gc = bg + g0 * gp2 + g1 * gp1 + g2 * G[m];
;                         const f32x2 vc = bv + v0 * vp2 + v1 * vp1 + v2 * V[m];
;                         const f32x2 xe = gc * (-LOG2E);
;                         f32x2 dn = {__builtin_amdgcn_exp2f(xe.x), __builtin_amdgcn_exp2f(xe.y)}; dn = dn + 1.0f;
;                         const f32x2 rc = {__builtin_amdgcn_rcpf(dn.x), __builtin_amdgcn_rcpf(dn.y)};
;                         const f32x2 rr = gc * rc * vc;
;                         wpk[m][jp] = pk2(rr.x, rr.y); }
	v_mov_b32_dpp v89, v77 row_shr:1 row_mask:0xf bank_mask:0xf
	v_mov_b32_dpp v18, v14 row_shr:1 row_mask:0xf bank_mask:0xf
	v_mov_b32_dpp v19, v15 row_shr:1 row_mask:0xf bank_mask:0xf
	v_pk_fma_f32 v[120:121], v[54:55], v[120:121], v[42:43]
	v_pk_fma_f32 v[92:93], v[52:53], v[92:93], v[40:41]
	v_pk_fma_f32 v[8:9], v[28:29], v[60:61], v[8:9]
	v_pk_fma_f32 v[18:19], v[58:59], v[18:19], v[120:121]
	v_pk_fma_f32 v[88:89], v[56:57], v[88:89], v[92:93]
	v_pk_mul_f32 v[12:13], v[8:9], s[0:1] op_sel_hi:[1,0]
	v_pk_fma_f32 v[18:19], v[14:15], v[62:63], v[18:19]
	v_pk_add_f32 v[86:87], v[86:87], 1.0 op_sel_hi:[1,0]
	v_pk_fma_f32 v[76:77], v[76:77], v[60:61], v[88:89]
	v_exp_f32_e32 v12, v12
	v_exp_f32_e32 v13, v13
	v_mov_b32_dpp v110, v72 row_ror:2 row_mask:0xf bank_mask:0xf
	v_mov_b32_dpp v111, v73 row_ror:2 row_mask:0xf bank_mask:0xf
	v_pk_mul_f32 v[120:121], v[18:19], s[0:1] op_sel_hi:[1,0]
	v_rcp_f32_e32 v86, v86
	v_rcp_f32_e32 v87, v87
	v_pk_mul_f32 v[88:89], v[76:77], s[0:1] op_sel_hi:[1,0]
	v_mov_b32_dpp v108, v72 row_ror:1 row_mask:0xf bank_mask:0xf
	v_mov_b32_dpp v109, v73 row_ror:1 row_mask:0xf bank_mask:0xf
	v_mov_b32_dpp v110, v84 row_shr:2 row_mask:0xf bank_mask:0xf
	v_mov_b32_dpp v111, v85 row_shr:2 row_mask:0xf bank_mask:0xf
	v_exp_f32_e32 v120, v120
	v_exp_f32_e32 v121, v121
	v_exp_f32_e32 v88, v88
	v_exp_f32_e32 v89, v89
	v_mov_b32_dpp v108, v84 row_shr:1 row_mask:0xf bank_mask:0xf
	v_mov_b32_dpp v109, v85 row_shr:1 row_mask:0xf bank_mask:0xf
	v_pk_mul_f32 v[2:3], v[2:3], v[96:97] op_sel_hi:[1,0]
	v_pk_mul_f32 v[6:7], v[6:7], v[96:97] op_sel_hi:[1,0]
	v_pk_fma_f32 v[96:97], v[36:37], v[110:111], v[32:33]
	v_pk_add_f32 v[12:13], v[12:13], 1.0 op_sel_hi:[1,0]
	v_pk_fma_f32 v[96:97], v[44:45], v[108:109], v[96:97]
	v_pk_mul_f32 v[30:31], v[30:31], v[86:87]
	v_pk_fma_f32 v[84:85], v[84:85], v[48:49], v[96:97]
	v_rcp_f32_e32 v12, v12
	v_rcp_f32_e32 v13, v13
	v_mov_b32_dpp v4, v24 row_shr:2 row_mask:0xf bank_mask:0xf
	v_mov_b32_dpp v5, v25 row_shr:2 row_mask:0xf bank_mask:0xf
	v_pk_add_f32 v[120:121], v[120:121], 1.0 op_sel_hi:[1,0]
	v_pk_mul_f32 v[30:31], v[84:85], v[30:31]
	v_pk_add_f32 v[84:85], v[88:89], 1.0 op_sel_hi:[1,0]
	v_mov_b32_dpp v0, v24 row_shr:1 row_mask:0xf bank_mask:0xf
	v_mov_b32_dpp v1, v25 row_shr:1 row_mask:0xf bank_mask:0xf
	v_mov_b32_dpp v94, v16 row_ror:2 row_mask:0xf bank_mask:0xf
	v_mov_b32_dpp v95, v17 row_ror:2 row_mask:0xf bank_mask:0xf
	v_rcp_f32_e32 v120, v120
	v_rcp_f32_e32 v121, v121
	v_rcp_f32_e32 v84, v84
	v_rcp_f32_e32 v85, v85
	v_pk_fma_f32 v[4:5], v[36:37], v[4:5], v[32:33]
	v_mov_b32_dpp v90, v16 row_ror:1 row_mask:0xf bank_mask:0xf
	v_mov_b32_dpp v91, v17 row_ror:1 row_mask:0xf bank_mask:0xf
	v_mov_b32_dpp v94, v72 row_shr:2 row_mask:0xf bank_mask:0xf
	v_mov_b32_dpp v95, v73 row_shr:2 row_mask:0xf bank_mask:0xf
	v_mov_b32_dpp v124, v10 row_shr:2 row_mask:0xf bank_mask:0xf
	v_mov_b32_dpp v125, v11 row_shr:2 row_mask:0xf bank_mask:0xf
	v_pk_fma_f32 v[0:1], v[44:45], v[0:1], v[4:5]
	v_mov_b32_dpp v90, v72 row_shr:1 row_mask:0xf bank_mask:0xf
	v_mov_b32_dpp v91, v73 row_shr:1 row_mask:0xf bank_mask:0xf
	v_mov_b32_dpp v122, v10 row_shr:1 row_mask:0xf bank_mask:0xf
	v_mov_b32_dpp v123, v11 row_shr:1 row_mask:0xf bank_mask:0xf
	v_pk_fma_f32 v[124:125], v[38:39], v[124:125], v[34:35]
	v_pk_fma_f32 v[86:87], v[36:37], v[94:95], v[32:33]
	v_pk_fma_f32 v[0:1], v[24:25], v[48:49], v[0:1]
	v_pk_mul_f32 v[4:5], v[8:9], v[12:13]
	v_pk_fma_f32 v[122:123], v[46:47], v[122:123], v[124:125]
	v_pk_fma_f32 v[86:87], v[44:45], v[90:91], v[86:87]
	v_pk_mul_f32 v[0:1], v[0:1], v[4:5]
	v_mov_b32_dpp v78, v28 row_ror:2 row_mask:0xf bank_mask:0xf
	v_mov_b32_dpp v79, v29 row_ror:2 row_mask:0xf bank_mask:0xf
	v_pk_fma_f32 v[122:123], v[10:11], v[50:51], v[122:123]
	v_pk_mul_f32 v[18:19], v[18:19], v[120:121]
; DI float dpp_prev1(float cur, float prevm) {
;     const int o = __builtin_amdgcn_update_dpp(0, __builtin_bit_cast(int, prevm), 0x121, 0xf, 0xf, false);
;     return __builtin_bit_cast(float, __builtin_amdgcn_update_dpp(o, __builtin_bit_cast(int, cur), 0x111, 0xf, 0xf, false));
; }
;     DI void operator()(const AccT& acc, const Unit& u, int wr, int wc, int fr, int fq) const {
;     ...
;                     const f32x2 bg = *(const LAS f32x2*)(P + lc + 2 * jp), g0 = *(const LAS f32x2*)(P + 32 + lc + 2 * jp), g1 = *(const LAS f32x2*)(P + 64 + lc + 2 * jp), g2 = *(const LAS f32x2*)(P + 96 + lc + 2 * jp);
;                     const f32x2 bv = *(const LAS f32x2*)(P + 128 + lc + 2 * jp), v0 = *(const LAS f32x2*)(P + 160 + lc + 2 * jp), v1 = *(const LAS f32x2*)(P + 192 + lc + 2 * jp), v2 = *(const LAS f32x2*)(P + 224 + lc + 2 * jp);
;                     f32x2 G[4], V[4];
; #pragma unroll
;                     for (int m = 0; m < 4; ++m) { G[m] = (f32x2){acc[ai][0][m][n][2 * jp], acc[ai][0][m][n][2 * jp + 1]} * rs[m]; V[m] = (f32x2){acc[ai][1][m][n][2 * jp], acc[ai][1][m][n][2 * jp + 1]} * rs[m]; }
; #pragma unroll
;                     for (int m = 0; m < 4; ++m) {
;                         const f32x2 zz = {0.f, 0.f}; const f32x2 Gp = m ? G[m - 1] : zz, Vp = m ? V[m - 1] : zz;
;                         const f32x2 gp1 = {dpp_prev1(G[m].x, Gp.x), dpp_prev1(G[m].y, Gp.y)}, gp2 = {dpp_prev2(G[m].x, Gp.x), dpp_prev2(G[m].y, Gp.y)};
;                         const f32x2 vp1 = {dpp_prev1(V[m].x, Vp.x), dpp_prev1(V[m].y, Vp.y)}, vp2 = {dpp_prev2(V[m].x, Vp.x), dpp_prev2(V[m].y, Vp.y)};
;                         const f32x2 gc = bg + g0 * gp2 + g1 * gp1 + g2 * G[m];
;                         const f32x2 vc = bv + v0 * vp2 + v1 * vp1 + v2 * V[m];
;                         const f32x2 xe = gc * (-LOG2E);
;                         f32x2 dn = {__builtin_amdgcn_exp2f(xe.x), __builtin_amdgcn_exp2f(xe.y)}; dn = dn + 1.0f;
;                         const f32x2 rc = {__builtin_amdgcn_rcpf(dn.x), __builtin_amdgcn_rcpf(dn.y)};
;                         const f32x2 rr = gc * rc * vc;
;                         wpk[m][jp] = pk2(rr.x, rr.y); }
;                 }
; #pragma unroll
;                 for (int m = 0; m < 4; ++m) { const int row = m ? tok0 + 16 * m : row0;
;                     *(u32x2*)(ACT + (size_t)row * 2816 + cl + 4 * n) = (u32x2){wpk[m][0], wpk[m][1]}; }
	v_cvt_pk_bf16_f32 v27, v26, v27
	v_pk_fma_f32 v[72:73], v[72:73], v[48:49], v[86:87]
	v_pk_mul_f32 v[76:77], v[76:77], v[84:85]
	v_cvt_pk_bf16_f32 v26, v0, v1
	v_mov_b32_dpp v4, v14 row_ror:2 row_mask:0xf bank_mask:0xf
	v_mov_b32_dpp v5, v15 row_ror:2 row_mask:0xf bank_mask:0xf
	v_mov_b32_dpp v74, v28 row_ror:1 row_mask:0xf bank_mask:0xf
	v_mov_b32_dpp v75, v29 row_ror:1 row_mask:0xf bank_mask:0xf
	v_mov_b32_dpp v78, v20 row_shr:2 row_mask:0xf bank_mask:0xf
	v_mov_b32_dpp v79, v21 row_shr:2 row_mask:0xf bank_mask:0xf
	v_pk_mul_f32 v[18:19], v[122:123], v[18:19]
	v_pk_mul_f32 v[72:73], v[72:73], v[76:77]
	v_mov_b32_dpp v0, v14 row_ror:1 row_mask:0xf bank_mask:0xf
	v_mov_b32_dpp v1, v15 row_ror:1 row_mask:0xf bank_mask:0xf
	v_mov_b32_dpp v4, v6 row_shr:2 row_mask:0xf bank_mask:0xf
	v_mov_b32_dpp v5, v7 row_shr:2 row_mask:0xf bank_mask:0xf
	v_mov_b32_dpp v74, v20 row_shr:1 row_mask:0xf bank_mask:0xf
	v_mov_b32_dpp v75, v21 row_shr:1 row_mask:0xf bank_mask:0xf
	v_cvt_pk_bf16_f32 v19, v18, v19
	v_cvt_pk_bf16_f32 v18, v72, v73
	v_pk_fma_f32 v[72:73], v[52:53], v[78:79], v[40:41]
	v_mov_b32_dpp v0, v6 row_shr:1 row_mask:0xf bank_mask:0xf
	v_mov_b32_dpp v1, v7 row_shr:1 row_mask:0xf bank_mask:0xf
	v_pk_fma_f32 v[4:5], v[54:55], v[4:5], v[42:43]
	v_pk_fma_f32 v[72:73], v[56:57], v[74:75], v[72:73]
	v_pk_fma_f32 v[0:1], v[58:59], v[0:1], v[4:5]
	v_pk_fma_f32 v[20:21], v[20:21], v[60:61], v[72:73]
	v_pk_fma_f32 v[0:1], v[6:7], v[62:63], v[0:1]
	v_pk_mul_f32 v[72:73], v[20:21], s[0:1] op_sel_hi:[1,0]
	v_pk_mul_f32 v[4:5], v[0:1], s[0:1] op_sel_hi:[1,0]
	v_exp_f32_e32 v72, v72
	v_exp_f32_e32 v73, v73
	v_exp_f32_e32 v4, v4
	v_exp_f32_e32 v5, v5
	v_pk_add_f32 v[72:73], v[72:73], 1.0 op_sel_hi:[1,0]
	v_pk_add_f32 v[4:5], v[4:5], 1.0 op_sel_hi:[1,0]
	v_mov_b32_dpp v82, v24 row_ror:2 row_mask:0xf bank_mask:0xf
	v_mov_b32_dpp v83, v25 row_ror:2 row_mask:0xf bank_mask:0xf
	v_rcp_f32_e32 v72, v72
	v_rcp_f32_e32 v73, v73
	v_mov_b32_dpp v12, v10 row_ror:2 row_mask:0xf bank_mask:0xf
	v_mov_b32_dpp v13, v11 row_ror:2 row_mask:0xf bank_mask:0xf
	v_rcp_f32_e32 v4, v4
	v_rcp_f32_e32 v5, v5
	v_mov_b32_dpp v80, v24 row_ror:1 row_mask:0xf bank_mask:0xf
	v_mov_b32_dpp v81, v25 row_ror:1 row_mask:0xf bank_mask:0xf
	v_mov_b32_dpp v82, v16 row_shr:2 row_mask:0xf bank_mask:0xf
	v_mov_b32_dpp v83, v17 row_shr:2 row_mask:0xf bank_mask:0xf
	v_mov_b32_dpp v8, v10 row_ror:1 row_mask:0xf bank_mask:0xf
	v_mov_b32_dpp v9, v11 row_ror:1 row_mask:0xf bank_mask:0xf
	v_mov_b32_dpp v12, v2 row_shr:2 row_mask:0xf bank_mask:0xf
	v_mov_b32_dpp v13, v3 row_shr:2 row_mask:0xf bank_mask:0xf
	v_mov_b32_dpp v80, v16 row_shr:1 row_mask:0xf bank_mask:0xf
	v_mov_b32_dpp v81, v17 row_shr:1 row_mask:0xf bank_mask:0xf
	v_pk_fma_f32 v[74:75], v[36:37], v[82:83], v[32:33]
	v_mov_b32_dpp v8, v2 row_shr:1 row_mask:0xf bank_mask:0xf
	v_mov_b32_dpp v9, v3 row_shr:1 row_mask:0xf bank_mask:0xf
	v_pk_fma_f32 v[6:7], v[38:39], v[12:13], v[34:35]
	v_pk_fma_f32 v[74:75], v[44:45], v[80:81], v[74:75]
	v_pk_fma_f32 v[6:7], v[46:47], v[8:9], v[6:7]
	v_pk_fma_f32 v[16:17], v[16:17], v[48:49], v[74:75]
	v_pk_mul_f32 v[20:21], v[20:21], v[72:73]
	v_pk_fma_f32 v[2:3], v[2:3], v[50:51], v[6:7]
	v_pk_mul_f32 v[0:1], v[0:1], v[4:5]
	v_pk_mul_f32 v[16:17], v[16:17], v[20:21]
	v_pk_mul_f32 v[0:1], v[2:3], v[0:1]
	v_cvt_pk_bf16_f32 v23, v22, v23
	v_cvt_pk_bf16_f32 v30, v30, v31
	v_cvt_pk_bf16_f32 v22, v16, v17
	v_cvt_pk_bf16_f32 v31, v0, v1
	global_store_dwordx2 v[64:65], v[26:27], off offset:8
	global_store_dwordx2 v[66:67], v[22:23], off offset:8
	global_store_dwordx2 v[68:69], v[18:19], off offset:8
	global_store_dwordx2 v[70:71], v[30:31], off offset:8
	s_and_b64 vcc, exec, s[8:9]
	s_mov_b64 s[8:9], -1
	s_cbranch_vccnz .LBB0_1108
	s_andn2_b64 vcc, exec, s[2:3]
	s_cbranch_vccnz .LBB0_1107
	s_barrier
	s_branch .LBB0_1107

; DI unsigned pk2(float lo, float hi) { f32x2 v = {lo, hi}; bf16x2_t b = __builtin_convertvector(v, bf16x2_t); return __builtin_bit_cast(unsigned, b); }
; DI float bflo(unsigned u) { return __uint_as_float(u << 16); }
; DI float bfhi(unsigned u) { return __uint_as_float(u & 0xffff0000u); }
; DI u64 ss_to_fix(float ss) { return (u64)(ss * 1048576.f); }
;     DI void operator()(const AccT& acc, const Unit& u, int wr, int wc, int fr, int fq) const {
;         const int row0 = u.pm * 256 + wr * 64 + fr, col0 = u.pn * 256 + wc * 32 + 8 * fq;
; #pragma unroll
;         for (int ai = 0; ai < 2; ++ai)
; #pragma unroll
;             for (int m = 0; m < 4; ++m) { const int t = row0 + ai * 128 + m * 16; float ss = 0.f;
; #pragma unroll
;                 for (int bj = 0; bj < 2; ++bj) { const size_t o = (size_t)t * 1024 + col0 + bj * 128;
;                     f32x4 r0, r1;
;                     if (RESBF) { const u32x4 rb = *(const u32x4*)(XB + o); r0 = (f32x4){bflo(rb.x), bfhi(rb.x), bflo(rb.y), bfhi(rb.y)}; r1 = (f32x4){bflo(rb.z), bfhi(rb.z), bflo(rb.w), bfhi(rb.w)}; }
;                     else { r0 = __builtin_nontemporal_load((const f32x4*)(res + o)); r1 = __builtin_nontemporal_load((const f32x4*)(res + o + 4)); }
;                     const f32x4 v0 = acc[ai][bj][m][0] + r0, v1 = acc[ai][bj][m][1] + r1;
;                     u32x4 w; w.x = pk2(v0[0], v0[1]); w.y = pk2(v0[2], v0[3]); w.z = pk2(v1[0], v1[1]); w.w = pk2(v1[2], v1[3]);
;                     if (!dry) *(u32x4*)(XB + o) = w;
;                     ss += v0[0] * v0[0] + v0[1] * v0[1] + v0[2] * v0[2] + v0[3] * v0[3] + v1[0] * v1[0] + v1[1] * v1[1] + v1[2] * v1[2] + v1[3] * v1[3]; }
;                 { const auto r16 = __builtin_amdgcn_permlane16_swap(__float_as_uint(ss), __float_as_uint(ss), false, false); ss = __uint_as_float(r16[0]) + __uint_as_float(r16[1]);
;                   const auto r32 = __builtin_amdgcn_permlane32_swap(__float_as_uint(ss), __float_as_uint(ss), false, false); ss = __uint_as_float(r32[0]) + __uint_as_float(r32[1]); }
;                 if (fq == 0 && !dry) atomicAdd(rowss + t, ss_to_fix(ss)); }
.LBB0_1208:
	v_lshl_add_u32 v146, s51, 8, v148
	v_ashrrev_i32_e32 v147, 31, v146
	v_lshl_or_b32 v144, s52, 8, v150
	v_lshlrev_b64 v[154:155], 11, v[146:147]
	v_ashrrev_i32_e32 v145, 31, v144
	v_lshl_add_u64 v[154:155], s[2:3], 0, v[154:155]
	v_lshl_add_u64 v[162:163], v[144:145], 1, v[154:155]
	global_load_dwordx4 v[154:157], v[162:163], off
	global_load_dwordx4 v[158:161], v[162:163], off offset:256
	v_or_b32_e32 v172, 16, v146
	v_ashrrev_i32_e32 v173, 31, v172
	v_lshlrev_b64 v[182:183], 11, v[172:173]
	v_lshl_add_u64 v[182:183], s[2:3], 0, v[182:183]
	v_lshl_add_u64 v[182:183], v[144:145], 1, v[182:183]
	global_load_dwordx4 v[174:177], v[182:183], off
	global_load_dwordx4 v[178:181], v[182:183], off offset:256
	v_or_b32_e32 v172, 32, v146
	v_ashrrev_i32_e32 v173, 31, v172
	v_lshlrev_b64 v[200:201], 11, v[172:173]
	v_lshl_add_u64 v[200:201], s[2:3], 0, v[200:201]
	v_lshl_add_u64 v[200:201], v[144:145], 1, v[200:201]
	global_load_dwordx4 v[184:187], v[200:201], off
	global_load_dwordx4 v[188:191], v[200:201], off offset:256
	v_or_b32_e32 v172, 48, v146
	v_ashrrev_i32_e32 v173, 31, v172
	v_lshlrev_b64 v[210:211], 11, v[172:173]
	v_lshl_add_u64 v[210:211], s[2:3], 0, v[210:211]
	v_lshl_add_u64 v[210:211], v[144:145], 1, v[210:211]
	global_load_dwordx4 v[202:205], v[210:211], off
	global_load_dwordx4 v[206:209], v[210:211], off offset:256
	v_add_u32_e32 v172, 0x80, v146
	v_ashrrev_i32_e32 v173, 31, v172
	v_lshlrev_b64 v[220:221], 11, v[172:173]
	v_lshl_add_u64 v[220:221], s[2:3], 0, v[220:221]
	v_lshl_add_u64 v[220:221], v[144:145], 1, v[220:221]
	global_load_dwordx4 v[212:215], v[220:221], off
	global_load_dwordx4 v[216:219], v[220:221], off offset:256
	v_add_u32_e32 v172, 0x90, v146
	v_ashrrev_i32_e32 v173, 31, v172
	v_lshlrev_b64 v[230:231], 11, v[172:173]
	v_lshl_add_u64 v[230:231], s[2:3], 0, v[230:231]
	v_lshl_add_u64 v[230:231], v[144:145], 1, v[230:231]
	global_load_dwordx4 v[222:225], v[230:231], off
	global_load_dwordx4 v[226:229], v[230:231], off offset:256
	v_add_u32_e32 v172, 0xa0, v146
	v_ashrrev_i32_e32 v173, 31, v172
	v_lshlrev_b64 v[242:243], 11, v[172:173]
	v_lshl_add_u64 v[242:243], s[2:3], 0, v[242:243]
	v_lshl_add_u64 v[242:243], v[144:145], 1, v[242:243]
	global_load_dwordx4 v[232:235], v[242:243], off
	global_load_dwordx4 v[236:239], v[242:243], off offset:256
	v_add_u32_e32 v172, 0xb0, v146
	v_ashrrev_i32_e32 v173, 31, v172
	v_lshlrev_b64 v[252:253], 11, v[172:173]
	v_lshl_add_u64 v[252:253], s[2:3], 0, v[252:253]
	v_lshl_add_u64 v[252:253], v[144:145], 1, v[252:253]
	global_load_dwordx4 v[244:247], v[252:253], off
	global_load_dwordx4 v[248:251], v[252:253], off offset:256
	s_waitcnt vmcnt(14)
	v_lshlrev_b32_e32 v164, 16, v154
	v_and_b32_e32 v165, 0xffff0000, v154
	v_lshlrev_b32_e32 v166, 16, v156
	v_and_b32_e32 v167, 0xffff0000, v156
	v_lshlrev_b32_e32 v156, 16, v157
	v_and_b32_e32 v157, 0xffff0000, v157
	v_lshlrev_b32_e32 v168, 16, v158
	v_and_b32_e32 v169, 0xffff0000, v158
	v_lshlrev_b32_e32 v154, 16, v155
	v_and_b32_e32 v155, 0xffff0000, v155
	v_lshlrev_b32_e32 v158, 16, v159
	v_and_b32_e32 v159, 0xffff0000, v159
	v_lshlrev_b32_e32 v170, 16, v160
	v_and_b32_e32 v171, 0xffff0000, v160
	v_lshlrev_b32_e32 v160, 16, v161
	v_and_b32_e32 v161, 0xffff0000, v161
	v_pk_add_f32 v[120:121], v[120:121], v[164:165]
	v_pk_add_f32 v[126:127], v[126:127], v[156:157]
	v_pk_add_f32 v[156:157], v[116:117], v[168:169]
	v_pk_add_f32 v[122:123], v[122:123], v[154:155]
	v_pk_add_f32 v[154:155], v[118:119], v[158:159]
	v_pk_add_f32 v[158:159], v[114:115], v[160:161]
	v_pk_add_f32 v[160:161], v[112:113], v[170:171]
	v_cvt_pk_bf16_f32 v112, v120, v121
	v_mul_f32_e32 v121, v121, v121
	v_cvt_pk_bf16_f32 v116, v156, v157
	v_mul_f32_e32 v157, v157, v157
	v_fmac_f32_e32 v121, v120, v120
	v_fmac_f32_e32 v157, v156, v156
	v_fmac_f32_e32 v121, v122, v122
	v_fmac_f32_e32 v157, v154, v154
	v_pk_add_f32 v[124:125], v[124:125], v[166:167]
	v_fmac_f32_e32 v121, v123, v123
	v_fmac_f32_e32 v157, v155, v155
	v_fmac_f32_e32 v121, v124, v124
	v_fmac_f32_e32 v157, v160, v160
	v_fmac_f32_e32 v121, v125, v125
	v_fmac_f32_e32 v157, v161, v161
	v_fmac_f32_e32 v121, v126, v126
	v_fmac_f32_e32 v157, v158, v158
	v_cvt_pk_bf16_f32 v113, v122, v123
	v_cvt_pk_bf16_f32 v114, v124, v125
	v_cvt_pk_bf16_f32 v115, v126, v127
	v_fmac_f32_e32 v121, v127, v127
	v_fmac_f32_e32 v157, v159, v159
	global_store_dwordx4 v[162:163], v[112:115], off
	v_cvt_pk_bf16_f32 v117, v154, v155
	v_cvt_pk_bf16_f32 v118, v160, v161
	v_add_f32_e32 v112, v121, v157
	v_mov_b32_e32 v113, v112
	s_nop 1
	v_permlane16_swap_b32_e32 v112, v113
	v_add_f32_e32 v112, v112, v113
	v_mov_b32_e32 v113, v112
	v_cvt_pk_bf16_f32 v119, v158, v159
	s_nop 0
	v_permlane32_swap_b32_e32 v112, v113
	global_store_dwordx4 v[162:163], v[116:119], off offset:256
	s_and_saveexec_b64 s[20:21], s[6:7]
	s_cbranch_execz .LBB0_1210
	v_add_f32_e32 v112, v112, v113
	v_mul_f32_e32 v112, 0x49800000, v112
	v_trunc_f32_e32 v112, v112
	v_mul_f32_e32 v113, 0x2f800000, v112
	v_floor_f32_e32 v113, v113
	v_fmac_f32_e32 v112, 0xcf800000, v113
	v_cvt_u32_f32_e32 v112, v112
	v_cvt_u32_f32_e32 v113, v113
	v_lshl_add_u64 v[114:115], v[146:147], 3, s[4:5]
	global_atomic_add_x2 v[114:115], v[112:113], off
; DI unsigned pk2(float lo, float hi) { f32x2 v = {lo, hi}; bf16x2_t b = __builtin_convertvector(v, bf16x2_t); return __builtin_bit_cast(unsigned, b); }
; DI float bflo(unsigned u) { return __uint_as_float(u << 16); }
; DI float bfhi(unsigned u) { return __uint_as_float(u & 0xffff0000u); }
; DI u64 ss_to_fix(float ss) { return (u64)(ss * 1048576.f); }
;     DI void operator()(const AccT& acc, const Unit& u, int wr, int wc, int fr, int fq) const {
;         const int row0 = u.pm * 256 + wr * 64 + fr, col0 = u.pn * 256 + wc * 32 + 8 * fq;
; #pragma unroll
;         for (int ai = 0; ai < 2; ++ai)
; #pragma unroll
;             for (int m = 0; m < 4; ++m) { const int t = row0 + ai * 128 + m * 16; float ss = 0.f;
; #pragma unroll
;                 for (int bj = 0; bj < 2; ++bj) { const size_t o = (size_t)t * 1024 + col0 + bj * 128;
;                     f32x4 r0, r1;
;                     if (RESBF) { const u32x4 rb = *(const u32x4*)(XB + o); r0 = (f32x4){bflo(rb.x), bfhi(rb.x), bflo(rb.y), bfhi(rb.y)}; r1 = (f32x4){bflo(rb.z), bfhi(rb.z), bflo(rb.w), bfhi(rb.w)}; }
;                     else { r0 = __builtin_nontemporal_load((const f32x4*)(res + o)); r1 = __builtin_nontemporal_load((const f32x4*)(res + o + 4)); }
;                     const f32x4 v0 = acc[ai][bj][m][0] + r0, v1 = acc[ai][bj][m][1] + r1;
;                     u32x4 w; w.x = pk2(v0[0], v0[1]); w.y = pk2(v0[2], v0[3]); w.z = pk2(v1[0], v1[1]); w.w = pk2(v1[2], v1[3]);
;                     if (!dry) *(u32x4*)(XB + o) = w;
;                     ss += v0[0] * v0[0] + v0[1] * v0[1] + v0[2] * v0[2] + v0[3] * v0[3] + v1[0] * v1[0] + v1[1] * v1[1] + v1[2] * v1[2] + v1[3] * v1[3]; }
;                 { const auto r16 = __builtin_amdgcn_permlane16_swap(__float_as_uint(ss), __float_as_uint(ss), false, false); ss = __uint_as_float(r16[0]) + __uint_as_float(r16[1]);
;                   const auto r32 = __builtin_amdgcn_permlane32_swap(__float_as_uint(ss), __float_as_uint(ss), false, false); ss = __uint_as_float(r32[0]) + __uint_as_float(r32[1]); }
;                 if (fq == 0 && !dry) atomicAdd(rowss + t, ss_to_fix(ss)); }
.LBB0_1210:
	s_or_b64 exec, exec, s[20:21]
	v_or_b32_e32 v112, 16, v146
	v_ashrrev_i32_e32 v113, 31, v112
	s_waitcnt vmcnt(14)
	v_lshlrev_b32_e32 v124, 16, v174
	v_and_b32_e32 v125, 0xffff0000, v174
	v_lshlrev_b32_e32 v126, 16, v176
	v_and_b32_e32 v127, 0xffff0000, v176
	v_lshlrev_b32_e32 v176, 16, v177
	v_and_b32_e32 v177, 0xffff0000, v177
	v_lshlrev_b32_e32 v154, 16, v178
	v_and_b32_e32 v155, 0xffff0000, v178
	v_lshlrev_b32_e32 v174, 16, v175
	v_and_b32_e32 v175, 0xffff0000, v175
	v_lshlrev_b32_e32 v178, 16, v179
	v_and_b32_e32 v179, 0xffff0000, v179
	v_lshlrev_b32_e32 v156, 16, v180
	v_and_b32_e32 v157, 0xffff0000, v180
	v_lshlrev_b32_e32 v180, 16, v181
	v_and_b32_e32 v181, 0xffff0000, v181
	v_pk_add_f32 v[108:109], v[108:109], v[124:125]
	v_pk_add_f32 v[106:107], v[106:107], v[176:177]
	v_pk_add_f32 v[176:177], v[100:101], v[154:155]
	v_pk_add_f32 v[110:111], v[110:111], v[174:175]
	v_pk_add_f32 v[174:175], v[102:103], v[178:179]
	v_pk_add_f32 v[178:179], v[98:99], v[180:181]
	v_pk_add_f32 v[180:181], v[96:97], v[156:157]
	v_cvt_pk_bf16_f32 v96, v108, v109
	v_mul_f32_e32 v109, v109, v109
	v_cvt_pk_bf16_f32 v100, v176, v177
	v_mul_f32_e32 v177, v177, v177
	v_fmac_f32_e32 v109, v108, v108
	v_fmac_f32_e32 v177, v176, v176
	v_fmac_f32_e32 v109, v110, v110
	v_fmac_f32_e32 v177, v174, v174
	v_pk_add_f32 v[104:105], v[104:105], v[126:127]
	v_fmac_f32_e32 v109, v111, v111
	v_fmac_f32_e32 v177, v175, v175
	v_fmac_f32_e32 v109, v104, v104
	v_fmac_f32_e32 v177, v180, v180
	v_fmac_f32_e32 v109, v105, v105
	v_fmac_f32_e32 v177, v181, v181
	v_fmac_f32_e32 v109, v106, v106
	v_fmac_f32_e32 v177, v178, v178
	v_cvt_pk_bf16_f32 v97, v110, v111
	v_cvt_pk_bf16_f32 v98, v104, v105
	v_cvt_pk_bf16_f32 v99, v106, v107
	v_fmac_f32_e32 v109, v107, v107
	v_fmac_f32_e32 v177, v179, v179
	global_store_dwordx4 v[182:183], v[96:99], off
	v_cvt_pk_bf16_f32 v101, v174, v175
	v_cvt_pk_bf16_f32 v102, v180, v181
	v_add_f32_e32 v96, v109, v177
	v_mov_b32_e32 v97, v96
	s_nop 1
	v_permlane16_swap_b32_e32 v96, v97
	v_add_f32_e32 v96, v96, v97
	v_mov_b32_e32 v97, v96
	v_cvt_pk_bf16_f32 v103, v178, v179
	s_nop 0
	v_permlane32_swap_b32_e32 v96, v97
	global_store_dwordx4 v[182:183], v[100:103], off offset:256
	s_and_saveexec_b64 s[20:21], s[6:7]
	s_cbranch_execz .LBB0_1212
	v_add_f32_e32 v96, v96, v97
	v_mul_f32_e32 v96, 0x49800000, v96
	v_trunc_f32_e32 v96, v96
	v_mul_f32_e32 v97, 0x2f800000, v96
	v_floor_f32_e32 v97, v97
	v_fmac_f32_e32 v96, 0xcf800000, v97
	v_cvt_u32_f32_e32 v96, v96
	v_cvt_u32_f32_e32 v97, v97
	v_lshl_add_u64 v[98:99], v[112:113], 3, s[4:5]
	global_atomic_add_x2 v[98:99], v[96:97], off
.LBB0_1212:
	s_or_b64 exec, exec, s[20:21]
	v_or_b32_e32 v96, 32, v146
	v_ashrrev_i32_e32 v97, 31, v96
	s_waitcnt vmcnt(14)
	v_lshlrev_b32_e32 v108, 16, v184
	v_and_b32_e32 v109, 0xffff0000, v184
	v_lshlrev_b32_e32 v110, 16, v186
	v_and_b32_e32 v111, 0xffff0000, v186
	v_lshlrev_b32_e32 v186, 16, v187
	v_and_b32_e32 v187, 0xffff0000, v187
	v_lshlrev_b32_e32 v112, 16, v188
	v_and_b32_e32 v113, 0xffff0000, v188
	v_lshlrev_b32_e32 v184, 16, v185
	v_and_b32_e32 v185, 0xffff0000, v185
	v_lshlrev_b32_e32 v188, 16, v189
	v_and_b32_e32 v189, 0xffff0000, v189
	v_lshlrev_b32_e32 v114, 16, v190
	v_and_b32_e32 v115, 0xffff0000, v190
	v_lshlrev_b32_e32 v190, 16, v191
	v_and_b32_e32 v191, 0xffff0000, v191
	v_pk_add_f32 v[92:93], v[92:93], v[108:109]
	v_pk_add_f32 v[90:91], v[90:91], v[186:187]
	v_pk_add_f32 v[186:187], v[84:85], v[112:113]
	v_pk_add_f32 v[94:95], v[94:95], v[184:185]
	v_pk_add_f32 v[184:185], v[86:87], v[188:189]
	v_pk_add_f32 v[188:189], v[82:83], v[190:191]
	v_pk_add_f32 v[190:191], v[80:81], v[114:115]
	v_cvt_pk_bf16_f32 v80, v92, v93
	v_mul_f32_e32 v93, v93, v93
	v_cvt_pk_bf16_f32 v84, v186, v187
	v_mul_f32_e32 v187, v187, v187
	v_fmac_f32_e32 v93, v92, v92
	v_fmac_f32_e32 v187, v186, v186
	v_fmac_f32_e32 v93, v94, v94
	v_fmac_f32_e32 v187, v184, v184
	v_pk_add_f32 v[88:89], v[88:89], v[110:111]
	v_fmac_f32_e32 v93, v95, v95
	v_fmac_f32_e32 v187, v185, v185
	v_fmac_f32_e32 v93, v88, v88
	v_fmac_f32_e32 v187, v190, v190
	v_fmac_f32_e32 v93, v89, v89
	v_fmac_f32_e32 v187, v191, v191
	v_fmac_f32_e32 v93, v90, v90
	v_fmac_f32_e32 v187, v188, v188
	v_cvt_pk_bf16_f32 v81, v94, v95
	v_cvt_pk_bf16_f32 v82, v88, v89
	v_cvt_pk_bf16_f32 v83, v90, v91
	v_fmac_f32_e32 v93, v91, v91
	v_fmac_f32_e32 v187, v189, v189
	global_store_dwordx4 v[200:201], v[80:83], off
	v_cvt_pk_bf16_f32 v85, v184, v185
	v_cvt_pk_bf16_f32 v86, v190, v191
	v_add_f32_e32 v80, v93, v187
	v_mov_b32_e32 v81, v80
	s_nop 1
	v_permlane16_swap_b32_e32 v80, v81
	v_add_f32_e32 v80, v80, v81
	v_mov_b32_e32 v81, v80
	v_cvt_pk_bf16_f32 v87, v188, v189
	s_nop 0
	v_permlane32_swap_b32_e32 v80, v81
	global_store_dwordx4 v[200:201], v[84:87], off offset:256
	s_and_saveexec_b64 s[20:21], s[6:7]
	s_cbranch_execz .LBB0_1214
	v_add_f32_e32 v80, v80, v81
	v_mul_f32_e32 v80, 0x49800000, v80
	v_trunc_f32_e32 v80, v80
	v_mul_f32_e32 v81, 0x2f800000, v80
	v_floor_f32_e32 v81, v81
	v_fmac_f32_e32 v80, 0xcf800000, v81
	v_cvt_u32_f32_e32 v80, v80
	v_cvt_u32_f32_e32 v81, v81
	v_lshl_add_u64 v[82:83], v[96:97], 3, s[4:5]
	global_atomic_add_x2 v[82:83], v[80:81], off
; DI unsigned pk2(float lo, float hi) { f32x2 v = {lo, hi}; bf16x2_t b = __builtin_convertvector(v, bf16x2_t); return __builtin_bit_cast(unsigned, b); }
; DI float bflo(unsigned u) { return __uint_as_float(u << 16); }
; DI float bfhi(unsigned u) { return __uint_as_float(u & 0xffff0000u); }
; DI u64 ss_to_fix(float ss) { return (u64)(ss * 1048576.f); }
;     DI void operator()(const AccT& acc, const Unit& u, int wr, int wc, int fr, int fq) const {
;         const int row0 = u.pm * 256 + wr * 64 + fr, col0 = u.pn * 256 + wc * 32 + 8 * fq;
; #pragma unroll
;         for (int ai = 0; ai < 2; ++ai)
; #pragma unroll
;             for (int m = 0; m < 4; ++m) { const int t = row0 + ai * 128 + m * 16; float ss = 0.f;
; #pragma unroll
;                 for (int bj = 0; bj < 2; ++bj) { const size_t o = (size_t)t * 1024 + col0 + bj * 128;
;                     f32x4 r0, r1;
;                     if (RESBF) { const u32x4 rb = *(const u32x4*)(XB + o); r0 = (f32x4){bflo(rb.x), bfhi(rb.x), bflo(rb.y), bfhi(rb.y)}; r1 = (f32x4){bflo(rb.z), bfhi(rb.z), bflo(rb.w), bfhi(rb.w)}; }
;                     else { r0 = __builtin_nontemporal_load((const f32x4*)(res + o)); r1 = __builtin_nontemporal_load((const f32x4*)(res + o + 4)); }
;                     const f32x4 v0 = acc[ai][bj][m][0] + r0, v1 = acc[ai][bj][m][1] + r1;
;                     u32x4 w; w.x = pk2(v0[0], v0[1]); w.y = pk2(v0[2], v0[3]); w.z = pk2(v1[0], v1[1]); w.w = pk2(v1[2], v1[3]);
;                     if (!dry) *(u32x4*)(XB + o) = w;
;                     ss += v0[0] * v0[0] + v0[1] * v0[1] + v0[2] * v0[2] + v0[3] * v0[3] + v1[0] * v1[0] + v1[1] * v1[1] + v1[2] * v1[2] + v1[3] * v1[3]; }
;                 { const auto r16 = __builtin_amdgcn_permlane16_swap(__float_as_uint(ss), __float_as_uint(ss), false, false); ss = __uint_as_float(r16[0]) + __uint_as_float(r16[1]);
;                   const auto r32 = __builtin_amdgcn_permlane32_swap(__float_as_uint(ss), __float_as_uint(ss), false, false); ss = __uint_as_float(r32[0]) + __uint_as_float(r32[1]); }
;                 if (fq == 0 && !dry) atomicAdd(rowss + t, ss_to_fix(ss)); }
.LBB0_1214:
	s_or_b64 exec, exec, s[20:21]
	v_or_b32_e32 v80, 48, v146
	v_ashrrev_i32_e32 v81, 31, v80
	s_waitcnt vmcnt(14)
	v_lshlrev_b32_e32 v92, 16, v202
	v_and_b32_e32 v93, 0xffff0000, v202
	v_lshlrev_b32_e32 v94, 16, v204
	v_and_b32_e32 v95, 0xffff0000, v204
	v_lshlrev_b32_e32 v204, 16, v205
	v_and_b32_e32 v205, 0xffff0000, v205
	v_lshlrev_b32_e32 v96, 16, v206
	v_and_b32_e32 v97, 0xffff0000, v206
	v_lshlrev_b32_e32 v202, 16, v203
	v_and_b32_e32 v203, 0xffff0000, v203
	v_lshlrev_b32_e32 v206, 16, v207
	v_and_b32_e32 v207, 0xffff0000, v207
	v_lshlrev_b32_e32 v98, 16, v208
	v_and_b32_e32 v99, 0xffff0000, v208
	v_lshlrev_b32_e32 v208, 16, v209
	v_and_b32_e32 v209, 0xffff0000, v209
	v_pk_add_f32 v[76:77], v[76:77], v[92:93]
	v_pk_add_f32 v[74:75], v[74:75], v[204:205]
	v_pk_add_f32 v[204:205], v[68:69], v[96:97]
	v_pk_add_f32 v[78:79], v[78:79], v[202:203]
	v_pk_add_f32 v[202:203], v[70:71], v[206:207]
	v_pk_add_f32 v[206:207], v[66:67], v[208:209]
	v_pk_add_f32 v[208:209], v[64:65], v[98:99]
	v_cvt_pk_bf16_f32 v64, v76, v77
	v_mul_f32_e32 v77, v77, v77
	v_cvt_pk_bf16_f32 v68, v204, v205
	v_mul_f32_e32 v205, v205, v205
	v_fmac_f32_e32 v77, v76, v76
	v_fmac_f32_e32 v205, v204, v204
	v_fmac_f32_e32 v77, v78, v78
	v_fmac_f32_e32 v205, v202, v202
	v_pk_add_f32 v[72:73], v[72:73], v[94:95]
	v_fmac_f32_e32 v77, v79, v79
	v_fmac_f32_e32 v205, v203, v203
	v_fmac_f32_e32 v77, v72, v72
	v_fmac_f32_e32 v205, v208, v208
	v_fmac_f32_e32 v77, v73, v73
	v_fmac_f32_e32 v205, v209, v209
	v_fmac_f32_e32 v77, v74, v74
	v_fmac_f32_e32 v205, v206, v206
	v_cvt_pk_bf16_f32 v65, v78, v79
	v_cvt_pk_bf16_f32 v66, v72, v73
	v_cvt_pk_bf16_f32 v67, v74, v75
	v_fmac_f32_e32 v77, v75, v75
	v_fmac_f32_e32 v205, v207, v207
	global_store_dwordx4 v[210:211], v[64:67], off
	v_cvt_pk_bf16_f32 v69, v202, v203
	v_cvt_pk_bf16_f32 v70, v208, v209
	v_add_f32_e32 v64, v77, v205
	v_mov_b32_e32 v65, v64
	s_nop 1
	v_permlane16_swap_b32_e32 v64, v65
	v_add_f32_e32 v64, v64, v65
	v_mov_b32_e32 v65, v64
	v_cvt_pk_bf16_f32 v71, v206, v207
	s_nop 0
	v_permlane32_swap_b32_e32 v64, v65
	global_store_dwordx4 v[210:211], v[68:71], off offset:256
	s_and_saveexec_b64 s[20:21], s[6:7]
	s_cbranch_execz .LBB0_1216
	v_add_f32_e32 v64, v64, v65
	v_mul_f32_e32 v64, 0x49800000, v64
	v_trunc_f32_e32 v64, v64
	v_mul_f32_e32 v65, 0x2f800000, v64
	v_floor_f32_e32 v65, v65
	v_fmac_f32_e32 v64, 0xcf800000, v65
	v_cvt_u32_f32_e32 v64, v64
	v_cvt_u32_f32_e32 v65, v65
	v_lshl_add_u64 v[66:67], v[80:81], 3, s[4:5]
	global_atomic_add_x2 v[66:67], v[64:65], off
.LBB0_1216:
	s_or_b64 exec, exec, s[20:21]
	v_add_u32_e32 v64, 0x80, v146
	v_ashrrev_i32_e32 v65, 31, v64
	s_waitcnt vmcnt(14)
	v_lshlrev_b32_e32 v76, 16, v212
	v_and_b32_e32 v77, 0xffff0000, v212
	v_lshlrev_b32_e32 v78, 16, v214
	v_and_b32_e32 v79, 0xffff0000, v214
	v_lshlrev_b32_e32 v214, 16, v215
	v_and_b32_e32 v215, 0xffff0000, v215
	v_lshlrev_b32_e32 v80, 16, v216
	v_and_b32_e32 v81, 0xffff0000, v216
	v_lshlrev_b32_e32 v212, 16, v213
	v_and_b32_e32 v213, 0xffff0000, v213
	v_lshlrev_b32_e32 v216, 16, v217
	v_and_b32_e32 v217, 0xffff0000, v217
	v_lshlrev_b32_e32 v82, 16, v218
	v_and_b32_e32 v83, 0xffff0000, v218
	v_lshlrev_b32_e32 v218, 16, v219
	v_and_b32_e32 v219, 0xffff0000, v219
	v_pk_add_f32 v[60:61], v[60:61], v[76:77]
	v_pk_add_f32 v[58:59], v[58:59], v[214:215]
	v_pk_add_f32 v[214:215], v[52:53], v[80:81]
	v_pk_add_f32 v[62:63], v[62:63], v[212:213]
	v_pk_add_f32 v[212:213], v[54:55], v[216:217]
	v_pk_add_f32 v[216:217], v[50:51], v[218:219]
	v_pk_add_f32 v[218:219], v[48:49], v[82:83]
	v_cvt_pk_bf16_f32 v48, v60, v61
	v_mul_f32_e32 v61, v61, v61
	v_cvt_pk_bf16_f32 v52, v214, v215
	v_mul_f32_e32 v215, v215, v215
	v_fmac_f32_e32 v61, v60, v60
	v_fmac_f32_e32 v215, v214, v214
	v_fmac_f32_e32 v61, v62, v62
	v_fmac_f32_e32 v215, v212, v212
	v_pk_add_f32 v[56:57], v[56:57], v[78:79]
	v_fmac_f32_e32 v61, v63, v63
	v_fmac_f32_e32 v215, v213, v213
	v_fmac_f32_e32 v61, v56, v56
	v_fmac_f32_e32 v215, v218, v218
	v_fmac_f32_e32 v61, v57, v57
	v_fmac_f32_e32 v215, v219, v219
	v_fmac_f32_e32 v61, v58, v58
	v_fmac_f32_e32 v215, v216, v216
	v_cvt_pk_bf16_f32 v49, v62, v63
	v_cvt_pk_bf16_f32 v50, v56, v57
	v_cvt_pk_bf16_f32 v51, v58, v59
	v_fmac_f32_e32 v61, v59, v59
	v_fmac_f32_e32 v215, v217, v217
	global_store_dwordx4 v[220:221], v[48:51], off
	v_cvt_pk_bf16_f32 v53, v212, v213
	v_cvt_pk_bf16_f32 v54, v218, v219
	v_add_f32_e32 v48, v61, v215
	v_mov_b32_e32 v49, v48
	s_nop 1
	v_permlane16_swap_b32_e32 v48, v49
	v_add_f32_e32 v48, v48, v49
	v_mov_b32_e32 v49, v48
	v_cvt_pk_bf16_f32 v55, v216, v217
	s_nop 0
	v_permlane32_swap_b32_e32 v48, v49
	global_store_dwordx4 v[220:221], v[52:55], off offset:256
	s_and_saveexec_b64 s[20:21], s[6:7]
	s_cbranch_execz .LBB0_1218
	v_add_f32_e32 v48, v48, v49
	v_mul_f32_e32 v48, 0x49800000, v48
	v_trunc_f32_e32 v48, v48
	v_mul_f32_e32 v49, 0x2f800000, v48
	v_floor_f32_e32 v49, v49
	v_fmac_f32_e32 v48, 0xcf800000, v49
	v_cvt_u32_f32_e32 v48, v48
	v_cvt_u32_f32_e32 v49, v49
	v_lshl_add_u64 v[50:51], v[64:65], 3, s[4:5]
	global_atomic_add_x2 v[50:51], v[48:49], off
; DI unsigned pk2(float lo, float hi) { f32x2 v = {lo, hi}; bf16x2_t b = __builtin_convertvector(v, bf16x2_t); return __builtin_bit_cast(unsigned, b); }
; DI float bflo(unsigned u) { return __uint_as_float(u << 16); }
; DI float bfhi(unsigned u) { return __uint_as_float(u & 0xffff0000u); }
; DI u64 ss_to_fix(float ss) { return (u64)(ss * 1048576.f); }
;     DI void operator()(const AccT& acc, const Unit& u, int wr, int wc, int fr, int fq) const {
;         const int row0 = u.pm * 256 + wr * 64 + fr, col0 = u.pn * 256 + wc * 32 + 8 * fq;
; #pragma unroll
;         for (int ai = 0; ai < 2; ++ai)
; #pragma unroll
;             for (int m = 0; m < 4; ++m) { const int t = row0 + ai * 128 + m * 16; float ss = 0.f;
; #pragma unroll
;                 for (int bj = 0; bj < 2; ++bj) { const size_t o = (size_t)t * 1024 + col0 + bj * 128;
;                     f32x4 r0, r1;
;                     if (RESBF) { const u32x4 rb = *(const u32x4*)(XB + o); r0 = (f32x4){bflo(rb.x), bfhi(rb.x), bflo(rb.y), bfhi(rb.y)}; r1 = (f32x4){bflo(rb.z), bfhi(rb.z), bflo(rb.w), bfhi(rb.w)}; }
;                     else { r0 = __builtin_nontemporal_load((const f32x4*)(res + o)); r1 = __builtin_nontemporal_load((const f32x4*)(res + o + 4)); }
;                     const f32x4 v0 = acc[ai][bj][m][0] + r0, v1 = acc[ai][bj][m][1] + r1;
;                     u32x4 w; w.x = pk2(v0[0], v0[1]); w.y = pk2(v0[2], v0[3]); w.z = pk2(v1[0], v1[1]); w.w = pk2(v1[2], v1[3]);
;                     if (!dry) *(u32x4*)(XB + o) = w;
;                     ss += v0[0] * v0[0] + v0[1] * v0[1] + v0[2] * v0[2] + v0[3] * v0[3] + v1[0] * v1[0] + v1[1] * v1[1] + v1[2] * v1[2] + v1[3] * v1[3]; }
;                 { const auto r16 = __builtin_amdgcn_permlane16_swap(__float_as_uint(ss), __float_as_uint(ss), false, false); ss = __uint_as_float(r16[0]) + __uint_as_float(r16[1]);
;                   const auto r32 = __builtin_amdgcn_permlane32_swap(__float_as_uint(ss), __float_as_uint(ss), false, false); ss = __uint_as_float(r32[0]) + __uint_as_float(r32[1]); }
;                 if (fq == 0 && !dry) atomicAdd(rowss + t, ss_to_fix(ss)); }
.LBB0_1218:
	s_or_b64 exec, exec, s[20:21]
	v_add_u32_e32 v48, 0x90, v146
	v_ashrrev_i32_e32 v49, 31, v48
	s_waitcnt vmcnt(14)
	v_lshlrev_b32_e32 v60, 16, v222
	v_and_b32_e32 v61, 0xffff0000, v222
	v_lshlrev_b32_e32 v62, 16, v224
	v_and_b32_e32 v63, 0xffff0000, v224
	v_lshlrev_b32_e32 v224, 16, v225
	v_and_b32_e32 v225, 0xffff0000, v225
	v_lshlrev_b32_e32 v64, 16, v226
	v_and_b32_e32 v65, 0xffff0000, v226
	v_lshlrev_b32_e32 v222, 16, v223
	v_and_b32_e32 v223, 0xffff0000, v223
	v_lshlrev_b32_e32 v226, 16, v227
	v_and_b32_e32 v227, 0xffff0000, v227
	v_lshlrev_b32_e32 v66, 16, v228
	v_and_b32_e32 v67, 0xffff0000, v228
	v_lshlrev_b32_e32 v228, 16, v229
	v_and_b32_e32 v229, 0xffff0000, v229
	v_pk_add_f32 v[44:45], v[44:45], v[60:61]
	v_pk_add_f32 v[42:43], v[42:43], v[224:225]
	v_pk_add_f32 v[224:225], v[36:37], v[64:65]
	v_pk_add_f32 v[46:47], v[46:47], v[222:223]
	v_pk_add_f32 v[222:223], v[38:39], v[226:227]
	v_pk_add_f32 v[226:227], v[34:35], v[228:229]
	v_pk_add_f32 v[228:229], v[32:33], v[66:67]
	v_cvt_pk_bf16_f32 v32, v44, v45
	v_mul_f32_e32 v45, v45, v45
	v_cvt_pk_bf16_f32 v36, v224, v225
	v_mul_f32_e32 v225, v225, v225
	v_fmac_f32_e32 v45, v44, v44
	v_fmac_f32_e32 v225, v224, v224
	v_fmac_f32_e32 v45, v46, v46
	v_fmac_f32_e32 v225, v222, v222
	v_pk_add_f32 v[40:41], v[40:41], v[62:63]
	v_fmac_f32_e32 v45, v47, v47
	v_fmac_f32_e32 v225, v223, v223
	v_fmac_f32_e32 v45, v40, v40
	v_fmac_f32_e32 v225, v228, v228
	v_fmac_f32_e32 v45, v41, v41
	v_fmac_f32_e32 v225, v229, v229
	v_fmac_f32_e32 v45, v42, v42
	v_fmac_f32_e32 v225, v226, v226
	v_cvt_pk_bf16_f32 v33, v46, v47
	v_cvt_pk_bf16_f32 v34, v40, v41
	v_cvt_pk_bf16_f32 v35, v42, v43
	v_fmac_f32_e32 v45, v43, v43
	v_fmac_f32_e32 v225, v227, v227
	global_store_dwordx4 v[230:231], v[32:35], off
	v_cvt_pk_bf16_f32 v37, v222, v223
	v_cvt_pk_bf16_f32 v38, v228, v229
	v_add_f32_e32 v32, v45, v225
	v_mov_b32_e32 v33, v32
	s_nop 1
	v_permlane16_swap_b32_e32 v32, v33
	v_add_f32_e32 v32, v32, v33
	v_mov_b32_e32 v33, v32
	v_cvt_pk_bf16_f32 v39, v226, v227
	s_nop 0
	v_permlane32_swap_b32_e32 v32, v33
	global_store_dwordx4 v[230:231], v[36:39], off offset:256
	s_and_saveexec_b64 s[20:21], s[6:7]
	s_cbranch_execz .LBB0_1220
	v_add_f32_e32 v32, v32, v33
	v_mul_f32_e32 v32, 0x49800000, v32
	v_trunc_f32_e32 v32, v32
	v_mul_f32_e32 v33, 0x2f800000, v32
	v_floor_f32_e32 v33, v33
	v_fmac_f32_e32 v32, 0xcf800000, v33
	v_cvt_u32_f32_e32 v32, v32
	v_cvt_u32_f32_e32 v33, v33
	v_lshl_add_u64 v[34:35], v[48:49], 3, s[4:5]
	global_atomic_add_x2 v[34:35], v[32:33], off
; DI unsigned pk2(float lo, float hi) { f32x2 v = {lo, hi}; bf16x2_t b = __builtin_convertvector(v, bf16x2_t); return __builtin_bit_cast(unsigned, b); }
; DI float bflo(unsigned u) { return __uint_as_float(u << 16); }
; DI float bfhi(unsigned u) { return __uint_as_float(u & 0xffff0000u); }
; DI u64 ss_to_fix(float ss) { return (u64)(ss * 1048576.f); }
;     DI void operator()(const AccT& acc, const Unit& u, int wr, int wc, int fr, int fq) const {
;     ...
;             for (int m = 0; m < 4; ++m) { const int t = row0 + ai * 128 + m * 16; float ss = 0.f;
; #pragma unroll
;                 for (int bj = 0; bj < 2; ++bj) { const size_t o = (size_t)t * 1024 + col0 + bj * 128;
;                     f32x4 r0, r1;
;                     if (RESBF) { const u32x4 rb = *(const u32x4*)(XB + o); r0 = (f32x4){bflo(rb.x), bfhi(rb.x), bflo(rb.y), bfhi(rb.y)}; r1 = (f32x4){bflo(rb.z), bfhi(rb.z), bflo(rb.w), bfhi(rb.w)}; }
;                     else { r0 = __builtin_nontemporal_load((const f32x4*)(res + o)); r1 = __builtin_nontemporal_load((const f32x4*)(res + o + 4)); }
;                     const f32x4 v0 = acc[ai][bj][m][0] + r0, v1 = acc[ai][bj][m][1] + r1;
;                     u32x4 w; w.x = pk2(v0[0], v0[1]); w.y = pk2(v0[2], v0[3]); w.z = pk2(v1[0], v1[1]); w.w = pk2(v1[2], v1[3]);
;                     if (!dry) *(u32x4*)(XB + o) = w;
;                     ss += v0[0] * v0[0] + v0[1] * v0[1] + v0[2] * v0[2] + v0[3] * v0[3] + v1[0] * v1[0] + v1[1] * v1[1] + v1[2] * v1[2] + v1[3] * v1[3]; }
;                 { const auto r16 = __builtin_amdgcn_permlane16_swap(__float_as_uint(ss), __float_as_uint(ss), false, false); ss = __uint_as_float(r16[0]) + __uint_as_float(r16[1]);
;                   const auto r32 = __builtin_amdgcn_permlane32_swap(__float_as_uint(ss), __float_as_uint(ss), false, false); ss = __uint_as_float(r32[0]) + __uint_as_float(r32[1]); }
;                 if (fq == 0 && !dry) atomicAdd(rowss + t, ss_to_fix(ss)); }
.LBB0_1220:
	s_or_b64 exec, exec, s[20:21]
	v_add_u32_e32 v32, 0xa0, v146
	v_ashrrev_i32_e32 v33, 31, v32
	s_waitcnt vmcnt(14)
	v_lshlrev_b32_e32 v44, 16, v232
	v_and_b32_e32 v45, 0xffff0000, v232
	v_lshlrev_b32_e32 v46, 16, v234
	v_and_b32_e32 v47, 0xffff0000, v234
	v_lshlrev_b32_e32 v234, 16, v235
	v_and_b32_e32 v235, 0xffff0000, v235
	v_lshlrev_b32_e32 v48, 16, v236
	v_and_b32_e32 v49, 0xffff0000, v236
	v_lshlrev_b32_e32 v232, 16, v233
	v_and_b32_e32 v233, 0xffff0000, v233
	v_lshlrev_b32_e32 v236, 16, v237
	v_and_b32_e32 v237, 0xffff0000, v237
	v_lshlrev_b32_e32 v50, 16, v238
	v_and_b32_e32 v51, 0xffff0000, v238
	v_lshlrev_b32_e32 v238, 16, v239
	v_and_b32_e32 v239, 0xffff0000, v239
	v_pk_add_f32 v[28:29], v[28:29], v[44:45]
	v_pk_add_f32 v[26:27], v[26:27], v[234:235]
	v_pk_add_f32 v[234:235], v[20:21], v[48:49]
	v_pk_add_f32 v[30:31], v[30:31], v[232:233]
	v_pk_add_f32 v[232:233], v[22:23], v[236:237]
	v_pk_add_f32 v[236:237], v[18:19], v[238:239]
	v_pk_add_f32 v[238:239], v[16:17], v[50:51]
	v_cvt_pk_bf16_f32 v16, v28, v29
	v_mul_f32_e32 v29, v29, v29
	v_cvt_pk_bf16_f32 v20, v234, v235
	v_mul_f32_e32 v235, v235, v235
	v_fmac_f32_e32 v29, v28, v28
	v_fmac_f32_e32 v235, v234, v234
	v_fmac_f32_e32 v29, v30, v30
	v_fmac_f32_e32 v235, v232, v232
	v_pk_add_f32 v[24:25], v[24:25], v[46:47]
	v_fmac_f32_e32 v29, v31, v31
	v_fmac_f32_e32 v235, v233, v233
	v_fmac_f32_e32 v29, v24, v24
	v_fmac_f32_e32 v235, v238, v238
	v_fmac_f32_e32 v29, v25, v25
	v_fmac_f32_e32 v235, v239, v239
	v_fmac_f32_e32 v29, v26, v26
	v_fmac_f32_e32 v235, v236, v236
	v_cvt_pk_bf16_f32 v17, v30, v31
	v_cvt_pk_bf16_f32 v18, v24, v25
	v_cvt_pk_bf16_f32 v19, v26, v27
	v_fmac_f32_e32 v29, v27, v27
	v_fmac_f32_e32 v235, v237, v237
	global_store_dwordx4 v[242:243], v[16:19], off
	v_cvt_pk_bf16_f32 v21, v232, v233
	v_cvt_pk_bf16_f32 v22, v238, v239
	v_add_f32_e32 v16, v29, v235
	v_mov_b32_e32 v17, v16
	s_nop 1
	v_permlane16_swap_b32_e32 v16, v17
	v_add_f32_e32 v16, v16, v17
	v_mov_b32_e32 v17, v16
	v_cvt_pk_bf16_f32 v23, v236, v237
	s_nop 0
	v_permlane32_swap_b32_e32 v16, v17
	global_store_dwordx4 v[242:243], v[20:23], off offset:256
	s_and_saveexec_b64 s[20:21], s[6:7]
	s_cbranch_execz .LBB0_1222
	v_add_f32_e32 v16, v16, v17
	v_mul_f32_e32 v16, 0x49800000, v16
	v_trunc_f32_e32 v16, v16
	v_mul_f32_e32 v17, 0x2f800000, v16
	v_floor_f32_e32 v17, v17
	v_fmac_f32_e32 v16, 0xcf800000, v17
	v_cvt_u32_f32_e32 v16, v16
	v_cvt_u32_f32_e32 v17, v17
	v_lshl_add_u64 v[18:19], v[32:33], 3, s[4:5]
	global_atomic_add_x2 v[18:19], v[16:17], off
.LBB0_1222:
	s_or_b64 exec, exec, s[20:21]
	v_add_u32_e32 v16, 0xb0, v146
	v_ashrrev_i32_e32 v17, 31, v16
	s_waitcnt vmcnt(14)
	v_lshlrev_b32_e32 v28, 16, v244
	v_and_b32_e32 v29, 0xffff0000, v244
	v_lshlrev_b32_e32 v30, 16, v246
	v_and_b32_e32 v31, 0xffff0000, v246
	v_lshlrev_b32_e32 v246, 16, v247
	v_and_b32_e32 v247, 0xffff0000, v247
	v_lshlrev_b32_e32 v32, 16, v248
	v_and_b32_e32 v33, 0xffff0000, v248
	v_lshlrev_b32_e32 v244, 16, v245
	v_and_b32_e32 v245, 0xffff0000, v245
	v_lshlrev_b32_e32 v248, 16, v249
	v_and_b32_e32 v249, 0xffff0000, v249
	v_lshlrev_b32_e32 v34, 16, v250
	v_and_b32_e32 v35, 0xffff0000, v250
	v_lshlrev_b32_e32 v250, 16, v251
	v_and_b32_e32 v251, 0xffff0000, v251
	v_pk_add_f32 v[12:13], v[12:13], v[28:29]
	v_pk_add_f32 v[10:11], v[10:11], v[246:247]
	v_pk_add_f32 v[246:247], v[4:5], v[32:33]
	v_pk_add_f32 v[14:15], v[14:15], v[244:245]
	v_pk_add_f32 v[244:245], v[6:7], v[248:249]
	v_pk_add_f32 v[248:249], v[2:3], v[250:251]
	v_pk_add_f32 v[250:251], v[0:1], v[34:35]
	v_cvt_pk_bf16_f32 v0, v12, v13
	v_mul_f32_e32 v13, v13, v13
	v_cvt_pk_bf16_f32 v4, v246, v247
	v_mul_f32_e32 v247, v247, v247
	v_fmac_f32_e32 v13, v12, v12
	v_fmac_f32_e32 v247, v246, v246
	v_fmac_f32_e32 v13, v14, v14
	v_fmac_f32_e32 v247, v244, v244
	v_pk_add_f32 v[8:9], v[8:9], v[30:31]
	v_fmac_f32_e32 v13, v15, v15
	v_fmac_f32_e32 v247, v245, v245
	v_fmac_f32_e32 v13, v8, v8
	v_fmac_f32_e32 v247, v250, v250
	v_fmac_f32_e32 v13, v9, v9
	v_fmac_f32_e32 v247, v251, v251
	v_fmac_f32_e32 v13, v10, v10
	v_fmac_f32_e32 v247, v248, v248
	v_cvt_pk_bf16_f32 v1, v14, v15
	v_cvt_pk_bf16_f32 v2, v8, v9
	v_cvt_pk_bf16_f32 v3, v10, v11
	v_fmac_f32_e32 v13, v11, v11
	v_fmac_f32_e32 v247, v249, v249
	global_store_dwordx4 v[252:253], v[0:3], off
	v_cvt_pk_bf16_f32 v5, v244, v245
	v_cvt_pk_bf16_f32 v6, v250, v251
	v_add_f32_e32 v0, v13, v247
	v_mov_b32_e32 v1, v0
	s_nop 1
	v_permlane16_swap_b32_e32 v0, v1
	v_add_f32_e32 v0, v0, v1
	v_mov_b32_e32 v1, v0
	v_cvt_pk_bf16_f32 v7, v248, v249
	s_nop 0
	v_permlane32_swap_b32_e32 v0, v1
	global_store_dwordx4 v[252:253], v[4:7], off offset:256
	s_and_saveexec_b64 s[20:21], s[6:7]
	s_cbranch_execz .LBB0_1224
	v_add_f32_e32 v0, v0, v1
	v_mul_f32_e32 v0, 0x49800000, v0
	v_trunc_f32_e32 v0, v0
	v_mul_f32_e32 v1, 0x2f800000, v0
	v_floor_f32_e32 v1, v1
	v_fmac_f32_e32 v0, 0xcf800000, v1
	v_cvt_u32_f32_e32 v0, v0
	v_cvt_u32_f32_e32 v1, v1
	v_lshl_add_u64 v[2:3], v[16:17], 3, s[4:5]
	global_atomic_add_x2 v[2:3], v[0:1], off

; DI unsigned pk2(float lo, float hi) { f32x2 v = {lo, hi}; bf16x2_t b = __builtin_convertvector(v, bf16x2_t); return __builtin_bit_cast(unsigned, b); }
; DI float bflo(unsigned u) { return __uint_as_float(u << 16); }
; DI float bfhi(unsigned u) { return __uint_as_float(u & 0xffff0000u); }
; DI u64 ss_to_fix(float ss) { return (u64)(ss * 1048576.f); }
;     DI void operator()(const AccT& acc, const Unit& u, int wr, int wc, int fr, int fq) const {
;     ...
;         for (int ai = 0; ai < 2; ++ai)
; #pragma unroll
;             for (int m = 0; m < 4; ++m) { const int t = row0 + ai * 128 + m * 16; float ss = 0.f;
; #pragma unroll
;                 for (int bj = 0; bj < 2; ++bj) { const size_t o = (size_t)t * 1024 + col0 + bj * 128;
;                     f32x4 r0, r1;
;                     if (RESBF) { const u32x4 rb = *(const u32x4*)(XB + o); r0 = (f32x4){bflo(rb.x), bfhi(rb.x), bflo(rb.y), bfhi(rb.y)}; r1 = (f32x4){bflo(rb.z), bfhi(rb.z), bflo(rb.w), bfhi(rb.w)}; }
;                     else { r0 = __builtin_nontemporal_load((const f32x4*)(res + o)); r1 = __builtin_nontemporal_load((const f32x4*)(res + o + 4)); }
;                     const f32x4 v0 = acc[ai][bj][m][0] + r0, v1 = acc[ai][bj][m][1] + r1;
;                     u32x4 w; w.x = pk2(v0[0], v0[1]); w.y = pk2(v0[2], v0[3]); w.z = pk2(v1[0], v1[1]); w.w = pk2(v1[2], v1[3]);
;                     if (!dry) *(u32x4*)(XB + o) = w;
;                     ss += v0[0] * v0[0] + v0[1] * v0[1] + v0[2] * v0[2] + v0[3] * v0[3] + v1[0] * v1[0] + v1[1] * v1[1] + v1[2] * v1[2] + v1[3] * v1[3]; }
;                 { const auto r16 = __builtin_amdgcn_permlane16_swap(__float_as_uint(ss), __float_as_uint(ss), false, false); ss = __uint_as_float(r16[0]) + __uint_as_float(r16[1]);
;                   const auto r32 = __builtin_amdgcn_permlane32_swap(__float_as_uint(ss), __float_as_uint(ss), false, false); ss = __uint_as_float(r32[0]) + __uint_as_float(r32[1]); }
;                 if (fq == 0 && !dry) atomicAdd(rowss + t, ss_to_fix(ss)); }
.LBB0_1732:
	v_lshl_add_u32 v146, s24, 8, v148
	v_ashrrev_i32_e32 v147, 31, v146
	v_lshl_or_b32 v144, s26, 8, v150
	v_lshlrev_b64 v[154:155], 11, v[146:147]
	v_ashrrev_i32_e32 v145, 31, v144
	v_lshl_add_u64 v[154:155], s[2:3], 0, v[154:155]
	v_lshl_add_u64 v[162:163], v[144:145], 1, v[154:155]
	global_load_dwordx4 v[154:157], v[162:163], off
	global_load_dwordx4 v[158:161], v[162:163], off offset:256
	v_or_b32_e32 v172, 16, v146
	v_ashrrev_i32_e32 v173, 31, v172
	v_lshlrev_b64 v[182:183], 11, v[172:173]
	v_lshl_add_u64 v[182:183], s[2:3], 0, v[182:183]
	v_lshl_add_u64 v[182:183], v[144:145], 1, v[182:183]
	global_load_dwordx4 v[174:177], v[182:183], off
	global_load_dwordx4 v[178:181], v[182:183], off offset:256
	v_or_b32_e32 v172, 32, v146
	v_ashrrev_i32_e32 v173, 31, v172
	v_lshlrev_b64 v[200:201], 11, v[172:173]
	v_lshl_add_u64 v[200:201], s[2:3], 0, v[200:201]
	v_lshl_add_u64 v[200:201], v[144:145], 1, v[200:201]
	global_load_dwordx4 v[184:187], v[200:201], off
	global_load_dwordx4 v[188:191], v[200:201], off offset:256
	v_or_b32_e32 v172, 48, v146
	v_ashrrev_i32_e32 v173, 31, v172
	v_lshlrev_b64 v[210:211], 11, v[172:173]
	v_lshl_add_u64 v[210:211], s[2:3], 0, v[210:211]
	v_lshl_add_u64 v[210:211], v[144:145], 1, v[210:211]
	global_load_dwordx4 v[202:205], v[210:211], off
	global_load_dwordx4 v[206:209], v[210:211], off offset:256
	v_add_u32_e32 v172, 0x80, v146
	v_ashrrev_i32_e32 v173, 31, v172
	v_lshlrev_b64 v[220:221], 11, v[172:173]
	v_lshl_add_u64 v[220:221], s[2:3], 0, v[220:221]
	v_lshl_add_u64 v[220:221], v[144:145], 1, v[220:221]
	global_load_dwordx4 v[212:215], v[220:221], off
	global_load_dwordx4 v[216:219], v[220:221], off offset:256
	v_add_u32_e32 v172, 0x90, v146
	v_ashrrev_i32_e32 v173, 31, v172
	v_lshlrev_b64 v[230:231], 11, v[172:173]
	v_lshl_add_u64 v[230:231], s[2:3], 0, v[230:231]
	v_lshl_add_u64 v[230:231], v[144:145], 1, v[230:231]
	global_load_dwordx4 v[222:225], v[230:231], off
	global_load_dwordx4 v[226:229], v[230:231], off offset:256
	v_add_u32_e32 v172, 0xa0, v146
	v_ashrrev_i32_e32 v173, 31, v172
	v_lshlrev_b64 v[242:243], 11, v[172:173]
	v_lshl_add_u64 v[242:243], s[2:3], 0, v[242:243]
	v_lshl_add_u64 v[242:243], v[144:145], 1, v[242:243]
	global_load_dwordx4 v[232:235], v[242:243], off
	global_load_dwordx4 v[236:239], v[242:243], off offset:256
	v_add_u32_e32 v172, 0xb0, v146
	v_ashrrev_i32_e32 v173, 31, v172
	v_lshlrev_b64 v[252:253], 11, v[172:173]
	v_lshl_add_u64 v[252:253], s[2:3], 0, v[252:253]
	v_lshl_add_u64 v[252:253], v[144:145], 1, v[252:253]
	global_load_dwordx4 v[244:247], v[252:253], off
	global_load_dwordx4 v[248:251], v[252:253], off offset:256
	s_waitcnt vmcnt(14)
	v_lshlrev_b32_e32 v164, 16, v154
	v_and_b32_e32 v165, 0xffff0000, v154
	v_lshlrev_b32_e32 v166, 16, v156
	v_and_b32_e32 v167, 0xffff0000, v156
	v_lshlrev_b32_e32 v156, 16, v157
	v_and_b32_e32 v157, 0xffff0000, v157
	v_lshlrev_b32_e32 v168, 16, v158
	v_and_b32_e32 v169, 0xffff0000, v158
	v_lshlrev_b32_e32 v154, 16, v155
	v_and_b32_e32 v155, 0xffff0000, v155
	v_lshlrev_b32_e32 v158, 16, v159
	v_and_b32_e32 v159, 0xffff0000, v159
	v_lshlrev_b32_e32 v170, 16, v160
	v_and_b32_e32 v171, 0xffff0000, v160
	v_lshlrev_b32_e32 v160, 16, v161
	v_and_b32_e32 v161, 0xffff0000, v161
	v_pk_add_f32 v[120:121], v[120:121], v[164:165]
	v_pk_add_f32 v[126:127], v[126:127], v[156:157]
	v_pk_add_f32 v[156:157], v[116:117], v[168:169]
	v_pk_add_f32 v[122:123], v[122:123], v[154:155]
	v_pk_add_f32 v[154:155], v[118:119], v[158:159]
	v_pk_add_f32 v[158:159], v[114:115], v[160:161]
	v_pk_add_f32 v[160:161], v[112:113], v[170:171]
	v_cvt_pk_bf16_f32 v112, v120, v121
	v_mul_f32_e32 v121, v121, v121
	v_cvt_pk_bf16_f32 v116, v156, v157
	v_mul_f32_e32 v157, v157, v157
	v_fmac_f32_e32 v121, v120, v120
	v_fmac_f32_e32 v157, v156, v156
	v_fmac_f32_e32 v121, v122, v122
	v_fmac_f32_e32 v157, v154, v154
	v_pk_add_f32 v[124:125], v[124:125], v[166:167]
	v_fmac_f32_e32 v121, v123, v123
	v_fmac_f32_e32 v157, v155, v155
	v_fmac_f32_e32 v121, v124, v124
	v_fmac_f32_e32 v157, v160, v160
	v_fmac_f32_e32 v121, v125, v125
	v_fmac_f32_e32 v157, v161, v161
	v_fmac_f32_e32 v121, v126, v126
	v_fmac_f32_e32 v157, v158, v158
	v_cvt_pk_bf16_f32 v113, v122, v123
	v_cvt_pk_bf16_f32 v114, v124, v125
	v_cvt_pk_bf16_f32 v115, v126, v127
	v_fmac_f32_e32 v121, v127, v127
	v_fmac_f32_e32 v157, v159, v159
	global_store_dwordx4 v[162:163], v[112:115], off
	v_cvt_pk_bf16_f32 v117, v154, v155
	v_cvt_pk_bf16_f32 v118, v160, v161
	v_add_f32_e32 v112, v121, v157
	v_mov_b32_e32 v113, v112
	s_nop 1
	v_permlane16_swap_b32_e32 v112, v113
	v_add_f32_e32 v112, v112, v113
	v_mov_b32_e32 v113, v112
	v_cvt_pk_bf16_f32 v119, v158, v159
	s_nop 0
	v_permlane32_swap_b32_e32 v112, v113
	global_store_dwordx4 v[162:163], v[116:119], off offset:256
	s_and_saveexec_b64 s[24:25], s[4:5]
	s_cbranch_execz .LBB0_1734
	v_add_f32_e32 v112, v112, v113
	v_mul_f32_e32 v112, 0x49800000, v112
	v_trunc_f32_e32 v112, v112
	v_mul_f32_e32 v113, 0x2f800000, v112
	v_floor_f32_e32 v113, v113
	v_fmac_f32_e32 v112, 0xcf800000, v113
	v_cvt_u32_f32_e32 v112, v112
	v_cvt_u32_f32_e32 v113, v113
	v_lshl_add_u64 v[114:115], v[146:147], 3, s[8:9]
	global_atomic_add_x2 v[114:115], v[112:113], off
; DI unsigned pk2(float lo, float hi) { f32x2 v = {lo, hi}; bf16x2_t b = __builtin_convertvector(v, bf16x2_t); return __builtin_bit_cast(unsigned, b); }
; DI float bflo(unsigned u) { return __uint_as_float(u << 16); }
; DI float bfhi(unsigned u) { return __uint_as_float(u & 0xffff0000u); }
; DI u64 ss_to_fix(float ss) { return (u64)(ss * 1048576.f); }
;     DI void operator()(const AccT& acc, const Unit& u, int wr, int wc, int fr, int fq) const {
;     ...
;             for (int m = 0; m < 4; ++m) { const int t = row0 + ai * 128 + m * 16; float ss = 0.f;
; #pragma unroll
;                 for (int bj = 0; bj < 2; ++bj) { const size_t o = (size_t)t * 1024 + col0 + bj * 128;
;                     f32x4 r0, r1;
;                     if (RESBF) { const u32x4 rb = *(const u32x4*)(XB + o); r0 = (f32x4){bflo(rb.x), bfhi(rb.x), bflo(rb.y), bfhi(rb.y)}; r1 = (f32x4){bflo(rb.z), bfhi(rb.z), bflo(rb.w), bfhi(rb.w)}; }
;                     else { r0 = __builtin_nontemporal_load((const f32x4*)(res + o)); r1 = __builtin_nontemporal_load((const f32x4*)(res + o + 4)); }
;                     const f32x4 v0 = acc[ai][bj][m][0] + r0, v1 = acc[ai][bj][m][1] + r1;
;                     u32x4 w; w.x = pk2(v0[0], v0[1]); w.y = pk2(v0[2], v0[3]); w.z = pk2(v1[0], v1[1]); w.w = pk2(v1[2], v1[3]);
;                     if (!dry) *(u32x4*)(XB + o) = w;
;                     ss += v0[0] * v0[0] + v0[1] * v0[1] + v0[2] * v0[2] + v0[3] * v0[3] + v1[0] * v1[0] + v1[1] * v1[1] + v1[2] * v1[2] + v1[3] * v1[3]; }
;                 { const auto r16 = __builtin_amdgcn_permlane16_swap(__float_as_uint(ss), __float_as_uint(ss), false, false); ss = __uint_as_float(r16[0]) + __uint_as_float(r16[1]);
;                   const auto r32 = __builtin_amdgcn_permlane32_swap(__float_as_uint(ss), __float_as_uint(ss), false, false); ss = __uint_as_float(r32[0]) + __uint_as_float(r32[1]); }
;                 if (fq == 0 && !dry) atomicAdd(rowss + t, ss_to_fix(ss)); }
.LBB0_1734:
	s_or_b64 exec, exec, s[24:25]
	v_or_b32_e32 v112, 16, v146
	v_ashrrev_i32_e32 v113, 31, v112
	s_waitcnt vmcnt(14)
	v_lshlrev_b32_e32 v124, 16, v174
	v_and_b32_e32 v125, 0xffff0000, v174
	v_lshlrev_b32_e32 v126, 16, v176
	v_and_b32_e32 v127, 0xffff0000, v176
	v_lshlrev_b32_e32 v176, 16, v177
	v_and_b32_e32 v177, 0xffff0000, v177
	v_lshlrev_b32_e32 v154, 16, v178
	v_and_b32_e32 v155, 0xffff0000, v178
	v_lshlrev_b32_e32 v174, 16, v175
	v_and_b32_e32 v175, 0xffff0000, v175
	v_lshlrev_b32_e32 v178, 16, v179
	v_and_b32_e32 v179, 0xffff0000, v179
	v_lshlrev_b32_e32 v156, 16, v180
	v_and_b32_e32 v157, 0xffff0000, v180
	v_lshlrev_b32_e32 v180, 16, v181
	v_and_b32_e32 v181, 0xffff0000, v181
	v_pk_add_f32 v[108:109], v[108:109], v[124:125]
	v_pk_add_f32 v[106:107], v[106:107], v[176:177]
	v_pk_add_f32 v[176:177], v[100:101], v[154:155]
	v_pk_add_f32 v[110:111], v[110:111], v[174:175]
	v_pk_add_f32 v[174:175], v[102:103], v[178:179]
	v_pk_add_f32 v[178:179], v[98:99], v[180:181]
	v_pk_add_f32 v[180:181], v[96:97], v[156:157]
	v_cvt_pk_bf16_f32 v96, v108, v109
	v_mul_f32_e32 v109, v109, v109
	v_cvt_pk_bf16_f32 v100, v176, v177
	v_mul_f32_e32 v177, v177, v177
	v_fmac_f32_e32 v109, v108, v108
	v_fmac_f32_e32 v177, v176, v176
	v_fmac_f32_e32 v109, v110, v110
	v_fmac_f32_e32 v177, v174, v174
	v_pk_add_f32 v[104:105], v[104:105], v[126:127]
	v_fmac_f32_e32 v109, v111, v111
	v_fmac_f32_e32 v177, v175, v175
	v_fmac_f32_e32 v109, v104, v104
	v_fmac_f32_e32 v177, v180, v180
	v_fmac_f32_e32 v109, v105, v105
	v_fmac_f32_e32 v177, v181, v181
	v_fmac_f32_e32 v109, v106, v106
	v_fmac_f32_e32 v177, v178, v178
	v_cvt_pk_bf16_f32 v97, v110, v111
	v_cvt_pk_bf16_f32 v98, v104, v105
	v_cvt_pk_bf16_f32 v99, v106, v107
	v_fmac_f32_e32 v109, v107, v107
	v_fmac_f32_e32 v177, v179, v179
	global_store_dwordx4 v[182:183], v[96:99], off
	v_cvt_pk_bf16_f32 v101, v174, v175
	v_cvt_pk_bf16_f32 v102, v180, v181
	v_add_f32_e32 v96, v109, v177
	v_mov_b32_e32 v97, v96
	s_nop 1
	v_permlane16_swap_b32_e32 v96, v97
	v_add_f32_e32 v96, v96, v97
	v_mov_b32_e32 v97, v96
	v_cvt_pk_bf16_f32 v103, v178, v179
	s_nop 0
	v_permlane32_swap_b32_e32 v96, v97
	global_store_dwordx4 v[182:183], v[100:103], off offset:256
	s_and_saveexec_b64 s[24:25], s[4:5]
	s_cbranch_execz .LBB0_1736
	v_add_f32_e32 v96, v96, v97
	v_mul_f32_e32 v96, 0x49800000, v96
	v_trunc_f32_e32 v96, v96
	v_mul_f32_e32 v97, 0x2f800000, v96
	v_floor_f32_e32 v97, v97
	v_fmac_f32_e32 v96, 0xcf800000, v97
	v_cvt_u32_f32_e32 v96, v96
	v_cvt_u32_f32_e32 v97, v97
	v_lshl_add_u64 v[98:99], v[112:113], 3, s[8:9]
	global_atomic_add_x2 v[98:99], v[96:97], off
.LBB0_1736:
	s_or_b64 exec, exec, s[24:25]
	v_or_b32_e32 v96, 32, v146
	v_ashrrev_i32_e32 v97, 31, v96
	s_waitcnt vmcnt(14)
	v_lshlrev_b32_e32 v108, 16, v184
	v_and_b32_e32 v109, 0xffff0000, v184
	v_lshlrev_b32_e32 v110, 16, v186
	v_and_b32_e32 v111, 0xffff0000, v186
	v_lshlrev_b32_e32 v186, 16, v187
	v_and_b32_e32 v187, 0xffff0000, v187
	v_lshlrev_b32_e32 v112, 16, v188
	v_and_b32_e32 v113, 0xffff0000, v188
	v_lshlrev_b32_e32 v184, 16, v185
	v_and_b32_e32 v185, 0xffff0000, v185
	v_lshlrev_b32_e32 v188, 16, v189
	v_and_b32_e32 v189, 0xffff0000, v189
	v_lshlrev_b32_e32 v114, 16, v190
	v_and_b32_e32 v115, 0xffff0000, v190
	v_lshlrev_b32_e32 v190, 16, v191
	v_and_b32_e32 v191, 0xffff0000, v191
	v_pk_add_f32 v[92:93], v[92:93], v[108:109]
	v_pk_add_f32 v[90:91], v[90:91], v[186:187]
	v_pk_add_f32 v[186:187], v[84:85], v[112:113]
	v_pk_add_f32 v[94:95], v[94:95], v[184:185]
	v_pk_add_f32 v[184:185], v[86:87], v[188:189]
	v_pk_add_f32 v[188:189], v[82:83], v[190:191]
	v_pk_add_f32 v[190:191], v[80:81], v[114:115]
	v_cvt_pk_bf16_f32 v80, v92, v93
	v_mul_f32_e32 v93, v93, v93
	v_cvt_pk_bf16_f32 v84, v186, v187
	v_mul_f32_e32 v187, v187, v187
	v_fmac_f32_e32 v93, v92, v92
	v_fmac_f32_e32 v187, v186, v186
	v_fmac_f32_e32 v93, v94, v94
	v_fmac_f32_e32 v187, v184, v184
	v_pk_add_f32 v[88:89], v[88:89], v[110:111]
	v_fmac_f32_e32 v93, v95, v95
	v_fmac_f32_e32 v187, v185, v185
	v_fmac_f32_e32 v93, v88, v88
	v_fmac_f32_e32 v187, v190, v190
	v_fmac_f32_e32 v93, v89, v89
	v_fmac_f32_e32 v187, v191, v191
	v_fmac_f32_e32 v93, v90, v90
	v_fmac_f32_e32 v187, v188, v188
	v_cvt_pk_bf16_f32 v81, v94, v95
	v_cvt_pk_bf16_f32 v82, v88, v89
	v_cvt_pk_bf16_f32 v83, v90, v91
	v_fmac_f32_e32 v93, v91, v91
	v_fmac_f32_e32 v187, v189, v189
	global_store_dwordx4 v[200:201], v[80:83], off
	v_cvt_pk_bf16_f32 v85, v184, v185
	v_cvt_pk_bf16_f32 v86, v190, v191
	v_add_f32_e32 v80, v93, v187
	v_mov_b32_e32 v81, v80
	s_nop 1
	v_permlane16_swap_b32_e32 v80, v81
	v_add_f32_e32 v80, v80, v81
	v_mov_b32_e32 v81, v80
	v_cvt_pk_bf16_f32 v87, v188, v189
	s_nop 0
	v_permlane32_swap_b32_e32 v80, v81
	global_store_dwordx4 v[200:201], v[84:87], off offset:256
	s_and_saveexec_b64 s[24:25], s[4:5]
	s_cbranch_execz .LBB0_1738
	v_add_f32_e32 v80, v80, v81
	v_mul_f32_e32 v80, 0x49800000, v80
	v_trunc_f32_e32 v80, v80
	v_mul_f32_e32 v81, 0x2f800000, v80
	v_floor_f32_e32 v81, v81
	v_fmac_f32_e32 v80, 0xcf800000, v81
	v_cvt_u32_f32_e32 v80, v80
	v_cvt_u32_f32_e32 v81, v81
	v_lshl_add_u64 v[82:83], v[96:97], 3, s[8:9]
	global_atomic_add_x2 v[82:83], v[80:81], off
; DI unsigned pk2(float lo, float hi) { f32x2 v = {lo, hi}; bf16x2_t b = __builtin_convertvector(v, bf16x2_t); return __builtin_bit_cast(unsigned, b); }
; DI float bflo(unsigned u) { return __uint_as_float(u << 16); }
; DI float bfhi(unsigned u) { return __uint_as_float(u & 0xffff0000u); }
; DI u64 ss_to_fix(float ss) { return (u64)(ss * 1048576.f); }
;     DI void operator()(const AccT& acc, const Unit& u, int wr, int wc, int fr, int fq) const {
;     ...
;             for (int m = 0; m < 4; ++m) { const int t = row0 + ai * 128 + m * 16; float ss = 0.f;
; #pragma unroll
;                 for (int bj = 0; bj < 2; ++bj) { const size_t o = (size_t)t * 1024 + col0 + bj * 128;
;                     f32x4 r0, r1;
;                     if (RESBF) { const u32x4 rb = *(const u32x4*)(XB + o); r0 = (f32x4){bflo(rb.x), bfhi(rb.x), bflo(rb.y), bfhi(rb.y)}; r1 = (f32x4){bflo(rb.z), bfhi(rb.z), bflo(rb.w), bfhi(rb.w)}; }
;                     else { r0 = __builtin_nontemporal_load((const f32x4*)(res + o)); r1 = __builtin_nontemporal_load((const f32x4*)(res + o + 4)); }
;                     const f32x4 v0 = acc[ai][bj][m][0] + r0, v1 = acc[ai][bj][m][1] + r1;
;                     u32x4 w; w.x = pk2(v0[0], v0[1]); w.y = pk2(v0[2], v0[3]); w.z = pk2(v1[0], v1[1]); w.w = pk2(v1[2], v1[3]);
;                     if (!dry) *(u32x4*)(XB + o) = w;
;                     ss += v0[0] * v0[0] + v0[1] * v0[1] + v0[2] * v0[2] + v0[3] * v0[3] + v1[0] * v1[0] + v1[1] * v1[1] + v1[2] * v1[2] + v1[3] * v1[3]; }
;                 { const auto r16 = __builtin_amdgcn_permlane16_swap(__float_as_uint(ss), __float_as_uint(ss), false, false); ss = __uint_as_float(r16[0]) + __uint_as_float(r16[1]);
;                   const auto r32 = __builtin_amdgcn_permlane32_swap(__float_as_uint(ss), __float_as_uint(ss), false, false); ss = __uint_as_float(r32[0]) + __uint_as_float(r32[1]); }
;                 if (fq == 0 && !dry) atomicAdd(rowss + t, ss_to_fix(ss)); }
.LBB0_1738:
	s_or_b64 exec, exec, s[24:25]
	v_or_b32_e32 v80, 48, v146
	v_ashrrev_i32_e32 v81, 31, v80
	s_waitcnt vmcnt(14)
	v_lshlrev_b32_e32 v92, 16, v202
	v_and_b32_e32 v93, 0xffff0000, v202
	v_lshlrev_b32_e32 v94, 16, v204
	v_and_b32_e32 v95, 0xffff0000, v204
	v_lshlrev_b32_e32 v204, 16, v205
	v_and_b32_e32 v205, 0xffff0000, v205
	v_lshlrev_b32_e32 v96, 16, v206
	v_and_b32_e32 v97, 0xffff0000, v206
	v_lshlrev_b32_e32 v202, 16, v203
	v_and_b32_e32 v203, 0xffff0000, v203
	v_lshlrev_b32_e32 v206, 16, v207
	v_and_b32_e32 v207, 0xffff0000, v207
	v_lshlrev_b32_e32 v98, 16, v208
	v_and_b32_e32 v99, 0xffff0000, v208
	v_lshlrev_b32_e32 v208, 16, v209
	v_and_b32_e32 v209, 0xffff0000, v209
	v_pk_add_f32 v[76:77], v[76:77], v[92:93]
	v_pk_add_f32 v[74:75], v[74:75], v[204:205]
	v_pk_add_f32 v[204:205], v[68:69], v[96:97]
	v_pk_add_f32 v[78:79], v[78:79], v[202:203]
	v_pk_add_f32 v[202:203], v[70:71], v[206:207]
	v_pk_add_f32 v[206:207], v[66:67], v[208:209]
	v_pk_add_f32 v[208:209], v[64:65], v[98:99]
	v_cvt_pk_bf16_f32 v64, v76, v77
	v_mul_f32_e32 v77, v77, v77
	v_cvt_pk_bf16_f32 v68, v204, v205
	v_mul_f32_e32 v205, v205, v205
	v_fmac_f32_e32 v77, v76, v76
	v_fmac_f32_e32 v205, v204, v204
	v_fmac_f32_e32 v77, v78, v78
	v_fmac_f32_e32 v205, v202, v202
	v_pk_add_f32 v[72:73], v[72:73], v[94:95]
	v_fmac_f32_e32 v77, v79, v79
	v_fmac_f32_e32 v205, v203, v203
	v_fmac_f32_e32 v77, v72, v72
	v_fmac_f32_e32 v205, v208, v208
	v_fmac_f32_e32 v77, v73, v73
	v_fmac_f32_e32 v205, v209, v209
	v_fmac_f32_e32 v77, v74, v74
	v_fmac_f32_e32 v205, v206, v206
	v_cvt_pk_bf16_f32 v65, v78, v79
	v_cvt_pk_bf16_f32 v66, v72, v73
	v_cvt_pk_bf16_f32 v67, v74, v75
	v_fmac_f32_e32 v77, v75, v75
	v_fmac_f32_e32 v205, v207, v207
	global_store_dwordx4 v[210:211], v[64:67], off
	v_cvt_pk_bf16_f32 v69, v202, v203
	v_cvt_pk_bf16_f32 v70, v208, v209
	v_add_f32_e32 v64, v77, v205
	v_mov_b32_e32 v65, v64
	s_nop 1
	v_permlane16_swap_b32_e32 v64, v65
	v_add_f32_e32 v64, v64, v65
	v_mov_b32_e32 v65, v64
	v_cvt_pk_bf16_f32 v71, v206, v207
	s_nop 0
	v_permlane32_swap_b32_e32 v64, v65
	global_store_dwordx4 v[210:211], v[68:71], off offset:256
	s_and_saveexec_b64 s[24:25], s[4:5]
	s_cbranch_execz .LBB0_1740
	v_add_f32_e32 v64, v64, v65
	v_mul_f32_e32 v64, 0x49800000, v64
	v_trunc_f32_e32 v64, v64
	v_mul_f32_e32 v65, 0x2f800000, v64
	v_floor_f32_e32 v65, v65
	v_fmac_f32_e32 v64, 0xcf800000, v65
	v_cvt_u32_f32_e32 v64, v64
	v_cvt_u32_f32_e32 v65, v65
	v_lshl_add_u64 v[66:67], v[80:81], 3, s[8:9]
	global_atomic_add_x2 v[66:67], v[64:65], off
.LBB0_1740:
	s_or_b64 exec, exec, s[24:25]
	v_add_u32_e32 v64, 0x80, v146
	v_ashrrev_i32_e32 v65, 31, v64
	s_waitcnt vmcnt(14)
	v_lshlrev_b32_e32 v76, 16, v212
	v_and_b32_e32 v77, 0xffff0000, v212
	v_lshlrev_b32_e32 v78, 16, v214
	v_and_b32_e32 v79, 0xffff0000, v214
	v_lshlrev_b32_e32 v214, 16, v215
	v_and_b32_e32 v215, 0xffff0000, v215
	v_lshlrev_b32_e32 v80, 16, v216
	v_and_b32_e32 v81, 0xffff0000, v216
	v_lshlrev_b32_e32 v212, 16, v213
	v_and_b32_e32 v213, 0xffff0000, v213
	v_lshlrev_b32_e32 v216, 16, v217
	v_and_b32_e32 v217, 0xffff0000, v217
	v_lshlrev_b32_e32 v82, 16, v218
	v_and_b32_e32 v83, 0xffff0000, v218
	v_lshlrev_b32_e32 v218, 16, v219
	v_and_b32_e32 v219, 0xffff0000, v219
	v_pk_add_f32 v[60:61], v[60:61], v[76:77]
	v_pk_add_f32 v[58:59], v[58:59], v[214:215]
	v_pk_add_f32 v[214:215], v[52:53], v[80:81]
	v_pk_add_f32 v[62:63], v[62:63], v[212:213]
	v_pk_add_f32 v[212:213], v[54:55], v[216:217]
	v_pk_add_f32 v[216:217], v[50:51], v[218:219]
	v_pk_add_f32 v[218:219], v[48:49], v[82:83]
	v_cvt_pk_bf16_f32 v48, v60, v61
	v_mul_f32_e32 v61, v61, v61
	v_cvt_pk_bf16_f32 v52, v214, v215
	v_mul_f32_e32 v215, v215, v215
	v_fmac_f32_e32 v61, v60, v60
	v_fmac_f32_e32 v215, v214, v214
	v_fmac_f32_e32 v61, v62, v62
	v_fmac_f32_e32 v215, v212, v212
	v_pk_add_f32 v[56:57], v[56:57], v[78:79]
	v_fmac_f32_e32 v61, v63, v63
	v_fmac_f32_e32 v215, v213, v213
	v_fmac_f32_e32 v61, v56, v56
	v_fmac_f32_e32 v215, v218, v218
	v_fmac_f32_e32 v61, v57, v57
	v_fmac_f32_e32 v215, v219, v219
	v_fmac_f32_e32 v61, v58, v58
	v_fmac_f32_e32 v215, v216, v216
	v_cvt_pk_bf16_f32 v49, v62, v63
	v_cvt_pk_bf16_f32 v50, v56, v57
	v_cvt_pk_bf16_f32 v51, v58, v59
	v_fmac_f32_e32 v61, v59, v59
	v_fmac_f32_e32 v215, v217, v217
	global_store_dwordx4 v[220:221], v[48:51], off
	v_cvt_pk_bf16_f32 v53, v212, v213
	v_cvt_pk_bf16_f32 v54, v218, v219
	v_add_f32_e32 v48, v61, v215
	v_mov_b32_e32 v49, v48
	s_nop 1
	v_permlane16_swap_b32_e32 v48, v49
	v_add_f32_e32 v48, v48, v49
	v_mov_b32_e32 v49, v48
	v_cvt_pk_bf16_f32 v55, v216, v217
	s_nop 0
	v_permlane32_swap_b32_e32 v48, v49
	global_store_dwordx4 v[220:221], v[52:55], off offset:256
	s_and_saveexec_b64 s[24:25], s[4:5]
	s_cbranch_execz .LBB0_1742
	v_add_f32_e32 v48, v48, v49
	v_mul_f32_e32 v48, 0x49800000, v48
	v_trunc_f32_e32 v48, v48
	v_mul_f32_e32 v49, 0x2f800000, v48
	v_floor_f32_e32 v49, v49
	v_fmac_f32_e32 v48, 0xcf800000, v49
	v_cvt_u32_f32_e32 v48, v48
	v_cvt_u32_f32_e32 v49, v49
	v_lshl_add_u64 v[50:51], v[64:65], 3, s[8:9]
	global_atomic_add_x2 v[50:51], v[48:49], off
; DI unsigned pk2(float lo, float hi) { f32x2 v = {lo, hi}; bf16x2_t b = __builtin_convertvector(v, bf16x2_t); return __builtin_bit_cast(unsigned, b); }
; DI float bflo(unsigned u) { return __uint_as_float(u << 16); }
; DI float bfhi(unsigned u) { return __uint_as_float(u & 0xffff0000u); }
; DI u64 ss_to_fix(float ss) { return (u64)(ss * 1048576.f); }
;     DI void operator()(const AccT& acc, const Unit& u, int wr, int wc, int fr, int fq) const {
;     ...
;             for (int m = 0; m < 4; ++m) { const int t = row0 + ai * 128 + m * 16; float ss = 0.f;
; #pragma unroll
;                 for (int bj = 0; bj < 2; ++bj) { const size_t o = (size_t)t * 1024 + col0 + bj * 128;
;                     f32x4 r0, r1;
;                     if (RESBF) { const u32x4 rb = *(const u32x4*)(XB + o); r0 = (f32x4){bflo(rb.x), bfhi(rb.x), bflo(rb.y), bfhi(rb.y)}; r1 = (f32x4){bflo(rb.z), bfhi(rb.z), bflo(rb.w), bfhi(rb.w)}; }
;                     else { r0 = __builtin_nontemporal_load((const f32x4*)(res + o)); r1 = __builtin_nontemporal_load((const f32x4*)(res + o + 4)); }
;                     const f32x4 v0 = acc[ai][bj][m][0] + r0, v1 = acc[ai][bj][m][1] + r1;
;                     u32x4 w; w.x = pk2(v0[0], v0[1]); w.y = pk2(v0[2], v0[3]); w.z = pk2(v1[0], v1[1]); w.w = pk2(v1[2], v1[3]);
;                     if (!dry) *(u32x4*)(XB + o) = w;
;                     ss += v0[0] * v0[0] + v0[1] * v0[1] + v0[2] * v0[2] + v0[3] * v0[3] + v1[0] * v1[0] + v1[1] * v1[1] + v1[2] * v1[2] + v1[3] * v1[3]; }
;                 { const auto r16 = __builtin_amdgcn_permlane16_swap(__float_as_uint(ss), __float_as_uint(ss), false, false); ss = __uint_as_float(r16[0]) + __uint_as_float(r16[1]);
;                   const auto r32 = __builtin_amdgcn_permlane32_swap(__float_as_uint(ss), __float_as_uint(ss), false, false); ss = __uint_as_float(r32[0]) + __uint_as_float(r32[1]); }
;                 if (fq == 0 && !dry) atomicAdd(rowss + t, ss_to_fix(ss)); }
.LBB0_1742:
	s_or_b64 exec, exec, s[24:25]
	v_add_u32_e32 v48, 0x90, v146
	v_ashrrev_i32_e32 v49, 31, v48
	s_waitcnt vmcnt(14)
	v_lshlrev_b32_e32 v60, 16, v222
	v_and_b32_e32 v61, 0xffff0000, v222
	v_lshlrev_b32_e32 v62, 16, v224
	v_and_b32_e32 v63, 0xffff0000, v224
	v_lshlrev_b32_e32 v224, 16, v225
	v_and_b32_e32 v225, 0xffff0000, v225
	v_lshlrev_b32_e32 v64, 16, v226
	v_and_b32_e32 v65, 0xffff0000, v226
	v_lshlrev_b32_e32 v222, 16, v223
	v_and_b32_e32 v223, 0xffff0000, v223
	v_lshlrev_b32_e32 v226, 16, v227
	v_and_b32_e32 v227, 0xffff0000, v227
	v_lshlrev_b32_e32 v66, 16, v228
	v_and_b32_e32 v67, 0xffff0000, v228
	v_lshlrev_b32_e32 v228, 16, v229
	v_and_b32_e32 v229, 0xffff0000, v229
	v_pk_add_f32 v[44:45], v[44:45], v[60:61]
	v_pk_add_f32 v[42:43], v[42:43], v[224:225]
	v_pk_add_f32 v[224:225], v[36:37], v[64:65]
	v_pk_add_f32 v[46:47], v[46:47], v[222:223]
	v_pk_add_f32 v[222:223], v[38:39], v[226:227]
	v_pk_add_f32 v[226:227], v[34:35], v[228:229]
	v_pk_add_f32 v[228:229], v[32:33], v[66:67]
	v_cvt_pk_bf16_f32 v32, v44, v45
	v_mul_f32_e32 v45, v45, v45
	v_cvt_pk_bf16_f32 v36, v224, v225
	v_mul_f32_e32 v225, v225, v225
	v_fmac_f32_e32 v45, v44, v44
	v_fmac_f32_e32 v225, v224, v224
	v_fmac_f32_e32 v45, v46, v46
	v_fmac_f32_e32 v225, v222, v222
	v_pk_add_f32 v[40:41], v[40:41], v[62:63]
	v_fmac_f32_e32 v45, v47, v47
	v_fmac_f32_e32 v225, v223, v223
	v_fmac_f32_e32 v45, v40, v40
	v_fmac_f32_e32 v225, v228, v228
	v_fmac_f32_e32 v45, v41, v41
	v_fmac_f32_e32 v225, v229, v229
	v_fmac_f32_e32 v45, v42, v42
	v_fmac_f32_e32 v225, v226, v226
	v_cvt_pk_bf16_f32 v33, v46, v47
	v_cvt_pk_bf16_f32 v34, v40, v41
	v_cvt_pk_bf16_f32 v35, v42, v43
	v_fmac_f32_e32 v45, v43, v43
	v_fmac_f32_e32 v225, v227, v227
	global_store_dwordx4 v[230:231], v[32:35], off
	v_cvt_pk_bf16_f32 v37, v222, v223
	v_cvt_pk_bf16_f32 v38, v228, v229
	v_add_f32_e32 v32, v45, v225
	v_mov_b32_e32 v33, v32
	s_nop 1
	v_permlane16_swap_b32_e32 v32, v33
	v_add_f32_e32 v32, v32, v33
	v_mov_b32_e32 v33, v32
	v_cvt_pk_bf16_f32 v39, v226, v227
	s_nop 0
	v_permlane32_swap_b32_e32 v32, v33
	global_store_dwordx4 v[230:231], v[36:39], off offset:256
	s_and_saveexec_b64 s[24:25], s[4:5]
	s_cbranch_execz .LBB0_1744
	v_add_f32_e32 v32, v32, v33
	v_mul_f32_e32 v32, 0x49800000, v32
	v_trunc_f32_e32 v32, v32
	v_mul_f32_e32 v33, 0x2f800000, v32
	v_floor_f32_e32 v33, v33
	v_fmac_f32_e32 v32, 0xcf800000, v33
	v_cvt_u32_f32_e32 v32, v32
	v_cvt_u32_f32_e32 v33, v33
	v_lshl_add_u64 v[34:35], v[48:49], 3, s[8:9]
	global_atomic_add_x2 v[34:35], v[32:33], off
; DI unsigned pk2(float lo, float hi) { f32x2 v = {lo, hi}; bf16x2_t b = __builtin_convertvector(v, bf16x2_t); return __builtin_bit_cast(unsigned, b); }
; DI float bflo(unsigned u) { return __uint_as_float(u << 16); }
; DI float bfhi(unsigned u) { return __uint_as_float(u & 0xffff0000u); }
; DI u64 ss_to_fix(float ss) { return (u64)(ss * 1048576.f); }
;     DI void operator()(const AccT& acc, const Unit& u, int wr, int wc, int fr, int fq) const {
;     ...
;             for (int m = 0; m < 4; ++m) { const int t = row0 + ai * 128 + m * 16; float ss = 0.f;
; #pragma unroll
;                 for (int bj = 0; bj < 2; ++bj) { const size_t o = (size_t)t * 1024 + col0 + bj * 128;
;                     f32x4 r0, r1;
;                     if (RESBF) { const u32x4 rb = *(const u32x4*)(XB + o); r0 = (f32x4){bflo(rb.x), bfhi(rb.x), bflo(rb.y), bfhi(rb.y)}; r1 = (f32x4){bflo(rb.z), bfhi(rb.z), bflo(rb.w), bfhi(rb.w)}; }
;                     else { r0 = __builtin_nontemporal_load((const f32x4*)(res + o)); r1 = __builtin_nontemporal_load((const f32x4*)(res + o + 4)); }
;                     const f32x4 v0 = acc[ai][bj][m][0] + r0, v1 = acc[ai][bj][m][1] + r1;
;                     u32x4 w; w.x = pk2(v0[0], v0[1]); w.y = pk2(v0[2], v0[3]); w.z = pk2(v1[0], v1[1]); w.w = pk2(v1[2], v1[3]);
;                     if (!dry) *(u32x4*)(XB + o) = w;
;                     ss += v0[0] * v0[0] + v0[1] * v0[1] + v0[2] * v0[2] + v0[3] * v0[3] + v1[0] * v1[0] + v1[1] * v1[1] + v1[2] * v1[2] + v1[3] * v1[3]; }
;                 { const auto r16 = __builtin_amdgcn_permlane16_swap(__float_as_uint(ss), __float_as_uint(ss), false, false); ss = __uint_as_float(r16[0]) + __uint_as_float(r16[1]);
;                   const auto r32 = __builtin_amdgcn_permlane32_swap(__float_as_uint(ss), __float_as_uint(ss), false, false); ss = __uint_as_float(r32[0]) + __uint_as_float(r32[1]); }
;                 if (fq == 0 && !dry) atomicAdd(rowss + t, ss_to_fix(ss)); }
.LBB0_1744:
	s_or_b64 exec, exec, s[24:25]
	v_add_u32_e32 v32, 0xa0, v146
	v_ashrrev_i32_e32 v33, 31, v32
	s_waitcnt vmcnt(14)
	v_lshlrev_b32_e32 v44, 16, v232
	v_and_b32_e32 v45, 0xffff0000, v232
	v_lshlrev_b32_e32 v46, 16, v234
	v_and_b32_e32 v47, 0xffff0000, v234
	v_lshlrev_b32_e32 v234, 16, v235
	v_and_b32_e32 v235, 0xffff0000, v235
	v_lshlrev_b32_e32 v48, 16, v236
	v_and_b32_e32 v49, 0xffff0000, v236
	v_lshlrev_b32_e32 v232, 16, v233
	v_and_b32_e32 v233, 0xffff0000, v233
	v_lshlrev_b32_e32 v236, 16, v237
	v_and_b32_e32 v237, 0xffff0000, v237
	v_lshlrev_b32_e32 v50, 16, v238
	v_and_b32_e32 v51, 0xffff0000, v238
	v_lshlrev_b32_e32 v238, 16, v239
	v_and_b32_e32 v239, 0xffff0000, v239
	v_pk_add_f32 v[28:29], v[28:29], v[44:45]
	v_pk_add_f32 v[26:27], v[26:27], v[234:235]
	v_pk_add_f32 v[234:235], v[20:21], v[48:49]
	v_pk_add_f32 v[30:31], v[30:31], v[232:233]
	v_pk_add_f32 v[232:233], v[22:23], v[236:237]
	v_pk_add_f32 v[236:237], v[18:19], v[238:239]
	v_pk_add_f32 v[238:239], v[16:17], v[50:51]
	v_cvt_pk_bf16_f32 v16, v28, v29
	v_mul_f32_e32 v29, v29, v29
	v_cvt_pk_bf16_f32 v20, v234, v235
	v_mul_f32_e32 v235, v235, v235
	v_fmac_f32_e32 v29, v28, v28
	v_fmac_f32_e32 v235, v234, v234
	v_fmac_f32_e32 v29, v30, v30
	v_fmac_f32_e32 v235, v232, v232
	v_pk_add_f32 v[24:25], v[24:25], v[46:47]
	v_fmac_f32_e32 v29, v31, v31
	v_fmac_f32_e32 v235, v233, v233
	v_fmac_f32_e32 v29, v24, v24
	v_fmac_f32_e32 v235, v238, v238
	v_fmac_f32_e32 v29, v25, v25
	v_fmac_f32_e32 v235, v239, v239
	v_fmac_f32_e32 v29, v26, v26
	v_fmac_f32_e32 v235, v236, v236
	v_cvt_pk_bf16_f32 v17, v30, v31
	v_cvt_pk_bf16_f32 v18, v24, v25
	v_cvt_pk_bf16_f32 v19, v26, v27
	v_fmac_f32_e32 v29, v27, v27
	v_fmac_f32_e32 v235, v237, v237
	global_store_dwordx4 v[242:243], v[16:19], off
	v_cvt_pk_bf16_f32 v21, v232, v233
	v_cvt_pk_bf16_f32 v22, v238, v239
	v_add_f32_e32 v16, v29, v235
	v_mov_b32_e32 v17, v16
	s_nop 1
	v_permlane16_swap_b32_e32 v16, v17
	v_add_f32_e32 v16, v16, v17
	v_mov_b32_e32 v17, v16
	v_cvt_pk_bf16_f32 v23, v236, v237
	s_nop 0
	v_permlane32_swap_b32_e32 v16, v17
	global_store_dwordx4 v[242:243], v[20:23], off offset:256
	s_and_saveexec_b64 s[24:25], s[4:5]
	s_cbranch_execz .LBB0_1746
	v_add_f32_e32 v16, v16, v17
	v_mul_f32_e32 v16, 0x49800000, v16
	v_trunc_f32_e32 v16, v16
	v_mul_f32_e32 v17, 0x2f800000, v16
	v_floor_f32_e32 v17, v17
	v_fmac_f32_e32 v16, 0xcf800000, v17
	v_cvt_u32_f32_e32 v16, v16
	v_cvt_u32_f32_e32 v17, v17
	v_lshl_add_u64 v[18:19], v[32:33], 3, s[8:9]
	global_atomic_add_x2 v[18:19], v[16:17], off
.LBB0_1746:
	s_or_b64 exec, exec, s[24:25]
	v_add_u32_e32 v16, 0xb0, v146
	v_ashrrev_i32_e32 v17, 31, v16
	s_waitcnt vmcnt(14)
	v_lshlrev_b32_e32 v28, 16, v244
	v_and_b32_e32 v29, 0xffff0000, v244
	v_lshlrev_b32_e32 v30, 16, v246
	v_and_b32_e32 v31, 0xffff0000, v246
	v_lshlrev_b32_e32 v246, 16, v247
	v_and_b32_e32 v247, 0xffff0000, v247
	v_lshlrev_b32_e32 v32, 16, v248
	v_and_b32_e32 v33, 0xffff0000, v248
	v_lshlrev_b32_e32 v244, 16, v245
	v_and_b32_e32 v245, 0xffff0000, v245
	v_lshlrev_b32_e32 v248, 16, v249
	v_and_b32_e32 v249, 0xffff0000, v249
	v_lshlrev_b32_e32 v34, 16, v250
	v_and_b32_e32 v35, 0xffff0000, v250
	v_lshlrev_b32_e32 v250, 16, v251
	v_and_b32_e32 v251, 0xffff0000, v251
	v_pk_add_f32 v[12:13], v[12:13], v[28:29]
	v_pk_add_f32 v[10:11], v[10:11], v[246:247]
	v_pk_add_f32 v[246:247], v[4:5], v[32:33]
	v_pk_add_f32 v[14:15], v[14:15], v[244:245]
	v_pk_add_f32 v[244:245], v[6:7], v[248:249]
	v_pk_add_f32 v[248:249], v[2:3], v[250:251]
	v_pk_add_f32 v[250:251], v[0:1], v[34:35]
	v_cvt_pk_bf16_f32 v0, v12, v13
	v_mul_f32_e32 v13, v13, v13
	v_cvt_pk_bf16_f32 v4, v246, v247
	v_mul_f32_e32 v247, v247, v247
	v_fmac_f32_e32 v13, v12, v12
	v_fmac_f32_e32 v247, v246, v246
	v_fmac_f32_e32 v13, v14, v14
	v_fmac_f32_e32 v247, v244, v244
	v_pk_add_f32 v[8:9], v[8:9], v[30:31]
	v_fmac_f32_e32 v13, v15, v15
	v_fmac_f32_e32 v247, v245, v245
	v_fmac_f32_e32 v13, v8, v8
	v_fmac_f32_e32 v247, v250, v250
	v_fmac_f32_e32 v13, v9, v9
	v_fmac_f32_e32 v247, v251, v251
	v_fmac_f32_e32 v13, v10, v10
	v_fmac_f32_e32 v247, v248, v248
	v_cvt_pk_bf16_f32 v1, v14, v15
	v_cvt_pk_bf16_f32 v2, v8, v9
	v_cvt_pk_bf16_f32 v3, v10, v11
	v_fmac_f32_e32 v13, v11, v11
	v_fmac_f32_e32 v247, v249, v249
	global_store_dwordx4 v[252:253], v[0:3], off
	v_cvt_pk_bf16_f32 v5, v244, v245
	v_cvt_pk_bf16_f32 v6, v250, v251
	v_add_f32_e32 v0, v13, v247
	v_mov_b32_e32 v1, v0
	s_nop 1
	v_permlane16_swap_b32_e32 v0, v1
	v_add_f32_e32 v0, v0, v1
	v_mov_b32_e32 v1, v0
	v_cvt_pk_bf16_f32 v7, v248, v249
	s_nop 0
	v_permlane32_swap_b32_e32 v0, v1
	global_store_dwordx4 v[252:253], v[4:7], off offset:256
	s_and_saveexec_b64 s[24:25], s[4:5]
	s_cbranch_execz .LBB0_1748
	v_add_f32_e32 v0, v0, v1
	v_mul_f32_e32 v0, 0x49800000, v0
	v_trunc_f32_e32 v0, v0
	v_mul_f32_e32 v1, 0x2f800000, v0
	v_floor_f32_e32 v1, v1
	v_fmac_f32_e32 v0, 0xcf800000, v1
	v_cvt_u32_f32_e32 v0, v0
	v_cvt_u32_f32_e32 v1, v1
	v_lshl_add_u64 v[2:3], v[16:17], 3, s[8:9]
	global_atomic_add_x2 v[2:3], v[0:1], off

; #define LAS __attribute__((address_space(3)))
;     DI void operator()(const AccT& acc, const Unit& u, int wr, int wc, int fr, int fq) const {
;     ...
;         { const int lane = fq * 16 + fr, kind = lane >> 3, c4 = 4 * (lane & 7), k3 = kind & 3;
;           const float* src = (k3 == 0 ? cb : cw + (k3 - 1) * 5632) + (kind >= 4 ? 2816 : 0) + u.pn * 128 + wc * 32 + c4;
;           *(LAS f32x4*)(P + kind * 32 + c4) = *(const f32x4*)src; }
; #pragma unroll
;         for (int ai = 0; ai < 2; ++ai) {
;             const int tok0 = u.pm * 248 + 62 * (2 * ai + wr) - 2 + fr;
;             float rs[4];
; #pragma unroll
;             for (int m = 0; m < 4; ++m) { const int t = tok0 + 16 * m; const int tc = t < 0 ? 0 : (t >= S ? S - 1 : t); const float r = rs_from_ss(rowss[tc]); rs[m] = t < 0 ? 0.f : r; }
;             const int row0 = fr < 2 ? (S + 236 + fr) : tok0;
; #pragma unroll
;             for (int n = 0; n < 2; ++n) {
;                 const int lc = 8 * fq + 4 * n;
;                 unsigned wpk[4][2];
; #pragma unroll
;                 for (int jp = 0; jp < 2; ++jp) {
;                     const f32x2 bg = *(const LAS f32x2*)(P + lc + 2 * jp), g0 = *(const LAS f32x2*)(P + 32 + lc + 2 * jp), g1 = *(const LAS f32x2*)(P + 64 + lc + 2 * jp), g2 = *(const LAS f32x2*)(P + 96 + lc + 2 * jp);
;                     const f32x2 bv = *(const LAS f32x2*)(P + 128 + lc + 2 * jp), v0 = *(const LAS f32x2*)(P + 160 + lc + 2 * jp), v1 = *(const LAS f32x2*)(P + 192 + lc + 2 * jp), v2 = *(const LAS f32x2*)(P + 224 + lc + 2 * jp);
;                     f32x2 G[4], V[4];
; #pragma unroll
;                     for (int m = 0; m < 4; ++m) { G[m] = (f32x2){acc[ai][0][m][n][2 * jp], acc[ai][0][m][n][2 * jp + 1]} * rs[m]; V[m] = (f32x2){acc[ai][1][m][n][2 * jp], acc[ai][1][m][n][2 * jp + 1]} * rs[m]; }
; #pragma unroll
;                     for (int m = 0; m < 4; ++m) {
;                         const f32x2 zz = {0.f, 0.f}; const f32x2 Gp = m ? G[m - 1] : zz, Vp = m ? V[m - 1] : zz;
;                         const f32x2 gp1 = {dpp_prev1(G[m].x, Gp.x), dpp_prev1(G[m].y, Gp.y)}, gp2 = {dpp_prev2(G[m].x, Gp.x), dpp_prev2(G[m].y, Gp.y)};
;                         const f32x2 vp1 = {dpp_prev1(V[m].x, Vp.x), dpp_prev1(V[m].y, Vp.y)}, vp2 = {dpp_prev2(V[m].x, Vp.x), dpp_prev2(V[m].y, Vp.y)};
;                         const f32x2 gc = bg + g0 * gp2 + g1 * gp1 + g2 * G[m];
.LBB0_1831:
	s_lshl_b32 s8, s58, 7
	s_ashr_i32 s9, s8, 31
	v_lshl_add_u64 v[128:129], s[8:9], 2, v[168:169]
	s_mul_i32 s9, s57, 0xf8
	v_add_u32_e32 v197, s9, v170
	v_med3_i32 v132, v197, 0, s51
	v_lshlrev_b32_e32 v132, 3, v132
	global_load_dwordx2 v[180:181], v132, s[18:19]
	v_add_u32_e32 v198, 16, v197
	v_med3_i32 v132, v198, 0, s51
	v_add_u32_e32 v199, 32, v197
	v_add_u32_e32 v200, 48, v197
	v_lshlrev_b32_e32 v132, 3, v132
	v_med3_i32 v133, v199, 0, s51
	v_med3_i32 v134, v200, 0, s51
	global_load_dwordx4 v[128:131], v[128:129], off
	v_lshlrev_b32_e32 v133, 3, v133
	v_lshlrev_b32_e32 v134, 3, v134
	global_load_dwordx2 v[182:183], v132, s[18:19]
	global_load_dwordx2 v[202:203], v133, s[18:19]
	global_load_dwordx2 v[204:205], v134, s[18:19]
	v_or_b32_e32 v188, s8, v187
	v_ashrrev_i32_e32 v189, 31, v188
	v_cndmask_b32_e64 v201, v197, v190, s[4:5]
	s_waitcnt vmcnt(0)
	v_ffbh_u32_e32 v184, v181
	v_min_u32_e32 v184, 32, v184
	v_lshlrev_b64 v[180:181], v184, v[180:181]
	v_min_u32_e32 v180, 1, v180
	v_or_b32_e32 v180, v181, v180
	v_cvt_f32_u32_e32 v180, v180
	v_sub_u32_e32 v184, 32, v184
	ds_write_b128 v191, v[128:131]
	v_ffbh_u32_e32 v186, v183
	v_ffbh_u32_e32 v206, v203
	v_min_u32_e32 v186, 32, v186
	v_ffbh_u32_e32 v207, v205
	v_min_u32_e32 v206, 32, v206
	v_lshlrev_b64 v[182:183], v186, v[182:183]
	v_min_u32_e32 v207, 32, v207
	v_lshlrev_b64 v[202:203], v206, v[202:203]
	v_min_u32_e32 v181, 1, v182
	v_lshlrev_b64 v[204:205], v207, v[204:205]
	v_min_u32_e32 v182, 1, v202
	v_or_b32_e32 v181, v183, v181
	v_min_u32_e32 v202, 1, v204
	v_or_b32_e32 v182, v203, v182
	v_cvt_f32_u32_e32 v181, v181
	v_or_b32_e32 v183, v205, v202
	v_cvt_f32_u32_e32 v182, v182
	v_cvt_f32_u32_e32 v183, v183
	v_sub_u32_e32 v186, 32, v186
	v_ldexp_f32 v180, v180, v184
	v_sub_u32_e32 v206, 32, v206
	v_fmamk_f32 v180, v180, 0x30800000, v196
	v_ldexp_f32 v181, v181, v186
	v_sub_u32_e32 v207, 32, v207
	v_ldexp_f32 v182, v182, v206
	v_mul_f32_e32 v184, 0x4b800000, v180
	v_fmamk_f32 v181, v181, 0x30800000, v196
	v_cmp_gt_f32_e32 vcc, s52, v180
	v_ldexp_f32 v183, v183, v207
	v_fmamk_f32 v182, v182, 0x30800000, v196
	v_cndmask_b32_e32 v180, v180, v184, vcc
	v_mul_f32_e32 v184, 0x4b800000, v181
	v_cmp_gt_f32_e64 s[8:9], s52, v181
	v_fmamk_f32 v183, v183, 0x30800000, v196
	v_mul_f32_e32 v186, 0x4b800000, v182
	v_rsq_f32_e32 v180, v180
	v_cndmask_b32_e64 v181, v181, v184, s[8:9]
	v_cmp_gt_f32_e64 s[10:11], s52, v182
	v_mul_f32_e32 v202, 0x4b800000, v183
	v_cmp_gt_f32_e64 s[12:13], s52, v183
	v_cndmask_b32_e64 v182, v182, v186, s[10:11]
	v_rsq_f32_e32 v181, v181
	v_cndmask_b32_e64 v183, v183, v202, s[12:13]
	v_rsq_f32_e32 v182, v182
	v_rsq_f32_e32 v183, v183
	v_mul_f32_e32 v184, 0x45800000, v180
	v_cndmask_b32_e32 v180, v180, v184, vcc
	v_mul_f32_e32 v184, 0x45800000, v181
	v_cmp_lt_i32_e32 vcc, -1, v197
	v_mul_f32_e32 v202, 0x45800000, v182
	v_mul_f32_e32 v203, 0x45800000, v183
	v_cndmask_b32_e32 v186, 0, v180, vcc
	v_cndmask_b32_e64 v180, v181, v184, s[8:9]
	v_cmp_lt_i32_e32 vcc, s53, v197
	v_cndmask_b32_e64 v181, v182, v202, s[10:11]
	v_cndmask_b32_e64 v183, v183, v203, s[12:13]
	v_cndmask_b32_e32 v184, 0, v180, vcc
	v_cmp_lt_i32_e32 vcc, s54, v197
	v_pk_mul_f32 v[124:125], v[124:125], v[186:187] op_sel_hi:[1,0]
	ds_read_b128 v[136:139], v193
	ds_read_b128 v[148:151], v193 offset:128
	ds_read_b128 v[152:155], v193 offset:256
	ds_read_b128 v[156:159], v193 offset:384
	ds_read_b128 v[128:131], v193 offset:512
	ds_read_b128 v[132:135], v193 offset:640
	ds_read_b128 v[140:143], v193 offset:768
	ds_read_b128 v[144:147], v193 offset:896
	v_cndmask_b32_e32 v182, 0, v181, vcc
	v_cmp_lt_i32_e32 vcc, s55, v197
	v_pk_mul_f32 v[108:109], v[108:109], v[182:183] op_sel_hi:[1,0]
	v_pk_mul_f32 v[202:203], v[104:105], v[182:183] op_sel_hi:[1,0]
	v_cndmask_b32_e32 v180, 0, v183, vcc
	v_mov_b32_e32 v183, 0
	v_pk_mul_f32 v[204:205], v[100:101], v[180:181] op_sel_hi:[1,0]
	v_pk_mul_f32 v[206:207], v[96:97], v[180:181] op_sel_hi:[1,0]
	v_mov_b32_e32 v181, 0
	v_mov_b32_dpp v183, v183 row_ror:2 row_mask:0xf bank_mask:0xf
	v_mov_b32_e32 v100, v183
	v_mov_b32_dpp v181, v181 row_ror:1 row_mask:0xf bank_mask:0xf
	v_mov_b32_e32 v101, v183
	v_mov_b32_e32 v96, v181
	v_mov_b32_e32 v97, v181
	v_mov_b32_dpp v100, v124 row_shr:2 row_mask:0xf bank_mask:0xf
	v_mov_b32_dpp v101, v125 row_shr:2 row_mask:0xf bank_mask:0xf
	v_mov_b32_dpp v96, v124 row_shr:1 row_mask:0xf bank_mask:0xf
	v_mov_b32_dpp v97, v125 row_shr:1 row_mask:0xf bank_mask:0xf
	s_waitcnt lgkmcnt(6)
	v_pk_fma_f32 v[100:101], v[148:149], v[100:101], v[136:137]
	v_pk_mul_f32 v[120:121], v[120:121], v[186:187] op_sel_hi:[1,0]
	s_waitcnt lgkmcnt(5)
	v_pk_fma_f32 v[96:97], v[152:153], v[96:97], v[100:101]
	v_mov_b32_e32 v208, v183
	s_waitcnt lgkmcnt(4)
	v_pk_fma_f32 v[96:97], v[156:157], v[124:125], v[96:97]
	v_mov_b32_e32 v209, v183
	v_pk_mul_f32 v[100:101], v[96:97], s[2:3] op_sel_hi:[1,0]
	v_mov_b32_e32 v104, v181
	v_exp_f32_e32 v100, v100
	v_exp_f32_e32 v101, v101
	v_mov_b32_e32 v105, v181
	v_mov_b32_dpp v208, v120 row_shr:2 row_mask:0xf bank_mask:0xf
	v_mov_b32_dpp v209, v121 row_shr:2 row_mask:0xf bank_mask:0xf
	v_pk_add_f32 v[100:101], v[100:101], 1.0 op_sel_hi:[1,0]
	v_mov_b32_dpp v104, v120 row_shr:1 row_mask:0xf bank_mask:0xf
	v_rcp_f32_e32 v100, v100
	v_rcp_f32_e32 v101, v101
	v_mov_b32_dpp v105, v121 row_shr:1 row_mask:0xf bank_mask:0xf
	s_waitcnt lgkmcnt(2)
	v_pk_fma_f32 v[208:209], v[132:133], v[208:209], v[128:129]
	v_pk_mul_f32 v[116:117], v[116:117], v[184:185] op_sel_hi:[1,0]
	s_waitcnt lgkmcnt(1)
	v_pk_fma_f32 v[104:105], v[140:141], v[104:105], v[208:209]
	v_pk_mul_f32 v[96:97], v[96:97], v[100:101]
	s_waitcnt lgkmcnt(0)
; DI unsigned pk2(float lo, float hi) { f32x2 v = {lo, hi}; bf16x2_t b = __builtin_convertvector(v, bf16x2_t); return __builtin_bit_cast(unsigned, b); }
;     DI void operator()(const AccT& acc, const Unit& u, int wr, int wc, int fr, int fq) const {
;     ...
;                     for (int m = 0; m < 4; ++m) { G[m] = (f32x2){acc[ai][0][m][n][2 * jp], acc[ai][0][m][n][2 * jp + 1]} * rs[m]; V[m] = (f32x2){acc[ai][1][m][n][2 * jp], acc[ai][1][m][n][2 * jp + 1]} * rs[m]; }
; #pragma unroll
;                     for (int m = 0; m < 4; ++m) {
;                         const f32x2 zz = {0.f, 0.f}; const f32x2 Gp = m ? G[m - 1] : zz, Vp = m ? V[m - 1] : zz;
;                         const f32x2 gp1 = {dpp_prev1(G[m].x, Gp.x), dpp_prev1(G[m].y, Gp.y)}, gp2 = {dpp_prev2(G[m].x, Gp.x), dpp_prev2(G[m].y, Gp.y)};
;                         const f32x2 vp1 = {dpp_prev1(V[m].x, Vp.x), dpp_prev1(V[m].y, Vp.y)}, vp2 = {dpp_prev2(V[m].x, Vp.x), dpp_prev2(V[m].y, Vp.y)};
;                         const f32x2 gc = bg + g0 * gp2 + g1 * gp1 + g2 * G[m];
;                         const f32x2 vc = bv + v0 * vp2 + v1 * vp1 + v2 * V[m];
;                         const f32x2 xe = gc * (-LOG2E);
;                         f32x2 dn = {__builtin_amdgcn_exp2f(xe.x), __builtin_amdgcn_exp2f(xe.y)}; dn = dn + 1.0f;
;                         const f32x2 rc = {__builtin_amdgcn_rcpf(dn.x), __builtin_amdgcn_rcpf(dn.y)};
;                         const f32x2 rr = gc * rc * vc;
;                         wpk[m][jp] = pk2(rr.x, rr.y); }
	v_pk_fma_f32 v[104:105], v[144:145], v[120:121], v[104:105]
	v_pk_mul_f32 v[96:97], v[104:105], v[96:97]
	v_mov_b32_dpp v104, v124 row_ror:2 row_mask:0xf bank_mask:0xf
	v_mov_b32_dpp v105, v125 row_ror:2 row_mask:0xf bank_mask:0xf
	v_mov_b32_dpp v100, v124 row_ror:1 row_mask:0xf bank_mask:0xf
	v_mov_b32_dpp v101, v125 row_ror:1 row_mask:0xf bank_mask:0xf
	v_mov_b32_dpp v104, v116 row_shr:2 row_mask:0xf bank_mask:0xf
	v_mov_b32_dpp v105, v117 row_shr:2 row_mask:0xf bank_mask:0xf
	v_mov_b32_dpp v100, v116 row_shr:1 row_mask:0xf bank_mask:0xf
	v_mov_b32_dpp v101, v117 row_shr:1 row_mask:0xf bank_mask:0xf
	v_pk_fma_f32 v[104:105], v[148:149], v[104:105], v[136:137]
	v_pk_fma_f32 v[100:101], v[152:153], v[100:101], v[104:105]
	v_pk_fma_f32 v[100:101], v[156:157], v[116:117], v[100:101]
	v_pk_mul_f32 v[112:113], v[112:113], v[184:185] op_sel_hi:[1,0]
	v_pk_mul_f32 v[104:105], v[100:101], s[2:3] op_sel_hi:[1,0]
	v_exp_f32_e32 v104, v104
	v_exp_f32_e32 v105, v105
	v_mov_b32_dpp v208, v120 row_ror:2 row_mask:0xf bank_mask:0xf
	v_mov_b32_dpp v209, v121 row_ror:2 row_mask:0xf bank_mask:0xf
	v_pk_add_f32 v[104:105], v[104:105], 1.0 op_sel_hi:[1,0]
	v_mov_b32_dpp v124, v120 row_ror:1 row_mask:0xf bank_mask:0xf
	v_rcp_f32_e32 v104, v104
	v_rcp_f32_e32 v105, v105
	v_mov_b32_dpp v125, v121 row_ror:1 row_mask:0xf bank_mask:0xf
	v_mov_b32_dpp v208, v112 row_shr:2 row_mask:0xf bank_mask:0xf
	v_mov_b32_dpp v209, v113 row_shr:2 row_mask:0xf bank_mask:0xf
	v_mov_b32_dpp v124, v112 row_shr:1 row_mask:0xf bank_mask:0xf
	v_mov_b32_dpp v125, v113 row_shr:1 row_mask:0xf bank_mask:0xf
	v_pk_fma_f32 v[120:121], v[132:133], v[208:209], v[128:129]
	v_pk_mul_f32 v[100:101], v[100:101], v[104:105]
	v_pk_fma_f32 v[120:121], v[140:141], v[124:125], v[120:121]
	v_pk_fma_f32 v[120:121], v[144:145], v[112:113], v[120:121]
	v_pk_mul_f32 v[100:101], v[120:121], v[100:101]
	v_mov_b32_dpp v104, v116 row_ror:1 row_mask:0xf bank_mask:0xf
	v_mov_b32_dpp v120, v116 row_ror:2 row_mask:0xf bank_mask:0xf
	v_mov_b32_dpp v121, v117 row_ror:2 row_mask:0xf bank_mask:0xf
	v_mov_b32_dpp v105, v117 row_ror:1 row_mask:0xf bank_mask:0xf
	v_mov_b32_dpp v120, v108 row_shr:2 row_mask:0xf bank_mask:0xf
	v_mov_b32_dpp v121, v109 row_shr:2 row_mask:0xf bank_mask:0xf
	v_mov_b32_dpp v104, v108 row_shr:1 row_mask:0xf bank_mask:0xf
	v_mov_b32_dpp v105, v109 row_shr:1 row_mask:0xf bank_mask:0xf
	v_pk_fma_f32 v[120:121], v[148:149], v[120:121], v[136:137]
	v_pk_fma_f32 v[104:105], v[152:153], v[104:105], v[120:121]
	v_pk_fma_f32 v[104:105], v[156:157], v[108:109], v[104:105]
	v_pk_mul_f32 v[120:121], v[104:105], s[2:3] op_sel_hi:[1,0]
	v_exp_f32_e32 v120, v120
	v_exp_f32_e32 v121, v121
	v_mov_b32_dpp v116, v112 row_ror:1 row_mask:0xf bank_mask:0xf
	v_mov_b32_dpp v117, v113 row_ror:1 row_mask:0xf bank_mask:0xf
	v_mov_b32_dpp v124, v112 row_ror:2 row_mask:0xf bank_mask:0xf
	v_mov_b32_dpp v125, v113 row_ror:2 row_mask:0xf bank_mask:0xf
	v_pk_add_f32 v[112:113], v[120:121], 1.0 op_sel_hi:[1,0]
	v_mov_b32_dpp v124, v202 row_shr:2 row_mask:0xf bank_mask:0xf
	v_rcp_f32_e32 v112, v112
	v_rcp_f32_e32 v113, v113
	v_mov_b32_dpp v125, v203 row_shr:2 row_mask:0xf bank_mask:0xf
	v_mov_b32_dpp v116, v202 row_shr:1 row_mask:0xf bank_mask:0xf
	v_mov_b32_dpp v117, v203 row_shr:1 row_mask:0xf bank_mask:0xf
	v_pk_fma_f32 v[120:121], v[132:133], v[124:125], v[128:129]
	v_pk_mul_f32 v[104:105], v[104:105], v[112:113]
	v_pk_fma_f32 v[116:117], v[140:141], v[116:117], v[120:121]
	v_pk_fma_f32 v[116:117], v[144:145], v[202:203], v[116:117]
	v_pk_mul_f32 v[104:105], v[116:117], v[104:105]
	v_mov_b32_dpp v112, v108 row_ror:1 row_mask:0xf bank_mask:0xf
	v_mov_b32_dpp v116, v108 row_ror:2 row_mask:0xf bank_mask:0xf
	v_mov_b32_dpp v117, v109 row_ror:2 row_mask:0xf bank_mask:0xf
	v_mov_b32_dpp v113, v109 row_ror:1 row_mask:0xf bank_mask:0xf
	v_mov_b32_dpp v116, v204 row_shr:2 row_mask:0xf bank_mask:0xf
	v_mov_b32_dpp v117, v205 row_shr:2 row_mask:0xf bank_mask:0xf
	v_mov_b32_dpp v112, v204 row_shr:1 row_mask:0xf bank_mask:0xf
	v_mov_b32_dpp v113, v205 row_shr:1 row_mask:0xf bank_mask:0xf
	v_pk_fma_f32 v[116:117], v[148:149], v[116:117], v[136:137]
	v_pk_fma_f32 v[112:113], v[152:153], v[112:113], v[116:117]
	v_pk_fma_f32 v[112:113], v[156:157], v[204:205], v[112:113]
	v_pk_mul_f32 v[116:117], v[112:113], s[2:3] op_sel_hi:[1,0]
	v_exp_f32_e32 v116, v116
	v_exp_f32_e32 v117, v117
	v_mov_b32_dpp v120, v202 row_ror:2 row_mask:0xf bank_mask:0xf
	v_mov_b32_dpp v121, v203 row_ror:2 row_mask:0xf bank_mask:0xf
	v_mov_b32_dpp v108, v202 row_ror:1 row_mask:0xf bank_mask:0xf
	v_pk_add_f32 v[116:117], v[116:117], 1.0 op_sel_hi:[1,0]
	v_mov_b32_dpp v109, v203 row_ror:1 row_mask:0xf bank_mask:0xf
	v_rcp_f32_e32 v116, v116
	v_rcp_f32_e32 v117, v117
	v_mov_b32_dpp v120, v206 row_shr:2 row_mask:0xf bank_mask:0xf
	v_mov_b32_dpp v121, v207 row_shr:2 row_mask:0xf bank_mask:0xf
	v_mov_b32_dpp v108, v206 row_shr:1 row_mask:0xf bank_mask:0xf
	v_mov_b32_dpp v109, v207 row_shr:1 row_mask:0xf bank_mask:0xf
	v_pk_fma_f32 v[120:121], v[132:133], v[120:121], v[128:129]
	v_pk_mul_f32 v[112:113], v[112:113], v[116:117]
	v_pk_fma_f32 v[108:109], v[140:141], v[108:109], v[120:121]
	v_pk_mul_f32 v[116:117], v[122:123], v[186:187] op_sel_hi:[1,0]
	v_pk_fma_f32 v[108:109], v[144:145], v[206:207], v[108:109]
	v_mov_b32_e32 v122, v183
	v_pk_mul_f32 v[108:109], v[108:109], v[112:113]
	v_pk_mul_f32 v[112:113], v[126:127], v[186:187] op_sel_hi:[1,0]
	v_mov_b32_e32 v123, v183
	v_mov_b32_e32 v120, v181
	v_mov_b32_e32 v121, v181
	v_mov_b32_dpp v122, v112 row_shr:2 row_mask:0xf bank_mask:0xf
	v_mov_b32_dpp v123, v113 row_shr:2 row_mask:0xf bank_mask:0xf
; DI unsigned pk2(float lo, float hi) { f32x2 v = {lo, hi}; bf16x2_t b = __builtin_convertvector(v, bf16x2_t); return __builtin_bit_cast(unsigned, b); }
;     DI void operator()(const AccT& acc, const Unit& u, int wr, int wc, int fr, int fq) const {
;     ...
;                     for (int m = 0; m < 4; ++m) { G[m] = (f32x2){acc[ai][0][m][n][2 * jp], acc[ai][0][m][n][2 * jp + 1]} * rs[m]; V[m] = (f32x2){acc[ai][1][m][n][2 * jp], acc[ai][1][m][n][2 * jp + 1]} * rs[m]; }
; #pragma unroll
;                     for (int m = 0; m < 4; ++m) {
;                         const f32x2 zz = {0.f, 0.f}; const f32x2 Gp = m ? G[m - 1] : zz, Vp = m ? V[m - 1] : zz;
;                         const f32x2 gp1 = {dpp_prev1(G[m].x, Gp.x), dpp_prev1(G[m].y, Gp.y)}, gp2 = {dpp_prev2(G[m].x, Gp.x), dpp_prev2(G[m].y, Gp.y)};
;                         const f32x2 vp1 = {dpp_prev1(V[m].x, Vp.x), dpp_prev1(V[m].y, Vp.y)}, vp2 = {dpp_prev2(V[m].x, Vp.x), dpp_prev2(V[m].y, Vp.y)};
;                         const f32x2 gc = bg + g0 * gp2 + g1 * gp1 + g2 * G[m];
;                         const f32x2 vc = bv + v0 * vp2 + v1 * vp1 + v2 * V[m];
;                         const f32x2 xe = gc * (-LOG2E);
;                         f32x2 dn = {__builtin_amdgcn_exp2f(xe.x), __builtin_amdgcn_exp2f(xe.y)}; dn = dn + 1.0f;
;                         const f32x2 rc = {__builtin_amdgcn_rcpf(dn.x), __builtin_amdgcn_rcpf(dn.y)};
;                         const f32x2 rr = gc * rc * vc;
;                         wpk[m][jp] = pk2(rr.x, rr.y); }
	v_mov_b32_dpp v120, v112 row_shr:1 row_mask:0xf bank_mask:0xf
	v_mov_b32_dpp v121, v113 row_shr:1 row_mask:0xf bank_mask:0xf
	v_pk_fma_f32 v[122:123], v[150:151], v[122:123], v[138:139]
	v_mov_b32_e32 v126, v183
	v_pk_fma_f32 v[120:121], v[154:155], v[120:121], v[122:123]
	v_mov_b32_e32 v127, v183
	v_pk_fma_f32 v[120:121], v[112:113], v[158:159], v[120:121]
	v_mov_b32_e32 v124, v181
	v_pk_mul_f32 v[122:123], v[120:121], s[2:3] op_sel_hi:[1,0]
	v_mov_b32_e32 v125, v181
	v_exp_f32_e32 v122, v122
	v_exp_f32_e32 v123, v123
	v_mov_b32_dpp v126, v116 row_shr:2 row_mask:0xf bank_mask:0xf
	v_mov_b32_dpp v127, v117 row_shr:2 row_mask:0xf bank_mask:0xf
	v_mov_b32_dpp v124, v116 row_shr:1 row_mask:0xf bank_mask:0xf
	v_pk_add_f32 v[122:123], v[122:123], 1.0 op_sel_hi:[1,0]
	v_mov_b32_dpp v125, v117 row_shr:1 row_mask:0xf bank_mask:0xf
	v_rcp_f32_e32 v122, v122
	v_rcp_f32_e32 v123, v123
	v_pk_fma_f32 v[126:127], v[134:135], v[126:127], v[130:131]
	v_cvt_pk_bf16_f32 v96, v96, v97
	v_pk_fma_f32 v[124:125], v[142:143], v[124:125], v[126:127]
	v_pk_mul_f32 v[120:121], v[120:121], v[122:123]
	v_pk_fma_f32 v[124:125], v[116:117], v[146:147], v[124:125]
	v_pk_mul_f32 v[120:121], v[124:125], v[120:121]
	v_pk_mul_f32 v[118:119], v[118:119], v[184:185] op_sel_hi:[1,0]
	v_cvt_pk_bf16_f32 v97, v120, v121
	v_mov_b32_dpp v122, v112 row_ror:2 row_mask:0xf bank_mask:0xf
	v_mov_b32_dpp v123, v113 row_ror:2 row_mask:0xf bank_mask:0xf
	v_mov_b32_dpp v120, v112 row_ror:1 row_mask:0xf bank_mask:0xf
	v_mov_b32_dpp v121, v113 row_ror:1 row_mask:0xf bank_mask:0xf
	v_mov_b32_dpp v122, v118 row_shr:2 row_mask:0xf bank_mask:0xf
	v_mov_b32_dpp v123, v119 row_shr:2 row_mask:0xf bank_mask:0xf
	v_mov_b32_dpp v120, v118 row_shr:1 row_mask:0xf bank_mask:0xf
	v_mov_b32_dpp v121, v119 row_shr:1 row_mask:0xf bank_mask:0xf
	v_pk_fma_f32 v[122:123], v[150:151], v[122:123], v[138:139]
	v_pk_fma_f32 v[120:121], v[154:155], v[120:121], v[122:123]
	v_pk_fma_f32 v[120:121], v[118:119], v[158:159], v[120:121]
	v_pk_mul_f32 v[122:123], v[120:121], s[2:3] op_sel_hi:[1,0]
	v_exp_f32_e32 v122, v122
	v_exp_f32_e32 v123, v123
	v_mov_b32_dpp v112, v116 row_ror:1 row_mask:0xf bank_mask:0xf
	v_mov_b32_dpp v113, v117 row_ror:1 row_mask:0xf bank_mask:0xf
	v_mov_b32_dpp v124, v116 row_ror:2 row_mask:0xf bank_mask:0xf
	v_mov_b32_dpp v125, v117 row_ror:2 row_mask:0xf bank_mask:0xf
	v_pk_add_f32 v[116:117], v[122:123], 1.0 op_sel_hi:[1,0]
	v_pk_mul_f32 v[114:115], v[114:115], v[184:185] op_sel_hi:[1,0]
	v_rcp_f32_e32 v116, v116
	v_rcp_f32_e32 v117, v117
	v_mov_b32_dpp v124, v114 row_shr:2 row_mask:0xf bank_mask:0xf
	v_mov_b32_dpp v125, v115 row_shr:2 row_mask:0xf bank_mask:0xf
	v_mov_b32_dpp v112, v114 row_shr:1 row_mask:0xf bank_mask:0xf
	v_mov_b32_dpp v113, v115 row_shr:1 row_mask:0xf bank_mask:0xf
	v_pk_fma_f32 v[122:123], v[134:135], v[124:125], v[130:131]
	v_pk_mul_f32 v[116:117], v[120:121], v[116:117]
	v_pk_fma_f32 v[112:113], v[142:143], v[112:113], v[122:123]
	v_cvt_pk_bf16_f32 v100, v100, v101
	v_pk_fma_f32 v[112:113], v[114:115], v[146:147], v[112:113]
	v_pk_mul_f32 v[110:111], v[110:111], v[182:183] op_sel_hi:[1,0]
	v_pk_mul_f32 v[112:113], v[112:113], v[116:117]
	v_cvt_pk_bf16_f32 v101, v112, v113
	v_mov_b32_dpp v116, v118 row_ror:2 row_mask:0xf bank_mask:0xf
	v_mov_b32_dpp v117, v119 row_ror:2 row_mask:0xf bank_mask:0xf
	v_mov_b32_dpp v112, v118 row_ror:1 row_mask:0xf bank_mask:0xf
	v_mov_b32_dpp v113, v119 row_ror:1 row_mask:0xf bank_mask:0xf
	v_mov_b32_dpp v116, v110 row_shr:2 row_mask:0xf bank_mask:0xf
	v_mov_b32_dpp v117, v111 row_shr:2 row_mask:0xf bank_mask:0xf
	v_mov_b32_dpp v112, v110 row_shr:1 row_mask:0xf bank_mask:0xf
	v_mov_b32_dpp v113, v111 row_shr:1 row_mask:0xf bank_mask:0xf
	v_pk_fma_f32 v[116:117], v[150:151], v[116:117], v[138:139]
	v_pk_fma_f32 v[112:113], v[154:155], v[112:113], v[116:117]
	v_pk_fma_f32 v[112:113], v[110:111], v[158:159], v[112:113]
	v_pk_mul_f32 v[116:117], v[112:113], s[2:3] op_sel_hi:[1,0]
	v_exp_f32_e32 v116, v116
	v_exp_f32_e32 v117, v117
	v_mov_b32_dpp v118, v114 row_ror:1 row_mask:0xf bank_mask:0xf
	v_mov_b32_dpp v119, v115 row_ror:1 row_mask:0xf bank_mask:0xf
	v_mov_b32_dpp v120, v114 row_ror:2 row_mask:0xf bank_mask:0xf
	v_mov_b32_dpp v121, v115 row_ror:2 row_mask:0xf bank_mask:0xf
	v_pk_add_f32 v[114:115], v[116:117], 1.0 op_sel_hi:[1,0]
	v_pk_mul_f32 v[106:107], v[106:107], v[182:183] op_sel_hi:[1,0]
	v_rcp_f32_e32 v114, v114
	v_rcp_f32_e32 v115, v115
	v_mov_b32_dpp v120, v106 row_shr:2 row_mask:0xf bank_mask:0xf
	v_mov_b32_dpp v121, v107 row_shr:2 row_mask:0xf bank_mask:0xf
	v_mov_b32_dpp v118, v106 row_shr:1 row_mask:0xf bank_mask:0xf
	v_mov_b32_dpp v119, v107 row_shr:1 row_mask:0xf bank_mask:0xf
	v_pk_fma_f32 v[116:117], v[134:135], v[120:121], v[130:131]
	v_pk_mul_f32 v[112:113], v[112:113], v[114:115]
	v_pk_fma_f32 v[116:117], v[142:143], v[118:119], v[116:117]
	v_pk_fma_f32 v[116:117], v[106:107], v[146:147], v[116:117]
	v_pk_mul_f32 v[112:113], v[116:117], v[112:113]
	v_cvt_pk_bf16_f32 v104, v104, v105
	v_pk_mul_f32 v[102:103], v[102:103], v[180:181] op_sel_hi:[1,0]
	v_cvt_pk_bf16_f32 v105, v112, v113
	v_mov_b32_dpp v114, v110 row_ror:2 row_mask:0xf bank_mask:0xf
	v_mov_b32_dpp v115, v111 row_ror:2 row_mask:0xf bank_mask:0xf
	v_mov_b32_dpp v112, v110 row_ror:1 row_mask:0xf bank_mask:0xf
	v_mov_b32_dpp v113, v111 row_ror:1 row_mask:0xf bank_mask:0xf
	v_mov_b32_dpp v114, v102 row_shr:2 row_mask:0xf bank_mask:0xf
	v_mov_b32_dpp v115, v103 row_shr:2 row_mask:0xf bank_mask:0xf
	v_mov_b32_dpp v112, v102 row_shr:1 row_mask:0xf bank_mask:0xf
	v_mov_b32_dpp v113, v103 row_shr:1 row_mask:0xf bank_mask:0xf
	v_pk_fma_f32 v[114:115], v[150:151], v[114:115], v[138:139]
; #define LAS __attribute__((address_space(3)))
; DI unsigned pk2(float lo, float hi) { f32x2 v = {lo, hi}; bf16x2_t b = __builtin_convertvector(v, bf16x2_t); return __builtin_bit_cast(unsigned, b); }
;     DI void operator()(const AccT& acc, const Unit& u, int wr, int wc, int fr, int fq) const {
;     ...
;                     const f32x2 bg = *(const LAS f32x2*)(P + lc + 2 * jp), g0 = *(const LAS f32x2*)(P + 32 + lc + 2 * jp), g1 = *(const LAS f32x2*)(P + 64 + lc + 2 * jp), g2 = *(const LAS f32x2*)(P + 96 + lc + 2 * jp);
;                     const f32x2 bv = *(const LAS f32x2*)(P + 128 + lc + 2 * jp), v0 = *(const LAS f32x2*)(P + 160 + lc + 2 * jp), v1 = *(const LAS f32x2*)(P + 192 + lc + 2 * jp), v2 = *(const LAS f32x2*)(P + 224 + lc + 2 * jp);
;                     f32x2 G[4], V[4];
; #pragma unroll
;                     for (int m = 0; m < 4; ++m) { G[m] = (f32x2){acc[ai][0][m][n][2 * jp], acc[ai][0][m][n][2 * jp + 1]} * rs[m]; V[m] = (f32x2){acc[ai][1][m][n][2 * jp], acc[ai][1][m][n][2 * jp + 1]} * rs[m]; }
; #pragma unroll
;                     for (int m = 0; m < 4; ++m) {
;                         const f32x2 zz = {0.f, 0.f}; const f32x2 Gp = m ? G[m - 1] : zz, Vp = m ? V[m - 1] : zz;
;                         const f32x2 gp1 = {dpp_prev1(G[m].x, Gp.x), dpp_prev1(G[m].y, Gp.y)}, gp2 = {dpp_prev2(G[m].x, Gp.x), dpp_prev2(G[m].y, Gp.y)};
;                         const f32x2 vp1 = {dpp_prev1(V[m].x, Vp.x), dpp_prev1(V[m].y, Vp.y)}, vp2 = {dpp_prev2(V[m].x, Vp.x), dpp_prev2(V[m].y, Vp.y)};
;                         const f32x2 gc = bg + g0 * gp2 + g1 * gp1 + g2 * G[m];
;                         const f32x2 vc = bv + v0 * vp2 + v1 * vp1 + v2 * V[m];
;                         const f32x2 xe = gc * (-LOG2E);
;                         f32x2 dn = {__builtin_amdgcn_exp2f(xe.x), __builtin_amdgcn_exp2f(xe.y)}; dn = dn + 1.0f;
;                         const f32x2 rc = {__builtin_amdgcn_rcpf(dn.x), __builtin_amdgcn_rcpf(dn.y)};
;                         const f32x2 rr = gc * rc * vc;
;                         wpk[m][jp] = pk2(rr.x, rr.y); }
;                 }
; #pragma unroll
;                 for (int m = 0; m < 4; ++m) { const int row = m ? tok0 + 16 * m : row0;
;                     *(u32x2*)(ACT + (size_t)row * 2816 + cl + 4 * n) = (u32x2){wpk[m][0], wpk[m][1]}; }
	v_pk_fma_f32 v[112:113], v[154:155], v[112:113], v[114:115]
	v_pk_fma_f32 v[102:103], v[102:103], v[158:159], v[112:113]
	v_pk_mul_f32 v[112:113], v[102:103], s[2:3] op_sel_hi:[1,0]
	v_exp_f32_e32 v112, v112
	v_exp_f32_e32 v113, v113
	v_mov_b32_dpp v110, v106 row_ror:1 row_mask:0xf bank_mask:0xf
	v_mov_b32_dpp v111, v107 row_ror:1 row_mask:0xf bank_mask:0xf
	v_mov_b32_dpp v116, v106 row_ror:2 row_mask:0xf bank_mask:0xf
	v_mov_b32_dpp v117, v107 row_ror:2 row_mask:0xf bank_mask:0xf
	v_pk_add_f32 v[106:107], v[112:113], 1.0 op_sel_hi:[1,0]
	v_pk_mul_f32 v[98:99], v[98:99], v[180:181] op_sel_hi:[1,0]
	v_rcp_f32_e32 v106, v106
	v_rcp_f32_e32 v107, v107
	v_mov_b32_dpp v116, v98 row_shr:2 row_mask:0xf bank_mask:0xf
	v_mov_b32_dpp v117, v99 row_shr:2 row_mask:0xf bank_mask:0xf
	v_mov_b32_dpp v110, v98 row_shr:1 row_mask:0xf bank_mask:0xf
	v_mov_b32_dpp v111, v99 row_shr:1 row_mask:0xf bank_mask:0xf
	v_pk_fma_f32 v[112:113], v[134:135], v[116:117], v[130:131]
	v_pk_mul_f32 v[102:103], v[102:103], v[106:107]
	v_pk_fma_f32 v[110:111], v[142:143], v[110:111], v[112:113]
	v_mov_b64_e32 v[128:129], s[16:17]
	v_pk_fma_f32 v[98:99], v[98:99], v[146:147], v[110:111]
	v_cvt_pk_bf16_f32 v108, v108, v109
	v_pk_mul_f32 v[98:99], v[98:99], v[102:103]
	v_lshlrev_b64 v[130:131], 1, v[188:189]
	v_cvt_pk_bf16_f32 v109, v98, v99
	v_mad_i64_i32 v[98:99], s[8:9], v201, s48, v[128:129]
	v_lshl_add_u64 v[132:133], v[98:99], 0, v[130:131]
	global_store_dwordx2 v[132:133], v[96:97], off
	v_mad_i64_i32 v[96:97], s[8:9], v198, s48, v[128:129]
	v_lshl_add_u64 v[134:135], v[96:97], 0, v[130:131]
	v_mad_i64_i32 v[96:97], s[8:9], v199, s48, v[128:129]
	v_lshl_add_u64 v[136:137], v[96:97], 0, v[130:131]
	v_mad_i64_i32 v[96:97], s[8:9], v200, s48, v[128:129]
	v_lshl_add_u64 v[138:139], v[96:97], 0, v[130:131]
	global_store_dwordx2 v[134:135], v[100:101], off
	global_store_dwordx2 v[136:137], v[104:105], off
	global_store_dwordx2 v[138:139], v[108:109], off
	v_pk_mul_f32 v[92:93], v[92:93], v[186:187] op_sel_hi:[1,0]
	v_pk_mul_f32 v[142:143], v[68:69], v[180:181] op_sel_hi:[1,0]
	v_mov_b32_e32 v68, v183
	v_mov_b32_e32 v69, v183
	v_pk_mul_f32 v[144:145], v[64:65], v[180:181] op_sel_hi:[1,0]
	v_mov_b32_e32 v64, v181
	v_mov_b32_e32 v65, v181
	v_mov_b32_dpp v68, v92 row_shr:2 row_mask:0xf bank_mask:0xf
	v_mov_b32_dpp v69, v93 row_shr:2 row_mask:0xf bank_mask:0xf
	ds_read_b128 v[104:107], v193 offset:16
	ds_read_b128 v[116:119], v193 offset:144
	ds_read_b128 v[120:123], v193 offset:272
	ds_read_b128 v[124:127], v193 offset:400
	ds_read_b128 v[96:99], v193 offset:528
	ds_read_b128 v[100:103], v193 offset:656
	ds_read_b128 v[108:111], v193 offset:784
	ds_read_b128 v[112:115], v193 offset:912
	v_mov_b32_dpp v64, v92 row_shr:1 row_mask:0xf bank_mask:0xf
	v_mov_b32_dpp v65, v93 row_shr:1 row_mask:0xf bank_mask:0xf
	s_waitcnt lgkmcnt(6)
	v_pk_fma_f32 v[68:69], v[116:117], v[68:69], v[104:105]
	v_pk_mul_f32 v[88:89], v[88:89], v[186:187] op_sel_hi:[1,0]
	s_waitcnt lgkmcnt(5)
	v_pk_fma_f32 v[64:65], v[120:121], v[64:65], v[68:69]
	v_mov_b32_e32 v146, v183
	s_waitcnt lgkmcnt(4)
	v_pk_fma_f32 v[64:65], v[92:93], v[124:125], v[64:65]
	v_mov_b32_e32 v147, v183
	v_pk_mul_f32 v[68:69], v[64:65], s[2:3] op_sel_hi:[1,0]
	v_pk_mul_f32 v[140:141], v[72:73], v[182:183] op_sel_hi:[1,0]
	v_exp_f32_e32 v68, v68
	v_exp_f32_e32 v69, v69
	v_mov_b32_e32 v72, v181
	v_mov_b32_e32 v73, v181
	v_mov_b32_dpp v146, v88 row_shr:2 row_mask:0xf bank_mask:0xf
	v_pk_add_f32 v[68:69], v[68:69], 1.0 op_sel_hi:[1,0]
	v_mov_b32_dpp v147, v89 row_shr:2 row_mask:0xf bank_mask:0xf
	v_rcp_f32_e32 v68, v68
	v_rcp_f32_e32 v69, v69
	v_mov_b32_dpp v72, v88 row_shr:1 row_mask:0xf bank_mask:0xf
	v_mov_b32_dpp v73, v89 row_shr:1 row_mask:0xf bank_mask:0xf
	s_waitcnt lgkmcnt(2)
	v_pk_fma_f32 v[146:147], v[100:101], v[146:147], v[96:97]
	v_pk_mul_f32 v[64:65], v[64:65], v[68:69]
	s_waitcnt lgkmcnt(1)
	v_pk_fma_f32 v[72:73], v[108:109], v[72:73], v[146:147]
	v_pk_mul_f32 v[84:85], v[84:85], v[184:185] op_sel_hi:[1,0]
	s_waitcnt lgkmcnt(0)
	v_pk_fma_f32 v[72:73], v[88:89], v[112:113], v[72:73]
	v_pk_mul_f32 v[64:65], v[72:73], v[64:65]
	v_mov_b32_dpp v72, v92 row_ror:2 row_mask:0xf bank_mask:0xf
	v_mov_b32_dpp v73, v93 row_ror:2 row_mask:0xf bank_mask:0xf
	v_mov_b32_dpp v68, v92 row_ror:1 row_mask:0xf bank_mask:0xf
	v_mov_b32_dpp v69, v93 row_ror:1 row_mask:0xf bank_mask:0xf
	v_mov_b32_dpp v72, v84 row_shr:2 row_mask:0xf bank_mask:0xf
	v_mov_b32_dpp v73, v85 row_shr:2 row_mask:0xf bank_mask:0xf
	v_mov_b32_dpp v68, v84 row_shr:1 row_mask:0xf bank_mask:0xf
	v_mov_b32_dpp v69, v85 row_shr:1 row_mask:0xf bank_mask:0xf
	v_pk_fma_f32 v[72:73], v[116:117], v[72:73], v[104:105]
	v_pk_fma_f32 v[68:69], v[120:121], v[68:69], v[72:73]
	v_pk_fma_f32 v[68:69], v[84:85], v[124:125], v[68:69]
	v_pk_mul_f32 v[80:81], v[80:81], v[184:185] op_sel_hi:[1,0]
	v_pk_mul_f32 v[72:73], v[68:69], s[2:3] op_sel_hi:[1,0]
	v_exp_f32_e32 v72, v72
	v_exp_f32_e32 v73, v73
	v_mov_b32_dpp v146, v88 row_ror:2 row_mask:0xf bank_mask:0xf
	v_mov_b32_dpp v147, v89 row_ror:2 row_mask:0xf bank_mask:0xf
	v_pk_add_f32 v[72:73], v[72:73], 1.0 op_sel_hi:[1,0]
	v_mov_b32_dpp v92, v88 row_ror:1 row_mask:0xf bank_mask:0xf
	v_rcp_f32_e32 v72, v72
	v_rcp_f32_e32 v73, v73
	v_mov_b32_dpp v93, v89 row_ror:1 row_mask:0xf bank_mask:0xf
	v_mov_b32_dpp v146, v80 row_shr:2 row_mask:0xf bank_mask:0xf
	v_mov_b32_dpp v147, v81 row_shr:2 row_mask:0xf bank_mask:0xf
	v_mov_b32_dpp v92, v80 row_shr:1 row_mask:0xf bank_mask:0xf
	v_mov_b32_dpp v93, v81 row_shr:1 row_mask:0xf bank_mask:0xf
	v_pk_fma_f32 v[88:89], v[100:101], v[146:147], v[96:97]
	v_pk_mul_f32 v[68:69], v[68:69], v[72:73]
; DI unsigned pk2(float lo, float hi) { f32x2 v = {lo, hi}; bf16x2_t b = __builtin_convertvector(v, bf16x2_t); return __builtin_bit_cast(unsigned, b); }
;     DI void operator()(const AccT& acc, const Unit& u, int wr, int wc, int fr, int fq) const {
;     ...
;                     for (int m = 0; m < 4; ++m) { G[m] = (f32x2){acc[ai][0][m][n][2 * jp], acc[ai][0][m][n][2 * jp + 1]} * rs[m]; V[m] = (f32x2){acc[ai][1][m][n][2 * jp], acc[ai][1][m][n][2 * jp + 1]} * rs[m]; }
; #pragma unroll
;                     for (int m = 0; m < 4; ++m) {
;                         const f32x2 zz = {0.f, 0.f}; const f32x2 Gp = m ? G[m - 1] : zz, Vp = m ? V[m - 1] : zz;
;                         const f32x2 gp1 = {dpp_prev1(G[m].x, Gp.x), dpp_prev1(G[m].y, Gp.y)}, gp2 = {dpp_prev2(G[m].x, Gp.x), dpp_prev2(G[m].y, Gp.y)};
;                         const f32x2 vp1 = {dpp_prev1(V[m].x, Vp.x), dpp_prev1(V[m].y, Vp.y)}, vp2 = {dpp_prev2(V[m].x, Vp.x), dpp_prev2(V[m].y, Vp.y)};
;                         const f32x2 gc = bg + g0 * gp2 + g1 * gp1 + g2 * G[m];
;                         const f32x2 vc = bv + v0 * vp2 + v1 * vp1 + v2 * V[m];
;                         const f32x2 xe = gc * (-LOG2E);
;                         f32x2 dn = {__builtin_amdgcn_exp2f(xe.x), __builtin_amdgcn_exp2f(xe.y)}; dn = dn + 1.0f;
;                         const f32x2 rc = {__builtin_amdgcn_rcpf(dn.x), __builtin_amdgcn_rcpf(dn.y)};
;                         const f32x2 rr = gc * rc * vc;
;                         wpk[m][jp] = pk2(rr.x, rr.y); }
	v_pk_fma_f32 v[88:89], v[108:109], v[92:93], v[88:89]
	v_pk_mul_f32 v[76:77], v[76:77], v[182:183] op_sel_hi:[1,0]
	v_pk_fma_f32 v[88:89], v[80:81], v[112:113], v[88:89]
	v_pk_mul_f32 v[68:69], v[88:89], v[68:69]
	v_mov_b32_dpp v88, v84 row_ror:2 row_mask:0xf bank_mask:0xf
	v_mov_b32_dpp v89, v85 row_ror:2 row_mask:0xf bank_mask:0xf
	v_mov_b32_dpp v72, v84 row_ror:1 row_mask:0xf bank_mask:0xf
	v_mov_b32_dpp v73, v85 row_ror:1 row_mask:0xf bank_mask:0xf
	v_mov_b32_dpp v88, v76 row_shr:2 row_mask:0xf bank_mask:0xf
	v_mov_b32_dpp v89, v77 row_shr:2 row_mask:0xf bank_mask:0xf
	v_mov_b32_dpp v72, v76 row_shr:1 row_mask:0xf bank_mask:0xf
	v_mov_b32_dpp v73, v77 row_shr:1 row_mask:0xf bank_mask:0xf
	v_pk_fma_f32 v[88:89], v[116:117], v[88:89], v[104:105]
	v_pk_fma_f32 v[72:73], v[120:121], v[72:73], v[88:89]
	v_pk_fma_f32 v[72:73], v[76:77], v[124:125], v[72:73]
	v_pk_mul_f32 v[88:89], v[72:73], s[2:3] op_sel_hi:[1,0]
	v_exp_f32_e32 v88, v88
	v_exp_f32_e32 v89, v89
	v_mov_b32_dpp v84, v80 row_ror:1 row_mask:0xf bank_mask:0xf
	v_mov_b32_dpp v85, v81 row_ror:1 row_mask:0xf bank_mask:0xf
	v_mov_b32_dpp v92, v80 row_ror:2 row_mask:0xf bank_mask:0xf
	v_mov_b32_dpp v93, v81 row_ror:2 row_mask:0xf bank_mask:0xf
	v_pk_add_f32 v[80:81], v[88:89], 1.0 op_sel_hi:[1,0]
	v_mov_b32_dpp v92, v140 row_shr:2 row_mask:0xf bank_mask:0xf
	v_rcp_f32_e32 v80, v80
	v_rcp_f32_e32 v81, v81
	v_mov_b32_dpp v93, v141 row_shr:2 row_mask:0xf bank_mask:0xf
	v_mov_b32_dpp v84, v140 row_shr:1 row_mask:0xf bank_mask:0xf
	v_mov_b32_dpp v85, v141 row_shr:1 row_mask:0xf bank_mask:0xf
	v_pk_fma_f32 v[88:89], v[100:101], v[92:93], v[96:97]
	v_pk_mul_f32 v[72:73], v[72:73], v[80:81]
	v_pk_fma_f32 v[84:85], v[108:109], v[84:85], v[88:89]
	v_pk_fma_f32 v[84:85], v[140:141], v[112:113], v[84:85]
	v_pk_mul_f32 v[72:73], v[84:85], v[72:73]
	v_mov_b32_dpp v80, v76 row_ror:1 row_mask:0xf bank_mask:0xf
	v_mov_b32_dpp v84, v76 row_ror:2 row_mask:0xf bank_mask:0xf
	v_mov_b32_dpp v85, v77 row_ror:2 row_mask:0xf bank_mask:0xf
	v_mov_b32_dpp v81, v77 row_ror:1 row_mask:0xf bank_mask:0xf
	v_mov_b32_dpp v84, v142 row_shr:2 row_mask:0xf bank_mask:0xf
	v_mov_b32_dpp v85, v143 row_shr:2 row_mask:0xf bank_mask:0xf
	v_mov_b32_dpp v80, v142 row_shr:1 row_mask:0xf bank_mask:0xf
	v_mov_b32_dpp v81, v143 row_shr:1 row_mask:0xf bank_mask:0xf
	v_pk_fma_f32 v[84:85], v[116:117], v[84:85], v[104:105]
	v_pk_fma_f32 v[80:81], v[120:121], v[80:81], v[84:85]
	v_pk_fma_f32 v[80:81], v[142:143], v[124:125], v[80:81]
	v_pk_mul_f32 v[84:85], v[80:81], s[2:3] op_sel_hi:[1,0]
	v_exp_f32_e32 v84, v84
	v_exp_f32_e32 v85, v85
	v_mov_b32_dpp v88, v140 row_ror:2 row_mask:0xf bank_mask:0xf
	v_mov_b32_dpp v89, v141 row_ror:2 row_mask:0xf bank_mask:0xf
	v_mov_b32_dpp v76, v140 row_ror:1 row_mask:0xf bank_mask:0xf
	v_pk_add_f32 v[84:85], v[84:85], 1.0 op_sel_hi:[1,0]
	v_mov_b32_dpp v77, v141 row_ror:1 row_mask:0xf bank_mask:0xf
	v_rcp_f32_e32 v84, v84
	v_rcp_f32_e32 v85, v85
	v_mov_b32_dpp v88, v144 row_shr:2 row_mask:0xf bank_mask:0xf
	v_mov_b32_dpp v89, v145 row_shr:2 row_mask:0xf bank_mask:0xf
	v_mov_b32_dpp v76, v144 row_shr:1 row_mask:0xf bank_mask:0xf
	v_mov_b32_dpp v77, v145 row_shr:1 row_mask:0xf bank_mask:0xf
	v_pk_fma_f32 v[88:89], v[100:101], v[88:89], v[96:97]
	v_pk_mul_f32 v[80:81], v[80:81], v[84:85]
	v_pk_fma_f32 v[76:77], v[108:109], v[76:77], v[88:89]
	v_pk_mul_f32 v[84:85], v[90:91], v[186:187] op_sel_hi:[1,0]
	v_pk_fma_f32 v[76:77], v[144:145], v[112:113], v[76:77]
	v_mov_b32_e32 v90, v183
	v_pk_mul_f32 v[76:77], v[76:77], v[80:81]
	v_pk_mul_f32 v[80:81], v[94:95], v[186:187] op_sel_hi:[1,0]
	v_mov_b32_e32 v91, v183
	v_mov_b32_e32 v88, v181
	v_mov_b32_e32 v89, v181
	v_mov_b32_dpp v90, v80 row_shr:2 row_mask:0xf bank_mask:0xf
	v_mov_b32_dpp v91, v81 row_shr:2 row_mask:0xf bank_mask:0xf
	v_mov_b32_dpp v88, v80 row_shr:1 row_mask:0xf bank_mask:0xf
	v_mov_b32_dpp v89, v81 row_shr:1 row_mask:0xf bank_mask:0xf
	v_pk_fma_f32 v[90:91], v[118:119], v[90:91], v[106:107]
	v_mov_b32_e32 v94, v183
	v_pk_fma_f32 v[88:89], v[122:123], v[88:89], v[90:91]
	v_mov_b32_e32 v95, v183
	v_pk_fma_f32 v[88:89], v[80:81], v[126:127], v[88:89]
	v_mov_b32_e32 v92, v181
	v_pk_mul_f32 v[90:91], v[88:89], s[2:3] op_sel_hi:[1,0]
	v_mov_b32_e32 v93, v181
	v_exp_f32_e32 v90, v90
	v_exp_f32_e32 v91, v91
	v_mov_b32_dpp v94, v84 row_shr:2 row_mask:0xf bank_mask:0xf
	v_mov_b32_dpp v95, v85 row_shr:2 row_mask:0xf bank_mask:0xf
	v_mov_b32_dpp v92, v84 row_shr:1 row_mask:0xf bank_mask:0xf
	v_pk_add_f32 v[90:91], v[90:91], 1.0 op_sel_hi:[1,0]
	v_mov_b32_dpp v93, v85 row_shr:1 row_mask:0xf bank_mask:0xf
	v_rcp_f32_e32 v90, v90
	v_rcp_f32_e32 v91, v91
	v_pk_fma_f32 v[94:95], v[102:103], v[94:95], v[98:99]
	v_cvt_pk_bf16_f32 v64, v64, v65
	v_pk_fma_f32 v[92:93], v[110:111], v[92:93], v[94:95]
	v_pk_mul_f32 v[88:89], v[88:89], v[90:91]
	v_pk_fma_f32 v[92:93], v[84:85], v[114:115], v[92:93]
	v_pk_mul_f32 v[88:89], v[92:93], v[88:89]
	v_pk_mul_f32 v[86:87], v[86:87], v[184:185] op_sel_hi:[1,0]
	v_cvt_pk_bf16_f32 v65, v88, v89
	v_mov_b32_dpp v90, v80 row_ror:2 row_mask:0xf bank_mask:0xf
	v_mov_b32_dpp v91, v81 row_ror:2 row_mask:0xf bank_mask:0xf
	v_mov_b32_dpp v88, v80 row_ror:1 row_mask:0xf bank_mask:0xf
	v_mov_b32_dpp v89, v81 row_ror:1 row_mask:0xf bank_mask:0xf
	v_mov_b32_dpp v90, v86 row_shr:2 row_mask:0xf bank_mask:0xf
	v_mov_b32_dpp v91, v87 row_shr:2 row_mask:0xf bank_mask:0xf
	v_mov_b32_dpp v88, v86 row_shr:1 row_mask:0xf bank_mask:0xf
	v_mov_b32_dpp v89, v87 row_shr:1 row_mask:0xf bank_mask:0xf
	v_pk_fma_f32 v[90:91], v[118:119], v[90:91], v[106:107]
	v_pk_fma_f32 v[88:89], v[122:123], v[88:89], v[90:91]
	v_pk_fma_f32 v[88:89], v[86:87], v[126:127], v[88:89]
;     DI void operator()(const AccT& acc, const Unit& u, int wr, int wc, int fr, int fq) const {
;     ...
;             for (int m = 0; m < 4; ++m) { const int t = tok0 + 16 * m; const int tc = t < 0 ? 0 : (t >= S ? S - 1 : t); const float r = rs_from_ss(rowss[tc]); rs[m] = t < 0 ? 0.f : r; }
;             const int row0 = fr < 2 ? (S + 236 + fr) : tok0;
; #pragma unroll
;             for (int n = 0; n < 2; ++n) {
;                 const int lc = 8 * fq + 4 * n;
;                 unsigned wpk[4][2];
; #pragma unroll
;                 for (int jp = 0; jp < 2; ++jp) {
;                     const f32x2 bg = *(const LAS f32x2*)(P + lc + 2 * jp), g0 = *(const LAS f32x2*)(P + 32 + lc + 2 * jp), g1 = *(const LAS f32x2*)(P + 64 + lc + 2 * jp), g2 = *(const LAS f32x2*)(P + 96 + lc + 2 * jp);
;                     const f32x2 bv = *(const LAS f32x2*)(P + 128 + lc + 2 * jp), v0 = *(const LAS f32x2*)(P + 160 + lc + 2 * jp), v1 = *(const LAS f32x2*)(P + 192 + lc + 2 * jp), v2 = *(const LAS f32x2*)(P + 224 + lc + 2 * jp);
;                     f32x2 G[4], V[4];
; #pragma unroll
;                     for (int m = 0; m < 4; ++m) { G[m] = (f32x2){acc[ai][0][m][n][2 * jp], acc[ai][0][m][n][2 * jp + 1]} * rs[m]; V[m] = (f32x2){acc[ai][1][m][n][2 * jp], acc[ai][1][m][n][2 * jp + 1]} * rs[m]; }
; #pragma unroll
;                     for (int m = 0; m < 4; ++m) {
;                         const f32x2 zz = {0.f, 0.f}; const f32x2 Gp = m ? G[m - 1] : zz, Vp = m ? V[m - 1] : zz;
;                         const f32x2 gp1 = {dpp_prev1(G[m].x, Gp.x), dpp_prev1(G[m].y, Gp.y)}, gp2 = {dpp_prev2(G[m].x, Gp.x), dpp_prev2(G[m].y, Gp.y)};
;                         const f32x2 vp1 = {dpp_prev1(V[m].x, Vp.x), dpp_prev1(V[m].y, Vp.y)}, vp2 = {dpp_prev2(V[m].x, Vp.x), dpp_prev2(V[m].y, Vp.y)};
;                         const f32x2 gc = bg + g0 * gp2 + g1 * gp1 + g2 * G[m];
;                         const f32x2 vc = bv + v0 * vp2 + v1 * vp1 + v2 * V[m];
;                         const f32x2 xe = gc * (-LOG2E);
;                         f32x2 dn = {__builtin_amdgcn_exp2f(xe.x), __builtin_amdgcn_exp2f(xe.y)}; dn = dn + 1.0f;
;                         const f32x2 rc = {__builtin_amdgcn_rcpf(dn.x), __builtin_amdgcn_rcpf(dn.y)};
;                         const f32x2 rr = gc * rc * vc;
;                         wpk[m][jp] = pk2(rr.x, rr.y); }
;                 }
; #pragma unroll
	v_pk_mul_f32 v[90:91], v[88:89], s[2:3] op_sel_hi:[1,0]
	v_exp_f32_e32 v90, v90
	v_exp_f32_e32 v91, v91
	v_mov_b32_dpp v80, v84 row_ror:1 row_mask:0xf bank_mask:0xf
	v_mov_b32_dpp v81, v85 row_ror:1 row_mask:0xf bank_mask:0xf
	v_mov_b32_dpp v92, v84 row_ror:2 row_mask:0xf bank_mask:0xf
	v_mov_b32_dpp v93, v85 row_ror:2 row_mask:0xf bank_mask:0xf
	v_pk_add_f32 v[84:85], v[90:91], 1.0 op_sel_hi:[1,0]
	v_pk_mul_f32 v[82:83], v[82:83], v[184:185] op_sel_hi:[1,0]
	v_rcp_f32_e32 v84, v84
	v_rcp_f32_e32 v85, v85
	v_mov_b32_dpp v92, v82 row_shr:2 row_mask:0xf bank_mask:0xf
	v_mov_b32_dpp v93, v83 row_shr:2 row_mask:0xf bank_mask:0xf
	v_mov_b32_dpp v80, v82 row_shr:1 row_mask:0xf bank_mask:0xf
	v_mov_b32_dpp v81, v83 row_shr:1 row_mask:0xf bank_mask:0xf
	v_pk_fma_f32 v[90:91], v[102:103], v[92:93], v[98:99]
	v_pk_mul_f32 v[84:85], v[88:89], v[84:85]
	v_pk_fma_f32 v[80:81], v[110:111], v[80:81], v[90:91]
	v_cvt_pk_bf16_f32 v68, v68, v69
	v_pk_fma_f32 v[80:81], v[82:83], v[114:115], v[80:81]
	v_pk_mul_f32 v[78:79], v[78:79], v[182:183] op_sel_hi:[1,0]
	v_pk_mul_f32 v[80:81], v[80:81], v[84:85]
	v_cvt_pk_bf16_f32 v69, v80, v81
	v_mov_b32_dpp v84, v86 row_ror:2 row_mask:0xf bank_mask:0xf
	v_mov_b32_dpp v85, v87 row_ror:2 row_mask:0xf bank_mask:0xf
	v_mov_b32_dpp v80, v86 row_ror:1 row_mask:0xf bank_mask:0xf
	v_mov_b32_dpp v81, v87 row_ror:1 row_mask:0xf bank_mask:0xf
	v_mov_b32_dpp v84, v78 row_shr:2 row_mask:0xf bank_mask:0xf
	v_mov_b32_dpp v85, v79 row_shr:2 row_mask:0xf bank_mask:0xf
	v_mov_b32_dpp v80, v78 row_shr:1 row_mask:0xf bank_mask:0xf
	v_mov_b32_dpp v81, v79 row_shr:1 row_mask:0xf bank_mask:0xf
	v_pk_fma_f32 v[84:85], v[118:119], v[84:85], v[106:107]
	v_pk_fma_f32 v[80:81], v[122:123], v[80:81], v[84:85]
	v_pk_fma_f32 v[80:81], v[78:79], v[126:127], v[80:81]
	v_pk_mul_f32 v[84:85], v[80:81], s[2:3] op_sel_hi:[1,0]
	v_exp_f32_e32 v84, v84
	v_exp_f32_e32 v85, v85
	v_mov_b32_dpp v86, v82 row_ror:1 row_mask:0xf bank_mask:0xf
	v_mov_b32_dpp v87, v83 row_ror:1 row_mask:0xf bank_mask:0xf
	v_mov_b32_dpp v88, v82 row_ror:2 row_mask:0xf bank_mask:0xf
	v_mov_b32_dpp v89, v83 row_ror:2 row_mask:0xf bank_mask:0xf
	v_pk_add_f32 v[82:83], v[84:85], 1.0 op_sel_hi:[1,0]
	v_pk_mul_f32 v[74:75], v[74:75], v[182:183] op_sel_hi:[1,0]
	v_rcp_f32_e32 v82, v82
	v_rcp_f32_e32 v83, v83
	v_mov_b32_dpp v88, v74 row_shr:2 row_mask:0xf bank_mask:0xf
	v_mov_b32_dpp v89, v75 row_shr:2 row_mask:0xf bank_mask:0xf
	v_mov_b32_dpp v86, v74 row_shr:1 row_mask:0xf bank_mask:0xf
	v_mov_b32_dpp v87, v75 row_shr:1 row_mask:0xf bank_mask:0xf
	v_pk_fma_f32 v[84:85], v[102:103], v[88:89], v[98:99]
	v_pk_mul_f32 v[80:81], v[80:81], v[82:83]
	v_pk_fma_f32 v[84:85], v[110:111], v[86:87], v[84:85]
	v_pk_fma_f32 v[84:85], v[74:75], v[114:115], v[84:85]
	v_pk_mul_f32 v[80:81], v[84:85], v[80:81]
	v_cvt_pk_bf16_f32 v72, v72, v73
	v_pk_mul_f32 v[70:71], v[70:71], v[180:181] op_sel_hi:[1,0]
	v_cvt_pk_bf16_f32 v73, v80, v81
	v_mov_b32_dpp v82, v78 row_ror:2 row_mask:0xf bank_mask:0xf
	v_mov_b32_dpp v83, v79 row_ror:2 row_mask:0xf bank_mask:0xf
	v_mov_b32_dpp v80, v78 row_ror:1 row_mask:0xf bank_mask:0xf
	v_mov_b32_dpp v81, v79 row_ror:1 row_mask:0xf bank_mask:0xf
	v_mov_b32_dpp v82, v70 row_shr:2 row_mask:0xf bank_mask:0xf
	v_mov_b32_dpp v83, v71 row_shr:2 row_mask:0xf bank_mask:0xf
	v_mov_b32_dpp v80, v70 row_shr:1 row_mask:0xf bank_mask:0xf
	v_mov_b32_dpp v81, v71 row_shr:1 row_mask:0xf bank_mask:0xf
	v_pk_fma_f32 v[82:83], v[118:119], v[82:83], v[106:107]
	v_pk_fma_f32 v[80:81], v[122:123], v[80:81], v[82:83]
	v_pk_fma_f32 v[70:71], v[70:71], v[126:127], v[80:81]
	v_pk_mul_f32 v[80:81], v[70:71], s[2:3] op_sel_hi:[1,0]
	v_exp_f32_e32 v80, v80
	v_exp_f32_e32 v81, v81
	v_mov_b32_dpp v78, v74 row_ror:1 row_mask:0xf bank_mask:0xf
	v_mov_b32_dpp v79, v75 row_ror:1 row_mask:0xf bank_mask:0xf
	v_mov_b32_dpp v84, v74 row_ror:2 row_mask:0xf bank_mask:0xf
	v_mov_b32_dpp v85, v75 row_ror:2 row_mask:0xf bank_mask:0xf
	v_pk_add_f32 v[74:75], v[80:81], 1.0 op_sel_hi:[1,0]
	v_pk_mul_f32 v[66:67], v[66:67], v[180:181] op_sel_hi:[1,0]
	v_rcp_f32_e32 v74, v74
	v_rcp_f32_e32 v75, v75
	v_mov_b32_dpp v84, v66 row_shr:2 row_mask:0xf bank_mask:0xf
	v_mov_b32_dpp v85, v67 row_shr:2 row_mask:0xf bank_mask:0xf
	v_mov_b32_dpp v78, v66 row_shr:1 row_mask:0xf bank_mask:0xf
	v_mov_b32_dpp v79, v67 row_shr:1 row_mask:0xf bank_mask:0xf
	v_pk_fma_f32 v[80:81], v[102:103], v[84:85], v[98:99]
	v_pk_mul_f32 v[70:71], v[70:71], v[74:75]
	v_pk_fma_f32 v[78:79], v[110:111], v[78:79], v[80:81]
	v_cvt_pk_bf16_f32 v76, v76, v77
	v_pk_fma_f32 v[66:67], v[66:67], v[114:115], v[78:79]
	s_nop 0
	v_pk_mul_f32 v[66:67], v[66:67], v[70:71]
	s_nop 0
	v_cvt_pk_bf16_f32 v77, v66, v67
	global_store_dwordx2 v[132:133], v[64:65], off offset:8
	global_store_dwordx2 v[134:135], v[68:69], off offset:8
	global_store_dwordx2 v[136:137], v[72:73], off offset:8
	global_store_dwordx2 v[138:139], v[76:77], off offset:8
	v_add_u32_e32 v96, 0x7c, v197
	v_med3_i32 v64, v96, 0, s51
	v_add_u32_e32 v97, 0x8c, v197
	v_add_u32_e32 v99, 0x9c, v197
	v_add_u32_e32 v101, 0xac, v197
	v_lshlrev_b32_e32 v64, 3, v64
	v_med3_i32 v65, v97, 0, s51
	v_med3_i32 v66, v99, 0, s51
	v_med3_i32 v67, v101, 0, s51
	v_lshlrev_b32_e32 v65, 3, v65
	v_lshlrev_b32_e32 v66, 3, v66
	v_lshlrev_b32_e32 v67, 3, v67
	global_load_dwordx2 v[104:105], v64, s[18:19]
	global_load_dwordx2 v[106:107], v65, s[18:19]
	global_load_dwordx2 v[108:109], v66, s[18:19]
	global_load_dwordx2 v[110:111], v67, s[18:19]
	v_cndmask_b32_e64 v103, v96, v190, s[4:5]
	v_mov_b32_e32 v112, v181
	v_mov_b32_e32 v113, v181
	ds_read_b128 v[72:75], v193
	ds_read_b128 v[84:87], v193 offset:128
	ds_read_b128 v[88:91], v193 offset:256
	ds_read_b128 v[92:95], v193 offset:384
	ds_read_b128 v[64:67], v193 offset:512
	ds_read_b128 v[68:71], v193 offset:640
	ds_read_b128 v[76:79], v193 offset:768
	ds_read_b128 v[80:83], v193 offset:896
	s_waitcnt vmcnt(3)
; #define LAS __attribute__((address_space(3)))
;     DI void operator()(const AccT& acc, const Unit& u, int wr, int wc, int fr, int fq) const {
;     ...
;             for (int m = 0; m < 4; ++m) { const int t = tok0 + 16 * m; const int tc = t < 0 ? 0 : (t >= S ? S - 1 : t); const float r = rs_from_ss(rowss[tc]); rs[m] = t < 0 ? 0.f : r; }
;             const int row0 = fr < 2 ? (S + 236 + fr) : tok0;
; #pragma unroll
;             for (int n = 0; n < 2; ++n) {
;                 const int lc = 8 * fq + 4 * n;
;                 unsigned wpk[4][2];
; #pragma unroll
;                 for (int jp = 0; jp < 2; ++jp) {
;                     const f32x2 bg = *(const LAS f32x2*)(P + lc + 2 * jp), g0 = *(const LAS f32x2*)(P + 32 + lc + 2 * jp), g1 = *(const LAS f32x2*)(P + 64 + lc + 2 * jp), g2 = *(const LAS f32x2*)(P + 96 + lc + 2 * jp);
;                     const f32x2 bv = *(const LAS f32x2*)(P + 128 + lc + 2 * jp), v0 = *(const LAS f32x2*)(P + 160 + lc + 2 * jp), v1 = *(const LAS f32x2*)(P + 192 + lc + 2 * jp), v2 = *(const LAS f32x2*)(P + 224 + lc + 2 * jp);
;                     f32x2 G[4], V[4];
; #pragma unroll
;                     for (int m = 0; m < 4; ++m) { G[m] = (f32x2){acc[ai][0][m][n][2 * jp], acc[ai][0][m][n][2 * jp + 1]} * rs[m]; V[m] = (f32x2){acc[ai][1][m][n][2 * jp], acc[ai][1][m][n][2 * jp + 1]} * rs[m]; }
; #pragma unroll
;                     for (int m = 0; m < 4; ++m) {
;                         const f32x2 zz = {0.f, 0.f}; const f32x2 Gp = m ? G[m - 1] : zz, Vp = m ? V[m - 1] : zz;
;                         const f32x2 gp1 = {dpp_prev1(G[m].x, Gp.x), dpp_prev1(G[m].y, Gp.y)}, gp2 = {dpp_prev2(G[m].x, Gp.x), dpp_prev2(G[m].y, Gp.y)};
;                         const f32x2 vp1 = {dpp_prev1(V[m].x, Vp.x), dpp_prev1(V[m].y, Vp.y)}, vp2 = {dpp_prev2(V[m].x, Vp.x), dpp_prev2(V[m].y, Vp.y)};
;                         const f32x2 gc = bg + g0 * gp2 + g1 * gp1 + g2 * G[m];
;                         const f32x2 vc = bv + v0 * vp2 + v1 * vp1 + v2 * V[m];
;                         const f32x2 xe = gc * (-LOG2E);
;                         f32x2 dn = {__builtin_amdgcn_exp2f(xe.x), __builtin_amdgcn_exp2f(xe.y)}; dn = dn + 1.0f;
;                         const f32x2 rc = {__builtin_amdgcn_rcpf(dn.x), __builtin_amdgcn_rcpf(dn.y)};
;                         const f32x2 rr = gc * rc * vc;
;                         wpk[m][jp] = pk2(rr.x, rr.y); }
	v_ffbh_u32_e32 v98, v105
	s_waitcnt vmcnt(2)
	v_ffbh_u32_e32 v100, v107
	s_waitcnt vmcnt(1)
	v_ffbh_u32_e32 v102, v109
	v_min_u32_e32 v98, 32, v98
	v_min_u32_e32 v100, 32, v100
	v_min_u32_e32 v102, 32, v102
	v_lshlrev_b64 v[104:105], v98, v[104:105]
	s_waitcnt vmcnt(0)
	v_ffbh_u32_e32 v114, v111
	v_lshlrev_b64 v[106:107], v100, v[106:107]
	v_lshlrev_b64 v[108:109], v102, v[108:109]
	v_min_u32_e32 v104, 1, v104
	v_min_u32_e32 v114, 32, v114
	v_min_u32_e32 v106, 1, v106
	v_min_u32_e32 v108, 1, v108
	v_or_b32_e32 v104, v105, v104
	v_lshlrev_b64 v[110:111], v114, v[110:111]
	v_or_b32_e32 v105, v107, v106
	v_or_b32_e32 v106, v109, v108
	v_cvt_f32_u32_e32 v104, v104
	v_min_u32_e32 v110, 1, v110
	v_cvt_f32_u32_e32 v105, v105
	v_cvt_f32_u32_e32 v106, v106
	v_or_b32_e32 v107, v111, v110
	v_sub_u32_e32 v98, 32, v98
	v_cvt_f32_u32_e32 v107, v107
	v_sub_u32_e32 v100, 32, v100
	v_sub_u32_e32 v102, 32, v102
	v_ldexp_f32 v98, v104, v98
	v_ldexp_f32 v100, v105, v100
	v_ldexp_f32 v102, v106, v102
	v_fmamk_f32 v98, v98, 0x30800000, v196
	v_sub_u32_e32 v114, 32, v114
	v_fmamk_f32 v100, v100, 0x30800000, v196
	v_fmamk_f32 v102, v102, 0x30800000, v196
	v_mul_f32_e32 v105, 0x4b800000, v98
	v_cmp_gt_f32_e32 vcc, s52, v98
	v_ldexp_f32 v104, v107, v114
	v_mul_f32_e32 v106, 0x4b800000, v100
	v_mul_f32_e32 v107, 0x4b800000, v102
	v_cndmask_b32_e32 v98, v98, v105, vcc
	v_cmp_gt_f32_e64 s[8:9], s52, v100
	v_cmp_gt_f32_e64 s[10:11], s52, v102
	v_fmamk_f32 v104, v104, 0x30800000, v196
	v_cndmask_b32_e64 v100, v100, v106, s[8:9]
	v_cndmask_b32_e64 v102, v102, v107, s[10:11]
	v_rsq_f32_e32 v98, v98
	v_mul_f32_e32 v108, 0x4b800000, v104
	v_cmp_gt_f32_e64 s[12:13], s52, v104
	v_rsq_f32_e32 v100, v100
	v_rsq_f32_e32 v102, v102
	v_cndmask_b32_e64 v104, v104, v108, s[12:13]
	v_rsq_f32_e32 v104, v104
	v_mul_f32_e32 v105, 0x45800000, v98
	v_mul_f32_e32 v106, 0x45800000, v100
	v_mul_f32_e32 v107, 0x45800000, v102
	v_cndmask_b32_e32 v98, v98, v105, vcc
	v_cmp_lt_i32_e32 vcc, -1, v96
	v_cndmask_b32_e64 v100, v100, v106, s[8:9]
	v_cndmask_b32_e64 v105, v102, v107, s[10:11]
	v_cndmask_b32_e32 v102, 0, v98, vcc
	v_cmp_lt_i32_e32 vcc, s53, v96
	v_mul_f32_e32 v108, 0x45800000, v104
	v_cndmask_b32_e64 v104, v104, v108, s[12:13]
	v_cndmask_b32_e32 v100, 0, v100, vcc
	v_cmp_lt_i32_e32 vcc, s54, v96
	v_pk_mul_f32 v[60:61], v[60:61], v[102:103] op_sel_hi:[1,0]
	v_pk_mul_f32 v[56:57], v[56:57], v[102:103] op_sel_hi:[1,0]
	v_cndmask_b32_e32 v98, 0, v105, vcc
	v_cmp_lt_i32_e32 vcc, s55, v96
	v_mov_b32_dpp v112, v60 row_shr:1 row_mask:0xf bank_mask:0xf
	v_mov_b32_dpp v113, v61 row_shr:1 row_mask:0xf bank_mask:0xf
	v_cndmask_b32_e32 v96, 0, v104, vcc
	v_pk_mul_f32 v[108:109], v[32:33], v[96:97] op_sel_hi:[1,0]
	v_mov_b32_e32 v32, v183
	v_mov_b32_e32 v33, v183
	v_pk_mul_f32 v[104:105], v[40:41], v[98:99] op_sel_hi:[1,0]
	v_mov_b32_dpp v32, v60 row_shr:2 row_mask:0xf bank_mask:0xf
	v_mov_b32_dpp v33, v61 row_shr:2 row_mask:0xf bank_mask:0xf
	s_waitcnt lgkmcnt(6)
	v_pk_fma_f32 v[32:33], v[84:85], v[32:33], v[72:73]
	v_mov_b32_e32 v40, v183
	s_waitcnt lgkmcnt(5)
	v_pk_fma_f32 v[32:33], v[88:89], v[112:113], v[32:33]
	v_mov_b32_e32 v41, v183
	s_waitcnt lgkmcnt(4)
	v_pk_fma_f32 v[32:33], v[92:93], v[60:61], v[32:33]
	v_pk_mul_f32 v[106:107], v[36:37], v[96:97] op_sel_hi:[1,0]
	v_pk_mul_f32 v[110:111], v[32:33], s[2:3] op_sel_hi:[1,0]
	v_mov_b32_e32 v36, v181
	v_exp_f32_e32 v110, v110
	v_exp_f32_e32 v111, v111
	v_mov_b32_e32 v37, v181
	v_mov_b32_dpp v40, v56 row_shr:2 row_mask:0xf bank_mask:0xf
	v_mov_b32_dpp v41, v57 row_shr:2 row_mask:0xf bank_mask:0xf
	v_pk_add_f32 v[110:111], v[110:111], 1.0 op_sel_hi:[1,0]
	v_mov_b32_dpp v36, v56 row_shr:1 row_mask:0xf bank_mask:0xf
	v_rcp_f32_e32 v110, v110
	v_rcp_f32_e32 v111, v111
	v_mov_b32_dpp v37, v57 row_shr:1 row_mask:0xf bank_mask:0xf
	s_waitcnt lgkmcnt(2)
	v_pk_fma_f32 v[40:41], v[68:69], v[40:41], v[64:65]
	v_pk_mul_f32 v[52:53], v[52:53], v[100:101] op_sel_hi:[1,0]
	s_waitcnt lgkmcnt(1)
	v_pk_fma_f32 v[36:37], v[76:77], v[36:37], v[40:41]
	v_pk_mul_f32 v[32:33], v[32:33], v[110:111]
	s_waitcnt lgkmcnt(0)
	v_pk_fma_f32 v[36:37], v[80:81], v[56:57], v[36:37]
	v_pk_mul_f32 v[32:33], v[36:37], v[32:33]
	v_mov_b32_dpp v40, v60 row_ror:2 row_mask:0xf bank_mask:0xf
	v_mov_b32_dpp v41, v61 row_ror:2 row_mask:0xf bank_mask:0xf
	v_mov_b32_dpp v36, v60 row_ror:1 row_mask:0xf bank_mask:0xf
	v_mov_b32_dpp v37, v61 row_ror:1 row_mask:0xf bank_mask:0xf
	v_mov_b32_dpp v40, v52 row_shr:2 row_mask:0xf bank_mask:0xf
	v_mov_b32_dpp v41, v53 row_shr:2 row_mask:0xf bank_mask:0xf
	v_mov_b32_dpp v36, v52 row_shr:1 row_mask:0xf bank_mask:0xf
	v_mov_b32_dpp v37, v53 row_shr:1 row_mask:0xf bank_mask:0xf
	v_pk_fma_f32 v[40:41], v[84:85], v[40:41], v[72:73]
	v_pk_fma_f32 v[36:37], v[88:89], v[36:37], v[40:41]
	v_pk_fma_f32 v[36:37], v[92:93], v[52:53], v[36:37]
	v_pk_mul_f32 v[48:49], v[48:49], v[100:101] op_sel_hi:[1,0]
	v_pk_mul_f32 v[40:41], v[36:37], s[2:3] op_sel_hi:[1,0]
	v_exp_f32_e32 v40, v40
	v_exp_f32_e32 v41, v41
	v_mov_b32_dpp v110, v56 row_ror:2 row_mask:0xf bank_mask:0xf
	v_mov_b32_dpp v111, v57 row_ror:2 row_mask:0xf bank_mask:0xf
	v_pk_add_f32 v[40:41], v[40:41], 1.0 op_sel_hi:[1,0]
	v_mov_b32_dpp v60, v56 row_ror:1 row_mask:0xf bank_mask:0xf
	v_rcp_f32_e32 v40, v40
	v_rcp_f32_e32 v41, v41
	v_mov_b32_dpp v61, v57 row_ror:1 row_mask:0xf bank_mask:0xf
	v_mov_b32_dpp v110, v48 row_shr:2 row_mask:0xf bank_mask:0xf
	v_mov_b32_dpp v111, v49 row_shr:2 row_mask:0xf bank_mask:0xf
	v_mov_b32_dpp v60, v48 row_shr:1 row_mask:0xf bank_mask:0xf
	v_mov_b32_dpp v61, v49 row_shr:1 row_mask:0xf bank_mask:0xf
	v_pk_fma_f32 v[56:57], v[68:69], v[110:111], v[64:65]
; DI unsigned pk2(float lo, float hi) { f32x2 v = {lo, hi}; bf16x2_t b = __builtin_convertvector(v, bf16x2_t); return __builtin_bit_cast(unsigned, b); }
;     DI void operator()(const AccT& acc, const Unit& u, int wr, int wc, int fr, int fq) const {
;     ...
;                     for (int m = 0; m < 4; ++m) { G[m] = (f32x2){acc[ai][0][m][n][2 * jp], acc[ai][0][m][n][2 * jp + 1]} * rs[m]; V[m] = (f32x2){acc[ai][1][m][n][2 * jp], acc[ai][1][m][n][2 * jp + 1]} * rs[m]; }
; #pragma unroll
;                     for (int m = 0; m < 4; ++m) {
;                         const f32x2 zz = {0.f, 0.f}; const f32x2 Gp = m ? G[m - 1] : zz, Vp = m ? V[m - 1] : zz;
;                         const f32x2 gp1 = {dpp_prev1(G[m].x, Gp.x), dpp_prev1(G[m].y, Gp.y)}, gp2 = {dpp_prev2(G[m].x, Gp.x), dpp_prev2(G[m].y, Gp.y)};
;                         const f32x2 vp1 = {dpp_prev1(V[m].x, Vp.x), dpp_prev1(V[m].y, Vp.y)}, vp2 = {dpp_prev2(V[m].x, Vp.x), dpp_prev2(V[m].y, Vp.y)};
;                         const f32x2 gc = bg + g0 * gp2 + g1 * gp1 + g2 * G[m];
;                         const f32x2 vc = bv + v0 * vp2 + v1 * vp1 + v2 * V[m];
;                         const f32x2 xe = gc * (-LOG2E);
;                         f32x2 dn = {__builtin_amdgcn_exp2f(xe.x), __builtin_amdgcn_exp2f(xe.y)}; dn = dn + 1.0f;
;                         const f32x2 rc = {__builtin_amdgcn_rcpf(dn.x), __builtin_amdgcn_rcpf(dn.y)};
;                         const f32x2 rr = gc * rc * vc;
;                         wpk[m][jp] = pk2(rr.x, rr.y); }
	v_pk_mul_f32 v[36:37], v[36:37], v[40:41]
	v_pk_fma_f32 v[56:57], v[76:77], v[60:61], v[56:57]
	v_pk_mul_f32 v[44:45], v[44:45], v[98:99] op_sel_hi:[1,0]
	v_pk_fma_f32 v[56:57], v[80:81], v[48:49], v[56:57]
	v_pk_mul_f32 v[36:37], v[56:57], v[36:37]
	v_mov_b32_dpp v56, v52 row_ror:2 row_mask:0xf bank_mask:0xf
	v_mov_b32_dpp v57, v53 row_ror:2 row_mask:0xf bank_mask:0xf
	v_mov_b32_dpp v40, v52 row_ror:1 row_mask:0xf bank_mask:0xf
	v_mov_b32_dpp v41, v53 row_ror:1 row_mask:0xf bank_mask:0xf
	v_mov_b32_dpp v56, v44 row_shr:2 row_mask:0xf bank_mask:0xf
	v_mov_b32_dpp v57, v45 row_shr:2 row_mask:0xf bank_mask:0xf
	v_mov_b32_dpp v40, v44 row_shr:1 row_mask:0xf bank_mask:0xf
	v_mov_b32_dpp v41, v45 row_shr:1 row_mask:0xf bank_mask:0xf
	v_pk_fma_f32 v[56:57], v[84:85], v[56:57], v[72:73]
	v_pk_fma_f32 v[40:41], v[88:89], v[40:41], v[56:57]
	v_pk_fma_f32 v[40:41], v[92:93], v[44:45], v[40:41]
	v_pk_mul_f32 v[56:57], v[40:41], s[2:3] op_sel_hi:[1,0]
	v_exp_f32_e32 v56, v56
	v_exp_f32_e32 v57, v57
	v_mov_b32_dpp v52, v48 row_ror:1 row_mask:0xf bank_mask:0xf
	v_mov_b32_dpp v53, v49 row_ror:1 row_mask:0xf bank_mask:0xf
	v_mov_b32_dpp v60, v48 row_ror:2 row_mask:0xf bank_mask:0xf
	v_mov_b32_dpp v61, v49 row_ror:2 row_mask:0xf bank_mask:0xf
	v_pk_add_f32 v[48:49], v[56:57], 1.0 op_sel_hi:[1,0]
	v_mov_b32_dpp v60, v104 row_shr:2 row_mask:0xf bank_mask:0xf
	v_rcp_f32_e32 v48, v48
	v_rcp_f32_e32 v49, v49
	v_mov_b32_dpp v61, v105 row_shr:2 row_mask:0xf bank_mask:0xf
	v_mov_b32_dpp v52, v104 row_shr:1 row_mask:0xf bank_mask:0xf
	v_mov_b32_dpp v53, v105 row_shr:1 row_mask:0xf bank_mask:0xf
	v_pk_fma_f32 v[56:57], v[68:69], v[60:61], v[64:65]
	v_pk_mul_f32 v[40:41], v[40:41], v[48:49]
	v_pk_fma_f32 v[52:53], v[76:77], v[52:53], v[56:57]
	v_pk_fma_f32 v[52:53], v[80:81], v[104:105], v[52:53]
	v_pk_mul_f32 v[40:41], v[52:53], v[40:41]
	v_mov_b32_dpp v48, v44 row_ror:1 row_mask:0xf bank_mask:0xf
	v_mov_b32_dpp v52, v44 row_ror:2 row_mask:0xf bank_mask:0xf
	v_mov_b32_dpp v53, v45 row_ror:2 row_mask:0xf bank_mask:0xf
	v_mov_b32_dpp v49, v45 row_ror:1 row_mask:0xf bank_mask:0xf
	v_mov_b32_dpp v52, v106 row_shr:2 row_mask:0xf bank_mask:0xf
	v_mov_b32_dpp v53, v107 row_shr:2 row_mask:0xf bank_mask:0xf
	v_mov_b32_dpp v48, v106 row_shr:1 row_mask:0xf bank_mask:0xf
	v_mov_b32_dpp v49, v107 row_shr:1 row_mask:0xf bank_mask:0xf
	v_pk_fma_f32 v[52:53], v[84:85], v[52:53], v[72:73]
	v_pk_fma_f32 v[48:49], v[88:89], v[48:49], v[52:53]
	v_pk_fma_f32 v[48:49], v[92:93], v[106:107], v[48:49]
	v_pk_mul_f32 v[52:53], v[48:49], s[2:3] op_sel_hi:[1,0]
	v_exp_f32_e32 v52, v52
	v_exp_f32_e32 v53, v53
	v_mov_b32_dpp v56, v104 row_ror:2 row_mask:0xf bank_mask:0xf
	v_mov_b32_dpp v57, v105 row_ror:2 row_mask:0xf bank_mask:0xf
	v_mov_b32_dpp v44, v104 row_ror:1 row_mask:0xf bank_mask:0xf
	v_pk_add_f32 v[52:53], v[52:53], 1.0 op_sel_hi:[1,0]
	v_mov_b32_dpp v45, v105 row_ror:1 row_mask:0xf bank_mask:0xf
	v_rcp_f32_e32 v52, v52
	v_rcp_f32_e32 v53, v53
	v_mov_b32_dpp v56, v108 row_shr:2 row_mask:0xf bank_mask:0xf
	v_mov_b32_dpp v57, v109 row_shr:2 row_mask:0xf bank_mask:0xf
	v_mov_b32_dpp v44, v108 row_shr:1 row_mask:0xf bank_mask:0xf
	v_mov_b32_dpp v45, v109 row_shr:1 row_mask:0xf bank_mask:0xf
	v_pk_fma_f32 v[56:57], v[68:69], v[56:57], v[64:65]
	v_pk_mul_f32 v[48:49], v[48:49], v[52:53]
	v_pk_fma_f32 v[44:45], v[76:77], v[44:45], v[56:57]
	v_pk_mul_f32 v[52:53], v[58:59], v[102:103] op_sel_hi:[1,0]
	v_pk_fma_f32 v[44:45], v[80:81], v[108:109], v[44:45]
	v_mov_b32_e32 v58, v183
	v_pk_mul_f32 v[44:45], v[44:45], v[48:49]
	v_pk_mul_f32 v[48:49], v[62:63], v[102:103] op_sel_hi:[1,0]
	v_mov_b32_e32 v59, v183
	v_mov_b32_e32 v56, v181
	v_mov_b32_e32 v57, v181
	v_mov_b32_dpp v58, v48 row_shr:2 row_mask:0xf bank_mask:0xf
	v_mov_b32_dpp v59, v49 row_shr:2 row_mask:0xf bank_mask:0xf
	v_mov_b32_dpp v56, v48 row_shr:1 row_mask:0xf bank_mask:0xf
	v_mov_b32_dpp v57, v49 row_shr:1 row_mask:0xf bank_mask:0xf
	v_pk_fma_f32 v[58:59], v[86:87], v[58:59], v[74:75]
	v_mov_b32_e32 v62, v183
	v_pk_fma_f32 v[56:57], v[90:91], v[56:57], v[58:59]
	v_mov_b32_e32 v63, v183
	v_pk_fma_f32 v[56:57], v[48:49], v[94:95], v[56:57]
	v_mov_b32_e32 v60, v181
	v_pk_mul_f32 v[58:59], v[56:57], s[2:3] op_sel_hi:[1,0]
	v_mov_b32_e32 v61, v181
	v_exp_f32_e32 v58, v58
	v_exp_f32_e32 v59, v59
	v_mov_b32_dpp v62, v52 row_shr:2 row_mask:0xf bank_mask:0xf
	v_mov_b32_dpp v63, v53 row_shr:2 row_mask:0xf bank_mask:0xf
	v_mov_b32_dpp v60, v52 row_shr:1 row_mask:0xf bank_mask:0xf
	v_pk_add_f32 v[58:59], v[58:59], 1.0 op_sel_hi:[1,0]
	v_mov_b32_dpp v61, v53 row_shr:1 row_mask:0xf bank_mask:0xf
	v_rcp_f32_e32 v58, v58
	v_rcp_f32_e32 v59, v59
	v_pk_fma_f32 v[62:63], v[70:71], v[62:63], v[66:67]
	v_cvt_pk_bf16_f32 v32, v32, v33
	v_pk_fma_f32 v[60:61], v[78:79], v[60:61], v[62:63]
	v_pk_mul_f32 v[56:57], v[56:57], v[58:59]
	v_pk_fma_f32 v[60:61], v[52:53], v[82:83], v[60:61]
	v_pk_mul_f32 v[56:57], v[60:61], v[56:57]
	v_pk_mul_f32 v[54:55], v[54:55], v[100:101] op_sel_hi:[1,0]
	v_cvt_pk_bf16_f32 v33, v56, v57
	v_mov_b32_dpp v58, v48 row_ror:2 row_mask:0xf bank_mask:0xf
	v_mov_b32_dpp v59, v49 row_ror:2 row_mask:0xf bank_mask:0xf
	v_mov_b32_dpp v56, v48 row_ror:1 row_mask:0xf bank_mask:0xf
	v_mov_b32_dpp v57, v49 row_ror:1 row_mask:0xf bank_mask:0xf
	v_mov_b32_dpp v58, v54 row_shr:2 row_mask:0xf bank_mask:0xf
	v_mov_b32_dpp v59, v55 row_shr:2 row_mask:0xf bank_mask:0xf
	v_mov_b32_dpp v56, v54 row_shr:1 row_mask:0xf bank_mask:0xf
	v_mov_b32_dpp v57, v55 row_shr:1 row_mask:0xf bank_mask:0xf
	v_pk_fma_f32 v[58:59], v[86:87], v[58:59], v[74:75]
	v_pk_fma_f32 v[56:57], v[90:91], v[56:57], v[58:59]
	v_pk_fma_f32 v[56:57], v[54:55], v[94:95], v[56:57]
; DI unsigned pk2(float lo, float hi) { f32x2 v = {lo, hi}; bf16x2_t b = __builtin_convertvector(v, bf16x2_t); return __builtin_bit_cast(unsigned, b); }
;     DI void operator()(const AccT& acc, const Unit& u, int wr, int wc, int fr, int fq) const {
;     ...
;                     for (int m = 0; m < 4; ++m) { G[m] = (f32x2){acc[ai][0][m][n][2 * jp], acc[ai][0][m][n][2 * jp + 1]} * rs[m]; V[m] = (f32x2){acc[ai][1][m][n][2 * jp], acc[ai][1][m][n][2 * jp + 1]} * rs[m]; }
; #pragma unroll
;                     for (int m = 0; m < 4; ++m) {
;                         const f32x2 zz = {0.f, 0.f}; const f32x2 Gp = m ? G[m - 1] : zz, Vp = m ? V[m - 1] : zz;
;                         const f32x2 gp1 = {dpp_prev1(G[m].x, Gp.x), dpp_prev1(G[m].y, Gp.y)}, gp2 = {dpp_prev2(G[m].x, Gp.x), dpp_prev2(G[m].y, Gp.y)};
;                         const f32x2 vp1 = {dpp_prev1(V[m].x, Vp.x), dpp_prev1(V[m].y, Vp.y)}, vp2 = {dpp_prev2(V[m].x, Vp.x), dpp_prev2(V[m].y, Vp.y)};
;                         const f32x2 gc = bg + g0 * gp2 + g1 * gp1 + g2 * G[m];
;                         const f32x2 vc = bv + v0 * vp2 + v1 * vp1 + v2 * V[m];
;                         const f32x2 xe = gc * (-LOG2E);
;                         f32x2 dn = {__builtin_amdgcn_exp2f(xe.x), __builtin_amdgcn_exp2f(xe.y)}; dn = dn + 1.0f;
;                         const f32x2 rc = {__builtin_amdgcn_rcpf(dn.x), __builtin_amdgcn_rcpf(dn.y)};
;                         const f32x2 rr = gc * rc * vc;
;                         wpk[m][jp] = pk2(rr.x, rr.y); }
;                 }
; #pragma unroll
;                 for (int m = 0; m < 4; ++m) { const int row = m ? tok0 + 16 * m : row0;
;                     *(u32x2*)(ACT + (size_t)row * 2816 + cl + 4 * n) = (u32x2){wpk[m][0], wpk[m][1]}; }
	v_pk_mul_f32 v[58:59], v[56:57], s[2:3] op_sel_hi:[1,0]
	v_exp_f32_e32 v58, v58
	v_exp_f32_e32 v59, v59
	v_mov_b32_dpp v48, v52 row_ror:1 row_mask:0xf bank_mask:0xf
	v_mov_b32_dpp v49, v53 row_ror:1 row_mask:0xf bank_mask:0xf
	v_mov_b32_dpp v60, v52 row_ror:2 row_mask:0xf bank_mask:0xf
	v_mov_b32_dpp v61, v53 row_ror:2 row_mask:0xf bank_mask:0xf
	v_pk_add_f32 v[52:53], v[58:59], 1.0 op_sel_hi:[1,0]
	v_pk_mul_f32 v[50:51], v[50:51], v[100:101] op_sel_hi:[1,0]
	v_rcp_f32_e32 v52, v52
	v_rcp_f32_e32 v53, v53
	v_mov_b32_dpp v60, v50 row_shr:2 row_mask:0xf bank_mask:0xf
	v_mov_b32_dpp v61, v51 row_shr:2 row_mask:0xf bank_mask:0xf
	v_mov_b32_dpp v48, v50 row_shr:1 row_mask:0xf bank_mask:0xf
	v_mov_b32_dpp v49, v51 row_shr:1 row_mask:0xf bank_mask:0xf
	v_pk_fma_f32 v[58:59], v[70:71], v[60:61], v[66:67]
	v_pk_mul_f32 v[52:53], v[56:57], v[52:53]
	v_pk_fma_f32 v[48:49], v[78:79], v[48:49], v[58:59]
	v_cvt_pk_bf16_f32 v36, v36, v37
	v_pk_fma_f32 v[48:49], v[50:51], v[82:83], v[48:49]
	v_pk_mul_f32 v[46:47], v[46:47], v[98:99] op_sel_hi:[1,0]
	v_pk_mul_f32 v[48:49], v[48:49], v[52:53]
	v_cvt_pk_bf16_f32 v37, v48, v49
	v_mov_b32_dpp v52, v54 row_ror:2 row_mask:0xf bank_mask:0xf
	v_mov_b32_dpp v53, v55 row_ror:2 row_mask:0xf bank_mask:0xf
	v_mov_b32_dpp v48, v54 row_ror:1 row_mask:0xf bank_mask:0xf
	v_mov_b32_dpp v49, v55 row_ror:1 row_mask:0xf bank_mask:0xf
	v_mov_b32_dpp v52, v46 row_shr:2 row_mask:0xf bank_mask:0xf
	v_mov_b32_dpp v53, v47 row_shr:2 row_mask:0xf bank_mask:0xf
	v_mov_b32_dpp v48, v46 row_shr:1 row_mask:0xf bank_mask:0xf
	v_mov_b32_dpp v49, v47 row_shr:1 row_mask:0xf bank_mask:0xf
	v_pk_fma_f32 v[52:53], v[86:87], v[52:53], v[74:75]
	v_pk_fma_f32 v[48:49], v[90:91], v[48:49], v[52:53]
	v_pk_fma_f32 v[48:49], v[46:47], v[94:95], v[48:49]
	v_pk_mul_f32 v[52:53], v[48:49], s[2:3] op_sel_hi:[1,0]
	v_exp_f32_e32 v52, v52
	v_exp_f32_e32 v53, v53
	v_mov_b32_dpp v54, v50 row_ror:1 row_mask:0xf bank_mask:0xf
	v_mov_b32_dpp v55, v51 row_ror:1 row_mask:0xf bank_mask:0xf
	v_mov_b32_dpp v56, v50 row_ror:2 row_mask:0xf bank_mask:0xf
	v_mov_b32_dpp v57, v51 row_ror:2 row_mask:0xf bank_mask:0xf
	v_pk_add_f32 v[50:51], v[52:53], 1.0 op_sel_hi:[1,0]
	v_pk_mul_f32 v[42:43], v[42:43], v[98:99] op_sel_hi:[1,0]
	v_rcp_f32_e32 v50, v50
	v_rcp_f32_e32 v51, v51
	v_mov_b32_dpp v56, v42 row_shr:2 row_mask:0xf bank_mask:0xf
	v_mov_b32_dpp v57, v43 row_shr:2 row_mask:0xf bank_mask:0xf
	v_mov_b32_dpp v54, v42 row_shr:1 row_mask:0xf bank_mask:0xf
	v_mov_b32_dpp v55, v43 row_shr:1 row_mask:0xf bank_mask:0xf
	v_pk_fma_f32 v[52:53], v[70:71], v[56:57], v[66:67]
	v_pk_mul_f32 v[48:49], v[48:49], v[50:51]
	v_pk_fma_f32 v[52:53], v[78:79], v[54:55], v[52:53]
	v_pk_fma_f32 v[52:53], v[42:43], v[82:83], v[52:53]
	v_pk_mul_f32 v[48:49], v[52:53], v[48:49]
	v_cvt_pk_bf16_f32 v40, v40, v41
	v_pk_mul_f32 v[38:39], v[38:39], v[96:97] op_sel_hi:[1,0]
	v_cvt_pk_bf16_f32 v41, v48, v49
	v_mov_b32_dpp v50, v46 row_ror:2 row_mask:0xf bank_mask:0xf
	v_mov_b32_dpp v51, v47 row_ror:2 row_mask:0xf bank_mask:0xf
	v_mov_b32_dpp v48, v46 row_ror:1 row_mask:0xf bank_mask:0xf
	v_mov_b32_dpp v49, v47 row_ror:1 row_mask:0xf bank_mask:0xf
	v_mov_b32_dpp v50, v38 row_shr:2 row_mask:0xf bank_mask:0xf
	v_mov_b32_dpp v51, v39 row_shr:2 row_mask:0xf bank_mask:0xf
	v_mov_b32_dpp v48, v38 row_shr:1 row_mask:0xf bank_mask:0xf
	v_mov_b32_dpp v49, v39 row_shr:1 row_mask:0xf bank_mask:0xf
	v_pk_fma_f32 v[50:51], v[86:87], v[50:51], v[74:75]
	v_pk_fma_f32 v[48:49], v[90:91], v[48:49], v[50:51]
	v_pk_fma_f32 v[38:39], v[38:39], v[94:95], v[48:49]
	v_pk_mul_f32 v[48:49], v[38:39], s[2:3] op_sel_hi:[1,0]
	v_exp_f32_e32 v48, v48
	v_exp_f32_e32 v49, v49
	v_mov_b32_dpp v46, v42 row_ror:1 row_mask:0xf bank_mask:0xf
	v_mov_b32_dpp v47, v43 row_ror:1 row_mask:0xf bank_mask:0xf
	v_mov_b32_dpp v52, v42 row_ror:2 row_mask:0xf bank_mask:0xf
	v_mov_b32_dpp v53, v43 row_ror:2 row_mask:0xf bank_mask:0xf
	v_pk_add_f32 v[42:43], v[48:49], 1.0 op_sel_hi:[1,0]
	v_pk_mul_f32 v[34:35], v[34:35], v[96:97] op_sel_hi:[1,0]
	v_rcp_f32_e32 v42, v42
	v_rcp_f32_e32 v43, v43
	v_mov_b32_dpp v52, v34 row_shr:2 row_mask:0xf bank_mask:0xf
	v_mov_b32_dpp v53, v35 row_shr:2 row_mask:0xf bank_mask:0xf
	v_mov_b32_dpp v46, v34 row_shr:1 row_mask:0xf bank_mask:0xf
	v_mov_b32_dpp v47, v35 row_shr:1 row_mask:0xf bank_mask:0xf
	v_pk_fma_f32 v[48:49], v[70:71], v[52:53], v[66:67]
	v_pk_mul_f32 v[38:39], v[38:39], v[42:43]
	v_pk_fma_f32 v[46:47], v[78:79], v[46:47], v[48:49]
	v_cvt_pk_bf16_f32 v44, v44, v45
	v_pk_fma_f32 v[34:35], v[34:35], v[82:83], v[46:47]
	s_nop 0
	v_pk_mul_f32 v[34:35], v[34:35], v[38:39]
	s_nop 0
	v_cvt_pk_bf16_f32 v45, v34, v35
	v_mad_i64_i32 v[34:35], s[8:9], v103, s48, v[128:129]
	v_lshl_add_u64 v[64:65], v[34:35], 0, v[130:131]
	global_store_dwordx2 v[64:65], v[32:33], off
	v_mad_i64_i32 v[32:33], s[8:9], v97, s48, v[128:129]
	v_lshl_add_u64 v[66:67], v[32:33], 0, v[130:131]
	v_mad_i64_i32 v[32:33], s[8:9], v99, s48, v[128:129]
	v_lshl_add_u64 v[68:69], v[32:33], 0, v[130:131]
	v_mad_i64_i32 v[32:33], s[8:9], v101, s48, v[128:129]
	v_lshl_add_u64 v[70:71], v[32:33], 0, v[130:131]
	global_store_dwordx2 v[66:67], v[36:37], off
	global_store_dwordx2 v[68:69], v[40:41], off
	global_store_dwordx2 v[70:71], v[44:45], off
	v_pk_mul_f32 v[30:31], v[30:31], v[102:103] op_sel_hi:[1,0]
	v_pk_mul_f32 v[22:23], v[22:23], v[100:101] op_sel_hi:[1,0]
	s_nop 0
	v_mov_b32_dpp v114, v30 row_ror:2 row_mask:0xf bank_mask:0xf
	v_mov_b32_dpp v115, v31 row_ror:2 row_mask:0xf bank_mask:0xf
	v_mov_b32_dpp v112, v30 row_ror:1 row_mask:0xf bank_mask:0xf
	v_mov_b32_dpp v113, v31 row_ror:1 row_mask:0xf bank_mask:0xf
	v_mov_b32_dpp v114, v22 row_shr:2 row_mask:0xf bank_mask:0xf
	v_mov_b32_dpp v115, v23 row_shr:2 row_mask:0xf bank_mask:0xf
	ds_read_b128 v[40:43], v193 offset:16
	ds_read_b128 v[52:55], v193 offset:144
	ds_read_b128 v[56:59], v193 offset:272
	ds_read_b128 v[60:63], v193 offset:400
	ds_read_b128 v[32:35], v193 offset:528
	ds_read_b128 v[36:39], v193 offset:656
	ds_read_b128 v[44:47], v193 offset:784
	ds_read_b128 v[48:51], v193 offset:912
	v_mov_b32_dpp v112, v22 row_shr:1 row_mask:0xf bank_mask:0xf
	v_mov_b32_dpp v113, v23 row_shr:1 row_mask:0xf bank_mask:0xf
	s_waitcnt lgkmcnt(6)
; DI unsigned pk2(float lo, float hi) { f32x2 v = {lo, hi}; bf16x2_t b = __builtin_convertvector(v, bf16x2_t); return __builtin_bit_cast(unsigned, b); }
;     DI void operator()(const AccT& acc, const Unit& u, int wr, int wc, int fr, int fq) const {
;     ...
;                     for (int m = 0; m < 4; ++m) { G[m] = (f32x2){acc[ai][0][m][n][2 * jp], acc[ai][0][m][n][2 * jp + 1]} * rs[m]; V[m] = (f32x2){acc[ai][1][m][n][2 * jp], acc[ai][1][m][n][2 * jp + 1]} * rs[m]; }
; #pragma unroll
;                     for (int m = 0; m < 4; ++m) {
;                         const f32x2 zz = {0.f, 0.f}; const f32x2 Gp = m ? G[m - 1] : zz, Vp = m ? V[m - 1] : zz;
;                         const f32x2 gp1 = {dpp_prev1(G[m].x, Gp.x), dpp_prev1(G[m].y, Gp.y)}, gp2 = {dpp_prev2(G[m].x, Gp.x), dpp_prev2(G[m].y, Gp.y)};
;                         const f32x2 vp1 = {dpp_prev1(V[m].x, Vp.x), dpp_prev1(V[m].y, Vp.y)}, vp2 = {dpp_prev2(V[m].x, Vp.x), dpp_prev2(V[m].y, Vp.y)};
;                         const f32x2 gc = bg + g0 * gp2 + g1 * gp1 + g2 * G[m];
;                         const f32x2 vc = bv + v0 * vp2 + v1 * vp1 + v2 * V[m];
;                         const f32x2 xe = gc * (-LOG2E);
;                         f32x2 dn = {__builtin_amdgcn_exp2f(xe.x), __builtin_amdgcn_exp2f(xe.y)}; dn = dn + 1.0f;
;                         const f32x2 rc = {__builtin_amdgcn_rcpf(dn.x), __builtin_amdgcn_rcpf(dn.y)};
;                         const f32x2 rr = gc * rc * vc;
;                         wpk[m][jp] = pk2(rr.x, rr.y); }
	v_pk_fma_f32 v[114:115], v[54:55], v[114:115], v[42:43]
	v_pk_mul_f32 v[28:29], v[28:29], v[102:103] op_sel_hi:[1,0]
	v_pk_mul_f32 v[24:25], v[24:25], v[102:103] op_sel_hi:[1,0]
	v_pk_mul_f32 v[20:21], v[20:21], v[100:101] op_sel_hi:[1,0]
	v_pk_mul_f32 v[16:17], v[16:17], v[100:101] op_sel_hi:[1,0]
	v_pk_mul_f32 v[26:27], v[26:27], v[102:103] op_sel_hi:[1,0]
	v_pk_mul_f32 v[100:101], v[18:19], v[100:101] op_sel_hi:[1,0]
	v_mov_b32_e32 v102, v183
	v_mov_b32_e32 v103, v183
	s_waitcnt lgkmcnt(5)
	v_pk_fma_f32 v[112:113], v[58:59], v[112:113], v[114:115]
	v_pk_mul_f32 v[76:77], v[12:13], v[98:99] op_sel_hi:[1,0]
	v_pk_mul_f32 v[72:73], v[8:9], v[98:99] op_sel_hi:[1,0]
	v_pk_mul_f32 v[14:15], v[14:15], v[98:99] op_sel_hi:[1,0]
	v_pk_mul_f32 v[10:11], v[10:11], v[98:99] op_sel_hi:[1,0]
	v_mov_b32_e32 v98, v181
	v_mov_b32_e32 v99, v181
	v_mov_b32_dpp v102, v30 row_shr:2 row_mask:0xf bank_mask:0xf
	v_mov_b32_dpp v103, v31 row_shr:2 row_mask:0xf bank_mask:0xf
	v_mov_b32_dpp v18, v22 row_ror:1 row_mask:0xf bank_mask:0xf
	v_mov_b32_dpp v19, v23 row_ror:1 row_mask:0xf bank_mask:0xf
	v_mov_b32_dpp v120, v22 row_ror:2 row_mask:0xf bank_mask:0xf
	v_mov_b32_dpp v121, v23 row_ror:2 row_mask:0xf bank_mask:0xf
	s_waitcnt lgkmcnt(4)
	v_pk_fma_f32 v[22:23], v[22:23], v[62:63], v[112:113]
	v_mov_b32_dpp v98, v30 row_shr:1 row_mask:0xf bank_mask:0xf
	v_mov_b32_dpp v99, v31 row_shr:1 row_mask:0xf bank_mask:0xf
	v_pk_mul_f32 v[112:113], v[22:23], s[2:3] op_sel_hi:[1,0]
	v_pk_fma_f32 v[102:103], v[54:55], v[102:103], v[42:43]
	v_exp_f32_e32 v112, v112
	v_exp_f32_e32 v113, v113
	v_pk_fma_f32 v[98:99], v[58:59], v[98:99], v[102:103]
	v_pk_fma_f32 v[30:31], v[30:31], v[62:63], v[98:99]
	v_pk_mul_f32 v[98:99], v[30:31], s[2:3] op_sel_hi:[1,0]
	v_pk_add_f32 v[112:113], v[112:113], 1.0 op_sel_hi:[1,0]
	v_exp_f32_e32 v98, v98
	v_exp_f32_e32 v99, v99
	v_mov_b32_dpp v118, v26 row_ror:2 row_mask:0xf bank_mask:0xf
	v_mov_b32_dpp v119, v27 row_ror:2 row_mask:0xf bank_mask:0xf
	v_rcp_f32_e32 v112, v112
	v_rcp_f32_e32 v113, v113
	v_mov_b32_dpp v116, v26 row_ror:1 row_mask:0xf bank_mask:0xf
	v_mov_b32_dpp v117, v27 row_ror:1 row_mask:0xf bank_mask:0xf
	v_mov_b32_dpp v118, v100 row_shr:2 row_mask:0xf bank_mask:0xf
	v_mov_b32_dpp v119, v101 row_shr:2 row_mask:0xf bank_mask:0xf
	v_mov_b32_dpp v116, v100 row_shr:1 row_mask:0xf bank_mask:0xf
	v_mov_b32_dpp v117, v101 row_shr:1 row_mask:0xf bank_mask:0xf
	s_waitcnt lgkmcnt(2)
	v_pk_fma_f32 v[114:115], v[38:39], v[118:119], v[34:35]
	v_pk_add_f32 v[98:99], v[98:99], 1.0 op_sel_hi:[1,0]
	v_mov_b32_e32 v182, v183
	s_waitcnt lgkmcnt(1)
	v_pk_fma_f32 v[114:115], v[46:47], v[116:117], v[114:115]
	v_rcp_f32_e32 v98, v98
	v_rcp_f32_e32 v99, v99
	v_pk_mul_f32 v[86:87], v[4:5], v[96:97] op_sel_hi:[1,0]
	v_mov_b32_e32 v12, v183
	v_mov_b32_e32 v13, v183
	v_mov_b32_e32 v4, v183
	v_mov_b32_e32 v5, v183
	v_mov_b32_e32 v180, v181
	v_mov_b32_dpp v182, v26 row_shr:2 row_mask:0xf bank_mask:0xf
	v_mov_b32_dpp v183, v27 row_shr:2 row_mask:0xf bank_mask:0xf
	v_mov_b32_dpp v122, v100 row_ror:1 row_mask:0xf bank_mask:0xf
	v_mov_b32_dpp v123, v101 row_ror:1 row_mask:0xf bank_mask:0xf
	v_mov_b32_dpp v124, v100 row_ror:2 row_mask:0xf bank_mask:0xf
	v_mov_b32_dpp v125, v101 row_ror:2 row_mask:0xf bank_mask:0xf
	s_waitcnt lgkmcnt(0)
	v_pk_fma_f32 v[100:101], v[100:101], v[50:51], v[114:115]
	v_pk_mul_f32 v[22:23], v[22:23], v[112:113]
	v_pk_mul_f32 v[84:85], v[0:1], v[96:97] op_sel_hi:[1,0]
	v_mov_b32_e32 v8, v181
	v_mov_b32_e32 v9, v181
	v_mov_b32_e32 v0, v181
	v_mov_b32_e32 v1, v181
	v_mov_b32_dpp v180, v26 row_shr:1 row_mask:0xf bank_mask:0xf
	v_mov_b32_dpp v181, v27 row_shr:1 row_mask:0xf bank_mask:0xf
	v_pk_mul_f32 v[22:23], v[100:101], v[22:23]
	v_pk_fma_f32 v[100:101], v[38:39], v[182:183], v[34:35]
	v_mov_b32_dpp v106, v76 row_ror:2 row_mask:0xf bank_mask:0xf
	v_mov_b32_dpp v107, v77 row_ror:2 row_mask:0xf bank_mask:0xf
	v_pk_fma_f32 v[100:101], v[46:47], v[180:181], v[100:101]
	v_mov_b32_dpp v104, v76 row_ror:1 row_mask:0xf bank_mask:0xf
	v_mov_b32_dpp v105, v77 row_ror:1 row_mask:0xf bank_mask:0xf
	v_mov_b32_dpp v106, v86 row_shr:2 row_mask:0xf bank_mask:0xf
	v_mov_b32_dpp v107, v87 row_shr:2 row_mask:0xf bank_mask:0xf
	v_pk_fma_f32 v[26:27], v[26:27], v[50:51], v[100:101]
	v_pk_mul_f32 v[30:31], v[30:31], v[98:99]
	v_mov_b32_dpp v104, v86 row_shr:1 row_mask:0xf bank_mask:0xf
	v_mov_b32_dpp v105, v87 row_shr:1 row_mask:0xf bank_mask:0xf
	v_pk_mul_f32 v[26:27], v[26:27], v[30:31]
	v_pk_fma_f32 v[30:31], v[52:53], v[106:107], v[40:41]
	v_mov_b32_dpp v12, v28 row_shr:2 row_mask:0xf bank_mask:0xf
	v_pk_fma_f32 v[30:31], v[56:57], v[104:105], v[30:31]
	v_mov_b32_dpp v13, v29 row_shr:2 row_mask:0xf bank_mask:0xf
	v_pk_fma_f32 v[30:31], v[86:87], v[60:61], v[30:31]
	v_pk_mul_f32 v[86:87], v[30:31], s[2:3] op_sel_hi:[1,0]
	v_mov_b32_dpp v8, v28 row_shr:1 row_mask:0xf bank_mask:0xf
	v_mov_b32_dpp v9, v29 row_shr:1 row_mask:0xf bank_mask:0xf
	v_mov_b32_dpp v92, v20 row_ror:2 row_mask:0xf bank_mask:0xf
	v_mov_b32_dpp v93, v21 row_ror:2 row_mask:0xf bank_mask:0xf
	v_exp_f32_e32 v86, v86
	v_exp_f32_e32 v87, v87
	v_pk_fma_f32 v[12:13], v[52:53], v[12:13], v[40:41]
	v_mov_b32_dpp v88, v20 row_ror:1 row_mask:0xf bank_mask:0xf
	v_mov_b32_dpp v89, v21 row_ror:1 row_mask:0xf bank_mask:0xf
	v_mov_b32_dpp v92, v76 row_shr:2 row_mask:0xf bank_mask:0xf
	v_mov_b32_dpp v93, v77 row_shr:2 row_mask:0xf bank_mask:0xf
	v_mov_b32_dpp v120, v14 row_shr:2 row_mask:0xf bank_mask:0xf
	v_mov_b32_dpp v121, v15 row_shr:2 row_mask:0xf bank_mask:0xf
	v_pk_fma_f32 v[8:9], v[56:57], v[8:9], v[12:13]
	v_mov_b32_dpp v88, v76 row_shr:1 row_mask:0xf bank_mask:0xf
; DI unsigned pk2(float lo, float hi) { f32x2 v = {lo, hi}; bf16x2_t b = __builtin_convertvector(v, bf16x2_t); return __builtin_bit_cast(unsigned, b); }
;     DI void operator()(const AccT& acc, const Unit& u, int wr, int wc, int fr, int fq) const {
;     ...
;                     for (int m = 0; m < 4; ++m) { G[m] = (f32x2){acc[ai][0][m][n][2 * jp], acc[ai][0][m][n][2 * jp + 1]} * rs[m]; V[m] = (f32x2){acc[ai][1][m][n][2 * jp], acc[ai][1][m][n][2 * jp + 1]} * rs[m]; }
; #pragma unroll
;                     for (int m = 0; m < 4; ++m) {
;                         const f32x2 zz = {0.f, 0.f}; const f32x2 Gp = m ? G[m - 1] : zz, Vp = m ? V[m - 1] : zz;
;                         const f32x2 gp1 = {dpp_prev1(G[m].x, Gp.x), dpp_prev1(G[m].y, Gp.y)}, gp2 = {dpp_prev2(G[m].x, Gp.x), dpp_prev2(G[m].y, Gp.y)};
;                         const f32x2 vp1 = {dpp_prev1(V[m].x, Vp.x), dpp_prev1(V[m].y, Vp.y)}, vp2 = {dpp_prev2(V[m].x, Vp.x), dpp_prev2(V[m].y, Vp.y)};
;                         const f32x2 gc = bg + g0 * gp2 + g1 * gp1 + g2 * G[m];
;                         const f32x2 vc = bv + v0 * vp2 + v1 * vp1 + v2 * V[m];
;                         const f32x2 xe = gc * (-LOG2E);
;                         f32x2 dn = {__builtin_amdgcn_exp2f(xe.x), __builtin_amdgcn_exp2f(xe.y)}; dn = dn + 1.0f;
;                         const f32x2 rc = {__builtin_amdgcn_rcpf(dn.x), __builtin_amdgcn_rcpf(dn.y)};
;                         const f32x2 rr = gc * rc * vc;
;                         wpk[m][jp] = pk2(rr.x, rr.y); }
	v_mov_b32_dpp v89, v77 row_shr:1 row_mask:0xf bank_mask:0xf
	v_mov_b32_dpp v18, v14 row_shr:1 row_mask:0xf bank_mask:0xf
	v_mov_b32_dpp v19, v15 row_shr:1 row_mask:0xf bank_mask:0xf
	v_pk_fma_f32 v[120:121], v[54:55], v[120:121], v[42:43]
	v_pk_fma_f32 v[92:93], v[52:53], v[92:93], v[40:41]
	v_pk_fma_f32 v[8:9], v[28:29], v[60:61], v[8:9]
	v_pk_fma_f32 v[18:19], v[58:59], v[18:19], v[120:121]
	v_pk_fma_f32 v[88:89], v[56:57], v[88:89], v[92:93]
	v_pk_mul_f32 v[12:13], v[8:9], s[2:3] op_sel_hi:[1,0]
	v_pk_fma_f32 v[18:19], v[14:15], v[62:63], v[18:19]
	v_pk_add_f32 v[86:87], v[86:87], 1.0 op_sel_hi:[1,0]
	v_pk_fma_f32 v[76:77], v[76:77], v[60:61], v[88:89]
	v_exp_f32_e32 v12, v12
	v_exp_f32_e32 v13, v13
	v_mov_b32_dpp v110, v72 row_ror:2 row_mask:0xf bank_mask:0xf
	v_mov_b32_dpp v111, v73 row_ror:2 row_mask:0xf bank_mask:0xf
	v_pk_mul_f32 v[120:121], v[18:19], s[2:3] op_sel_hi:[1,0]
	v_rcp_f32_e32 v86, v86
	v_rcp_f32_e32 v87, v87
	v_pk_mul_f32 v[88:89], v[76:77], s[2:3] op_sel_hi:[1,0]
	v_mov_b32_dpp v108, v72 row_ror:1 row_mask:0xf bank_mask:0xf
	v_mov_b32_dpp v109, v73 row_ror:1 row_mask:0xf bank_mask:0xf
	v_mov_b32_dpp v110, v84 row_shr:2 row_mask:0xf bank_mask:0xf
	v_mov_b32_dpp v111, v85 row_shr:2 row_mask:0xf bank_mask:0xf
	v_exp_f32_e32 v120, v120
	v_exp_f32_e32 v121, v121
	v_exp_f32_e32 v88, v88
	v_exp_f32_e32 v89, v89
	v_mov_b32_dpp v108, v84 row_shr:1 row_mask:0xf bank_mask:0xf
	v_mov_b32_dpp v109, v85 row_shr:1 row_mask:0xf bank_mask:0xf
	v_pk_mul_f32 v[2:3], v[2:3], v[96:97] op_sel_hi:[1,0]
	v_pk_mul_f32 v[6:7], v[6:7], v[96:97] op_sel_hi:[1,0]
	v_pk_fma_f32 v[96:97], v[36:37], v[110:111], v[32:33]
	v_pk_add_f32 v[12:13], v[12:13], 1.0 op_sel_hi:[1,0]
	v_pk_fma_f32 v[96:97], v[44:45], v[108:109], v[96:97]
	v_pk_mul_f32 v[30:31], v[30:31], v[86:87]
	v_pk_fma_f32 v[84:85], v[84:85], v[48:49], v[96:97]
	v_rcp_f32_e32 v12, v12
	v_rcp_f32_e32 v13, v13
	v_mov_b32_dpp v4, v24 row_shr:2 row_mask:0xf bank_mask:0xf
	v_mov_b32_dpp v5, v25 row_shr:2 row_mask:0xf bank_mask:0xf
	v_pk_add_f32 v[120:121], v[120:121], 1.0 op_sel_hi:[1,0]
	v_pk_mul_f32 v[30:31], v[84:85], v[30:31]
	v_pk_add_f32 v[84:85], v[88:89], 1.0 op_sel_hi:[1,0]
	v_mov_b32_dpp v0, v24 row_shr:1 row_mask:0xf bank_mask:0xf
	v_mov_b32_dpp v1, v25 row_shr:1 row_mask:0xf bank_mask:0xf
	v_mov_b32_dpp v94, v16 row_ror:2 row_mask:0xf bank_mask:0xf
	v_mov_b32_dpp v95, v17 row_ror:2 row_mask:0xf bank_mask:0xf
	v_rcp_f32_e32 v120, v120
	v_rcp_f32_e32 v121, v121
	v_rcp_f32_e32 v84, v84
	v_rcp_f32_e32 v85, v85
	v_pk_fma_f32 v[4:5], v[36:37], v[4:5], v[32:33]
	v_mov_b32_dpp v90, v16 row_ror:1 row_mask:0xf bank_mask:0xf
	v_mov_b32_dpp v91, v17 row_ror:1 row_mask:0xf bank_mask:0xf
	v_mov_b32_dpp v94, v72 row_shr:2 row_mask:0xf bank_mask:0xf
	v_mov_b32_dpp v95, v73 row_shr:2 row_mask:0xf bank_mask:0xf
	v_mov_b32_dpp v124, v10 row_shr:2 row_mask:0xf bank_mask:0xf
	v_mov_b32_dpp v125, v11 row_shr:2 row_mask:0xf bank_mask:0xf
	v_pk_fma_f32 v[0:1], v[44:45], v[0:1], v[4:5]
	v_mov_b32_dpp v90, v72 row_shr:1 row_mask:0xf bank_mask:0xf
	v_mov_b32_dpp v91, v73 row_shr:1 row_mask:0xf bank_mask:0xf
	v_mov_b32_dpp v122, v10 row_shr:1 row_mask:0xf bank_mask:0xf
	v_mov_b32_dpp v123, v11 row_shr:1 row_mask:0xf bank_mask:0xf
	v_pk_fma_f32 v[124:125], v[38:39], v[124:125], v[34:35]
	v_pk_fma_f32 v[86:87], v[36:37], v[94:95], v[32:33]
	v_pk_fma_f32 v[0:1], v[24:25], v[48:49], v[0:1]
	v_pk_mul_f32 v[4:5], v[8:9], v[12:13]
	v_pk_fma_f32 v[122:123], v[46:47], v[122:123], v[124:125]
	v_pk_fma_f32 v[86:87], v[44:45], v[90:91], v[86:87]
	v_pk_mul_f32 v[0:1], v[0:1], v[4:5]
	v_mov_b32_dpp v78, v28 row_ror:2 row_mask:0xf bank_mask:0xf
	v_mov_b32_dpp v79, v29 row_ror:2 row_mask:0xf bank_mask:0xf
	v_pk_fma_f32 v[122:123], v[10:11], v[50:51], v[122:123]
	v_pk_mul_f32 v[18:19], v[18:19], v[120:121]
; DI unsigned pk2(float lo, float hi) { f32x2 v = {lo, hi}; bf16x2_t b = __builtin_convertvector(v, bf16x2_t); return __builtin_bit_cast(unsigned, b); }
; #define PG8_BAR __builtin_amdgcn_s_barrier()
;     ...
;         if (wr == 0) PG8_BAR;
;         E(acc, cur, wr, wc, fr, fq);
;         if (!has_next) break;
; #pragma unroll
;         for (int a = 0; a < 2; ++a)
; #pragma unroll
;             for (int b = 0; b < 2; ++b)
; #pragma unroll
;                 for (int m = 0; m < 4; ++m)
; #pragma unroll
;                     for (int n = 0; n < 2; ++n) acc[a][b][m][n] = (f32x4){0.f, 0.f, 0.f, 0.f};
;         cur = nxt; cA = nA; cB = nB; ++ui;
;         if (wr == 1) PG8_BAR;
;     }
;     DI void operator()(const AccT& acc, const Unit& u, int wr, int wc, int fr, int fq) const {
;     ...
;                     for (int m = 0; m < 4; ++m) {
;                         const f32x2 zz = {0.f, 0.f}; const f32x2 Gp = m ? G[m - 1] : zz, Vp = m ? V[m - 1] : zz;
;                         const f32x2 gp1 = {dpp_prev1(G[m].x, Gp.x), dpp_prev1(G[m].y, Gp.y)}, gp2 = {dpp_prev2(G[m].x, Gp.x), dpp_prev2(G[m].y, Gp.y)};
;                         const f32x2 vp1 = {dpp_prev1(V[m].x, Vp.x), dpp_prev1(V[m].y, Vp.y)}, vp2 = {dpp_prev2(V[m].x, Vp.x), dpp_prev2(V[m].y, Vp.y)};
;                         const f32x2 gc = bg + g0 * gp2 + g1 * gp1 + g2 * G[m];
;                         const f32x2 vc = bv + v0 * vp2 + v1 * vp1 + v2 * V[m];
;                         const f32x2 xe = gc * (-LOG2E);
;                         f32x2 dn = {__builtin_amdgcn_exp2f(xe.x), __builtin_amdgcn_exp2f(xe.y)}; dn = dn + 1.0f;
;                         const f32x2 rc = {__builtin_amdgcn_rcpf(dn.x), __builtin_amdgcn_rcpf(dn.y)};
;                         const f32x2 rr = gc * rc * vc;
;                         wpk[m][jp] = pk2(rr.x, rr.y); }
;                 }
; #pragma unroll
;                 for (int m = 0; m < 4; ++m) { const int row = m ? tok0 + 16 * m : row0;
;                     *(u32x2*)(ACT + (size_t)row * 2816 + cl + 4 * n) = (u32x2){wpk[m][0], wpk[m][1]}; }
	v_cvt_pk_bf16_f32 v27, v26, v27
	v_pk_fma_f32 v[72:73], v[72:73], v[48:49], v[86:87]
	v_pk_mul_f32 v[76:77], v[76:77], v[84:85]
	v_cvt_pk_bf16_f32 v26, v0, v1
	v_mov_b32_dpp v4, v14 row_ror:2 row_mask:0xf bank_mask:0xf
	v_mov_b32_dpp v5, v15 row_ror:2 row_mask:0xf bank_mask:0xf
	v_mov_b32_dpp v74, v28 row_ror:1 row_mask:0xf bank_mask:0xf
	v_mov_b32_dpp v75, v29 row_ror:1 row_mask:0xf bank_mask:0xf
	v_mov_b32_dpp v78, v20 row_shr:2 row_mask:0xf bank_mask:0xf
	v_mov_b32_dpp v79, v21 row_shr:2 row_mask:0xf bank_mask:0xf
	v_pk_mul_f32 v[18:19], v[122:123], v[18:19]
	v_pk_mul_f32 v[72:73], v[72:73], v[76:77]
	v_mov_b32_dpp v0, v14 row_ror:1 row_mask:0xf bank_mask:0xf
	v_mov_b32_dpp v1, v15 row_ror:1 row_mask:0xf bank_mask:0xf
	v_mov_b32_dpp v4, v6 row_shr:2 row_mask:0xf bank_mask:0xf
	v_mov_b32_dpp v5, v7 row_shr:2 row_mask:0xf bank_mask:0xf
	v_mov_b32_dpp v74, v20 row_shr:1 row_mask:0xf bank_mask:0xf
	v_mov_b32_dpp v75, v21 row_shr:1 row_mask:0xf bank_mask:0xf
	v_cvt_pk_bf16_f32 v19, v18, v19
	v_cvt_pk_bf16_f32 v18, v72, v73
	v_pk_fma_f32 v[72:73], v[52:53], v[78:79], v[40:41]
	v_mov_b32_dpp v0, v6 row_shr:1 row_mask:0xf bank_mask:0xf
	v_mov_b32_dpp v1, v7 row_shr:1 row_mask:0xf bank_mask:0xf
	v_pk_fma_f32 v[4:5], v[54:55], v[4:5], v[42:43]
	v_pk_fma_f32 v[72:73], v[56:57], v[74:75], v[72:73]
	v_pk_fma_f32 v[0:1], v[58:59], v[0:1], v[4:5]
	v_pk_fma_f32 v[20:21], v[20:21], v[60:61], v[72:73]
	v_pk_fma_f32 v[0:1], v[6:7], v[62:63], v[0:1]
	v_pk_mul_f32 v[72:73], v[20:21], s[2:3] op_sel_hi:[1,0]
	v_pk_mul_f32 v[4:5], v[0:1], s[2:3] op_sel_hi:[1,0]
	v_exp_f32_e32 v72, v72
	v_exp_f32_e32 v73, v73
	v_exp_f32_e32 v4, v4
	v_exp_f32_e32 v5, v5
	v_pk_add_f32 v[72:73], v[72:73], 1.0 op_sel_hi:[1,0]
	v_pk_add_f32 v[4:5], v[4:5], 1.0 op_sel_hi:[1,0]
	v_mov_b32_dpp v82, v24 row_ror:2 row_mask:0xf bank_mask:0xf
	v_mov_b32_dpp v83, v25 row_ror:2 row_mask:0xf bank_mask:0xf
	v_rcp_f32_e32 v72, v72
	v_rcp_f32_e32 v73, v73
	v_mov_b32_dpp v12, v10 row_ror:2 row_mask:0xf bank_mask:0xf
	v_mov_b32_dpp v13, v11 row_ror:2 row_mask:0xf bank_mask:0xf
	v_rcp_f32_e32 v4, v4
	v_rcp_f32_e32 v5, v5
	v_mov_b32_dpp v80, v24 row_ror:1 row_mask:0xf bank_mask:0xf
	v_mov_b32_dpp v81, v25 row_ror:1 row_mask:0xf bank_mask:0xf
	v_mov_b32_dpp v82, v16 row_shr:2 row_mask:0xf bank_mask:0xf
	v_mov_b32_dpp v83, v17 row_shr:2 row_mask:0xf bank_mask:0xf
	v_mov_b32_dpp v8, v10 row_ror:1 row_mask:0xf bank_mask:0xf
	v_mov_b32_dpp v9, v11 row_ror:1 row_mask:0xf bank_mask:0xf
	v_mov_b32_dpp v12, v2 row_shr:2 row_mask:0xf bank_mask:0xf
	v_mov_b32_dpp v13, v3 row_shr:2 row_mask:0xf bank_mask:0xf
	v_mov_b32_dpp v80, v16 row_shr:1 row_mask:0xf bank_mask:0xf
	v_mov_b32_dpp v81, v17 row_shr:1 row_mask:0xf bank_mask:0xf
	v_pk_fma_f32 v[74:75], v[36:37], v[82:83], v[32:33]
	v_mov_b32_dpp v8, v2 row_shr:1 row_mask:0xf bank_mask:0xf
	v_mov_b32_dpp v9, v3 row_shr:1 row_mask:0xf bank_mask:0xf
	v_pk_fma_f32 v[6:7], v[38:39], v[12:13], v[34:35]
	v_pk_fma_f32 v[74:75], v[44:45], v[80:81], v[74:75]
	v_pk_fma_f32 v[6:7], v[46:47], v[8:9], v[6:7]
	v_pk_fma_f32 v[16:17], v[16:17], v[48:49], v[74:75]
	v_pk_mul_f32 v[20:21], v[20:21], v[72:73]
	v_pk_fma_f32 v[2:3], v[2:3], v[50:51], v[6:7]
	v_pk_mul_f32 v[0:1], v[0:1], v[4:5]
	v_pk_mul_f32 v[16:17], v[16:17], v[20:21]
	v_pk_mul_f32 v[0:1], v[2:3], v[0:1]
	v_cvt_pk_bf16_f32 v23, v22, v23
	v_cvt_pk_bf16_f32 v30, v30, v31
	v_cvt_pk_bf16_f32 v22, v16, v17
	v_cvt_pk_bf16_f32 v31, v0, v1
	global_store_dwordx2 v[64:65], v[26:27], off offset:8
	global_store_dwordx2 v[66:67], v[22:23], off offset:8
	global_store_dwordx2 v[68:69], v[18:19], off offset:8
	global_store_dwordx2 v[70:71], v[30:31], off offset:8
	s_and_b64 vcc, exec, s[6:7]
	s_mov_b64 s[6:7], -1
	s_cbranch_vccnz .LBB0_1817
	s_andn2_b64 vcc, exec, s[14:15]
	s_cbranch_vccnz .LBB0_1816
	s_barrier
	s_branch .LBB0_1816

; DI unsigned pk2(float lo, float hi) { f32x2 v = {lo, hi}; bf16x2_t b = __builtin_convertvector(v, bf16x2_t); return __builtin_bit_cast(unsigned, b); }
; DI float bflo(unsigned u) { return __uint_as_float(u << 16); }
; DI float bfhi(unsigned u) { return __uint_as_float(u & 0xffff0000u); }
; DI u64 ss_to_fix(float ss) { return (u64)(ss * 1048576.f); }
;     DI void operator()(const AccT& acc, const Unit& u, int wr, int wc, int fr, int fq) const {
;     ...
;         for (int ai = 0; ai < 2; ++ai)
; #pragma unroll
;             for (int m = 0; m < 4; ++m) { const int t = row0 + ai * 128 + m * 16; float ss = 0.f;
; #pragma unroll
;                 for (int bj = 0; bj < 2; ++bj) { const size_t o = (size_t)t * 1024 + col0 + bj * 128;
;                     f32x4 r0, r1;
;                     if (RESBF) { const u32x4 rb = *(const u32x4*)(XB + o); r0 = (f32x4){bflo(rb.x), bfhi(rb.x), bflo(rb.y), bfhi(rb.y)}; r1 = (f32x4){bflo(rb.z), bfhi(rb.z), bflo(rb.w), bfhi(rb.w)}; }
;                     else { r0 = __builtin_nontemporal_load((const f32x4*)(res + o)); r1 = __builtin_nontemporal_load((const f32x4*)(res + o + 4)); }
;                     const f32x4 v0 = acc[ai][bj][m][0] + r0, v1 = acc[ai][bj][m][1] + r1;
;                     u32x4 w; w.x = pk2(v0[0], v0[1]); w.y = pk2(v0[2], v0[3]); w.z = pk2(v1[0], v1[1]); w.w = pk2(v1[2], v1[3]);
;                     if (!dry) *(u32x4*)(XB + o) = w;
;                     ss += v0[0] * v0[0] + v0[1] * v0[1] + v0[2] * v0[2] + v0[3] * v0[3] + v1[0] * v1[0] + v1[1] * v1[1] + v1[2] * v1[2] + v1[3] * v1[3]; }
;                 { const auto r16 = __builtin_amdgcn_permlane16_swap(__float_as_uint(ss), __float_as_uint(ss), false, false); ss = __uint_as_float(r16[0]) + __uint_as_float(r16[1]);
;                   const auto r32 = __builtin_amdgcn_permlane32_swap(__float_as_uint(ss), __float_as_uint(ss), false, false); ss = __uint_as_float(r32[0]) + __uint_as_float(r32[1]); }
;                 if (fq == 0 && !dry) atomicAdd(rowss + t, ss_to_fix(ss)); }
.LBB0_1917:
	v_lshl_add_u32 v146, s51, 8, v148
	v_ashrrev_i32_e32 v147, 31, v146
	v_lshl_or_b32 v144, s52, 8, v150
	v_lshlrev_b64 v[154:155], 11, v[146:147]
	v_ashrrev_i32_e32 v145, 31, v144
	v_lshl_add_u64 v[154:155], s[2:3], 0, v[154:155]
	v_lshl_add_u64 v[162:163], v[144:145], 1, v[154:155]
	global_load_dwordx4 v[154:157], v[162:163], off
	global_load_dwordx4 v[158:161], v[162:163], off offset:256
	v_or_b32_e32 v172, 16, v146
	v_ashrrev_i32_e32 v173, 31, v172
	v_lshlrev_b64 v[182:183], 11, v[172:173]
	v_lshl_add_u64 v[182:183], s[2:3], 0, v[182:183]
	v_lshl_add_u64 v[182:183], v[144:145], 1, v[182:183]
	global_load_dwordx4 v[174:177], v[182:183], off
	global_load_dwordx4 v[178:181], v[182:183], off offset:256
	v_or_b32_e32 v172, 32, v146
	v_ashrrev_i32_e32 v173, 31, v172
	v_lshlrev_b64 v[200:201], 11, v[172:173]
	v_lshl_add_u64 v[200:201], s[2:3], 0, v[200:201]
	v_lshl_add_u64 v[200:201], v[144:145], 1, v[200:201]
	global_load_dwordx4 v[184:187], v[200:201], off
	global_load_dwordx4 v[188:191], v[200:201], off offset:256
	v_or_b32_e32 v172, 48, v146
	v_ashrrev_i32_e32 v173, 31, v172
	v_lshlrev_b64 v[210:211], 11, v[172:173]
	v_lshl_add_u64 v[210:211], s[2:3], 0, v[210:211]
	v_lshl_add_u64 v[210:211], v[144:145], 1, v[210:211]
	global_load_dwordx4 v[202:205], v[210:211], off
	global_load_dwordx4 v[206:209], v[210:211], off offset:256
	v_add_u32_e32 v172, 0x80, v146
	v_ashrrev_i32_e32 v173, 31, v172
	v_lshlrev_b64 v[220:221], 11, v[172:173]
	v_lshl_add_u64 v[220:221], s[2:3], 0, v[220:221]
	v_lshl_add_u64 v[220:221], v[144:145], 1, v[220:221]
	global_load_dwordx4 v[212:215], v[220:221], off
	global_load_dwordx4 v[216:219], v[220:221], off offset:256
	v_add_u32_e32 v172, 0x90, v146
	v_ashrrev_i32_e32 v173, 31, v172
	v_lshlrev_b64 v[230:231], 11, v[172:173]
	v_lshl_add_u64 v[230:231], s[2:3], 0, v[230:231]
	v_lshl_add_u64 v[230:231], v[144:145], 1, v[230:231]
	global_load_dwordx4 v[222:225], v[230:231], off
	global_load_dwordx4 v[226:229], v[230:231], off offset:256
	v_add_u32_e32 v172, 0xa0, v146
	v_ashrrev_i32_e32 v173, 31, v172
	v_lshlrev_b64 v[242:243], 11, v[172:173]
	v_lshl_add_u64 v[242:243], s[2:3], 0, v[242:243]
	v_lshl_add_u64 v[242:243], v[144:145], 1, v[242:243]
	global_load_dwordx4 v[232:235], v[242:243], off
	global_load_dwordx4 v[236:239], v[242:243], off offset:256
	v_add_u32_e32 v172, 0xb0, v146
	v_ashrrev_i32_e32 v173, 31, v172
	v_lshlrev_b64 v[252:253], 11, v[172:173]
	v_lshl_add_u64 v[252:253], s[2:3], 0, v[252:253]
	v_lshl_add_u64 v[252:253], v[144:145], 1, v[252:253]
	global_load_dwordx4 v[244:247], v[252:253], off
	global_load_dwordx4 v[248:251], v[252:253], off offset:256
	s_waitcnt vmcnt(14)
	v_lshlrev_b32_e32 v164, 16, v154
	v_and_b32_e32 v165, 0xffff0000, v154
	v_lshlrev_b32_e32 v166, 16, v156
	v_and_b32_e32 v167, 0xffff0000, v156
	v_lshlrev_b32_e32 v156, 16, v157
	v_and_b32_e32 v157, 0xffff0000, v157
	v_lshlrev_b32_e32 v168, 16, v158
	v_and_b32_e32 v169, 0xffff0000, v158
	v_lshlrev_b32_e32 v154, 16, v155
	v_and_b32_e32 v155, 0xffff0000, v155
	v_lshlrev_b32_e32 v158, 16, v159
	v_and_b32_e32 v159, 0xffff0000, v159
	v_lshlrev_b32_e32 v170, 16, v160
	v_and_b32_e32 v171, 0xffff0000, v160
	v_lshlrev_b32_e32 v160, 16, v161
	v_and_b32_e32 v161, 0xffff0000, v161
	v_pk_add_f32 v[120:121], v[120:121], v[164:165]
	v_pk_add_f32 v[126:127], v[126:127], v[156:157]
	v_pk_add_f32 v[156:157], v[116:117], v[168:169]
	v_pk_add_f32 v[122:123], v[122:123], v[154:155]
	v_pk_add_f32 v[154:155], v[118:119], v[158:159]
	v_pk_add_f32 v[158:159], v[114:115], v[160:161]
	v_pk_add_f32 v[160:161], v[112:113], v[170:171]
	v_cvt_pk_bf16_f32 v112, v120, v121
	v_mul_f32_e32 v121, v121, v121
	v_cvt_pk_bf16_f32 v116, v156, v157
	v_mul_f32_e32 v157, v157, v157
	v_fmac_f32_e32 v121, v120, v120
	v_fmac_f32_e32 v157, v156, v156
	v_fmac_f32_e32 v121, v122, v122
	v_fmac_f32_e32 v157, v154, v154
	v_pk_add_f32 v[124:125], v[124:125], v[166:167]
	v_fmac_f32_e32 v121, v123, v123
	v_fmac_f32_e32 v157, v155, v155
	v_fmac_f32_e32 v121, v124, v124
	v_fmac_f32_e32 v157, v160, v160
	v_fmac_f32_e32 v121, v125, v125
	v_fmac_f32_e32 v157, v161, v161
	v_fmac_f32_e32 v121, v126, v126
	v_fmac_f32_e32 v157, v158, v158
	v_cvt_pk_bf16_f32 v113, v122, v123
	v_cvt_pk_bf16_f32 v114, v124, v125
	v_cvt_pk_bf16_f32 v115, v126, v127
	v_fmac_f32_e32 v121, v127, v127
	v_fmac_f32_e32 v157, v159, v159
	global_store_dwordx4 v[162:163], v[112:115], off
	v_cvt_pk_bf16_f32 v117, v154, v155
	v_cvt_pk_bf16_f32 v118, v160, v161
	v_add_f32_e32 v112, v121, v157
	v_mov_b32_e32 v113, v112
	s_nop 1
	v_permlane16_swap_b32_e32 v112, v113
	v_add_f32_e32 v112, v112, v113
	v_mov_b32_e32 v113, v112
	v_cvt_pk_bf16_f32 v119, v158, v159
	s_nop 0
	v_permlane32_swap_b32_e32 v112, v113
	global_store_dwordx4 v[162:163], v[116:119], off offset:256
	s_and_saveexec_b64 s[20:21], s[4:5]
	s_cbranch_execz .LBB0_1919
	v_add_f32_e32 v112, v112, v113
	v_mul_f32_e32 v112, 0x49800000, v112
	v_trunc_f32_e32 v112, v112
	v_mul_f32_e32 v113, 0x2f800000, v112
	v_floor_f32_e32 v113, v113
	v_fmac_f32_e32 v112, 0xcf800000, v113
	v_cvt_u32_f32_e32 v112, v112
	v_cvt_u32_f32_e32 v113, v113
	v_lshl_add_u64 v[114:115], v[146:147], 3, s[10:11]
	global_atomic_add_x2 v[114:115], v[112:113], off
; DI unsigned pk2(float lo, float hi) { f32x2 v = {lo, hi}; bf16x2_t b = __builtin_convertvector(v, bf16x2_t); return __builtin_bit_cast(unsigned, b); }
; DI float bflo(unsigned u) { return __uint_as_float(u << 16); }
; DI float bfhi(unsigned u) { return __uint_as_float(u & 0xffff0000u); }
; DI u64 ss_to_fix(float ss) { return (u64)(ss * 1048576.f); }
;     DI void operator()(const AccT& acc, const Unit& u, int wr, int wc, int fr, int fq) const {
;     ...
;             for (int m = 0; m < 4; ++m) { const int t = row0 + ai * 128 + m * 16; float ss = 0.f;
; #pragma unroll
;                 for (int bj = 0; bj < 2; ++bj) { const size_t o = (size_t)t * 1024 + col0 + bj * 128;
;                     f32x4 r0, r1;
;                     if (RESBF) { const u32x4 rb = *(const u32x4*)(XB + o); r0 = (f32x4){bflo(rb.x), bfhi(rb.x), bflo(rb.y), bfhi(rb.y)}; r1 = (f32x4){bflo(rb.z), bfhi(rb.z), bflo(rb.w), bfhi(rb.w)}; }
;                     else { r0 = __builtin_nontemporal_load((const f32x4*)(res + o)); r1 = __builtin_nontemporal_load((const f32x4*)(res + o + 4)); }
;                     const f32x4 v0 = acc[ai][bj][m][0] + r0, v1 = acc[ai][bj][m][1] + r1;
;                     u32x4 w; w.x = pk2(v0[0], v0[1]); w.y = pk2(v0[2], v0[3]); w.z = pk2(v1[0], v1[1]); w.w = pk2(v1[2], v1[3]);
;                     if (!dry) *(u32x4*)(XB + o) = w;
;                     ss += v0[0] * v0[0] + v0[1] * v0[1] + v0[2] * v0[2] + v0[3] * v0[3] + v1[0] * v1[0] + v1[1] * v1[1] + v1[2] * v1[2] + v1[3] * v1[3]; }
;                 { const auto r16 = __builtin_amdgcn_permlane16_swap(__float_as_uint(ss), __float_as_uint(ss), false, false); ss = __uint_as_float(r16[0]) + __uint_as_float(r16[1]);
;                   const auto r32 = __builtin_amdgcn_permlane32_swap(__float_as_uint(ss), __float_as_uint(ss), false, false); ss = __uint_as_float(r32[0]) + __uint_as_float(r32[1]); }
;                 if (fq == 0 && !dry) atomicAdd(rowss + t, ss_to_fix(ss)); }
.LBB0_1919:
	s_or_b64 exec, exec, s[20:21]
	v_or_b32_e32 v112, 16, v146
	v_ashrrev_i32_e32 v113, 31, v112
	s_waitcnt vmcnt(14)
	v_lshlrev_b32_e32 v124, 16, v174
	v_and_b32_e32 v125, 0xffff0000, v174
	v_lshlrev_b32_e32 v126, 16, v176
	v_and_b32_e32 v127, 0xffff0000, v176
	v_lshlrev_b32_e32 v176, 16, v177
	v_and_b32_e32 v177, 0xffff0000, v177
	v_lshlrev_b32_e32 v154, 16, v178
	v_and_b32_e32 v155, 0xffff0000, v178
	v_lshlrev_b32_e32 v174, 16, v175
	v_and_b32_e32 v175, 0xffff0000, v175
	v_lshlrev_b32_e32 v178, 16, v179
	v_and_b32_e32 v179, 0xffff0000, v179
	v_lshlrev_b32_e32 v156, 16, v180
	v_and_b32_e32 v157, 0xffff0000, v180
	v_lshlrev_b32_e32 v180, 16, v181
	v_and_b32_e32 v181, 0xffff0000, v181
	v_pk_add_f32 v[108:109], v[108:109], v[124:125]
	v_pk_add_f32 v[106:107], v[106:107], v[176:177]
	v_pk_add_f32 v[176:177], v[100:101], v[154:155]
	v_pk_add_f32 v[110:111], v[110:111], v[174:175]
	v_pk_add_f32 v[174:175], v[102:103], v[178:179]
	v_pk_add_f32 v[178:179], v[98:99], v[180:181]
	v_pk_add_f32 v[180:181], v[96:97], v[156:157]
	v_cvt_pk_bf16_f32 v96, v108, v109
	v_mul_f32_e32 v109, v109, v109
	v_cvt_pk_bf16_f32 v100, v176, v177
	v_mul_f32_e32 v177, v177, v177
	v_fmac_f32_e32 v109, v108, v108
	v_fmac_f32_e32 v177, v176, v176
	v_fmac_f32_e32 v109, v110, v110
	v_fmac_f32_e32 v177, v174, v174
	v_pk_add_f32 v[104:105], v[104:105], v[126:127]
	v_fmac_f32_e32 v109, v111, v111
	v_fmac_f32_e32 v177, v175, v175
	v_fmac_f32_e32 v109, v104, v104
	v_fmac_f32_e32 v177, v180, v180
	v_fmac_f32_e32 v109, v105, v105
	v_fmac_f32_e32 v177, v181, v181
	v_fmac_f32_e32 v109, v106, v106
	v_fmac_f32_e32 v177, v178, v178
	v_cvt_pk_bf16_f32 v97, v110, v111
	v_cvt_pk_bf16_f32 v98, v104, v105
	v_cvt_pk_bf16_f32 v99, v106, v107
	v_fmac_f32_e32 v109, v107, v107
	v_fmac_f32_e32 v177, v179, v179
	global_store_dwordx4 v[182:183], v[96:99], off
	v_cvt_pk_bf16_f32 v101, v174, v175
	v_cvt_pk_bf16_f32 v102, v180, v181
	v_add_f32_e32 v96, v109, v177
	v_mov_b32_e32 v97, v96
	s_nop 1
	v_permlane16_swap_b32_e32 v96, v97
	v_add_f32_e32 v96, v96, v97
	v_mov_b32_e32 v97, v96
	v_cvt_pk_bf16_f32 v103, v178, v179
	s_nop 0
	v_permlane32_swap_b32_e32 v96, v97
	global_store_dwordx4 v[182:183], v[100:103], off offset:256
	s_and_saveexec_b64 s[20:21], s[4:5]
	s_cbranch_execz .LBB0_1921
	v_add_f32_e32 v96, v96, v97
	v_mul_f32_e32 v96, 0x49800000, v96
	v_trunc_f32_e32 v96, v96
	v_mul_f32_e32 v97, 0x2f800000, v96
	v_floor_f32_e32 v97, v97
	v_fmac_f32_e32 v96, 0xcf800000, v97
	v_cvt_u32_f32_e32 v96, v96
	v_cvt_u32_f32_e32 v97, v97
	v_lshl_add_u64 v[98:99], v[112:113], 3, s[10:11]
	global_atomic_add_x2 v[98:99], v[96:97], off
.LBB0_1921:
	s_or_b64 exec, exec, s[20:21]
	v_or_b32_e32 v96, 32, v146
	v_ashrrev_i32_e32 v97, 31, v96
	s_waitcnt vmcnt(14)
	v_lshlrev_b32_e32 v108, 16, v184
	v_and_b32_e32 v109, 0xffff0000, v184
	v_lshlrev_b32_e32 v110, 16, v186
	v_and_b32_e32 v111, 0xffff0000, v186
	v_lshlrev_b32_e32 v186, 16, v187
	v_and_b32_e32 v187, 0xffff0000, v187
	v_lshlrev_b32_e32 v112, 16, v188
	v_and_b32_e32 v113, 0xffff0000, v188
	v_lshlrev_b32_e32 v184, 16, v185
	v_and_b32_e32 v185, 0xffff0000, v185
	v_lshlrev_b32_e32 v188, 16, v189
	v_and_b32_e32 v189, 0xffff0000, v189
	v_lshlrev_b32_e32 v114, 16, v190
	v_and_b32_e32 v115, 0xffff0000, v190
	v_lshlrev_b32_e32 v190, 16, v191
	v_and_b32_e32 v191, 0xffff0000, v191
	v_pk_add_f32 v[92:93], v[92:93], v[108:109]
	v_pk_add_f32 v[90:91], v[90:91], v[186:187]
	v_pk_add_f32 v[186:187], v[84:85], v[112:113]
	v_pk_add_f32 v[94:95], v[94:95], v[184:185]
	v_pk_add_f32 v[184:185], v[86:87], v[188:189]
	v_pk_add_f32 v[188:189], v[82:83], v[190:191]
	v_pk_add_f32 v[190:191], v[80:81], v[114:115]
	v_cvt_pk_bf16_f32 v80, v92, v93
	v_mul_f32_e32 v93, v93, v93
	v_cvt_pk_bf16_f32 v84, v186, v187
	v_mul_f32_e32 v187, v187, v187
	v_fmac_f32_e32 v93, v92, v92
	v_fmac_f32_e32 v187, v186, v186
	v_fmac_f32_e32 v93, v94, v94
	v_fmac_f32_e32 v187, v184, v184
	v_pk_add_f32 v[88:89], v[88:89], v[110:111]
	v_fmac_f32_e32 v93, v95, v95
	v_fmac_f32_e32 v187, v185, v185
	v_fmac_f32_e32 v93, v88, v88
	v_fmac_f32_e32 v187, v190, v190
	v_fmac_f32_e32 v93, v89, v89
	v_fmac_f32_e32 v187, v191, v191
	v_fmac_f32_e32 v93, v90, v90
	v_fmac_f32_e32 v187, v188, v188
	v_cvt_pk_bf16_f32 v81, v94, v95
	v_cvt_pk_bf16_f32 v82, v88, v89
	v_cvt_pk_bf16_f32 v83, v90, v91
	v_fmac_f32_e32 v93, v91, v91
	v_fmac_f32_e32 v187, v189, v189
	global_store_dwordx4 v[200:201], v[80:83], off
	v_cvt_pk_bf16_f32 v85, v184, v185
	v_cvt_pk_bf16_f32 v86, v190, v191
	v_add_f32_e32 v80, v93, v187
	v_mov_b32_e32 v81, v80
	s_nop 1
	v_permlane16_swap_b32_e32 v80, v81
	v_add_f32_e32 v80, v80, v81
	v_mov_b32_e32 v81, v80
	v_cvt_pk_bf16_f32 v87, v188, v189
	s_nop 0
	v_permlane32_swap_b32_e32 v80, v81
	global_store_dwordx4 v[200:201], v[84:87], off offset:256
	s_and_saveexec_b64 s[20:21], s[4:5]
	s_cbranch_execz .LBB0_1923
	v_add_f32_e32 v80, v80, v81
	v_mul_f32_e32 v80, 0x49800000, v80
	v_trunc_f32_e32 v80, v80
	v_mul_f32_e32 v81, 0x2f800000, v80
	v_floor_f32_e32 v81, v81
	v_fmac_f32_e32 v80, 0xcf800000, v81
	v_cvt_u32_f32_e32 v80, v80
	v_cvt_u32_f32_e32 v81, v81
	v_lshl_add_u64 v[82:83], v[96:97], 3, s[10:11]
	global_atomic_add_x2 v[82:83], v[80:81], off
; DI unsigned pk2(float lo, float hi) { f32x2 v = {lo, hi}; bf16x2_t b = __builtin_convertvector(v, bf16x2_t); return __builtin_bit_cast(unsigned, b); }
; DI float bflo(unsigned u) { return __uint_as_float(u << 16); }
; DI float bfhi(unsigned u) { return __uint_as_float(u & 0xffff0000u); }
; DI u64 ss_to_fix(float ss) { return (u64)(ss * 1048576.f); }
;     DI void operator()(const AccT& acc, const Unit& u, int wr, int wc, int fr, int fq) const {
;     ...
;             for (int m = 0; m < 4; ++m) { const int t = row0 + ai * 128 + m * 16; float ss = 0.f;
; #pragma unroll
;                 for (int bj = 0; bj < 2; ++bj) { const size_t o = (size_t)t * 1024 + col0 + bj * 128;
;                     f32x4 r0, r1;
;                     if (RESBF) { const u32x4 rb = *(const u32x4*)(XB + o); r0 = (f32x4){bflo(rb.x), bfhi(rb.x), bflo(rb.y), bfhi(rb.y)}; r1 = (f32x4){bflo(rb.z), bfhi(rb.z), bflo(rb.w), bfhi(rb.w)}; }
;                     else { r0 = __builtin_nontemporal_load((const f32x4*)(res + o)); r1 = __builtin_nontemporal_load((const f32x4*)(res + o + 4)); }
;                     const f32x4 v0 = acc[ai][bj][m][0] + r0, v1 = acc[ai][bj][m][1] + r1;
;                     u32x4 w; w.x = pk2(v0[0], v0[1]); w.y = pk2(v0[2], v0[3]); w.z = pk2(v1[0], v1[1]); w.w = pk2(v1[2], v1[3]);
;                     if (!dry) *(u32x4*)(XB + o) = w;
;                     ss += v0[0] * v0[0] + v0[1] * v0[1] + v0[2] * v0[2] + v0[3] * v0[3] + v1[0] * v1[0] + v1[1] * v1[1] + v1[2] * v1[2] + v1[3] * v1[3]; }
;                 { const auto r16 = __builtin_amdgcn_permlane16_swap(__float_as_uint(ss), __float_as_uint(ss), false, false); ss = __uint_as_float(r16[0]) + __uint_as_float(r16[1]);
;                   const auto r32 = __builtin_amdgcn_permlane32_swap(__float_as_uint(ss), __float_as_uint(ss), false, false); ss = __uint_as_float(r32[0]) + __uint_as_float(r32[1]); }
;                 if (fq == 0 && !dry) atomicAdd(rowss + t, ss_to_fix(ss)); }
.LBB0_1923:
	s_or_b64 exec, exec, s[20:21]
	v_or_b32_e32 v80, 48, v146
	v_ashrrev_i32_e32 v81, 31, v80
	s_waitcnt vmcnt(14)
	v_lshlrev_b32_e32 v92, 16, v202
	v_and_b32_e32 v93, 0xffff0000, v202
	v_lshlrev_b32_e32 v94, 16, v204
	v_and_b32_e32 v95, 0xffff0000, v204
	v_lshlrev_b32_e32 v204, 16, v205
	v_and_b32_e32 v205, 0xffff0000, v205
	v_lshlrev_b32_e32 v96, 16, v206
	v_and_b32_e32 v97, 0xffff0000, v206
	v_lshlrev_b32_e32 v202, 16, v203
	v_and_b32_e32 v203, 0xffff0000, v203
	v_lshlrev_b32_e32 v206, 16, v207
	v_and_b32_e32 v207, 0xffff0000, v207
	v_lshlrev_b32_e32 v98, 16, v208
	v_and_b32_e32 v99, 0xffff0000, v208
	v_lshlrev_b32_e32 v208, 16, v209
	v_and_b32_e32 v209, 0xffff0000, v209
	v_pk_add_f32 v[76:77], v[76:77], v[92:93]
	v_pk_add_f32 v[74:75], v[74:75], v[204:205]
	v_pk_add_f32 v[204:205], v[68:69], v[96:97]
	v_pk_add_f32 v[78:79], v[78:79], v[202:203]
	v_pk_add_f32 v[202:203], v[70:71], v[206:207]
	v_pk_add_f32 v[206:207], v[66:67], v[208:209]
	v_pk_add_f32 v[208:209], v[64:65], v[98:99]
	v_cvt_pk_bf16_f32 v64, v76, v77
	v_mul_f32_e32 v77, v77, v77
	v_cvt_pk_bf16_f32 v68, v204, v205
	v_mul_f32_e32 v205, v205, v205
	v_fmac_f32_e32 v77, v76, v76
	v_fmac_f32_e32 v205, v204, v204
	v_fmac_f32_e32 v77, v78, v78
	v_fmac_f32_e32 v205, v202, v202
	v_pk_add_f32 v[72:73], v[72:73], v[94:95]
	v_fmac_f32_e32 v77, v79, v79
	v_fmac_f32_e32 v205, v203, v203
	v_fmac_f32_e32 v77, v72, v72
	v_fmac_f32_e32 v205, v208, v208
	v_fmac_f32_e32 v77, v73, v73
	v_fmac_f32_e32 v205, v209, v209
	v_fmac_f32_e32 v77, v74, v74
	v_fmac_f32_e32 v205, v206, v206
	v_cvt_pk_bf16_f32 v65, v78, v79
	v_cvt_pk_bf16_f32 v66, v72, v73
	v_cvt_pk_bf16_f32 v67, v74, v75
	v_fmac_f32_e32 v77, v75, v75
	v_fmac_f32_e32 v205, v207, v207
	global_store_dwordx4 v[210:211], v[64:67], off
	v_cvt_pk_bf16_f32 v69, v202, v203
	v_cvt_pk_bf16_f32 v70, v208, v209
	v_add_f32_e32 v64, v77, v205
	v_mov_b32_e32 v65, v64
	s_nop 1
	v_permlane16_swap_b32_e32 v64, v65
	v_add_f32_e32 v64, v64, v65
	v_mov_b32_e32 v65, v64
	v_cvt_pk_bf16_f32 v71, v206, v207
	s_nop 0
	v_permlane32_swap_b32_e32 v64, v65
	global_store_dwordx4 v[210:211], v[68:71], off offset:256
	s_and_saveexec_b64 s[20:21], s[4:5]
	s_cbranch_execz .LBB0_1925
	v_add_f32_e32 v64, v64, v65
	v_mul_f32_e32 v64, 0x49800000, v64
	v_trunc_f32_e32 v64, v64
	v_mul_f32_e32 v65, 0x2f800000, v64
	v_floor_f32_e32 v65, v65
	v_fmac_f32_e32 v64, 0xcf800000, v65
	v_cvt_u32_f32_e32 v64, v64
	v_cvt_u32_f32_e32 v65, v65
	v_lshl_add_u64 v[66:67], v[80:81], 3, s[10:11]
	global_atomic_add_x2 v[66:67], v[64:65], off
.LBB0_1925:
	s_or_b64 exec, exec, s[20:21]
	v_add_u32_e32 v64, 0x80, v146
	v_ashrrev_i32_e32 v65, 31, v64
	s_waitcnt vmcnt(14)
	v_lshlrev_b32_e32 v76, 16, v212
	v_and_b32_e32 v77, 0xffff0000, v212
	v_lshlrev_b32_e32 v78, 16, v214
	v_and_b32_e32 v79, 0xffff0000, v214
	v_lshlrev_b32_e32 v214, 16, v215
	v_and_b32_e32 v215, 0xffff0000, v215
	v_lshlrev_b32_e32 v80, 16, v216
	v_and_b32_e32 v81, 0xffff0000, v216
	v_lshlrev_b32_e32 v212, 16, v213
	v_and_b32_e32 v213, 0xffff0000, v213
	v_lshlrev_b32_e32 v216, 16, v217
	v_and_b32_e32 v217, 0xffff0000, v217
	v_lshlrev_b32_e32 v82, 16, v218
	v_and_b32_e32 v83, 0xffff0000, v218
	v_lshlrev_b32_e32 v218, 16, v219
	v_and_b32_e32 v219, 0xffff0000, v219
	v_pk_add_f32 v[60:61], v[60:61], v[76:77]
	v_pk_add_f32 v[58:59], v[58:59], v[214:215]
	v_pk_add_f32 v[214:215], v[52:53], v[80:81]
	v_pk_add_f32 v[62:63], v[62:63], v[212:213]
	v_pk_add_f32 v[212:213], v[54:55], v[216:217]
	v_pk_add_f32 v[216:217], v[50:51], v[218:219]
	v_pk_add_f32 v[218:219], v[48:49], v[82:83]
	v_cvt_pk_bf16_f32 v48, v60, v61
	v_mul_f32_e32 v61, v61, v61
	v_cvt_pk_bf16_f32 v52, v214, v215
	v_mul_f32_e32 v215, v215, v215
	v_fmac_f32_e32 v61, v60, v60
	v_fmac_f32_e32 v215, v214, v214
	v_fmac_f32_e32 v61, v62, v62
	v_fmac_f32_e32 v215, v212, v212
	v_pk_add_f32 v[56:57], v[56:57], v[78:79]
	v_fmac_f32_e32 v61, v63, v63
	v_fmac_f32_e32 v215, v213, v213
	v_fmac_f32_e32 v61, v56, v56
	v_fmac_f32_e32 v215, v218, v218
	v_fmac_f32_e32 v61, v57, v57
	v_fmac_f32_e32 v215, v219, v219
	v_fmac_f32_e32 v61, v58, v58
	v_fmac_f32_e32 v215, v216, v216
	v_cvt_pk_bf16_f32 v49, v62, v63
	v_cvt_pk_bf16_f32 v50, v56, v57
	v_cvt_pk_bf16_f32 v51, v58, v59
	v_fmac_f32_e32 v61, v59, v59
	v_fmac_f32_e32 v215, v217, v217
	global_store_dwordx4 v[220:221], v[48:51], off
	v_cvt_pk_bf16_f32 v53, v212, v213
	v_cvt_pk_bf16_f32 v54, v218, v219
	v_add_f32_e32 v48, v61, v215
	v_mov_b32_e32 v49, v48
	s_nop 1
	v_permlane16_swap_b32_e32 v48, v49
	v_add_f32_e32 v48, v48, v49
	v_mov_b32_e32 v49, v48
	v_cvt_pk_bf16_f32 v55, v216, v217
	s_nop 0
	v_permlane32_swap_b32_e32 v48, v49
	global_store_dwordx4 v[220:221], v[52:55], off offset:256
	s_and_saveexec_b64 s[20:21], s[4:5]
	s_cbranch_execz .LBB0_1927
	v_add_f32_e32 v48, v48, v49
	v_mul_f32_e32 v48, 0x49800000, v48
	v_trunc_f32_e32 v48, v48
	v_mul_f32_e32 v49, 0x2f800000, v48
	v_floor_f32_e32 v49, v49
	v_fmac_f32_e32 v48, 0xcf800000, v49
	v_cvt_u32_f32_e32 v48, v48
	v_cvt_u32_f32_e32 v49, v49
	v_lshl_add_u64 v[50:51], v[64:65], 3, s[10:11]
	global_atomic_add_x2 v[50:51], v[48:49], off
; DI unsigned pk2(float lo, float hi) { f32x2 v = {lo, hi}; bf16x2_t b = __builtin_convertvector(v, bf16x2_t); return __builtin_bit_cast(unsigned, b); }
; DI float bflo(unsigned u) { return __uint_as_float(u << 16); }
; DI float bfhi(unsigned u) { return __uint_as_float(u & 0xffff0000u); }
; DI u64 ss_to_fix(float ss) { return (u64)(ss * 1048576.f); }
;     DI void operator()(const AccT& acc, const Unit& u, int wr, int wc, int fr, int fq) const {
;     ...
;             for (int m = 0; m < 4; ++m) { const int t = row0 + ai * 128 + m * 16; float ss = 0.f;
; #pragma unroll
;                 for (int bj = 0; bj < 2; ++bj) { const size_t o = (size_t)t * 1024 + col0 + bj * 128;
;                     f32x4 r0, r1;
;                     if (RESBF) { const u32x4 rb = *(const u32x4*)(XB + o); r0 = (f32x4){bflo(rb.x), bfhi(rb.x), bflo(rb.y), bfhi(rb.y)}; r1 = (f32x4){bflo(rb.z), bfhi(rb.z), bflo(rb.w), bfhi(rb.w)}; }
;                     else { r0 = __builtin_nontemporal_load((const f32x4*)(res + o)); r1 = __builtin_nontemporal_load((const f32x4*)(res + o + 4)); }
;                     const f32x4 v0 = acc[ai][bj][m][0] + r0, v1 = acc[ai][bj][m][1] + r1;
;                     u32x4 w; w.x = pk2(v0[0], v0[1]); w.y = pk2(v0[2], v0[3]); w.z = pk2(v1[0], v1[1]); w.w = pk2(v1[2], v1[3]);
;                     if (!dry) *(u32x4*)(XB + o) = w;
;                     ss += v0[0] * v0[0] + v0[1] * v0[1] + v0[2] * v0[2] + v0[3] * v0[3] + v1[0] * v1[0] + v1[1] * v1[1] + v1[2] * v1[2] + v1[3] * v1[3]; }
;                 { const auto r16 = __builtin_amdgcn_permlane16_swap(__float_as_uint(ss), __float_as_uint(ss), false, false); ss = __uint_as_float(r16[0]) + __uint_as_float(r16[1]);
;                   const auto r32 = __builtin_amdgcn_permlane32_swap(__float_as_uint(ss), __float_as_uint(ss), false, false); ss = __uint_as_float(r32[0]) + __uint_as_float(r32[1]); }
;                 if (fq == 0 && !dry) atomicAdd(rowss + t, ss_to_fix(ss)); }
.LBB0_1927:
	s_or_b64 exec, exec, s[20:21]
	v_add_u32_e32 v48, 0x90, v146
	v_ashrrev_i32_e32 v49, 31, v48
	s_waitcnt vmcnt(14)
	v_lshlrev_b32_e32 v60, 16, v222
	v_and_b32_e32 v61, 0xffff0000, v222
	v_lshlrev_b32_e32 v62, 16, v224
	v_and_b32_e32 v63, 0xffff0000, v224
	v_lshlrev_b32_e32 v224, 16, v225
	v_and_b32_e32 v225, 0xffff0000, v225
	v_lshlrev_b32_e32 v64, 16, v226
	v_and_b32_e32 v65, 0xffff0000, v226
	v_lshlrev_b32_e32 v222, 16, v223
	v_and_b32_e32 v223, 0xffff0000, v223
	v_lshlrev_b32_e32 v226, 16, v227
	v_and_b32_e32 v227, 0xffff0000, v227
	v_lshlrev_b32_e32 v66, 16, v228
	v_and_b32_e32 v67, 0xffff0000, v228
	v_lshlrev_b32_e32 v228, 16, v229
	v_and_b32_e32 v229, 0xffff0000, v229
	v_pk_add_f32 v[44:45], v[44:45], v[60:61]
	v_pk_add_f32 v[42:43], v[42:43], v[224:225]
	v_pk_add_f32 v[224:225], v[36:37], v[64:65]
	v_pk_add_f32 v[46:47], v[46:47], v[222:223]
	v_pk_add_f32 v[222:223], v[38:39], v[226:227]
	v_pk_add_f32 v[226:227], v[34:35], v[228:229]
	v_pk_add_f32 v[228:229], v[32:33], v[66:67]
	v_cvt_pk_bf16_f32 v32, v44, v45
	v_mul_f32_e32 v45, v45, v45
	v_cvt_pk_bf16_f32 v36, v224, v225
	v_mul_f32_e32 v225, v225, v225
	v_fmac_f32_e32 v45, v44, v44
	v_fmac_f32_e32 v225, v224, v224
	v_fmac_f32_e32 v45, v46, v46
	v_fmac_f32_e32 v225, v222, v222
	v_pk_add_f32 v[40:41], v[40:41], v[62:63]
	v_fmac_f32_e32 v45, v47, v47
	v_fmac_f32_e32 v225, v223, v223
	v_fmac_f32_e32 v45, v40, v40
	v_fmac_f32_e32 v225, v228, v228
	v_fmac_f32_e32 v45, v41, v41
	v_fmac_f32_e32 v225, v229, v229
	v_fmac_f32_e32 v45, v42, v42
	v_fmac_f32_e32 v225, v226, v226
	v_cvt_pk_bf16_f32 v33, v46, v47
	v_cvt_pk_bf16_f32 v34, v40, v41
	v_cvt_pk_bf16_f32 v35, v42, v43
	v_fmac_f32_e32 v45, v43, v43
	v_fmac_f32_e32 v225, v227, v227
	global_store_dwordx4 v[230:231], v[32:35], off
	v_cvt_pk_bf16_f32 v37, v222, v223
	v_cvt_pk_bf16_f32 v38, v228, v229
	v_add_f32_e32 v32, v45, v225
	v_mov_b32_e32 v33, v32
	s_nop 1
	v_permlane16_swap_b32_e32 v32, v33
	v_add_f32_e32 v32, v32, v33
	v_mov_b32_e32 v33, v32
	v_cvt_pk_bf16_f32 v39, v226, v227
	s_nop 0
	v_permlane32_swap_b32_e32 v32, v33
	global_store_dwordx4 v[230:231], v[36:39], off offset:256
	s_and_saveexec_b64 s[20:21], s[4:5]
	s_cbranch_execz .LBB0_1929
	v_add_f32_e32 v32, v32, v33
	v_mul_f32_e32 v32, 0x49800000, v32
	v_trunc_f32_e32 v32, v32
	v_mul_f32_e32 v33, 0x2f800000, v32
	v_floor_f32_e32 v33, v33
	v_fmac_f32_e32 v32, 0xcf800000, v33
	v_cvt_u32_f32_e32 v32, v32
	v_cvt_u32_f32_e32 v33, v33
	v_lshl_add_u64 v[34:35], v[48:49], 3, s[10:11]
	global_atomic_add_x2 v[34:35], v[32:33], off
; DI unsigned pk2(float lo, float hi) { f32x2 v = {lo, hi}; bf16x2_t b = __builtin_convertvector(v, bf16x2_t); return __builtin_bit_cast(unsigned, b); }
; DI float bflo(unsigned u) { return __uint_as_float(u << 16); }
; DI float bfhi(unsigned u) { return __uint_as_float(u & 0xffff0000u); }
; DI u64 ss_to_fix(float ss) { return (u64)(ss * 1048576.f); }
;     DI void operator()(const AccT& acc, const Unit& u, int wr, int wc, int fr, int fq) const {
;     ...
;             for (int m = 0; m < 4; ++m) { const int t = row0 + ai * 128 + m * 16; float ss = 0.f;
; #pragma unroll
;                 for (int bj = 0; bj < 2; ++bj) { const size_t o = (size_t)t * 1024 + col0 + bj * 128;
;                     f32x4 r0, r1;
;                     if (RESBF) { const u32x4 rb = *(const u32x4*)(XB + o); r0 = (f32x4){bflo(rb.x), bfhi(rb.x), bflo(rb.y), bfhi(rb.y)}; r1 = (f32x4){bflo(rb.z), bfhi(rb.z), bflo(rb.w), bfhi(rb.w)}; }
;                     else { r0 = __builtin_nontemporal_load((const f32x4*)(res + o)); r1 = __builtin_nontemporal_load((const f32x4*)(res + o + 4)); }
;                     const f32x4 v0 = acc[ai][bj][m][0] + r0, v1 = acc[ai][bj][m][1] + r1;
;                     u32x4 w; w.x = pk2(v0[0], v0[1]); w.y = pk2(v0[2], v0[3]); w.z = pk2(v1[0], v1[1]); w.w = pk2(v1[2], v1[3]);
;                     if (!dry) *(u32x4*)(XB + o) = w;
;                     ss += v0[0] * v0[0] + v0[1] * v0[1] + v0[2] * v0[2] + v0[3] * v0[3] + v1[0] * v1[0] + v1[1] * v1[1] + v1[2] * v1[2] + v1[3] * v1[3]; }
;                 { const auto r16 = __builtin_amdgcn_permlane16_swap(__float_as_uint(ss), __float_as_uint(ss), false, false); ss = __uint_as_float(r16[0]) + __uint_as_float(r16[1]);
;                   const auto r32 = __builtin_amdgcn_permlane32_swap(__float_as_uint(ss), __float_as_uint(ss), false, false); ss = __uint_as_float(r32[0]) + __uint_as_float(r32[1]); }
;                 if (fq == 0 && !dry) atomicAdd(rowss + t, ss_to_fix(ss)); }
.LBB0_1929:
	s_or_b64 exec, exec, s[20:21]
	v_add_u32_e32 v32, 0xa0, v146
	v_ashrrev_i32_e32 v33, 31, v32
	s_waitcnt vmcnt(14)
	v_lshlrev_b32_e32 v44, 16, v232
	v_and_b32_e32 v45, 0xffff0000, v232
	v_lshlrev_b32_e32 v46, 16, v234
	v_and_b32_e32 v47, 0xffff0000, v234
	v_lshlrev_b32_e32 v234, 16, v235
	v_and_b32_e32 v235, 0xffff0000, v235
	v_lshlrev_b32_e32 v48, 16, v236
	v_and_b32_e32 v49, 0xffff0000, v236
	v_lshlrev_b32_e32 v232, 16, v233
	v_and_b32_e32 v233, 0xffff0000, v233
	v_lshlrev_b32_e32 v236, 16, v237
	v_and_b32_e32 v237, 0xffff0000, v237
	v_lshlrev_b32_e32 v50, 16, v238
	v_and_b32_e32 v51, 0xffff0000, v238
	v_lshlrev_b32_e32 v238, 16, v239
	v_and_b32_e32 v239, 0xffff0000, v239
	v_pk_add_f32 v[28:29], v[28:29], v[44:45]
	v_pk_add_f32 v[26:27], v[26:27], v[234:235]
	v_pk_add_f32 v[234:235], v[20:21], v[48:49]
	v_pk_add_f32 v[30:31], v[30:31], v[232:233]
	v_pk_add_f32 v[232:233], v[22:23], v[236:237]
	v_pk_add_f32 v[236:237], v[18:19], v[238:239]
	v_pk_add_f32 v[238:239], v[16:17], v[50:51]
	v_cvt_pk_bf16_f32 v16, v28, v29
	v_mul_f32_e32 v29, v29, v29
	v_cvt_pk_bf16_f32 v20, v234, v235
	v_mul_f32_e32 v235, v235, v235
	v_fmac_f32_e32 v29, v28, v28
	v_fmac_f32_e32 v235, v234, v234
	v_fmac_f32_e32 v29, v30, v30
	v_fmac_f32_e32 v235, v232, v232
	v_pk_add_f32 v[24:25], v[24:25], v[46:47]
	v_fmac_f32_e32 v29, v31, v31
	v_fmac_f32_e32 v235, v233, v233
	v_fmac_f32_e32 v29, v24, v24
	v_fmac_f32_e32 v235, v238, v238
	v_fmac_f32_e32 v29, v25, v25
	v_fmac_f32_e32 v235, v239, v239
	v_fmac_f32_e32 v29, v26, v26
	v_fmac_f32_e32 v235, v236, v236
	v_cvt_pk_bf16_f32 v17, v30, v31
	v_cvt_pk_bf16_f32 v18, v24, v25
	v_cvt_pk_bf16_f32 v19, v26, v27
	v_fmac_f32_e32 v29, v27, v27
	v_fmac_f32_e32 v235, v237, v237
	global_store_dwordx4 v[242:243], v[16:19], off
	v_cvt_pk_bf16_f32 v21, v232, v233
	v_cvt_pk_bf16_f32 v22, v238, v239
	v_add_f32_e32 v16, v29, v235
	v_mov_b32_e32 v17, v16
	s_nop 1
	v_permlane16_swap_b32_e32 v16, v17
	v_add_f32_e32 v16, v16, v17
	v_mov_b32_e32 v17, v16
	v_cvt_pk_bf16_f32 v23, v236, v237
	s_nop 0
	v_permlane32_swap_b32_e32 v16, v17
	global_store_dwordx4 v[242:243], v[20:23], off offset:256
	s_and_saveexec_b64 s[20:21], s[4:5]
	s_cbranch_execz .LBB0_1931
	v_add_f32_e32 v16, v16, v17
	v_mul_f32_e32 v16, 0x49800000, v16
	v_trunc_f32_e32 v16, v16
	v_mul_f32_e32 v17, 0x2f800000, v16
	v_floor_f32_e32 v17, v17
	v_fmac_f32_e32 v16, 0xcf800000, v17
	v_cvt_u32_f32_e32 v16, v16
	v_cvt_u32_f32_e32 v17, v17
	v_lshl_add_u64 v[18:19], v[32:33], 3, s[10:11]
	global_atomic_add_x2 v[18:19], v[16:17], off
.LBB0_1931:
	s_or_b64 exec, exec, s[20:21]
	v_add_u32_e32 v16, 0xb0, v146
	v_ashrrev_i32_e32 v17, 31, v16
	s_waitcnt vmcnt(14)
	v_lshlrev_b32_e32 v28, 16, v244
	v_and_b32_e32 v29, 0xffff0000, v244
	v_lshlrev_b32_e32 v30, 16, v246
	v_and_b32_e32 v31, 0xffff0000, v246
	v_lshlrev_b32_e32 v246, 16, v247
	v_and_b32_e32 v247, 0xffff0000, v247
	v_lshlrev_b32_e32 v32, 16, v248
	v_and_b32_e32 v33, 0xffff0000, v248
	v_lshlrev_b32_e32 v244, 16, v245
	v_and_b32_e32 v245, 0xffff0000, v245
	v_lshlrev_b32_e32 v248, 16, v249
	v_and_b32_e32 v249, 0xffff0000, v249
	v_lshlrev_b32_e32 v34, 16, v250
	v_and_b32_e32 v35, 0xffff0000, v250
	v_lshlrev_b32_e32 v250, 16, v251
	v_and_b32_e32 v251, 0xffff0000, v251
	v_pk_add_f32 v[12:13], v[12:13], v[28:29]
	v_pk_add_f32 v[10:11], v[10:11], v[246:247]
	v_pk_add_f32 v[246:247], v[4:5], v[32:33]
	v_pk_add_f32 v[14:15], v[14:15], v[244:245]
	v_pk_add_f32 v[244:245], v[6:7], v[248:249]
	v_pk_add_f32 v[248:249], v[2:3], v[250:251]
	v_pk_add_f32 v[250:251], v[0:1], v[34:35]
	v_cvt_pk_bf16_f32 v0, v12, v13
	v_mul_f32_e32 v13, v13, v13
	v_cvt_pk_bf16_f32 v4, v246, v247
	v_mul_f32_e32 v247, v247, v247
	v_fmac_f32_e32 v13, v12, v12
	v_fmac_f32_e32 v247, v246, v246
	v_fmac_f32_e32 v13, v14, v14
	v_fmac_f32_e32 v247, v244, v244
	v_pk_add_f32 v[8:9], v[8:9], v[30:31]
	v_fmac_f32_e32 v13, v15, v15
	v_fmac_f32_e32 v247, v245, v245
	v_fmac_f32_e32 v13, v8, v8
	v_fmac_f32_e32 v247, v250, v250
	v_fmac_f32_e32 v13, v9, v9
	v_fmac_f32_e32 v247, v251, v251
	v_fmac_f32_e32 v13, v10, v10
	v_fmac_f32_e32 v247, v248, v248
	v_cvt_pk_bf16_f32 v1, v14, v15
	v_cvt_pk_bf16_f32 v2, v8, v9
	v_cvt_pk_bf16_f32 v3, v10, v11
	v_fmac_f32_e32 v13, v11, v11
	v_fmac_f32_e32 v247, v249, v249
	global_store_dwordx4 v[252:253], v[0:3], off
	v_cvt_pk_bf16_f32 v5, v244, v245
	v_cvt_pk_bf16_f32 v6, v250, v251
	v_add_f32_e32 v0, v13, v247
	v_mov_b32_e32 v1, v0
	s_nop 1
	v_permlane16_swap_b32_e32 v0, v1
	v_add_f32_e32 v0, v0, v1
	v_mov_b32_e32 v1, v0
	v_cvt_pk_bf16_f32 v7, v248, v249
	s_nop 0
	v_permlane32_swap_b32_e32 v0, v1
	global_store_dwordx4 v[252:253], v[4:7], off offset:256
	s_and_saveexec_b64 s[20:21], s[4:5]
	s_cbranch_execz .LBB0_1933
	v_add_f32_e32 v0, v0, v1
	v_mul_f32_e32 v0, 0x49800000, v0
	v_trunc_f32_e32 v0, v0
	v_mul_f32_e32 v1, 0x2f800000, v0
	v_floor_f32_e32 v1, v1
	v_fmac_f32_e32 v0, 0xcf800000, v1
	v_cvt_u32_f32_e32 v0, v0
	v_cvt_u32_f32_e32 v1, v1
	v_lshl_add_u64 v[2:3], v[16:17], 3, s[10:11]
	global_atomic_add_x2 v[2:3], v[0:1], off

; __global__ void __launch_bounds__(512, 2) fwd_kernel(Args a_unused) {
	.amdhsa_kernel _Z10fwd_kernel4Args
		.amdhsa_group_segment_fixed_size 0
		.amdhsa_private_segment_fixed_size 0
		.amdhsa_kernarg_size 504
		.amdhsa_user_sgpr_count 2
		.amdhsa_user_sgpr_dispatch_ptr 0
		.amdhsa_user_sgpr_queue_ptr 0
		.amdhsa_user_sgpr_kernarg_segment_ptr 1
		.amdhsa_user_sgpr_dispatch_id 0
		.amdhsa_user_sgpr_kernarg_preload_length 0
		.amdhsa_user_sgpr_kernarg_preload_offset 0
		.amdhsa_user_sgpr_private_segment_size 0
		.amdhsa_uses_dynamic_stack 0
		.amdhsa_enable_private_segment 0
		.amdhsa_system_sgpr_workgroup_id_x 1
		.amdhsa_system_sgpr_workgroup_id_y 0
		.amdhsa_system_sgpr_workgroup_id_z 0
		.amdhsa_system_sgpr_workgroup_info 0
		.amdhsa_system_vgpr_workitem_id 2
		.amdhsa_next_free_vgpr 256
		.amdhsa_next_free_sgpr 98
		.amdhsa_accum_offset 256
		.amdhsa_reserve_vcc 1
		.amdhsa_float_round_mode_32 0
		.amdhsa_float_round_mode_16_64 0
		.amdhsa_float_denorm_mode_32 3
		.amdhsa_float_denorm_mode_16_64 3
		.amdhsa_dx10_clamp 1
		.amdhsa_ieee_mode 1
		.amdhsa_fp16_overflow 0
		.amdhsa_tg_split 0
		.amdhsa_exception_fp_ieee_invalid_op 0
		.amdhsa_exception_fp_denorm_src 0
		.amdhsa_exception_fp_ieee_div_zero 0
		.amdhsa_exception_fp_ieee_overflow 0
		.amdhsa_exception_fp_ieee_underflow 0
		.amdhsa_exception_fp_ieee_inexact 0
		.amdhsa_exception_int_div_zero 0
	.end_amdhsa_kernel

; __global__ void __launch_bounds__(512, 2) fwd_kernel(Args a_unused) {
amdhsa.kernels:
  - .agpr_count:     0
    .args:
      - .offset:         0
        .size:           248
        .value_kind:     by_value
      - .offset:         248
        .size:           4
        .value_kind:     hidden_block_count_x
      - .offset:         252
        .size:           4
        .value_kind:     hidden_block_count_y
      - .offset:         256
        .size:           4
        .value_kind:     hidden_block_count_z
      - .offset:         260
        .size:           2
        .value_kind:     hidden_group_size_x
      - .offset:         262
        .size:           2
        .value_kind:     hidden_group_size_y
      - .offset:         264
        .size:           2
        .value_kind:     hidden_group_size_z
      - .offset:         266
        .size:           2
        .value_kind:     hidden_remainder_x
      - .offset:         268
        .size:           2
        .value_kind:     hidden_remainder_y
      - .offset:         270
        .size:           2
        .value_kind:     hidden_remainder_z
      - .offset:         288
        .size:           8
        .value_kind:     hidden_global_offset_x
      - .offset:         296
        .size:           8
        .value_kind:     hidden_global_offset_y
      - .offset:         304
        .size:           8
        .value_kind:     hidden_global_offset_z
      - .offset:         312
        .size:           2
        .value_kind:     hidden_grid_dims
      - .offset:         336
        .size:           8
        .value_kind:     hidden_multigrid_sync_arg
      - .offset:         368
        .size:           4
        .value_kind:     hidden_dynamic_lds_size
    .group_segment_fixed_size: 0
    .kernarg_segment_align: 8
    .kernarg_segment_size: 504
    .language:       OpenCL C
    .language_version:
      - 2
      - 0
    .max_flat_workgroup_size: 512
    .name:           _Z10fwd_kernel4Args
    .private_segment_fixed_size: 0
    .sgpr_count:     104
    .sgpr_spill_count: 24
    .symbol:         _Z10fwd_kernel4Args.kd
    .uniform_work_group_size: 1
    .uses_dynamic_stack: false
    .vgpr_count:     256
    .vgpr_spill_count: 0
    .wavefront_size: 64
